# GEMM kind-0 dt epilogue: dt bias loaded once per column group instead of once per accumulator element (each reload waited for all outstanding memory ops)
# speedup vs baseline: 1.2169x; 1.0082x over previous
.LBB0_1080:
	s_cmp_lg_u64 s[34:35], 0
	s_cselect_b64 s[4:5], -1, 0
	s_waitcnt vmcnt(7)
	v_add_u32_e32 v66, s11, v113
	v_cndmask_b32_e64 v69, 0, 1, s[4:5]
	s_waitcnt vmcnt(5)
	v_add_u32_e32 v74, s29, v115
	v_cmp_gt_i32_e64 s[6:7], s52, v66
	v_ashrrev_i32_e32 v67, 31, v66
	v_add_u32_e32 v68, s80, v66
	v_cmp_ne_u32_e64 s[4:5], 1, v69
	s_and_saveexec_b64 s[8:9], s[6:7]
	s_cbranch_execz .LBB0_1101
	v_ashrrev_i32_e32 v69, 31, v68
	s_and_b64 vcc, exec, s[4:5]
	v_lshl_add_u64 v[70:71], v[66:67], 2, s[34:35]
	s_cbranch_vccnz .LBB0_1673
	s_andn2_b64 vcc, exec, s[36:37]
	v_mov_b32_e32 v72, v62
	s_cbranch_vccnz .LBB0_1084
	s_load_dwordx2 s[10:11], s[14:15], 0xb0
	s_waitcnt lgkmcnt(0)
	v_lshl_add_u64 v[72:73], v[68:69], 2, s[10:11]
	global_load_dword v72, v[72:73], off
	s_waitcnt vmcnt(0)
	v_mov_b32_e32 v248, v72
	v_add_f32_e32 v73, v62, v72
	v_max_f32_e32 v72, 0, v73
	v_mul_f32_e64 v73, |v73|, s73
	v_exp_f32_e32 v73, v73
	s_nop 0
	v_add_f32_e32 v75, 1.0, v73
	v_add_f32_e32 v76, -1.0, v75
	v_sub_f32_e32 v77, v76, v75
	v_add_f32_e32 v77, 1.0, v77
	v_sub_f32_e32 v76, v73, v76
	v_add_f32_e32 v78, v76, v77
	v_frexp_mant_f32_e32 v76, v75
	v_cmp_gt_f32_e32 vcc, s46, v76
	v_cvt_f64_f32_e32 v[76:77], v75
	v_frexp_exp_i32_f64_e32 v76, v[76:77]
	v_subbrev_co_u32_e32 v84, vcc, 0, v76, vcc
	v_sub_u32_e32 v76, 0, v84
	v_ldexp_f32 v75, v75, v76
	v_ldexp_f32 v76, v78, v76
	v_add_f32_e32 v78, -1.0, v75
	v_add_f32_e32 v77, 1.0, v78
	v_sub_f32_e32 v77, v75, v77
	v_add_f32_e32 v79, v76, v77
	v_add_f32_e32 v77, 1.0, v75
	v_add_f32_e32 v80, -1.0, v77
	v_sub_f32_e32 v75, v75, v80
	v_add_f32_e32 v75, v76, v75
	v_add_f32_e32 v85, v77, v75
	v_rcp_f32_e32 v86, v85
	v_sub_f32_e32 v76, v85, v77
	v_add_f32_e32 v77, v78, v79
	v_sub_f32_e32 v75, v75, v76
	v_mul_f32_e32 v88, v77, v86
	v_sub_f32_e32 v76, v77, v78
	v_mul_f32_e32 v78, v85, v88
	v_fma_f32 v80, v88, v85, -v78
	v_fmac_f32_e32 v80, v88, v75
	v_sub_f32_e32 v87, v79, v76
	v_add_f32_e32 v76, v78, v80
	v_sub_f32_e32 v79, v77, v76
	v_pk_add_f32 v[82:83], v[76:77], v[78:79] neg_lo:[0,1] neg_hi:[0,1]
	v_mov_b32_e32 v81, v76
	v_pk_add_f32 v[76:77], v[82:83], v[80:81] neg_lo:[0,1] neg_hi:[0,1]
	v_cmp_neq_f32_e32 vcc, s0, v73
	v_add_f32_e32 v77, v87, v77
	v_add_f32_e32 v76, v76, v77
	v_add_f32_e32 v77, v79, v76
	v_mul_f32_e32 v87, v86, v77
	v_mul_f32_e32 v78, v85, v87
	v_fma_f32 v80, v87, v85, -v78
	v_fmac_f32_e32 v80, v87, v75
	v_sub_f32_e32 v75, v79, v77
	v_add_f32_e32 v75, v76, v75
	v_add_f32_e32 v76, v78, v80
	v_sub_f32_e32 v79, v77, v76
	v_pk_add_f32 v[82:83], v[76:77], v[78:79] neg_lo:[0,1] neg_hi:[0,1]
	v_mov_b32_e32 v81, v76
	v_pk_add_f32 v[76:77], v[82:83], v[80:81] neg_lo:[0,1] neg_hi:[0,1]
	s_nop 0
	v_add_f32_e32 v75, v75, v77
	v_add_f32_e32 v75, v76, v75
	v_add_f32_e32 v77, v88, v87
	v_add_f32_e32 v75, v79, v75
	v_sub_f32_e32 v76, v77, v88
	v_mul_f32_e32 v75, v86, v75
	v_sub_f32_e32 v76, v87, v76
	v_add_f32_e32 v75, v76, v75
	v_add_f32_e32 v78, v77, v75
	v_mul_f32_e32 v80, v78, v78
	v_fmamk_f32 v76, v80, 0x3e9b6dac, v210
	v_fmaak_f32 v121, v80, v76, 0x3f2aaada
	v_cvt_f32_i32_e32 v76, v84
	v_sub_f32_e32 v77, v78, v77
	v_sub_f32_e32 v75, v75, v77
	v_mul_f32_e32 v77, v78, v80
	v_pk_mul_f32 v[80:81], v[76:77], v[120:121]
	v_ldexp_f32 v79, v78, 1
	v_fma_f32 v78, v76, s1, -v80
	v_fmac_f32_e32 v78, 0xb102e308, v76
	v_pk_add_f32 v[76:77], v[80:81], v[78:79]
	v_ldexp_f32 v75, v75, 1
	v_sub_f32_e32 v79, v77, v79
	v_sub_f32_e32 v79, v81, v79
	v_add_f32_e32 v83, v75, v79
	v_mov_b32_e32 v82, v80
	v_pk_add_f32 v[80:81], v[76:77], v[80:81] neg_lo:[0,1] neg_hi:[0,1]
	v_pk_add_f32 v[84:85], v[76:77], v[82:83]
	v_mov_b32_e32 v79, v76
	v_mov_b32_e32 v81, v85
	v_pk_add_f32 v[86:87], v[78:79], v[80:81] neg_lo:[0,1] neg_hi:[0,1]
	v_pk_add_f32 v[78:79], v[78:79], v[80:81]
	v_mov_b32_e32 v82, v83
	v_pk_add_f32 v[80:81], v[78:79], v[76:77] op_sel:[1,0] op_sel_hi:[0,1] neg_lo:[0,1] neg_hi:[0,1]
	v_pk_add_f32 v[88:89], v[84:85], v[80:81] op_sel_hi:[1,0] neg_lo:[0,1] neg_hi:[0,1]
	v_mov_b32_e32 v84, v85
	v_mov_b32_e32 v85, v79
	v_pk_mov_b32 v[80:81], v[76:77], v[80:81] op_sel:[1,0]
	v_mov_b32_e32 v83, v76
	v_pk_add_f32 v[80:81], v[84:85], v[80:81] neg_lo:[0,1] neg_hi:[0,1]
	v_mov_b32_e32 v88, v86
	v_pk_add_f32 v[76:77], v[82:83], v[80:81] neg_lo:[0,1] neg_hi:[0,1]
	v_mov_b32_e32 v87, v79
	v_pk_add_f32 v[80:81], v[88:89], v[76:77]
	s_nop 0
	v_pk_add_f32 v[82:83], v[80:81], v[80:81] op_sel:[0,1] op_sel_hi:[1,0]
	s_nop 0
	v_pk_add_f32 v[78:79], v[78:79], v[82:83] op_sel:[1,0] op_sel_hi:[0,1]
	v_mov_b32_e32 v81, v78
	v_pk_add_f32 v[84:85], v[80:81], v[86:87] neg_lo:[0,1] neg_hi:[0,1]
	v_mov_b32_e32 v77, v82
	v_sub_f32_e32 v75, v80, v84
	v_pk_add_f32 v[76:77], v[76:77], v[84:85] neg_lo:[0,1] neg_hi:[0,1]
	v_sub_f32_e32 v75, v86, v75
	v_add_f32_e32 v75, v76, v75
	v_add_f32_e32 v75, v75, v77
	v_add_f32_e32 v75, v78, v75
	v_cndmask_b32_e32 v75, v224, v75, vcc
	v_cmp_ngt_f32_e32 vcc, -1.0, v73
	s_nop 1
	v_cndmask_b32_e32 v75, v225, v75, vcc
	v_cmp_neq_f32_e32 vcc, -1.0, v73
	s_nop 1
	v_cndmask_b32_e32 v75, v226, v75, vcc
	v_cmp_lt_f32_e64 vcc, |v73|, s56
	s_nop 1
	v_cndmask_b32_e32 v73, v75, v73, vcc
	v_add_f32_e32 v72, v72, v73

.LBB0_1086:
	s_and_b64 vcc, exec, s[4:5]
	v_or_b32_e32 v75, 1, v74
	s_cbranch_vccnz .LBB0_1674
	s_andn2_b64 vcc, exec, s[36:37]
	v_mov_b32_e32 v76, v63
	s_cbranch_vccnz .LBB0_1089
	s_nop 0
	s_waitcnt lgkmcnt(0)
	v_lshl_add_u64 v[76:77], v[68:69], 2, s[10:11]
	v_mov_b32_e32 v76, v248
	s_nop 0
	v_add_f32_e32 v77, v63, v76
	v_max_f32_e32 v76, 0, v77
	v_mul_f32_e64 v77, |v77|, s73
	v_exp_f32_e32 v77, v77
	s_nop 0
	v_add_f32_e32 v80, 1.0, v77
	v_add_f32_e32 v78, -1.0, v80
	v_sub_f32_e32 v79, v78, v80
	v_add_f32_e32 v79, 1.0, v79
	v_sub_f32_e32 v78, v77, v78
	v_add_f32_e32 v81, v78, v79
	v_frexp_mant_f32_e32 v78, v80
	v_cmp_gt_f32_e32 vcc, s46, v78
	v_cvt_f64_f32_e32 v[78:79], v80
	v_frexp_exp_i32_f64_e32 v78, v[78:79]
	v_subbrev_co_u32_e32 v86, vcc, 0, v78, vcc
	v_sub_u32_e32 v78, 0, v86
	v_ldexp_f32 v79, v80, v78
	v_add_f32_e32 v80, -1.0, v79
	v_add_f32_e32 v82, 1.0, v79
	v_ldexp_f32 v78, v81, v78
	v_add_f32_e32 v81, 1.0, v80
	v_add_f32_e32 v83, -1.0, v82
	v_sub_f32_e32 v81, v79, v81
	v_sub_f32_e32 v79, v79, v83
	v_add_f32_e32 v81, v78, v81
	v_add_f32_e32 v78, v78, v79
	v_add_f32_e32 v87, v82, v78
	v_rcp_f32_e32 v89, v87
	v_sub_f32_e32 v79, v87, v82
	v_sub_f32_e32 v88, v78, v79
	v_add_f32_e32 v79, v80, v81
	v_mul_f32_e32 v91, v79, v89
	v_sub_f32_e32 v78, v79, v80
	v_mul_f32_e32 v80, v87, v91
	v_fma_f32 v82, v91, v87, -v80
	v_fmac_f32_e32 v82, v91, v88
	v_sub_f32_e32 v90, v81, v78
	v_add_f32_e32 v78, v80, v82
	v_sub_f32_e32 v81, v79, v78
	v_pk_add_f32 v[84:85], v[78:79], v[80:81] neg_lo:[0,1] neg_hi:[0,1]
	v_mov_b32_e32 v83, v78
	v_pk_add_f32 v[78:79], v[84:85], v[82:83] neg_lo:[0,1] neg_hi:[0,1]
	v_cmp_neq_f32_e32 vcc, s0, v77
	v_add_f32_e32 v79, v90, v79
	v_add_f32_e32 v78, v78, v79
	v_add_f32_e32 v79, v81, v78
	v_mul_f32_e32 v90, v89, v79
	v_mul_f32_e32 v80, v87, v90
	v_fma_f32 v82, v90, v87, -v80
	v_fmac_f32_e32 v82, v90, v88
	v_sub_f32_e32 v81, v81, v79
	v_add_f32_e32 v87, v78, v81
	v_add_f32_e32 v78, v80, v82
	v_sub_f32_e32 v81, v79, v78
	v_pk_add_f32 v[84:85], v[78:79], v[80:81] neg_lo:[0,1] neg_hi:[0,1]
	v_mov_b32_e32 v83, v78
	v_pk_add_f32 v[78:79], v[84:85], v[82:83] neg_lo:[0,1] neg_hi:[0,1]
	s_nop 0
	v_add_f32_e32 v79, v87, v79
	v_add_f32_e32 v78, v78, v79
	v_add_f32_e32 v79, v91, v90
	v_add_f32_e32 v78, v81, v78
	v_sub_f32_e32 v80, v79, v91
	v_mul_f32_e32 v78, v89, v78
	v_sub_f32_e32 v80, v90, v80
	v_add_f32_e32 v80, v80, v78
	v_add_f32_e32 v82, v79, v80
	v_mul_f32_e32 v83, v82, v82
	v_fmamk_f32 v78, v83, 0x3e9b6dac, v210
	v_fmaak_f32 v121, v83, v78, 0x3f2aaada
	v_cvt_f32_i32_e32 v78, v86
	v_sub_f32_e32 v79, v82, v79
	v_sub_f32_e32 v79, v80, v79
	v_ldexp_f32 v84, v79, 1
	v_mul_f32_e32 v79, v82, v83
	v_ldexp_f32 v81, v82, 1
	v_pk_mul_f32 v[82:83], v[78:79], v[120:121]
	s_nop 0
	v_fma_f32 v80, v78, s1, -v82
	v_fmac_f32_e32 v80, 0xb102e308, v78
	v_pk_add_f32 v[78:79], v[82:83], v[80:81]
	s_nop 0
	v_sub_f32_e32 v81, v79, v81
	v_sub_f32_e32 v81, v83, v81
	v_add_f32_e32 v85, v84, v81
	v_mov_b32_e32 v84, v82
	v_pk_add_f32 v[82:83], v[78:79], v[82:83] neg_lo:[0,1] neg_hi:[0,1]
	v_pk_add_f32 v[86:87], v[78:79], v[84:85]
	v_mov_b32_e32 v81, v78
	v_mov_b32_e32 v83, v87
	v_pk_add_f32 v[88:89], v[80:81], v[82:83] neg_lo:[0,1] neg_hi:[0,1]
	v_pk_add_f32 v[80:81], v[80:81], v[82:83]
	v_mov_b32_e32 v84, v85
	v_pk_add_f32 v[82:83], v[80:81], v[78:79] op_sel:[1,0] op_sel_hi:[0,1] neg_lo:[0,1] neg_hi:[0,1]
	v_pk_add_f32 v[90:91], v[86:87], v[82:83] op_sel_hi:[1,0] neg_lo:[0,1] neg_hi:[0,1]
	v_mov_b32_e32 v86, v87
	v_mov_b32_e32 v87, v81
	v_pk_mov_b32 v[82:83], v[78:79], v[82:83] op_sel:[1,0]
	v_mov_b32_e32 v85, v78
	v_pk_add_f32 v[82:83], v[86:87], v[82:83] neg_lo:[0,1] neg_hi:[0,1]
	v_mov_b32_e32 v90, v88
	v_pk_add_f32 v[78:79], v[84:85], v[82:83] neg_lo:[0,1] neg_hi:[0,1]
	v_mov_b32_e32 v89, v81
	v_pk_add_f32 v[82:83], v[90:91], v[78:79]
	s_nop 0
	v_pk_add_f32 v[84:85], v[82:83], v[82:83] op_sel:[0,1] op_sel_hi:[1,0]
	s_nop 0
	v_pk_add_f32 v[80:81], v[80:81], v[84:85] op_sel:[1,0] op_sel_hi:[0,1]
	v_mov_b32_e32 v83, v80
	v_pk_add_f32 v[86:87], v[82:83], v[88:89] neg_lo:[0,1] neg_hi:[0,1]
	v_mov_b32_e32 v79, v84
	v_sub_f32_e32 v81, v82, v86
	v_pk_add_f32 v[78:79], v[78:79], v[86:87] neg_lo:[0,1] neg_hi:[0,1]
	v_sub_f32_e32 v81, v88, v81
	v_add_f32_e32 v78, v78, v81
	v_add_f32_e32 v78, v78, v79
	v_add_f32_e32 v78, v80, v78
	v_cndmask_b32_e32 v78, v224, v78, vcc
	v_cmp_ngt_f32_e32 vcc, -1.0, v77
	s_nop 1
	v_cndmask_b32_e32 v78, v225, v78, vcc
	v_cmp_neq_f32_e32 vcc, -1.0, v77
	s_nop 1
	v_cndmask_b32_e32 v78, v226, v78, vcc
	v_cmp_lt_f32_e64 vcc, |v77|, s56
	s_nop 1
	v_cndmask_b32_e32 v77, v78, v77, vcc
	v_add_f32_e32 v76, v76, v77

.LBB0_1091:
	s_and_b64 vcc, exec, s[4:5]
	v_or_b32_e32 v75, 2, v74
	s_cbranch_vccnz .LBB0_1675
	s_andn2_b64 vcc, exec, s[36:37]
	v_mov_b32_e32 v76, v64
	s_cbranch_vccnz .LBB0_1094
	s_nop 0
	s_waitcnt lgkmcnt(0)
	v_lshl_add_u64 v[76:77], v[68:69], 2, s[10:11]
	v_mov_b32_e32 v76, v248
	s_nop 0
	v_add_f32_e32 v77, v64, v76
	v_max_f32_e32 v76, 0, v77
	v_mul_f32_e64 v77, |v77|, s73
	v_exp_f32_e32 v77, v77
	s_nop 0
	v_add_f32_e32 v80, 1.0, v77
	v_add_f32_e32 v78, -1.0, v80
	v_sub_f32_e32 v79, v78, v80
	v_add_f32_e32 v79, 1.0, v79
	v_sub_f32_e32 v78, v77, v78
	v_add_f32_e32 v81, v78, v79
	v_frexp_mant_f32_e32 v78, v80
	v_cmp_gt_f32_e32 vcc, s46, v78
	v_cvt_f64_f32_e32 v[78:79], v80
	v_frexp_exp_i32_f64_e32 v78, v[78:79]
	v_subbrev_co_u32_e32 v86, vcc, 0, v78, vcc
	v_sub_u32_e32 v78, 0, v86
	v_ldexp_f32 v79, v80, v78
	v_add_f32_e32 v80, -1.0, v79
	v_add_f32_e32 v82, 1.0, v79
	v_ldexp_f32 v78, v81, v78
	v_add_f32_e32 v81, 1.0, v80
	v_add_f32_e32 v83, -1.0, v82
	v_sub_f32_e32 v81, v79, v81
	v_sub_f32_e32 v79, v79, v83
	v_add_f32_e32 v81, v78, v81
	v_add_f32_e32 v78, v78, v79
	v_add_f32_e32 v87, v82, v78
	v_rcp_f32_e32 v89, v87
	v_sub_f32_e32 v79, v87, v82
	v_sub_f32_e32 v88, v78, v79
	v_add_f32_e32 v79, v80, v81
	v_mul_f32_e32 v91, v79, v89
	v_sub_f32_e32 v78, v79, v80
	v_mul_f32_e32 v80, v87, v91
	v_fma_f32 v82, v91, v87, -v80
	v_fmac_f32_e32 v82, v91, v88
	v_sub_f32_e32 v90, v81, v78
	v_add_f32_e32 v78, v80, v82
	v_sub_f32_e32 v81, v79, v78
	v_pk_add_f32 v[84:85], v[78:79], v[80:81] neg_lo:[0,1] neg_hi:[0,1]
	v_mov_b32_e32 v83, v78
	v_pk_add_f32 v[78:79], v[84:85], v[82:83] neg_lo:[0,1] neg_hi:[0,1]
	v_cmp_neq_f32_e32 vcc, s0, v77
	v_add_f32_e32 v79, v90, v79
	v_add_f32_e32 v78, v78, v79
	v_add_f32_e32 v79, v81, v78
	v_mul_f32_e32 v90, v89, v79
	v_mul_f32_e32 v80, v87, v90
	v_fma_f32 v82, v90, v87, -v80
	v_fmac_f32_e32 v82, v90, v88
	v_sub_f32_e32 v81, v81, v79
	v_add_f32_e32 v87, v78, v81
	v_add_f32_e32 v78, v80, v82
	v_sub_f32_e32 v81, v79, v78
	v_pk_add_f32 v[84:85], v[78:79], v[80:81] neg_lo:[0,1] neg_hi:[0,1]
	v_mov_b32_e32 v83, v78
	v_pk_add_f32 v[78:79], v[84:85], v[82:83] neg_lo:[0,1] neg_hi:[0,1]
	s_nop 0
	v_add_f32_e32 v79, v87, v79
	v_add_f32_e32 v78, v78, v79
	v_add_f32_e32 v79, v91, v90
	v_add_f32_e32 v78, v81, v78
	v_sub_f32_e32 v80, v79, v91
	v_mul_f32_e32 v78, v89, v78
	v_sub_f32_e32 v80, v90, v80
	v_add_f32_e32 v80, v80, v78
	v_add_f32_e32 v82, v79, v80
	v_mul_f32_e32 v83, v82, v82
	v_fmamk_f32 v78, v83, 0x3e9b6dac, v210
	v_fmaak_f32 v121, v83, v78, 0x3f2aaada
	v_cvt_f32_i32_e32 v78, v86
	v_sub_f32_e32 v79, v82, v79
	v_sub_f32_e32 v79, v80, v79
	v_ldexp_f32 v84, v79, 1
	v_mul_f32_e32 v79, v82, v83
	v_ldexp_f32 v81, v82, 1
	v_pk_mul_f32 v[82:83], v[78:79], v[120:121]
	s_nop 0
	v_fma_f32 v80, v78, s1, -v82
	v_fmac_f32_e32 v80, 0xb102e308, v78
	v_pk_add_f32 v[78:79], v[82:83], v[80:81]
	s_nop 0
	v_sub_f32_e32 v81, v79, v81
	v_sub_f32_e32 v81, v83, v81
	v_add_f32_e32 v85, v84, v81
	v_mov_b32_e32 v84, v82
	v_pk_add_f32 v[82:83], v[78:79], v[82:83] neg_lo:[0,1] neg_hi:[0,1]
	v_pk_add_f32 v[86:87], v[78:79], v[84:85]
	v_mov_b32_e32 v81, v78
	v_mov_b32_e32 v83, v87
	v_pk_add_f32 v[88:89], v[80:81], v[82:83] neg_lo:[0,1] neg_hi:[0,1]
	v_pk_add_f32 v[80:81], v[80:81], v[82:83]
	v_mov_b32_e32 v84, v85
	v_pk_add_f32 v[82:83], v[80:81], v[78:79] op_sel:[1,0] op_sel_hi:[0,1] neg_lo:[0,1] neg_hi:[0,1]
	v_pk_add_f32 v[90:91], v[86:87], v[82:83] op_sel_hi:[1,0] neg_lo:[0,1] neg_hi:[0,1]
	v_mov_b32_e32 v86, v87
	v_mov_b32_e32 v87, v81
	v_pk_mov_b32 v[82:83], v[78:79], v[82:83] op_sel:[1,0]
	v_mov_b32_e32 v85, v78
	v_pk_add_f32 v[82:83], v[86:87], v[82:83] neg_lo:[0,1] neg_hi:[0,1]
	v_mov_b32_e32 v90, v88
	v_pk_add_f32 v[78:79], v[84:85], v[82:83] neg_lo:[0,1] neg_hi:[0,1]
	v_mov_b32_e32 v89, v81
	v_pk_add_f32 v[82:83], v[90:91], v[78:79]
	s_nop 0
	v_pk_add_f32 v[84:85], v[82:83], v[82:83] op_sel:[0,1] op_sel_hi:[1,0]
	s_nop 0
	v_pk_add_f32 v[80:81], v[80:81], v[84:85] op_sel:[1,0] op_sel_hi:[0,1]
	v_mov_b32_e32 v83, v80
	v_pk_add_f32 v[86:87], v[82:83], v[88:89] neg_lo:[0,1] neg_hi:[0,1]
	v_mov_b32_e32 v79, v84
	v_sub_f32_e32 v81, v82, v86
	v_pk_add_f32 v[78:79], v[78:79], v[86:87] neg_lo:[0,1] neg_hi:[0,1]
	v_sub_f32_e32 v81, v88, v81
	v_add_f32_e32 v78, v78, v81
	v_add_f32_e32 v78, v78, v79
	v_add_f32_e32 v78, v80, v78
	v_cndmask_b32_e32 v78, v224, v78, vcc
	v_cmp_ngt_f32_e32 vcc, -1.0, v77
	s_nop 1
	v_cndmask_b32_e32 v78, v225, v78, vcc
	v_cmp_neq_f32_e32 vcc, -1.0, v77
	s_nop 1
	v_cndmask_b32_e32 v78, v226, v78, vcc
	v_cmp_lt_f32_e64 vcc, |v77|, s56
	s_nop 1
	v_cndmask_b32_e32 v77, v78, v77, vcc
	v_add_f32_e32 v76, v76, v77

.LBB0_1096:
	s_and_b64 vcc, exec, s[4:5]
	v_or_b32_e32 v75, 3, v74
	s_cbranch_vccnz .LBB0_1676
	s_andn2_b64 vcc, exec, s[36:37]
	v_mov_b32_e32 v76, v65
	s_cbranch_vccnz .LBB0_1099
	s_nop 0
	s_waitcnt lgkmcnt(0)
	v_lshl_add_u64 v[76:77], v[68:69], 2, s[10:11]
	v_mov_b32_e32 v69, v248
	s_nop 0
	v_add_f32_e32 v76, v65, v69
	v_max_f32_e32 v69, 0, v76
	v_mul_f32_e64 v76, |v76|, s73
	v_exp_f32_e32 v76, v76
	s_nop 0
	v_add_f32_e32 v77, 1.0, v76
	v_add_f32_e32 v78, -1.0, v77
	v_sub_f32_e32 v79, v78, v77
	v_add_f32_e32 v79, 1.0, v79
	v_sub_f32_e32 v78, v76, v78
	v_add_f32_e32 v80, v78, v79
	v_frexp_mant_f32_e32 v78, v77
	v_cmp_gt_f32_e32 vcc, s46, v78
	v_cvt_f64_f32_e32 v[78:79], v77
	v_frexp_exp_i32_f64_e32 v78, v[78:79]
	v_subbrev_co_u32_e32 v86, vcc, 0, v78, vcc
	v_sub_u32_e32 v78, 0, v86
	v_ldexp_f32 v77, v77, v78
	v_ldexp_f32 v78, v80, v78
	v_add_f32_e32 v80, -1.0, v77
	v_add_f32_e32 v79, 1.0, v80
	v_sub_f32_e32 v79, v77, v79
	v_add_f32_e32 v81, v78, v79
	v_add_f32_e32 v79, 1.0, v77
	v_add_f32_e32 v82, -1.0, v79
	v_sub_f32_e32 v77, v77, v82
	v_add_f32_e32 v77, v78, v77
	v_add_f32_e32 v87, v79, v77
	v_rcp_f32_e32 v88, v87
	v_sub_f32_e32 v78, v87, v79
	v_add_f32_e32 v79, v80, v81
	v_sub_f32_e32 v77, v77, v78
	v_mul_f32_e32 v90, v79, v88
	v_sub_f32_e32 v78, v79, v80
	v_mul_f32_e32 v80, v87, v90
	v_fma_f32 v82, v90, v87, -v80
	v_fmac_f32_e32 v82, v90, v77
	v_sub_f32_e32 v89, v81, v78
	v_add_f32_e32 v78, v80, v82
	v_sub_f32_e32 v81, v79, v78
	v_pk_add_f32 v[84:85], v[78:79], v[80:81] neg_lo:[0,1] neg_hi:[0,1]
	v_mov_b32_e32 v83, v78
	v_pk_add_f32 v[78:79], v[84:85], v[82:83] neg_lo:[0,1] neg_hi:[0,1]
	v_cmp_neq_f32_e32 vcc, s0, v76
	v_add_f32_e32 v79, v89, v79
	v_add_f32_e32 v78, v78, v79
	v_add_f32_e32 v79, v81, v78
	v_mul_f32_e32 v89, v88, v79
	v_mul_f32_e32 v80, v87, v89
	v_fma_f32 v82, v89, v87, -v80
	v_fmac_f32_e32 v82, v89, v77
	v_sub_f32_e32 v77, v81, v79
	v_add_f32_e32 v77, v78, v77
	v_add_f32_e32 v78, v80, v82
	v_sub_f32_e32 v81, v79, v78
	v_pk_add_f32 v[84:85], v[78:79], v[80:81] neg_lo:[0,1] neg_hi:[0,1]
	v_mov_b32_e32 v83, v78
	v_pk_add_f32 v[78:79], v[84:85], v[82:83] neg_lo:[0,1] neg_hi:[0,1]
	s_nop 0
	v_add_f32_e32 v77, v77, v79
	v_add_f32_e32 v77, v78, v77
	v_add_f32_e32 v79, v90, v89
	v_add_f32_e32 v77, v81, v77
	v_sub_f32_e32 v78, v79, v90
	v_mul_f32_e32 v77, v88, v77
	v_sub_f32_e32 v78, v89, v78
	v_add_f32_e32 v77, v78, v77
	v_add_f32_e32 v80, v79, v77
	v_mul_f32_e32 v82, v80, v80
	v_fmamk_f32 v78, v82, 0x3e9b6dac, v210
	v_fmaak_f32 v121, v82, v78, 0x3f2aaada
	v_cvt_f32_i32_e32 v78, v86
	v_sub_f32_e32 v79, v80, v79
	v_sub_f32_e32 v77, v77, v79
	v_mul_f32_e32 v79, v80, v82
	v_pk_mul_f32 v[82:83], v[78:79], v[120:121]
	v_ldexp_f32 v81, v80, 1
	v_fma_f32 v80, v78, s1, -v82
	v_fmac_f32_e32 v80, 0xb102e308, v78
	v_pk_add_f32 v[78:79], v[82:83], v[80:81]
	v_ldexp_f32 v77, v77, 1
	v_sub_f32_e32 v81, v79, v81
	v_sub_f32_e32 v81, v83, v81
	v_add_f32_e32 v85, v77, v81
	v_mov_b32_e32 v84, v82
	v_pk_add_f32 v[82:83], v[78:79], v[82:83] neg_lo:[0,1] neg_hi:[0,1]
	v_pk_add_f32 v[86:87], v[78:79], v[84:85]
	v_mov_b32_e32 v81, v78
	v_mov_b32_e32 v83, v87
	v_pk_add_f32 v[88:89], v[80:81], v[82:83] neg_lo:[0,1] neg_hi:[0,1]
	v_pk_add_f32 v[80:81], v[80:81], v[82:83]
	v_mov_b32_e32 v84, v85
	v_pk_add_f32 v[82:83], v[80:81], v[78:79] op_sel:[1,0] op_sel_hi:[0,1] neg_lo:[0,1] neg_hi:[0,1]
	v_pk_add_f32 v[90:91], v[86:87], v[82:83] op_sel_hi:[1,0] neg_lo:[0,1] neg_hi:[0,1]
	v_mov_b32_e32 v86, v87
	v_mov_b32_e32 v87, v81
	v_pk_mov_b32 v[82:83], v[78:79], v[82:83] op_sel:[1,0]
	v_mov_b32_e32 v85, v78
	v_pk_add_f32 v[82:83], v[86:87], v[82:83] neg_lo:[0,1] neg_hi:[0,1]
	v_mov_b32_e32 v90, v88
	v_pk_add_f32 v[78:79], v[84:85], v[82:83] neg_lo:[0,1] neg_hi:[0,1]
	v_mov_b32_e32 v89, v81
	v_pk_add_f32 v[82:83], v[90:91], v[78:79]
	s_nop 0
	v_pk_add_f32 v[84:85], v[82:83], v[82:83] op_sel:[0,1] op_sel_hi:[1,0]
	s_nop 0
	v_pk_add_f32 v[80:81], v[80:81], v[84:85] op_sel:[1,0] op_sel_hi:[0,1]
	v_mov_b32_e32 v83, v80
	v_pk_add_f32 v[86:87], v[82:83], v[88:89] neg_lo:[0,1] neg_hi:[0,1]
	v_mov_b32_e32 v79, v84
	v_sub_f32_e32 v77, v82, v86
	v_pk_add_f32 v[78:79], v[78:79], v[86:87] neg_lo:[0,1] neg_hi:[0,1]
	v_sub_f32_e32 v77, v88, v77
	v_add_f32_e32 v77, v78, v77
	v_add_f32_e32 v77, v77, v79
	v_add_f32_e32 v77, v80, v77
	v_cndmask_b32_e32 v77, v224, v77, vcc
	v_cmp_ngt_f32_e32 vcc, -1.0, v76
	s_nop 1
	v_cndmask_b32_e32 v77, v225, v77, vcc
	v_cmp_neq_f32_e32 vcc, -1.0, v76
	s_nop 1
	v_cndmask_b32_e32 v77, v226, v77, vcc
	v_cmp_lt_f32_e64 vcc, |v76|, s56
	s_nop 1
	v_cndmask_b32_e32 v76, v77, v76, vcc
	v_add_f32_e32 v76, v69, v76

.LBB0_1101:
	s_or_b64 exec, exec, s[8:9]
	v_add_u32_e32 v69, 16, v66
	v_cmp_gt_i32_e64 s[8:9], s52, v69
	s_and_saveexec_b64 s[10:11], s[8:9]
	s_cbranch_execz .LBB0_1122
	s_and_b64 vcc, exec, s[4:5]
	v_lshl_add_u64 v[70:71], v[66:67], 2, s[34:35]
	s_cbranch_vccnz .LBB0_1677
	s_andn2_b64 vcc, exec, s[36:37]
	v_mov_b32_e32 v69, v58
	s_cbranch_vccnz .LBB0_1105
	s_load_dwordx2 s[12:13], s[14:15], 0xb0
	v_lshl_add_u64 v[72:73], v[66:67], 0, s[80:81]
	s_waitcnt lgkmcnt(0)
	v_lshl_add_u64 v[72:73], v[72:73], 2, s[12:13]
	global_load_dword v69, v[72:73], off offset:64
	s_waitcnt vmcnt(0)
	v_mov_b32_e32 v249, v69
	v_add_f32_e32 v72, v58, v69
	v_max_f32_e32 v69, 0, v72
	v_mul_f32_e64 v72, |v72|, s73
	v_exp_f32_e32 v72, v72
	s_nop 0
	v_add_f32_e32 v73, 1.0, v72
	v_add_f32_e32 v75, -1.0, v73
	v_sub_f32_e32 v76, v75, v73
	v_add_f32_e32 v76, 1.0, v76
	v_sub_f32_e32 v75, v72, v75
	v_add_f32_e32 v75, v75, v76
	v_frexp_mant_f32_e32 v76, v73
	v_cmp_gt_f32_e32 vcc, s46, v76
	v_cvt_f64_f32_e32 v[76:77], v73
	v_frexp_exp_i32_f64_e32 v76, v[76:77]
	v_subbrev_co_u32_e32 v84, vcc, 0, v76, vcc
	v_sub_u32_e32 v76, 0, v84
	v_ldexp_f32 v73, v73, v76
	v_ldexp_f32 v75, v75, v76
	v_add_f32_e32 v76, -1.0, v73
	v_add_f32_e32 v77, 1.0, v76
	v_sub_f32_e32 v77, v73, v77
	v_add_f32_e32 v78, v75, v77
	v_add_f32_e32 v77, 1.0, v73
	v_add_f32_e32 v79, -1.0, v77
	v_sub_f32_e32 v73, v73, v79
	v_add_f32_e32 v73, v75, v73
	v_add_f32_e32 v75, v77, v73
	v_rcp_f32_e32 v85, v75
	v_sub_f32_e32 v77, v75, v77
	v_sub_f32_e32 v73, v73, v77
	v_add_f32_e32 v77, v76, v78
	v_sub_f32_e32 v76, v77, v76
	v_mul_f32_e32 v87, v77, v85
	v_sub_f32_e32 v86, v78, v76
	v_mul_f32_e32 v78, v75, v87
	v_fma_f32 v80, v87, v75, -v78
	v_fmac_f32_e32 v80, v87, v73
	v_add_f32_e32 v76, v78, v80
	v_sub_f32_e32 v79, v77, v76
	v_pk_add_f32 v[82:83], v[76:77], v[78:79] neg_lo:[0,1] neg_hi:[0,1]
	v_mov_b32_e32 v81, v76
	v_pk_add_f32 v[76:77], v[82:83], v[80:81] neg_lo:[0,1] neg_hi:[0,1]
	v_cmp_neq_f32_e32 vcc, s0, v72
	v_add_f32_e32 v77, v86, v77
	v_add_f32_e32 v76, v76, v77
	v_add_f32_e32 v77, v79, v76
	v_mul_f32_e32 v86, v85, v77
	v_mul_f32_e32 v78, v75, v86
	v_fma_f32 v80, v86, v75, -v78
	v_fmac_f32_e32 v80, v86, v73
	v_sub_f32_e32 v73, v79, v77
	v_add_f32_e32 v73, v76, v73
	v_add_f32_e32 v76, v78, v80
	v_sub_f32_e32 v79, v77, v76
	v_pk_add_f32 v[82:83], v[76:77], v[78:79] neg_lo:[0,1] neg_hi:[0,1]
	v_mov_b32_e32 v81, v76
	v_pk_add_f32 v[76:77], v[82:83], v[80:81] neg_lo:[0,1] neg_hi:[0,1]
	v_add_f32_e32 v75, v87, v86
	v_add_f32_e32 v73, v73, v77
	v_add_f32_e32 v73, v76, v73
	v_add_f32_e32 v73, v79, v73
	v_sub_f32_e32 v76, v75, v87
	v_mul_f32_e32 v73, v85, v73
	v_sub_f32_e32 v76, v86, v76
	v_add_f32_e32 v73, v76, v73
	v_add_f32_e32 v77, v75, v73
	v_mul_f32_e32 v78, v77, v77
	v_fmamk_f32 v76, v78, 0x3e9b6dac, v210
	v_fmaak_f32 v121, v78, v76, 0x3f2aaada
	v_cvt_f32_i32_e32 v76, v84
	v_sub_f32_e32 v75, v77, v75
	v_ldexp_f32 v79, v77, 1
	v_mul_f32_e32 v77, v77, v78
	v_pk_mul_f32 v[80:81], v[76:77], v[120:121]
	v_sub_f32_e32 v73, v73, v75
	v_fma_f32 v78, v76, s1, -v80
	v_fmac_f32_e32 v78, 0xb102e308, v76
	v_pk_add_f32 v[76:77], v[80:81], v[78:79]
	v_ldexp_f32 v73, v73, 1
	v_sub_f32_e32 v75, v77, v79
	v_sub_f32_e32 v75, v81, v75
	v_add_f32_e32 v83, v73, v75
	v_mov_b32_e32 v82, v80
	v_pk_add_f32 v[80:81], v[76:77], v[80:81] neg_lo:[0,1] neg_hi:[0,1]
	v_pk_add_f32 v[84:85], v[76:77], v[82:83]
	v_mov_b32_e32 v79, v76
	v_mov_b32_e32 v81, v85
	v_pk_add_f32 v[86:87], v[78:79], v[80:81] neg_lo:[0,1] neg_hi:[0,1]
	v_pk_add_f32 v[78:79], v[78:79], v[80:81]
	v_mov_b32_e32 v82, v83
	v_pk_add_f32 v[80:81], v[78:79], v[76:77] op_sel:[1,0] op_sel_hi:[0,1] neg_lo:[0,1] neg_hi:[0,1]
	v_pk_add_f32 v[88:89], v[84:85], v[80:81] op_sel_hi:[1,0] neg_lo:[0,1] neg_hi:[0,1]
	v_mov_b32_e32 v84, v85
	v_mov_b32_e32 v85, v79
	v_pk_mov_b32 v[80:81], v[76:77], v[80:81] op_sel:[1,0]
	v_mov_b32_e32 v83, v76
	v_pk_add_f32 v[80:81], v[84:85], v[80:81] neg_lo:[0,1] neg_hi:[0,1]
	v_mov_b32_e32 v88, v86
	v_pk_add_f32 v[76:77], v[82:83], v[80:81] neg_lo:[0,1] neg_hi:[0,1]
	v_mov_b32_e32 v87, v79
	v_pk_add_f32 v[80:81], v[88:89], v[76:77]
	s_nop 0
	v_pk_add_f32 v[82:83], v[80:81], v[80:81] op_sel:[0,1] op_sel_hi:[1,0]
	s_nop 0
	v_pk_add_f32 v[78:79], v[78:79], v[82:83] op_sel:[1,0] op_sel_hi:[0,1]
	v_mov_b32_e32 v81, v78
	v_pk_add_f32 v[84:85], v[80:81], v[86:87] neg_lo:[0,1] neg_hi:[0,1]
	v_mov_b32_e32 v77, v82
	v_sub_f32_e32 v73, v80, v84
	v_pk_add_f32 v[76:77], v[76:77], v[84:85] neg_lo:[0,1] neg_hi:[0,1]
	v_sub_f32_e32 v73, v86, v73
	v_add_f32_e32 v73, v76, v73
	v_add_f32_e32 v73, v73, v77
	v_add_f32_e32 v73, v78, v73
	v_cndmask_b32_e32 v73, v224, v73, vcc
	v_cmp_ngt_f32_e32 vcc, -1.0, v72
	s_nop 1
	v_cndmask_b32_e32 v73, v225, v73, vcc
	v_cmp_neq_f32_e32 vcc, -1.0, v72
	s_nop 1
	v_cndmask_b32_e32 v73, v226, v73, vcc
	v_cmp_lt_f32_e64 vcc, |v72|, s56
	s_nop 1
	v_cndmask_b32_e32 v72, v73, v72, vcc
	v_add_f32_e32 v69, v69, v72

.LBB0_1107:
	s_and_b64 vcc, exec, s[4:5]
	v_or_b32_e32 v69, 1, v74
	s_cbranch_vccnz .LBB0_1678
	s_andn2_b64 vcc, exec, s[36:37]
	v_mov_b32_e32 v75, v59
	s_cbranch_vccnz .LBB0_1110
	s_nop 0
	v_lshl_add_u64 v[76:77], v[66:67], 0, s[80:81]
	s_waitcnt lgkmcnt(0)
	v_lshl_add_u64 v[76:77], v[76:77], 2, s[12:13]
	v_mov_b32_e32 v75, v249
	s_nop 0
	v_add_f32_e32 v76, v59, v75
	v_max_f32_e32 v75, 0, v76
	v_mul_f32_e64 v76, |v76|, s73
	v_exp_f32_e32 v76, v76
	s_nop 0
	v_add_f32_e32 v77, 1.0, v76
	v_add_f32_e32 v78, -1.0, v77
	v_sub_f32_e32 v79, v78, v77
	v_add_f32_e32 v79, 1.0, v79
	v_sub_f32_e32 v78, v76, v78
	v_add_f32_e32 v80, v78, v79
	v_frexp_mant_f32_e32 v78, v77
	v_cmp_gt_f32_e32 vcc, s46, v78
	v_cvt_f64_f32_e32 v[78:79], v77
	v_frexp_exp_i32_f64_e32 v78, v[78:79]
	v_subbrev_co_u32_e32 v86, vcc, 0, v78, vcc
	v_sub_u32_e32 v78, 0, v86
	v_ldexp_f32 v77, v77, v78
	v_ldexp_f32 v78, v80, v78
	v_add_f32_e32 v80, -1.0, v77
	v_add_f32_e32 v79, 1.0, v80
	v_sub_f32_e32 v79, v77, v79
	v_add_f32_e32 v81, v78, v79
	v_add_f32_e32 v79, 1.0, v77
	v_add_f32_e32 v82, -1.0, v79
	v_sub_f32_e32 v77, v77, v82
	v_add_f32_e32 v77, v78, v77
	v_add_f32_e32 v87, v79, v77
	v_rcp_f32_e32 v88, v87
	v_sub_f32_e32 v78, v87, v79
	v_add_f32_e32 v79, v80, v81
	v_sub_f32_e32 v77, v77, v78
	v_mul_f32_e32 v90, v79, v88
	v_sub_f32_e32 v78, v79, v80
	v_mul_f32_e32 v80, v87, v90
	v_fma_f32 v82, v90, v87, -v80
	v_fmac_f32_e32 v82, v90, v77
	v_sub_f32_e32 v89, v81, v78
	v_add_f32_e32 v78, v80, v82
	v_sub_f32_e32 v81, v79, v78
	v_pk_add_f32 v[84:85], v[78:79], v[80:81] neg_lo:[0,1] neg_hi:[0,1]
	v_mov_b32_e32 v83, v78
	v_pk_add_f32 v[78:79], v[84:85], v[82:83] neg_lo:[0,1] neg_hi:[0,1]
	v_cmp_neq_f32_e32 vcc, s0, v76
	v_add_f32_e32 v79, v89, v79
	v_add_f32_e32 v78, v78, v79
	v_add_f32_e32 v79, v81, v78
	v_mul_f32_e32 v89, v88, v79
	v_mul_f32_e32 v80, v87, v89
	v_fma_f32 v82, v89, v87, -v80
	v_fmac_f32_e32 v82, v89, v77
	v_sub_f32_e32 v77, v81, v79
	v_add_f32_e32 v77, v78, v77
	v_add_f32_e32 v78, v80, v82
	v_sub_f32_e32 v81, v79, v78
	v_pk_add_f32 v[84:85], v[78:79], v[80:81] neg_lo:[0,1] neg_hi:[0,1]
	v_mov_b32_e32 v83, v78
	v_pk_add_f32 v[78:79], v[84:85], v[82:83] neg_lo:[0,1] neg_hi:[0,1]
	s_nop 0
	v_add_f32_e32 v77, v77, v79
	v_add_f32_e32 v77, v78, v77
	v_add_f32_e32 v79, v90, v89
	v_add_f32_e32 v77, v81, v77
	v_sub_f32_e32 v78, v79, v90
	v_mul_f32_e32 v77, v88, v77
	v_sub_f32_e32 v78, v89, v78
	v_add_f32_e32 v77, v78, v77
	v_add_f32_e32 v80, v79, v77
	v_mul_f32_e32 v82, v80, v80
	v_fmamk_f32 v78, v82, 0x3e9b6dac, v210
	v_fmaak_f32 v121, v82, v78, 0x3f2aaada
	v_cvt_f32_i32_e32 v78, v86
	v_sub_f32_e32 v79, v80, v79
	v_sub_f32_e32 v77, v77, v79
	v_mul_f32_e32 v79, v80, v82
	v_pk_mul_f32 v[82:83], v[78:79], v[120:121]
	v_ldexp_f32 v81, v80, 1
	v_fma_f32 v80, v78, s1, -v82
	v_fmac_f32_e32 v80, 0xb102e308, v78
	v_pk_add_f32 v[78:79], v[82:83], v[80:81]
	v_ldexp_f32 v77, v77, 1
	v_sub_f32_e32 v81, v79, v81
	v_sub_f32_e32 v81, v83, v81
	v_add_f32_e32 v85, v77, v81
	v_mov_b32_e32 v84, v82
	v_pk_add_f32 v[82:83], v[78:79], v[82:83] neg_lo:[0,1] neg_hi:[0,1]
	v_pk_add_f32 v[86:87], v[78:79], v[84:85]
	v_mov_b32_e32 v81, v78
	v_mov_b32_e32 v83, v87
	v_pk_add_f32 v[88:89], v[80:81], v[82:83] neg_lo:[0,1] neg_hi:[0,1]
	v_pk_add_f32 v[80:81], v[80:81], v[82:83]
	v_mov_b32_e32 v84, v85
	v_pk_add_f32 v[82:83], v[80:81], v[78:79] op_sel:[1,0] op_sel_hi:[0,1] neg_lo:[0,1] neg_hi:[0,1]
	v_pk_add_f32 v[90:91], v[86:87], v[82:83] op_sel_hi:[1,0] neg_lo:[0,1] neg_hi:[0,1]
	v_mov_b32_e32 v86, v87
	v_mov_b32_e32 v87, v81
	v_pk_mov_b32 v[82:83], v[78:79], v[82:83] op_sel:[1,0]
	v_mov_b32_e32 v85, v78
	v_pk_add_f32 v[82:83], v[86:87], v[82:83] neg_lo:[0,1] neg_hi:[0,1]
	v_mov_b32_e32 v90, v88
	v_pk_add_f32 v[78:79], v[84:85], v[82:83] neg_lo:[0,1] neg_hi:[0,1]
	v_mov_b32_e32 v89, v81
	v_pk_add_f32 v[82:83], v[90:91], v[78:79]
	s_nop 0
	v_pk_add_f32 v[84:85], v[82:83], v[82:83] op_sel:[0,1] op_sel_hi:[1,0]
	s_nop 0
	v_pk_add_f32 v[80:81], v[80:81], v[84:85] op_sel:[1,0] op_sel_hi:[0,1]
	v_mov_b32_e32 v83, v80
	v_pk_add_f32 v[86:87], v[82:83], v[88:89] neg_lo:[0,1] neg_hi:[0,1]
	v_mov_b32_e32 v79, v84
	v_sub_f32_e32 v77, v82, v86
	v_pk_add_f32 v[78:79], v[78:79], v[86:87] neg_lo:[0,1] neg_hi:[0,1]
	v_sub_f32_e32 v77, v88, v77
	v_add_f32_e32 v77, v78, v77
	v_add_f32_e32 v77, v77, v79
	v_add_f32_e32 v77, v80, v77
	v_cndmask_b32_e32 v77, v224, v77, vcc
	v_cmp_ngt_f32_e32 vcc, -1.0, v76
	s_nop 1
	v_cndmask_b32_e32 v77, v225, v77, vcc
	v_cmp_neq_f32_e32 vcc, -1.0, v76
	s_nop 1
	v_cndmask_b32_e32 v77, v226, v77, vcc
	v_cmp_lt_f32_e64 vcc, |v76|, s56
	s_nop 1
	v_cndmask_b32_e32 v76, v77, v76, vcc
	v_add_f32_e32 v75, v75, v76

.LBB0_1112:
	s_and_b64 vcc, exec, s[4:5]
	v_or_b32_e32 v69, 2, v74
	s_cbranch_vccnz .LBB0_1679
	s_andn2_b64 vcc, exec, s[36:37]
	v_mov_b32_e32 v75, v60
	s_cbranch_vccnz .LBB0_1115
	s_nop 0
	v_lshl_add_u64 v[76:77], v[66:67], 0, s[80:81]
	s_waitcnt lgkmcnt(0)
	v_lshl_add_u64 v[76:77], v[76:77], 2, s[12:13]
	v_mov_b32_e32 v75, v249
	s_nop 0
	v_add_f32_e32 v76, v60, v75
	v_max_f32_e32 v75, 0, v76
	v_mul_f32_e64 v76, |v76|, s73
	v_exp_f32_e32 v76, v76
	s_nop 0
	v_add_f32_e32 v77, 1.0, v76
	v_add_f32_e32 v78, -1.0, v77
	v_sub_f32_e32 v79, v78, v77
	v_add_f32_e32 v79, 1.0, v79
	v_sub_f32_e32 v78, v76, v78
	v_add_f32_e32 v80, v78, v79
	v_frexp_mant_f32_e32 v78, v77
	v_cmp_gt_f32_e32 vcc, s46, v78
	v_cvt_f64_f32_e32 v[78:79], v77
	v_frexp_exp_i32_f64_e32 v78, v[78:79]
	v_subbrev_co_u32_e32 v86, vcc, 0, v78, vcc
	v_sub_u32_e32 v78, 0, v86
	v_ldexp_f32 v77, v77, v78
	v_ldexp_f32 v78, v80, v78
	v_add_f32_e32 v80, -1.0, v77
	v_add_f32_e32 v79, 1.0, v80
	v_sub_f32_e32 v79, v77, v79
	v_add_f32_e32 v81, v78, v79
	v_add_f32_e32 v79, 1.0, v77
	v_add_f32_e32 v82, -1.0, v79
	v_sub_f32_e32 v77, v77, v82
	v_add_f32_e32 v77, v78, v77
	v_add_f32_e32 v87, v79, v77
	v_rcp_f32_e32 v88, v87
	v_sub_f32_e32 v78, v87, v79
	v_add_f32_e32 v79, v80, v81
	v_sub_f32_e32 v77, v77, v78
	v_mul_f32_e32 v90, v79, v88
	v_sub_f32_e32 v78, v79, v80
	v_mul_f32_e32 v80, v87, v90
	v_fma_f32 v82, v90, v87, -v80
	v_fmac_f32_e32 v82, v90, v77
	v_sub_f32_e32 v89, v81, v78
	v_add_f32_e32 v78, v80, v82
	v_sub_f32_e32 v81, v79, v78
	v_pk_add_f32 v[84:85], v[78:79], v[80:81] neg_lo:[0,1] neg_hi:[0,1]
	v_mov_b32_e32 v83, v78
	v_pk_add_f32 v[78:79], v[84:85], v[82:83] neg_lo:[0,1] neg_hi:[0,1]
	v_cmp_neq_f32_e32 vcc, s0, v76
	v_add_f32_e32 v79, v89, v79
	v_add_f32_e32 v78, v78, v79
	v_add_f32_e32 v79, v81, v78
	v_mul_f32_e32 v89, v88, v79
	v_mul_f32_e32 v80, v87, v89
	v_fma_f32 v82, v89, v87, -v80
	v_fmac_f32_e32 v82, v89, v77
	v_sub_f32_e32 v77, v81, v79
	v_add_f32_e32 v77, v78, v77
	v_add_f32_e32 v78, v80, v82
	v_sub_f32_e32 v81, v79, v78
	v_pk_add_f32 v[84:85], v[78:79], v[80:81] neg_lo:[0,1] neg_hi:[0,1]
	v_mov_b32_e32 v83, v78
	v_pk_add_f32 v[78:79], v[84:85], v[82:83] neg_lo:[0,1] neg_hi:[0,1]
	s_nop 0
	v_add_f32_e32 v77, v77, v79
	v_add_f32_e32 v77, v78, v77
	v_add_f32_e32 v79, v90, v89
	v_add_f32_e32 v77, v81, v77
	v_sub_f32_e32 v78, v79, v90
	v_mul_f32_e32 v77, v88, v77
	v_sub_f32_e32 v78, v89, v78
	v_add_f32_e32 v77, v78, v77
	v_add_f32_e32 v80, v79, v77
	v_mul_f32_e32 v82, v80, v80
	v_fmamk_f32 v78, v82, 0x3e9b6dac, v210
	v_fmaak_f32 v121, v82, v78, 0x3f2aaada
	v_cvt_f32_i32_e32 v78, v86
	v_sub_f32_e32 v79, v80, v79
	v_sub_f32_e32 v77, v77, v79
	v_mul_f32_e32 v79, v80, v82
	v_pk_mul_f32 v[82:83], v[78:79], v[120:121]
	v_ldexp_f32 v81, v80, 1
	v_fma_f32 v80, v78, s1, -v82
	v_fmac_f32_e32 v80, 0xb102e308, v78
	v_pk_add_f32 v[78:79], v[82:83], v[80:81]
	v_ldexp_f32 v77, v77, 1
	v_sub_f32_e32 v81, v79, v81
	v_sub_f32_e32 v81, v83, v81
	v_add_f32_e32 v85, v77, v81
	v_mov_b32_e32 v84, v82
	v_pk_add_f32 v[82:83], v[78:79], v[82:83] neg_lo:[0,1] neg_hi:[0,1]
	v_pk_add_f32 v[86:87], v[78:79], v[84:85]
	v_mov_b32_e32 v81, v78
	v_mov_b32_e32 v83, v87
	v_pk_add_f32 v[88:89], v[80:81], v[82:83] neg_lo:[0,1] neg_hi:[0,1]
	v_pk_add_f32 v[80:81], v[80:81], v[82:83]
	v_mov_b32_e32 v84, v85
	v_pk_add_f32 v[82:83], v[80:81], v[78:79] op_sel:[1,0] op_sel_hi:[0,1] neg_lo:[0,1] neg_hi:[0,1]
	v_pk_add_f32 v[90:91], v[86:87], v[82:83] op_sel_hi:[1,0] neg_lo:[0,1] neg_hi:[0,1]
	v_mov_b32_e32 v86, v87
	v_mov_b32_e32 v87, v81
	v_pk_mov_b32 v[82:83], v[78:79], v[82:83] op_sel:[1,0]
	v_mov_b32_e32 v85, v78
	v_pk_add_f32 v[82:83], v[86:87], v[82:83] neg_lo:[0,1] neg_hi:[0,1]
	v_mov_b32_e32 v90, v88
	v_pk_add_f32 v[78:79], v[84:85], v[82:83] neg_lo:[0,1] neg_hi:[0,1]
	v_mov_b32_e32 v89, v81
	v_pk_add_f32 v[82:83], v[90:91], v[78:79]
	s_nop 0
	v_pk_add_f32 v[84:85], v[82:83], v[82:83] op_sel:[0,1] op_sel_hi:[1,0]
	s_nop 0
	v_pk_add_f32 v[80:81], v[80:81], v[84:85] op_sel:[1,0] op_sel_hi:[0,1]
	v_mov_b32_e32 v83, v80
	v_pk_add_f32 v[86:87], v[82:83], v[88:89] neg_lo:[0,1] neg_hi:[0,1]
	v_mov_b32_e32 v79, v84
	v_sub_f32_e32 v77, v82, v86
	v_pk_add_f32 v[78:79], v[78:79], v[86:87] neg_lo:[0,1] neg_hi:[0,1]
	v_sub_f32_e32 v77, v88, v77
	v_add_f32_e32 v77, v78, v77
	v_add_f32_e32 v77, v77, v79
	v_add_f32_e32 v77, v80, v77
	v_cndmask_b32_e32 v77, v224, v77, vcc
	v_cmp_ngt_f32_e32 vcc, -1.0, v76
	s_nop 1
	v_cndmask_b32_e32 v77, v225, v77, vcc
	v_cmp_neq_f32_e32 vcc, -1.0, v76
	s_nop 1
	v_cndmask_b32_e32 v77, v226, v77, vcc
	v_cmp_lt_f32_e64 vcc, |v76|, s56
	s_nop 1
	v_cndmask_b32_e32 v76, v77, v76, vcc
	v_add_f32_e32 v75, v75, v76

.LBB0_1117:
	s_and_b64 vcc, exec, s[4:5]
	v_or_b32_e32 v69, 3, v74
	s_cbranch_vccnz .LBB0_1680
	s_andn2_b64 vcc, exec, s[36:37]
	v_mov_b32_e32 v75, v61
	s_cbranch_vccnz .LBB0_1120
	s_nop 0
	v_lshl_add_u64 v[76:77], v[66:67], 0, s[80:81]
	s_waitcnt lgkmcnt(0)
	v_lshl_add_u64 v[76:77], v[76:77], 2, s[12:13]
	v_mov_b32_e32 v75, v249
	s_nop 0
	v_add_f32_e32 v76, v61, v75
	v_max_f32_e32 v75, 0, v76
	v_mul_f32_e64 v76, |v76|, s73
	v_exp_f32_e32 v76, v76
	s_nop 0
	v_add_f32_e32 v77, 1.0, v76
	v_add_f32_e32 v78, -1.0, v77
	v_sub_f32_e32 v79, v78, v77
	v_add_f32_e32 v79, 1.0, v79
	v_sub_f32_e32 v78, v76, v78
	v_add_f32_e32 v80, v78, v79
	v_frexp_mant_f32_e32 v78, v77
	v_cmp_gt_f32_e32 vcc, s46, v78
	v_cvt_f64_f32_e32 v[78:79], v77
	v_frexp_exp_i32_f64_e32 v78, v[78:79]
	v_subbrev_co_u32_e32 v86, vcc, 0, v78, vcc
	v_sub_u32_e32 v78, 0, v86
	v_ldexp_f32 v77, v77, v78
	v_ldexp_f32 v78, v80, v78
	v_add_f32_e32 v80, -1.0, v77
	v_add_f32_e32 v79, 1.0, v80
	v_sub_f32_e32 v79, v77, v79
	v_add_f32_e32 v81, v78, v79
	v_add_f32_e32 v79, 1.0, v77
	v_add_f32_e32 v82, -1.0, v79
	v_sub_f32_e32 v77, v77, v82
	v_add_f32_e32 v77, v78, v77
	v_add_f32_e32 v87, v79, v77
	v_rcp_f32_e32 v88, v87
	v_sub_f32_e32 v78, v87, v79
	v_add_f32_e32 v79, v80, v81
	v_sub_f32_e32 v77, v77, v78
	v_mul_f32_e32 v90, v79, v88
	v_sub_f32_e32 v78, v79, v80
	v_mul_f32_e32 v80, v87, v90
	v_fma_f32 v82, v90, v87, -v80
	v_fmac_f32_e32 v82, v90, v77
	v_sub_f32_e32 v89, v81, v78
	v_add_f32_e32 v78, v80, v82
	v_sub_f32_e32 v81, v79, v78
	v_pk_add_f32 v[84:85], v[78:79], v[80:81] neg_lo:[0,1] neg_hi:[0,1]
	v_mov_b32_e32 v83, v78
	v_pk_add_f32 v[78:79], v[84:85], v[82:83] neg_lo:[0,1] neg_hi:[0,1]
	v_cmp_neq_f32_e32 vcc, s0, v76
	v_add_f32_e32 v79, v89, v79
	v_add_f32_e32 v78, v78, v79
	v_add_f32_e32 v79, v81, v78
	v_mul_f32_e32 v89, v88, v79
	v_mul_f32_e32 v80, v87, v89
	v_fma_f32 v82, v89, v87, -v80
	v_fmac_f32_e32 v82, v89, v77
	v_sub_f32_e32 v77, v81, v79
	v_add_f32_e32 v77, v78, v77
	v_add_f32_e32 v78, v80, v82
	v_sub_f32_e32 v81, v79, v78
	v_pk_add_f32 v[84:85], v[78:79], v[80:81] neg_lo:[0,1] neg_hi:[0,1]
	v_mov_b32_e32 v83, v78
	v_pk_add_f32 v[78:79], v[84:85], v[82:83] neg_lo:[0,1] neg_hi:[0,1]
	s_nop 0
	v_add_f32_e32 v77, v77, v79
	v_add_f32_e32 v77, v78, v77
	v_add_f32_e32 v79, v90, v89
	v_add_f32_e32 v77, v81, v77
	v_sub_f32_e32 v78, v79, v90
	v_mul_f32_e32 v77, v88, v77
	v_sub_f32_e32 v78, v89, v78
	v_add_f32_e32 v77, v78, v77
	v_add_f32_e32 v80, v79, v77
	v_mul_f32_e32 v82, v80, v80
	v_fmamk_f32 v78, v82, 0x3e9b6dac, v210
	v_fmaak_f32 v121, v82, v78, 0x3f2aaada
	v_cvt_f32_i32_e32 v78, v86
	v_sub_f32_e32 v79, v80, v79
	v_sub_f32_e32 v77, v77, v79
	v_mul_f32_e32 v79, v80, v82
	v_pk_mul_f32 v[82:83], v[78:79], v[120:121]
	v_ldexp_f32 v81, v80, 1
	v_fma_f32 v80, v78, s1, -v82
	v_fmac_f32_e32 v80, 0xb102e308, v78
	v_pk_add_f32 v[78:79], v[82:83], v[80:81]
	v_ldexp_f32 v77, v77, 1
	v_sub_f32_e32 v81, v79, v81
	v_sub_f32_e32 v81, v83, v81
	v_add_f32_e32 v85, v77, v81
	v_mov_b32_e32 v84, v82
	v_pk_add_f32 v[82:83], v[78:79], v[82:83] neg_lo:[0,1] neg_hi:[0,1]
	v_pk_add_f32 v[86:87], v[78:79], v[84:85]
	v_mov_b32_e32 v81, v78
	v_mov_b32_e32 v83, v87
	v_pk_add_f32 v[88:89], v[80:81], v[82:83] neg_lo:[0,1] neg_hi:[0,1]
	v_pk_add_f32 v[80:81], v[80:81], v[82:83]
	v_mov_b32_e32 v84, v85
	v_pk_add_f32 v[82:83], v[80:81], v[78:79] op_sel:[1,0] op_sel_hi:[0,1] neg_lo:[0,1] neg_hi:[0,1]
	v_pk_add_f32 v[90:91], v[86:87], v[82:83] op_sel_hi:[1,0] neg_lo:[0,1] neg_hi:[0,1]
	v_mov_b32_e32 v86, v87
	v_mov_b32_e32 v87, v81
	v_pk_mov_b32 v[82:83], v[78:79], v[82:83] op_sel:[1,0]
	v_mov_b32_e32 v85, v78
	v_pk_add_f32 v[82:83], v[86:87], v[82:83] neg_lo:[0,1] neg_hi:[0,1]
	v_mov_b32_e32 v90, v88
	v_pk_add_f32 v[78:79], v[84:85], v[82:83] neg_lo:[0,1] neg_hi:[0,1]
	v_mov_b32_e32 v89, v81
	v_pk_add_f32 v[82:83], v[90:91], v[78:79]
	s_nop 0
	v_pk_add_f32 v[84:85], v[82:83], v[82:83] op_sel:[0,1] op_sel_hi:[1,0]
	s_nop 0
	v_pk_add_f32 v[80:81], v[80:81], v[84:85] op_sel:[1,0] op_sel_hi:[0,1]
	v_mov_b32_e32 v83, v80
	v_pk_add_f32 v[86:87], v[82:83], v[88:89] neg_lo:[0,1] neg_hi:[0,1]
	v_mov_b32_e32 v79, v84
	v_sub_f32_e32 v77, v82, v86
	v_pk_add_f32 v[78:79], v[78:79], v[86:87] neg_lo:[0,1] neg_hi:[0,1]
	v_sub_f32_e32 v77, v88, v77
	v_add_f32_e32 v77, v78, v77
	v_add_f32_e32 v77, v77, v79
	v_add_f32_e32 v77, v80, v77
	v_cndmask_b32_e32 v77, v224, v77, vcc
	v_cmp_ngt_f32_e32 vcc, -1.0, v76
	s_nop 1
	v_cndmask_b32_e32 v77, v225, v77, vcc
	v_cmp_neq_f32_e32 vcc, -1.0, v76
	s_nop 1
	v_cndmask_b32_e32 v77, v226, v77, vcc
	v_cmp_lt_f32_e64 vcc, |v76|, s56
	s_nop 1
	v_cndmask_b32_e32 v76, v77, v76, vcc
	v_add_f32_e32 v75, v75, v76

.LBB0_1122:
	s_or_b64 exec, exec, s[10:11]
	v_add_u32_e32 v69, 32, v66
	v_cmp_gt_i32_e64 s[10:11], s52, v69
	s_and_saveexec_b64 s[12:13], s[10:11]
	s_cbranch_execz .LBB0_1143
	s_and_b64 vcc, exec, s[4:5]
	v_lshl_add_u64 v[70:71], v[66:67], 2, s[34:35]
	s_cbranch_vccnz .LBB0_1681
	s_andn2_b64 vcc, exec, s[36:37]
	v_mov_b32_e32 v69, v54
	s_cbranch_vccnz .LBB0_1126
	s_load_dwordx2 s[58:59], s[14:15], 0xb0
	v_lshl_add_u64 v[72:73], v[66:67], 0, s[80:81]
	s_waitcnt lgkmcnt(0)
	v_lshl_add_u64 v[72:73], v[72:73], 2, s[58:59]
	global_load_dword v69, v[72:73], off offset:128
	s_waitcnt vmcnt(0)
	v_mov_b32_e32 v250, v69
	v_add_f32_e32 v72, v54, v69
	v_max_f32_e32 v69, 0, v72
	v_mul_f32_e64 v72, |v72|, s73
	v_exp_f32_e32 v72, v72
	s_nop 0
	v_add_f32_e32 v73, 1.0, v72
	v_add_f32_e32 v75, -1.0, v73
	v_sub_f32_e32 v76, v75, v73
	v_add_f32_e32 v76, 1.0, v76
	v_sub_f32_e32 v75, v72, v75
	v_add_f32_e32 v75, v75, v76
	v_frexp_mant_f32_e32 v76, v73
	v_cmp_gt_f32_e32 vcc, s46, v76
	v_cvt_f64_f32_e32 v[76:77], v73
	v_frexp_exp_i32_f64_e32 v76, v[76:77]
	v_subbrev_co_u32_e32 v84, vcc, 0, v76, vcc
	v_sub_u32_e32 v76, 0, v84
	v_ldexp_f32 v73, v73, v76
	v_ldexp_f32 v75, v75, v76
	v_add_f32_e32 v76, -1.0, v73
	v_add_f32_e32 v77, 1.0, v76
	v_sub_f32_e32 v77, v73, v77
	v_add_f32_e32 v78, v75, v77
	v_add_f32_e32 v77, 1.0, v73
	v_add_f32_e32 v79, -1.0, v77
	v_sub_f32_e32 v73, v73, v79
	v_add_f32_e32 v73, v75, v73
	v_add_f32_e32 v75, v77, v73
	v_rcp_f32_e32 v85, v75
	v_sub_f32_e32 v77, v75, v77
	v_sub_f32_e32 v73, v73, v77
	v_add_f32_e32 v77, v76, v78
	v_sub_f32_e32 v76, v77, v76
	v_mul_f32_e32 v87, v77, v85
	v_sub_f32_e32 v86, v78, v76
	v_mul_f32_e32 v78, v75, v87
	v_fma_f32 v80, v87, v75, -v78
	v_fmac_f32_e32 v80, v87, v73
	v_add_f32_e32 v76, v78, v80
	v_sub_f32_e32 v79, v77, v76
	v_pk_add_f32 v[82:83], v[76:77], v[78:79] neg_lo:[0,1] neg_hi:[0,1]
	v_mov_b32_e32 v81, v76
	v_pk_add_f32 v[76:77], v[82:83], v[80:81] neg_lo:[0,1] neg_hi:[0,1]
	v_cmp_neq_f32_e32 vcc, s0, v72
	v_add_f32_e32 v77, v86, v77
	v_add_f32_e32 v76, v76, v77
	v_add_f32_e32 v77, v79, v76
	v_mul_f32_e32 v86, v85, v77
	v_mul_f32_e32 v78, v75, v86
	v_fma_f32 v80, v86, v75, -v78
	v_fmac_f32_e32 v80, v86, v73
	v_sub_f32_e32 v73, v79, v77
	v_add_f32_e32 v73, v76, v73
	v_add_f32_e32 v76, v78, v80
	v_sub_f32_e32 v79, v77, v76
	v_pk_add_f32 v[82:83], v[76:77], v[78:79] neg_lo:[0,1] neg_hi:[0,1]
	v_mov_b32_e32 v81, v76
	v_pk_add_f32 v[76:77], v[82:83], v[80:81] neg_lo:[0,1] neg_hi:[0,1]
	v_add_f32_e32 v75, v87, v86
	v_add_f32_e32 v73, v73, v77
	v_add_f32_e32 v73, v76, v73
	v_add_f32_e32 v73, v79, v73
	v_sub_f32_e32 v76, v75, v87
	v_mul_f32_e32 v73, v85, v73
	v_sub_f32_e32 v76, v86, v76
	v_add_f32_e32 v73, v76, v73
	v_add_f32_e32 v77, v75, v73
	v_mul_f32_e32 v78, v77, v77
	v_fmamk_f32 v76, v78, 0x3e9b6dac, v210
	v_fmaak_f32 v121, v78, v76, 0x3f2aaada
	v_cvt_f32_i32_e32 v76, v84
	v_sub_f32_e32 v75, v77, v75
	v_ldexp_f32 v79, v77, 1
	v_mul_f32_e32 v77, v77, v78
	v_pk_mul_f32 v[80:81], v[76:77], v[120:121]
	v_sub_f32_e32 v73, v73, v75
	v_fma_f32 v78, v76, s1, -v80
	v_fmac_f32_e32 v78, 0xb102e308, v76
	v_pk_add_f32 v[76:77], v[80:81], v[78:79]
	v_ldexp_f32 v73, v73, 1
	v_sub_f32_e32 v75, v77, v79
	v_sub_f32_e32 v75, v81, v75
	v_add_f32_e32 v83, v73, v75
	v_mov_b32_e32 v82, v80
	v_pk_add_f32 v[80:81], v[76:77], v[80:81] neg_lo:[0,1] neg_hi:[0,1]
	v_pk_add_f32 v[84:85], v[76:77], v[82:83]
	v_mov_b32_e32 v79, v76
	v_mov_b32_e32 v81, v85
	v_pk_add_f32 v[86:87], v[78:79], v[80:81] neg_lo:[0,1] neg_hi:[0,1]
	v_pk_add_f32 v[78:79], v[78:79], v[80:81]
	v_mov_b32_e32 v82, v83
	v_pk_add_f32 v[80:81], v[78:79], v[76:77] op_sel:[1,0] op_sel_hi:[0,1] neg_lo:[0,1] neg_hi:[0,1]
	v_pk_add_f32 v[88:89], v[84:85], v[80:81] op_sel_hi:[1,0] neg_lo:[0,1] neg_hi:[0,1]
	v_mov_b32_e32 v84, v85
	v_mov_b32_e32 v85, v79
	v_pk_mov_b32 v[80:81], v[76:77], v[80:81] op_sel:[1,0]
	v_mov_b32_e32 v83, v76
	v_pk_add_f32 v[80:81], v[84:85], v[80:81] neg_lo:[0,1] neg_hi:[0,1]
	v_mov_b32_e32 v88, v86
	v_pk_add_f32 v[76:77], v[82:83], v[80:81] neg_lo:[0,1] neg_hi:[0,1]
	v_mov_b32_e32 v87, v79
	v_pk_add_f32 v[80:81], v[88:89], v[76:77]
	s_nop 0
	v_pk_add_f32 v[82:83], v[80:81], v[80:81] op_sel:[0,1] op_sel_hi:[1,0]
	s_nop 0
	v_pk_add_f32 v[78:79], v[78:79], v[82:83] op_sel:[1,0] op_sel_hi:[0,1]
	v_mov_b32_e32 v81, v78
	v_pk_add_f32 v[84:85], v[80:81], v[86:87] neg_lo:[0,1] neg_hi:[0,1]
	v_mov_b32_e32 v77, v82
	v_sub_f32_e32 v73, v80, v84
	v_pk_add_f32 v[76:77], v[76:77], v[84:85] neg_lo:[0,1] neg_hi:[0,1]
	v_sub_f32_e32 v73, v86, v73
	v_add_f32_e32 v73, v76, v73
	v_add_f32_e32 v73, v73, v77
	v_add_f32_e32 v73, v78, v73
	v_cndmask_b32_e32 v73, v224, v73, vcc
	v_cmp_ngt_f32_e32 vcc, -1.0, v72
	s_nop 1
	v_cndmask_b32_e32 v73, v225, v73, vcc
	v_cmp_neq_f32_e32 vcc, -1.0, v72
	s_nop 1
	v_cndmask_b32_e32 v73, v226, v73, vcc
	v_cmp_lt_f32_e64 vcc, |v72|, s56
	s_nop 1
	v_cndmask_b32_e32 v72, v73, v72, vcc
	v_add_f32_e32 v69, v69, v72

.LBB0_1128:
	s_and_b64 vcc, exec, s[4:5]
	v_or_b32_e32 v69, 1, v74
	s_cbranch_vccnz .LBB0_1682
	s_andn2_b64 vcc, exec, s[36:37]
	v_mov_b32_e32 v75, v55
	s_cbranch_vccnz .LBB0_1131
	s_nop 0
	v_lshl_add_u64 v[76:77], v[66:67], 0, s[80:81]
	s_waitcnt lgkmcnt(0)
	v_lshl_add_u64 v[76:77], v[76:77], 2, s[58:59]
	v_mov_b32_e32 v75, v250
	s_nop 0
	v_add_f32_e32 v76, v55, v75
	v_max_f32_e32 v75, 0, v76
	v_mul_f32_e64 v76, |v76|, s73
	v_exp_f32_e32 v76, v76
	s_nop 0
	v_add_f32_e32 v77, 1.0, v76
	v_add_f32_e32 v78, -1.0, v77
	v_sub_f32_e32 v79, v78, v77
	v_add_f32_e32 v79, 1.0, v79
	v_sub_f32_e32 v78, v76, v78
	v_add_f32_e32 v80, v78, v79
	v_frexp_mant_f32_e32 v78, v77
	v_cmp_gt_f32_e32 vcc, s46, v78
	v_cvt_f64_f32_e32 v[78:79], v77
	v_frexp_exp_i32_f64_e32 v78, v[78:79]
	v_subbrev_co_u32_e32 v86, vcc, 0, v78, vcc
	v_sub_u32_e32 v78, 0, v86
	v_ldexp_f32 v77, v77, v78
	v_ldexp_f32 v78, v80, v78
	v_add_f32_e32 v80, -1.0, v77
	v_add_f32_e32 v79, 1.0, v80
	v_sub_f32_e32 v79, v77, v79
	v_add_f32_e32 v81, v78, v79
	v_add_f32_e32 v79, 1.0, v77
	v_add_f32_e32 v82, -1.0, v79
	v_sub_f32_e32 v77, v77, v82
	v_add_f32_e32 v77, v78, v77
	v_add_f32_e32 v87, v79, v77
	v_rcp_f32_e32 v88, v87
	v_sub_f32_e32 v78, v87, v79
	v_add_f32_e32 v79, v80, v81
	v_sub_f32_e32 v77, v77, v78
	v_mul_f32_e32 v90, v79, v88
	v_sub_f32_e32 v78, v79, v80
	v_mul_f32_e32 v80, v87, v90
	v_fma_f32 v82, v90, v87, -v80
	v_fmac_f32_e32 v82, v90, v77
	v_sub_f32_e32 v89, v81, v78
	v_add_f32_e32 v78, v80, v82
	v_sub_f32_e32 v81, v79, v78
	v_pk_add_f32 v[84:85], v[78:79], v[80:81] neg_lo:[0,1] neg_hi:[0,1]
	v_mov_b32_e32 v83, v78
	v_pk_add_f32 v[78:79], v[84:85], v[82:83] neg_lo:[0,1] neg_hi:[0,1]
	v_cmp_neq_f32_e32 vcc, s0, v76
	v_add_f32_e32 v79, v89, v79
	v_add_f32_e32 v78, v78, v79
	v_add_f32_e32 v79, v81, v78
	v_mul_f32_e32 v89, v88, v79
	v_mul_f32_e32 v80, v87, v89
	v_fma_f32 v82, v89, v87, -v80
	v_fmac_f32_e32 v82, v89, v77
	v_sub_f32_e32 v77, v81, v79
	v_add_f32_e32 v77, v78, v77
	v_add_f32_e32 v78, v80, v82
	v_sub_f32_e32 v81, v79, v78
	v_pk_add_f32 v[84:85], v[78:79], v[80:81] neg_lo:[0,1] neg_hi:[0,1]
	v_mov_b32_e32 v83, v78
	v_pk_add_f32 v[78:79], v[84:85], v[82:83] neg_lo:[0,1] neg_hi:[0,1]
	s_nop 0
	v_add_f32_e32 v77, v77, v79
	v_add_f32_e32 v77, v78, v77
	v_add_f32_e32 v79, v90, v89
	v_add_f32_e32 v77, v81, v77
	v_sub_f32_e32 v78, v79, v90
	v_mul_f32_e32 v77, v88, v77
	v_sub_f32_e32 v78, v89, v78
	v_add_f32_e32 v77, v78, v77
	v_add_f32_e32 v80, v79, v77
	v_mul_f32_e32 v82, v80, v80
	v_fmamk_f32 v78, v82, 0x3e9b6dac, v210
	v_fmaak_f32 v121, v82, v78, 0x3f2aaada
	v_cvt_f32_i32_e32 v78, v86
	v_sub_f32_e32 v79, v80, v79
	v_sub_f32_e32 v77, v77, v79
	v_mul_f32_e32 v79, v80, v82
	v_pk_mul_f32 v[82:83], v[78:79], v[120:121]
	v_ldexp_f32 v81, v80, 1
	v_fma_f32 v80, v78, s1, -v82
	v_fmac_f32_e32 v80, 0xb102e308, v78
	v_pk_add_f32 v[78:79], v[82:83], v[80:81]
	v_ldexp_f32 v77, v77, 1
	v_sub_f32_e32 v81, v79, v81
	v_sub_f32_e32 v81, v83, v81
	v_add_f32_e32 v85, v77, v81
	v_mov_b32_e32 v84, v82
	v_pk_add_f32 v[82:83], v[78:79], v[82:83] neg_lo:[0,1] neg_hi:[0,1]
	v_pk_add_f32 v[86:87], v[78:79], v[84:85]
	v_mov_b32_e32 v81, v78
	v_mov_b32_e32 v83, v87
	v_pk_add_f32 v[88:89], v[80:81], v[82:83] neg_lo:[0,1] neg_hi:[0,1]
	v_pk_add_f32 v[80:81], v[80:81], v[82:83]
	v_mov_b32_e32 v84, v85
	v_pk_add_f32 v[82:83], v[80:81], v[78:79] op_sel:[1,0] op_sel_hi:[0,1] neg_lo:[0,1] neg_hi:[0,1]
	v_pk_add_f32 v[90:91], v[86:87], v[82:83] op_sel_hi:[1,0] neg_lo:[0,1] neg_hi:[0,1]
	v_mov_b32_e32 v86, v87
	v_mov_b32_e32 v87, v81
	v_pk_mov_b32 v[82:83], v[78:79], v[82:83] op_sel:[1,0]
	v_mov_b32_e32 v85, v78
	v_pk_add_f32 v[82:83], v[86:87], v[82:83] neg_lo:[0,1] neg_hi:[0,1]
	v_mov_b32_e32 v90, v88
	v_pk_add_f32 v[78:79], v[84:85], v[82:83] neg_lo:[0,1] neg_hi:[0,1]
	v_mov_b32_e32 v89, v81
	v_pk_add_f32 v[82:83], v[90:91], v[78:79]
	s_nop 0
	v_pk_add_f32 v[84:85], v[82:83], v[82:83] op_sel:[0,1] op_sel_hi:[1,0]
	s_nop 0
	v_pk_add_f32 v[80:81], v[80:81], v[84:85] op_sel:[1,0] op_sel_hi:[0,1]
	v_mov_b32_e32 v83, v80
	v_pk_add_f32 v[86:87], v[82:83], v[88:89] neg_lo:[0,1] neg_hi:[0,1]
	v_mov_b32_e32 v79, v84
	v_sub_f32_e32 v77, v82, v86
	v_pk_add_f32 v[78:79], v[78:79], v[86:87] neg_lo:[0,1] neg_hi:[0,1]
	v_sub_f32_e32 v77, v88, v77
	v_add_f32_e32 v77, v78, v77
	v_add_f32_e32 v77, v77, v79
	v_add_f32_e32 v77, v80, v77
	v_cndmask_b32_e32 v77, v224, v77, vcc
	v_cmp_ngt_f32_e32 vcc, -1.0, v76
	s_nop 1
	v_cndmask_b32_e32 v77, v225, v77, vcc
	v_cmp_neq_f32_e32 vcc, -1.0, v76
	s_nop 1
	v_cndmask_b32_e32 v77, v226, v77, vcc
	v_cmp_lt_f32_e64 vcc, |v76|, s56
	s_nop 1
	v_cndmask_b32_e32 v76, v77, v76, vcc
	v_add_f32_e32 v75, v75, v76

.LBB0_1133:
	s_and_b64 vcc, exec, s[4:5]
	v_or_b32_e32 v69, 2, v74
	s_cbranch_vccnz .LBB0_1683
	s_andn2_b64 vcc, exec, s[36:37]
	v_mov_b32_e32 v75, v56
	s_cbranch_vccnz .LBB0_1136
	s_nop 0
	v_lshl_add_u64 v[76:77], v[66:67], 0, s[80:81]
	s_waitcnt lgkmcnt(0)
	v_lshl_add_u64 v[76:77], v[76:77], 2, s[58:59]
	v_mov_b32_e32 v75, v250
	s_nop 0
	v_add_f32_e32 v76, v56, v75
	v_max_f32_e32 v75, 0, v76
	v_mul_f32_e64 v76, |v76|, s73
	v_exp_f32_e32 v76, v76
	s_nop 0
	v_add_f32_e32 v77, 1.0, v76
	v_add_f32_e32 v78, -1.0, v77
	v_sub_f32_e32 v79, v78, v77
	v_add_f32_e32 v79, 1.0, v79
	v_sub_f32_e32 v78, v76, v78
	v_add_f32_e32 v80, v78, v79
	v_frexp_mant_f32_e32 v78, v77
	v_cmp_gt_f32_e32 vcc, s46, v78
	v_cvt_f64_f32_e32 v[78:79], v77
	v_frexp_exp_i32_f64_e32 v78, v[78:79]
	v_subbrev_co_u32_e32 v86, vcc, 0, v78, vcc
	v_sub_u32_e32 v78, 0, v86
	v_ldexp_f32 v77, v77, v78
	v_ldexp_f32 v78, v80, v78
	v_add_f32_e32 v80, -1.0, v77
	v_add_f32_e32 v79, 1.0, v80
	v_sub_f32_e32 v79, v77, v79
	v_add_f32_e32 v81, v78, v79
	v_add_f32_e32 v79, 1.0, v77
	v_add_f32_e32 v82, -1.0, v79
	v_sub_f32_e32 v77, v77, v82
	v_add_f32_e32 v77, v78, v77
	v_add_f32_e32 v87, v79, v77
	v_rcp_f32_e32 v88, v87
	v_sub_f32_e32 v78, v87, v79
	v_add_f32_e32 v79, v80, v81
	v_sub_f32_e32 v77, v77, v78
	v_mul_f32_e32 v90, v79, v88
	v_sub_f32_e32 v78, v79, v80
	v_mul_f32_e32 v80, v87, v90
	v_fma_f32 v82, v90, v87, -v80
	v_fmac_f32_e32 v82, v90, v77
	v_sub_f32_e32 v89, v81, v78
	v_add_f32_e32 v78, v80, v82
	v_sub_f32_e32 v81, v79, v78
	v_pk_add_f32 v[84:85], v[78:79], v[80:81] neg_lo:[0,1] neg_hi:[0,1]
	v_mov_b32_e32 v83, v78
	v_pk_add_f32 v[78:79], v[84:85], v[82:83] neg_lo:[0,1] neg_hi:[0,1]
	v_cmp_neq_f32_e32 vcc, s0, v76
	v_add_f32_e32 v79, v89, v79
	v_add_f32_e32 v78, v78, v79
	v_add_f32_e32 v79, v81, v78
	v_mul_f32_e32 v89, v88, v79
	v_mul_f32_e32 v80, v87, v89
	v_fma_f32 v82, v89, v87, -v80
	v_fmac_f32_e32 v82, v89, v77
	v_sub_f32_e32 v77, v81, v79
	v_add_f32_e32 v77, v78, v77
	v_add_f32_e32 v78, v80, v82
	v_sub_f32_e32 v81, v79, v78
	v_pk_add_f32 v[84:85], v[78:79], v[80:81] neg_lo:[0,1] neg_hi:[0,1]
	v_mov_b32_e32 v83, v78
	v_pk_add_f32 v[78:79], v[84:85], v[82:83] neg_lo:[0,1] neg_hi:[0,1]
	s_nop 0
	v_add_f32_e32 v77, v77, v79
	v_add_f32_e32 v77, v78, v77
	v_add_f32_e32 v79, v90, v89
	v_add_f32_e32 v77, v81, v77
	v_sub_f32_e32 v78, v79, v90
	v_mul_f32_e32 v77, v88, v77
	v_sub_f32_e32 v78, v89, v78
	v_add_f32_e32 v77, v78, v77
	v_add_f32_e32 v80, v79, v77
	v_mul_f32_e32 v82, v80, v80
	v_fmamk_f32 v78, v82, 0x3e9b6dac, v210
	v_fmaak_f32 v121, v82, v78, 0x3f2aaada
	v_cvt_f32_i32_e32 v78, v86
	v_sub_f32_e32 v79, v80, v79
	v_sub_f32_e32 v77, v77, v79
	v_mul_f32_e32 v79, v80, v82
	v_pk_mul_f32 v[82:83], v[78:79], v[120:121]
	v_ldexp_f32 v81, v80, 1
	v_fma_f32 v80, v78, s1, -v82
	v_fmac_f32_e32 v80, 0xb102e308, v78
	v_pk_add_f32 v[78:79], v[82:83], v[80:81]
	v_ldexp_f32 v77, v77, 1
	v_sub_f32_e32 v81, v79, v81
	v_sub_f32_e32 v81, v83, v81
	v_add_f32_e32 v85, v77, v81
	v_mov_b32_e32 v84, v82
	v_pk_add_f32 v[82:83], v[78:79], v[82:83] neg_lo:[0,1] neg_hi:[0,1]
	v_pk_add_f32 v[86:87], v[78:79], v[84:85]
	v_mov_b32_e32 v81, v78
	v_mov_b32_e32 v83, v87
	v_pk_add_f32 v[88:89], v[80:81], v[82:83] neg_lo:[0,1] neg_hi:[0,1]
	v_pk_add_f32 v[80:81], v[80:81], v[82:83]
	v_mov_b32_e32 v84, v85
	v_pk_add_f32 v[82:83], v[80:81], v[78:79] op_sel:[1,0] op_sel_hi:[0,1] neg_lo:[0,1] neg_hi:[0,1]
	v_pk_add_f32 v[90:91], v[86:87], v[82:83] op_sel_hi:[1,0] neg_lo:[0,1] neg_hi:[0,1]
	v_mov_b32_e32 v86, v87
	v_mov_b32_e32 v87, v81
	v_pk_mov_b32 v[82:83], v[78:79], v[82:83] op_sel:[1,0]
	v_mov_b32_e32 v85, v78
	v_pk_add_f32 v[82:83], v[86:87], v[82:83] neg_lo:[0,1] neg_hi:[0,1]
	v_mov_b32_e32 v90, v88
	v_pk_add_f32 v[78:79], v[84:85], v[82:83] neg_lo:[0,1] neg_hi:[0,1]
	v_mov_b32_e32 v89, v81
	v_pk_add_f32 v[82:83], v[90:91], v[78:79]
	s_nop 0
	v_pk_add_f32 v[84:85], v[82:83], v[82:83] op_sel:[0,1] op_sel_hi:[1,0]
	s_nop 0
	v_pk_add_f32 v[80:81], v[80:81], v[84:85] op_sel:[1,0] op_sel_hi:[0,1]
	v_mov_b32_e32 v83, v80
	v_pk_add_f32 v[86:87], v[82:83], v[88:89] neg_lo:[0,1] neg_hi:[0,1]
	v_mov_b32_e32 v79, v84
	v_sub_f32_e32 v77, v82, v86
	v_pk_add_f32 v[78:79], v[78:79], v[86:87] neg_lo:[0,1] neg_hi:[0,1]
	v_sub_f32_e32 v77, v88, v77
	v_add_f32_e32 v77, v78, v77
	v_add_f32_e32 v77, v77, v79
	v_add_f32_e32 v77, v80, v77
	v_cndmask_b32_e32 v77, v224, v77, vcc
	v_cmp_ngt_f32_e32 vcc, -1.0, v76
	s_nop 1
	v_cndmask_b32_e32 v77, v225, v77, vcc
	v_cmp_neq_f32_e32 vcc, -1.0, v76
	s_nop 1
	v_cndmask_b32_e32 v77, v226, v77, vcc
	v_cmp_lt_f32_e64 vcc, |v76|, s56
	s_nop 1
	v_cndmask_b32_e32 v76, v77, v76, vcc
	v_add_f32_e32 v75, v75, v76

.LBB0_1138:
	s_and_b64 vcc, exec, s[4:5]
	v_or_b32_e32 v69, 3, v74
	s_cbranch_vccnz .LBB0_1684
	s_andn2_b64 vcc, exec, s[36:37]
	v_mov_b32_e32 v75, v57
	s_cbranch_vccnz .LBB0_1141
	s_nop 0
	v_lshl_add_u64 v[76:77], v[66:67], 0, s[80:81]
	s_waitcnt lgkmcnt(0)
	v_lshl_add_u64 v[76:77], v[76:77], 2, s[58:59]
	v_mov_b32_e32 v75, v250
	s_nop 0
	v_add_f32_e32 v76, v57, v75
	v_max_f32_e32 v75, 0, v76
	v_mul_f32_e64 v76, |v76|, s73
	v_exp_f32_e32 v76, v76
	s_nop 0
	v_add_f32_e32 v77, 1.0, v76
	v_add_f32_e32 v78, -1.0, v77
	v_sub_f32_e32 v79, v78, v77
	v_add_f32_e32 v79, 1.0, v79
	v_sub_f32_e32 v78, v76, v78
	v_add_f32_e32 v80, v78, v79
	v_frexp_mant_f32_e32 v78, v77
	v_cmp_gt_f32_e32 vcc, s46, v78
	v_cvt_f64_f32_e32 v[78:79], v77
	v_frexp_exp_i32_f64_e32 v78, v[78:79]
	v_subbrev_co_u32_e32 v86, vcc, 0, v78, vcc
	v_sub_u32_e32 v78, 0, v86
	v_ldexp_f32 v77, v77, v78
	v_ldexp_f32 v78, v80, v78
	v_add_f32_e32 v80, -1.0, v77
	v_add_f32_e32 v79, 1.0, v80
	v_sub_f32_e32 v79, v77, v79
	v_add_f32_e32 v81, v78, v79
	v_add_f32_e32 v79, 1.0, v77
	v_add_f32_e32 v82, -1.0, v79
	v_sub_f32_e32 v77, v77, v82
	v_add_f32_e32 v77, v78, v77
	v_add_f32_e32 v87, v79, v77
	v_rcp_f32_e32 v88, v87
	v_sub_f32_e32 v78, v87, v79
	v_add_f32_e32 v79, v80, v81
	v_sub_f32_e32 v77, v77, v78
	v_mul_f32_e32 v90, v79, v88
	v_sub_f32_e32 v78, v79, v80
	v_mul_f32_e32 v80, v87, v90
	v_fma_f32 v82, v90, v87, -v80
	v_fmac_f32_e32 v82, v90, v77
	v_sub_f32_e32 v89, v81, v78
	v_add_f32_e32 v78, v80, v82
	v_sub_f32_e32 v81, v79, v78
	v_pk_add_f32 v[84:85], v[78:79], v[80:81] neg_lo:[0,1] neg_hi:[0,1]
	v_mov_b32_e32 v83, v78
	v_pk_add_f32 v[78:79], v[84:85], v[82:83] neg_lo:[0,1] neg_hi:[0,1]
	v_cmp_neq_f32_e32 vcc, s0, v76
	v_add_f32_e32 v79, v89, v79
	v_add_f32_e32 v78, v78, v79
	v_add_f32_e32 v79, v81, v78
	v_mul_f32_e32 v89, v88, v79
	v_mul_f32_e32 v80, v87, v89
	v_fma_f32 v82, v89, v87, -v80
	v_fmac_f32_e32 v82, v89, v77
	v_sub_f32_e32 v77, v81, v79
	v_add_f32_e32 v77, v78, v77
	v_add_f32_e32 v78, v80, v82
	v_sub_f32_e32 v81, v79, v78
	v_pk_add_f32 v[84:85], v[78:79], v[80:81] neg_lo:[0,1] neg_hi:[0,1]
	v_mov_b32_e32 v83, v78
	v_pk_add_f32 v[78:79], v[84:85], v[82:83] neg_lo:[0,1] neg_hi:[0,1]
	s_nop 0
	v_add_f32_e32 v77, v77, v79
	v_add_f32_e32 v77, v78, v77
	v_add_f32_e32 v79, v90, v89
	v_add_f32_e32 v77, v81, v77
	v_sub_f32_e32 v78, v79, v90
	v_mul_f32_e32 v77, v88, v77
	v_sub_f32_e32 v78, v89, v78
	v_add_f32_e32 v77, v78, v77
	v_add_f32_e32 v80, v79, v77
	v_mul_f32_e32 v82, v80, v80
	v_fmamk_f32 v78, v82, 0x3e9b6dac, v210
	v_fmaak_f32 v121, v82, v78, 0x3f2aaada
	v_cvt_f32_i32_e32 v78, v86
	v_sub_f32_e32 v79, v80, v79
	v_sub_f32_e32 v77, v77, v79
	v_mul_f32_e32 v79, v80, v82
	v_pk_mul_f32 v[82:83], v[78:79], v[120:121]
	v_ldexp_f32 v81, v80, 1
	v_fma_f32 v80, v78, s1, -v82
	v_fmac_f32_e32 v80, 0xb102e308, v78
	v_pk_add_f32 v[78:79], v[82:83], v[80:81]
	v_ldexp_f32 v77, v77, 1
	v_sub_f32_e32 v81, v79, v81
	v_sub_f32_e32 v81, v83, v81
	v_add_f32_e32 v85, v77, v81
	v_mov_b32_e32 v84, v82
	v_pk_add_f32 v[82:83], v[78:79], v[82:83] neg_lo:[0,1] neg_hi:[0,1]
	v_pk_add_f32 v[86:87], v[78:79], v[84:85]
	v_mov_b32_e32 v81, v78
	v_mov_b32_e32 v83, v87
	v_pk_add_f32 v[88:89], v[80:81], v[82:83] neg_lo:[0,1] neg_hi:[0,1]
	v_pk_add_f32 v[80:81], v[80:81], v[82:83]
	v_mov_b32_e32 v84, v85
	v_pk_add_f32 v[82:83], v[80:81], v[78:79] op_sel:[1,0] op_sel_hi:[0,1] neg_lo:[0,1] neg_hi:[0,1]
	v_pk_add_f32 v[90:91], v[86:87], v[82:83] op_sel_hi:[1,0] neg_lo:[0,1] neg_hi:[0,1]
	v_mov_b32_e32 v86, v87
	v_mov_b32_e32 v87, v81
	v_pk_mov_b32 v[82:83], v[78:79], v[82:83] op_sel:[1,0]
	v_mov_b32_e32 v85, v78
	v_pk_add_f32 v[82:83], v[86:87], v[82:83] neg_lo:[0,1] neg_hi:[0,1]
	v_mov_b32_e32 v90, v88
	v_pk_add_f32 v[78:79], v[84:85], v[82:83] neg_lo:[0,1] neg_hi:[0,1]
	v_mov_b32_e32 v89, v81
	v_pk_add_f32 v[82:83], v[90:91], v[78:79]
	s_nop 0
	v_pk_add_f32 v[84:85], v[82:83], v[82:83] op_sel:[0,1] op_sel_hi:[1,0]
	s_nop 0
	v_pk_add_f32 v[80:81], v[80:81], v[84:85] op_sel:[1,0] op_sel_hi:[0,1]
	v_mov_b32_e32 v83, v80
	v_pk_add_f32 v[86:87], v[82:83], v[88:89] neg_lo:[0,1] neg_hi:[0,1]
	v_mov_b32_e32 v79, v84
	v_sub_f32_e32 v77, v82, v86
	v_pk_add_f32 v[78:79], v[78:79], v[86:87] neg_lo:[0,1] neg_hi:[0,1]
	v_sub_f32_e32 v77, v88, v77
	v_add_f32_e32 v77, v78, v77
	v_add_f32_e32 v77, v77, v79
	v_add_f32_e32 v77, v80, v77
	v_cndmask_b32_e32 v77, v224, v77, vcc
	v_cmp_ngt_f32_e32 vcc, -1.0, v76
	s_nop 1
	v_cndmask_b32_e32 v77, v225, v77, vcc
	v_cmp_neq_f32_e32 vcc, -1.0, v76
	s_nop 1
	v_cndmask_b32_e32 v77, v226, v77, vcc
	v_cmp_lt_f32_e64 vcc, |v76|, s56
	s_nop 1
	v_cndmask_b32_e32 v76, v77, v76, vcc
	v_add_f32_e32 v75, v75, v76

.LBB0_1143:
	s_or_b64 exec, exec, s[12:13]
	v_add_u32_e32 v69, 48, v66
	v_cmp_gt_i32_e64 s[12:13], s52, v69
	s_and_saveexec_b64 s[58:59], s[12:13]
	s_cbranch_execz .LBB0_1164
	s_and_b64 vcc, exec, s[4:5]
	v_lshl_add_u64 v[70:71], v[66:67], 2, s[34:35]
	s_cbranch_vccnz .LBB0_1685
	s_andn2_b64 vcc, exec, s[36:37]
	v_mov_b32_e32 v69, v50
	s_cbranch_vccnz .LBB0_1147
	s_load_dwordx2 vcc, s[14:15], 0xb0
	v_lshl_add_u64 v[72:73], v[66:67], 0, s[80:81]
	s_waitcnt lgkmcnt(0)
	v_lshl_add_u64 v[72:73], v[72:73], 2, vcc
	global_load_dword v69, v[72:73], off offset:192
	s_waitcnt vmcnt(0)
	v_mov_b32_e32 v251, v69
	v_add_f32_e32 v72, v50, v69
	v_max_f32_e32 v69, 0, v72
	v_mul_f32_e64 v72, |v72|, s73
	v_exp_f32_e32 v72, v72
	s_nop 0
	v_add_f32_e32 v73, 1.0, v72
	v_add_f32_e32 v75, -1.0, v73
	v_sub_f32_e32 v76, v75, v73
	v_add_f32_e32 v76, 1.0, v76
	v_sub_f32_e32 v75, v72, v75
	v_add_f32_e32 v75, v75, v76
	v_frexp_mant_f32_e32 v76, v73
	v_cmp_gt_f32_e32 vcc, s46, v76
	v_cvt_f64_f32_e32 v[76:77], v73
	v_frexp_exp_i32_f64_e32 v76, v[76:77]
	v_subbrev_co_u32_e32 v84, vcc, 0, v76, vcc
	v_sub_u32_e32 v76, 0, v84
	v_ldexp_f32 v73, v73, v76
	v_ldexp_f32 v75, v75, v76
	v_add_f32_e32 v76, -1.0, v73
	v_add_f32_e32 v77, 1.0, v76
	v_sub_f32_e32 v77, v73, v77
	v_add_f32_e32 v78, v75, v77
	v_add_f32_e32 v77, 1.0, v73
	v_add_f32_e32 v79, -1.0, v77
	v_sub_f32_e32 v73, v73, v79
	v_add_f32_e32 v73, v75, v73
	v_add_f32_e32 v75, v77, v73
	v_rcp_f32_e32 v85, v75
	v_sub_f32_e32 v77, v75, v77
	v_sub_f32_e32 v73, v73, v77
	v_add_f32_e32 v77, v76, v78
	v_sub_f32_e32 v76, v77, v76
	v_mul_f32_e32 v87, v77, v85
	v_sub_f32_e32 v86, v78, v76
	v_mul_f32_e32 v78, v75, v87
	v_fma_f32 v80, v87, v75, -v78
	v_fmac_f32_e32 v80, v87, v73
	v_add_f32_e32 v76, v78, v80
	v_sub_f32_e32 v79, v77, v76
	v_pk_add_f32 v[82:83], v[76:77], v[78:79] neg_lo:[0,1] neg_hi:[0,1]
	v_mov_b32_e32 v81, v76
	v_pk_add_f32 v[76:77], v[82:83], v[80:81] neg_lo:[0,1] neg_hi:[0,1]
	v_cmp_neq_f32_e32 vcc, s0, v72
	v_add_f32_e32 v77, v86, v77
	v_add_f32_e32 v76, v76, v77
	v_add_f32_e32 v77, v79, v76
	v_mul_f32_e32 v86, v85, v77
	v_mul_f32_e32 v78, v75, v86
	v_fma_f32 v80, v86, v75, -v78
	v_fmac_f32_e32 v80, v86, v73
	v_sub_f32_e32 v73, v79, v77
	v_add_f32_e32 v73, v76, v73
	v_add_f32_e32 v76, v78, v80
	v_sub_f32_e32 v79, v77, v76
	v_pk_add_f32 v[82:83], v[76:77], v[78:79] neg_lo:[0,1] neg_hi:[0,1]
	v_mov_b32_e32 v81, v76
	v_pk_add_f32 v[76:77], v[82:83], v[80:81] neg_lo:[0,1] neg_hi:[0,1]
	v_add_f32_e32 v75, v87, v86
	v_add_f32_e32 v73, v73, v77
	v_add_f32_e32 v73, v76, v73
	v_add_f32_e32 v73, v79, v73
	v_sub_f32_e32 v76, v75, v87
	v_mul_f32_e32 v73, v85, v73
	v_sub_f32_e32 v76, v86, v76
	v_add_f32_e32 v73, v76, v73
	v_add_f32_e32 v77, v75, v73
	v_mul_f32_e32 v78, v77, v77
	v_fmamk_f32 v76, v78, 0x3e9b6dac, v210
	v_fmaak_f32 v121, v78, v76, 0x3f2aaada
	v_cvt_f32_i32_e32 v76, v84
	v_sub_f32_e32 v75, v77, v75
	v_ldexp_f32 v79, v77, 1
	v_mul_f32_e32 v77, v77, v78
	v_pk_mul_f32 v[80:81], v[76:77], v[120:121]
	v_sub_f32_e32 v73, v73, v75
	v_fma_f32 v78, v76, s1, -v80
	v_fmac_f32_e32 v78, 0xb102e308, v76
	v_pk_add_f32 v[76:77], v[80:81], v[78:79]
	v_ldexp_f32 v73, v73, 1
	v_sub_f32_e32 v75, v77, v79
	v_sub_f32_e32 v75, v81, v75
	v_add_f32_e32 v83, v73, v75
	v_mov_b32_e32 v82, v80
	v_pk_add_f32 v[80:81], v[76:77], v[80:81] neg_lo:[0,1] neg_hi:[0,1]
	v_pk_add_f32 v[84:85], v[76:77], v[82:83]
	v_mov_b32_e32 v79, v76
	v_mov_b32_e32 v81, v85
	v_pk_add_f32 v[86:87], v[78:79], v[80:81] neg_lo:[0,1] neg_hi:[0,1]
	v_pk_add_f32 v[78:79], v[78:79], v[80:81]
	v_mov_b32_e32 v82, v83
	v_pk_add_f32 v[80:81], v[78:79], v[76:77] op_sel:[1,0] op_sel_hi:[0,1] neg_lo:[0,1] neg_hi:[0,1]
	v_pk_add_f32 v[88:89], v[84:85], v[80:81] op_sel_hi:[1,0] neg_lo:[0,1] neg_hi:[0,1]
	v_mov_b32_e32 v84, v85
	v_mov_b32_e32 v85, v79
	v_pk_mov_b32 v[80:81], v[76:77], v[80:81] op_sel:[1,0]
	v_mov_b32_e32 v83, v76
	v_pk_add_f32 v[80:81], v[84:85], v[80:81] neg_lo:[0,1] neg_hi:[0,1]
	v_mov_b32_e32 v88, v86
	v_pk_add_f32 v[76:77], v[82:83], v[80:81] neg_lo:[0,1] neg_hi:[0,1]
	v_mov_b32_e32 v87, v79
	v_pk_add_f32 v[80:81], v[88:89], v[76:77]
	s_nop 0
	v_pk_add_f32 v[82:83], v[80:81], v[80:81] op_sel:[0,1] op_sel_hi:[1,0]
	s_nop 0
	v_pk_add_f32 v[78:79], v[78:79], v[82:83] op_sel:[1,0] op_sel_hi:[0,1]
	v_mov_b32_e32 v81, v78
	v_pk_add_f32 v[84:85], v[80:81], v[86:87] neg_lo:[0,1] neg_hi:[0,1]
	v_mov_b32_e32 v77, v82
	v_sub_f32_e32 v73, v80, v84
	v_pk_add_f32 v[76:77], v[76:77], v[84:85] neg_lo:[0,1] neg_hi:[0,1]
	v_sub_f32_e32 v73, v86, v73
	v_add_f32_e32 v73, v76, v73
	v_add_f32_e32 v73, v73, v77
	v_add_f32_e32 v73, v78, v73
	v_cndmask_b32_e32 v73, v224, v73, vcc
	v_cmp_ngt_f32_e32 vcc, -1.0, v72
	s_nop 1
	v_cndmask_b32_e32 v73, v225, v73, vcc
	v_cmp_neq_f32_e32 vcc, -1.0, v72
	s_nop 1
	v_cndmask_b32_e32 v73, v226, v73, vcc
	v_cmp_lt_f32_e64 vcc, |v72|, s56
	s_nop 1
	v_cndmask_b32_e32 v72, v73, v72, vcc
	v_add_f32_e32 v69, v69, v72

.LBB0_1149:
	s_and_b64 vcc, exec, s[4:5]
	v_or_b32_e32 v69, 1, v74
	s_cbranch_vccnz .LBB0_1686
	s_andn2_b64 vcc, exec, s[36:37]
	v_mov_b32_e32 v75, v51
	s_cbranch_vccnz .LBB0_1152
	s_nop 0
	v_lshl_add_u64 v[76:77], v[66:67], 0, s[80:81]
	s_waitcnt lgkmcnt(0)
	v_lshl_add_u64 v[76:77], v[76:77], 2, vcc
	v_mov_b32_e32 v75, v251
	s_nop 0
	v_add_f32_e32 v76, v51, v75
	v_max_f32_e32 v75, 0, v76
	v_mul_f32_e64 v76, |v76|, s73
	v_exp_f32_e32 v76, v76
	s_nop 0
	v_add_f32_e32 v77, 1.0, v76
	v_add_f32_e32 v78, -1.0, v77
	v_sub_f32_e32 v79, v78, v77
	v_add_f32_e32 v79, 1.0, v79
	v_sub_f32_e32 v78, v76, v78
	v_add_f32_e32 v80, v78, v79
	v_frexp_mant_f32_e32 v78, v77
	v_cmp_gt_f32_e32 vcc, s46, v78
	v_cvt_f64_f32_e32 v[78:79], v77
	v_frexp_exp_i32_f64_e32 v78, v[78:79]
	v_subbrev_co_u32_e32 v86, vcc, 0, v78, vcc
	v_sub_u32_e32 v78, 0, v86
	v_ldexp_f32 v77, v77, v78
	v_ldexp_f32 v78, v80, v78
	v_add_f32_e32 v80, -1.0, v77
	v_add_f32_e32 v79, 1.0, v80
	v_sub_f32_e32 v79, v77, v79
	v_add_f32_e32 v81, v78, v79
	v_add_f32_e32 v79, 1.0, v77
	v_add_f32_e32 v82, -1.0, v79
	v_sub_f32_e32 v77, v77, v82
	v_add_f32_e32 v77, v78, v77
	v_add_f32_e32 v87, v79, v77
	v_rcp_f32_e32 v88, v87
	v_sub_f32_e32 v78, v87, v79
	v_add_f32_e32 v79, v80, v81
	v_sub_f32_e32 v77, v77, v78
	v_mul_f32_e32 v90, v79, v88
	v_sub_f32_e32 v78, v79, v80
	v_mul_f32_e32 v80, v87, v90
	v_fma_f32 v82, v90, v87, -v80
	v_fmac_f32_e32 v82, v90, v77
	v_sub_f32_e32 v89, v81, v78
	v_add_f32_e32 v78, v80, v82
	v_sub_f32_e32 v81, v79, v78
	v_pk_add_f32 v[84:85], v[78:79], v[80:81] neg_lo:[0,1] neg_hi:[0,1]
	v_mov_b32_e32 v83, v78
	v_pk_add_f32 v[78:79], v[84:85], v[82:83] neg_lo:[0,1] neg_hi:[0,1]
	v_cmp_neq_f32_e32 vcc, s0, v76
	v_add_f32_e32 v79, v89, v79
	v_add_f32_e32 v78, v78, v79
	v_add_f32_e32 v79, v81, v78
	v_mul_f32_e32 v89, v88, v79
	v_mul_f32_e32 v80, v87, v89
	v_fma_f32 v82, v89, v87, -v80
	v_fmac_f32_e32 v82, v89, v77
	v_sub_f32_e32 v77, v81, v79
	v_add_f32_e32 v77, v78, v77
	v_add_f32_e32 v78, v80, v82
	v_sub_f32_e32 v81, v79, v78
	v_pk_add_f32 v[84:85], v[78:79], v[80:81] neg_lo:[0,1] neg_hi:[0,1]
	v_mov_b32_e32 v83, v78
	v_pk_add_f32 v[78:79], v[84:85], v[82:83] neg_lo:[0,1] neg_hi:[0,1]
	s_nop 0
	v_add_f32_e32 v77, v77, v79
	v_add_f32_e32 v77, v78, v77
	v_add_f32_e32 v79, v90, v89
	v_add_f32_e32 v77, v81, v77
	v_sub_f32_e32 v78, v79, v90
	v_mul_f32_e32 v77, v88, v77
	v_sub_f32_e32 v78, v89, v78
	v_add_f32_e32 v77, v78, v77
	v_add_f32_e32 v80, v79, v77
	v_mul_f32_e32 v82, v80, v80
	v_fmamk_f32 v78, v82, 0x3e9b6dac, v210
	v_fmaak_f32 v121, v82, v78, 0x3f2aaada
	v_cvt_f32_i32_e32 v78, v86
	v_sub_f32_e32 v79, v80, v79
	v_sub_f32_e32 v77, v77, v79
	v_mul_f32_e32 v79, v80, v82
	v_pk_mul_f32 v[82:83], v[78:79], v[120:121]
	v_ldexp_f32 v81, v80, 1
	v_fma_f32 v80, v78, s1, -v82
	v_fmac_f32_e32 v80, 0xb102e308, v78
	v_pk_add_f32 v[78:79], v[82:83], v[80:81]
	v_ldexp_f32 v77, v77, 1
	v_sub_f32_e32 v81, v79, v81
	v_sub_f32_e32 v81, v83, v81
	v_add_f32_e32 v85, v77, v81
	v_mov_b32_e32 v84, v82
	v_pk_add_f32 v[82:83], v[78:79], v[82:83] neg_lo:[0,1] neg_hi:[0,1]
	v_pk_add_f32 v[86:87], v[78:79], v[84:85]
	v_mov_b32_e32 v81, v78
	v_mov_b32_e32 v83, v87
	v_pk_add_f32 v[88:89], v[80:81], v[82:83] neg_lo:[0,1] neg_hi:[0,1]
	v_pk_add_f32 v[80:81], v[80:81], v[82:83]
	v_mov_b32_e32 v84, v85
	v_pk_add_f32 v[82:83], v[80:81], v[78:79] op_sel:[1,0] op_sel_hi:[0,1] neg_lo:[0,1] neg_hi:[0,1]
	v_pk_add_f32 v[90:91], v[86:87], v[82:83] op_sel_hi:[1,0] neg_lo:[0,1] neg_hi:[0,1]
	v_mov_b32_e32 v86, v87
	v_mov_b32_e32 v87, v81
	v_pk_mov_b32 v[82:83], v[78:79], v[82:83] op_sel:[1,0]
	v_mov_b32_e32 v85, v78
	v_pk_add_f32 v[82:83], v[86:87], v[82:83] neg_lo:[0,1] neg_hi:[0,1]
	v_mov_b32_e32 v90, v88
	v_pk_add_f32 v[78:79], v[84:85], v[82:83] neg_lo:[0,1] neg_hi:[0,1]
	v_mov_b32_e32 v89, v81
	v_pk_add_f32 v[82:83], v[90:91], v[78:79]
	s_nop 0
	v_pk_add_f32 v[84:85], v[82:83], v[82:83] op_sel:[0,1] op_sel_hi:[1,0]
	s_nop 0
	v_pk_add_f32 v[80:81], v[80:81], v[84:85] op_sel:[1,0] op_sel_hi:[0,1]
	v_mov_b32_e32 v83, v80
	v_pk_add_f32 v[86:87], v[82:83], v[88:89] neg_lo:[0,1] neg_hi:[0,1]
	v_mov_b32_e32 v79, v84
	v_sub_f32_e32 v77, v82, v86
	v_pk_add_f32 v[78:79], v[78:79], v[86:87] neg_lo:[0,1] neg_hi:[0,1]
	v_sub_f32_e32 v77, v88, v77
	v_add_f32_e32 v77, v78, v77
	v_add_f32_e32 v77, v77, v79
	v_add_f32_e32 v77, v80, v77
	v_cndmask_b32_e32 v77, v224, v77, vcc
	v_cmp_ngt_f32_e32 vcc, -1.0, v76
	s_nop 1
	v_cndmask_b32_e32 v77, v225, v77, vcc
	v_cmp_neq_f32_e32 vcc, -1.0, v76
	s_nop 1
	v_cndmask_b32_e32 v77, v226, v77, vcc
	v_cmp_lt_f32_e64 vcc, |v76|, s56
	s_nop 1
	v_cndmask_b32_e32 v76, v77, v76, vcc
	v_add_f32_e32 v75, v75, v76

.LBB0_1154:
	s_and_b64 vcc, exec, s[4:5]
	v_or_b32_e32 v69, 2, v74
	s_cbranch_vccnz .LBB0_1687
	s_andn2_b64 vcc, exec, s[36:37]
	v_mov_b32_e32 v75, v52
	s_cbranch_vccnz .LBB0_1157
	s_nop 0
	v_lshl_add_u64 v[76:77], v[66:67], 0, s[80:81]
	s_waitcnt lgkmcnt(0)
	v_lshl_add_u64 v[76:77], v[76:77], 2, vcc
	v_mov_b32_e32 v75, v251
	s_nop 0
	v_add_f32_e32 v76, v52, v75
	v_max_f32_e32 v75, 0, v76
	v_mul_f32_e64 v76, |v76|, s73
	v_exp_f32_e32 v76, v76
	s_nop 0
	v_add_f32_e32 v77, 1.0, v76
	v_add_f32_e32 v78, -1.0, v77
	v_sub_f32_e32 v79, v78, v77
	v_add_f32_e32 v79, 1.0, v79
	v_sub_f32_e32 v78, v76, v78
	v_add_f32_e32 v80, v78, v79
	v_frexp_mant_f32_e32 v78, v77
	v_cmp_gt_f32_e32 vcc, s46, v78
	v_cvt_f64_f32_e32 v[78:79], v77
	v_frexp_exp_i32_f64_e32 v78, v[78:79]
	v_subbrev_co_u32_e32 v86, vcc, 0, v78, vcc
	v_sub_u32_e32 v78, 0, v86
	v_ldexp_f32 v77, v77, v78
	v_ldexp_f32 v78, v80, v78
	v_add_f32_e32 v80, -1.0, v77
	v_add_f32_e32 v79, 1.0, v80
	v_sub_f32_e32 v79, v77, v79
	v_add_f32_e32 v81, v78, v79
	v_add_f32_e32 v79, 1.0, v77
	v_add_f32_e32 v82, -1.0, v79
	v_sub_f32_e32 v77, v77, v82
	v_add_f32_e32 v77, v78, v77
	v_add_f32_e32 v87, v79, v77
	v_rcp_f32_e32 v88, v87
	v_sub_f32_e32 v78, v87, v79
	v_add_f32_e32 v79, v80, v81
	v_sub_f32_e32 v77, v77, v78
	v_mul_f32_e32 v90, v79, v88
	v_sub_f32_e32 v78, v79, v80
	v_mul_f32_e32 v80, v87, v90
	v_fma_f32 v82, v90, v87, -v80
	v_fmac_f32_e32 v82, v90, v77
	v_sub_f32_e32 v89, v81, v78
	v_add_f32_e32 v78, v80, v82
	v_sub_f32_e32 v81, v79, v78
	v_pk_add_f32 v[84:85], v[78:79], v[80:81] neg_lo:[0,1] neg_hi:[0,1]
	v_mov_b32_e32 v83, v78
	v_pk_add_f32 v[78:79], v[84:85], v[82:83] neg_lo:[0,1] neg_hi:[0,1]
	v_cmp_neq_f32_e32 vcc, s0, v76
	v_add_f32_e32 v79, v89, v79
	v_add_f32_e32 v78, v78, v79
	v_add_f32_e32 v79, v81, v78
	v_mul_f32_e32 v89, v88, v79
	v_mul_f32_e32 v80, v87, v89
	v_fma_f32 v82, v89, v87, -v80
	v_fmac_f32_e32 v82, v89, v77
	v_sub_f32_e32 v77, v81, v79
	v_add_f32_e32 v77, v78, v77
	v_add_f32_e32 v78, v80, v82
	v_sub_f32_e32 v81, v79, v78
	v_pk_add_f32 v[84:85], v[78:79], v[80:81] neg_lo:[0,1] neg_hi:[0,1]
	v_mov_b32_e32 v83, v78
	v_pk_add_f32 v[78:79], v[84:85], v[82:83] neg_lo:[0,1] neg_hi:[0,1]
	s_nop 0
	v_add_f32_e32 v77, v77, v79
	v_add_f32_e32 v77, v78, v77
	v_add_f32_e32 v79, v90, v89
	v_add_f32_e32 v77, v81, v77
	v_sub_f32_e32 v78, v79, v90
	v_mul_f32_e32 v77, v88, v77
	v_sub_f32_e32 v78, v89, v78
	v_add_f32_e32 v77, v78, v77
	v_add_f32_e32 v80, v79, v77
	v_mul_f32_e32 v82, v80, v80
	v_fmamk_f32 v78, v82, 0x3e9b6dac, v210
	v_fmaak_f32 v121, v82, v78, 0x3f2aaada
	v_cvt_f32_i32_e32 v78, v86
	v_sub_f32_e32 v79, v80, v79
	v_sub_f32_e32 v77, v77, v79
	v_mul_f32_e32 v79, v80, v82
	v_pk_mul_f32 v[82:83], v[78:79], v[120:121]
	v_ldexp_f32 v81, v80, 1
	v_fma_f32 v80, v78, s1, -v82
	v_fmac_f32_e32 v80, 0xb102e308, v78
	v_pk_add_f32 v[78:79], v[82:83], v[80:81]
	v_ldexp_f32 v77, v77, 1
	v_sub_f32_e32 v81, v79, v81
	v_sub_f32_e32 v81, v83, v81
	v_add_f32_e32 v85, v77, v81
	v_mov_b32_e32 v84, v82
	v_pk_add_f32 v[82:83], v[78:79], v[82:83] neg_lo:[0,1] neg_hi:[0,1]
	v_pk_add_f32 v[86:87], v[78:79], v[84:85]
	v_mov_b32_e32 v81, v78
	v_mov_b32_e32 v83, v87
	v_pk_add_f32 v[88:89], v[80:81], v[82:83] neg_lo:[0,1] neg_hi:[0,1]
	v_pk_add_f32 v[80:81], v[80:81], v[82:83]
	v_mov_b32_e32 v84, v85
	v_pk_add_f32 v[82:83], v[80:81], v[78:79] op_sel:[1,0] op_sel_hi:[0,1] neg_lo:[0,1] neg_hi:[0,1]
	v_pk_add_f32 v[90:91], v[86:87], v[82:83] op_sel_hi:[1,0] neg_lo:[0,1] neg_hi:[0,1]
	v_mov_b32_e32 v86, v87
	v_mov_b32_e32 v87, v81
	v_pk_mov_b32 v[82:83], v[78:79], v[82:83] op_sel:[1,0]
	v_mov_b32_e32 v85, v78
	v_pk_add_f32 v[82:83], v[86:87], v[82:83] neg_lo:[0,1] neg_hi:[0,1]
	v_mov_b32_e32 v90, v88
	v_pk_add_f32 v[78:79], v[84:85], v[82:83] neg_lo:[0,1] neg_hi:[0,1]
	v_mov_b32_e32 v89, v81
	v_pk_add_f32 v[82:83], v[90:91], v[78:79]
	s_nop 0
	v_pk_add_f32 v[84:85], v[82:83], v[82:83] op_sel:[0,1] op_sel_hi:[1,0]
	s_nop 0
	v_pk_add_f32 v[80:81], v[80:81], v[84:85] op_sel:[1,0] op_sel_hi:[0,1]
	v_mov_b32_e32 v83, v80
	v_pk_add_f32 v[86:87], v[82:83], v[88:89] neg_lo:[0,1] neg_hi:[0,1]
	v_mov_b32_e32 v79, v84
	v_sub_f32_e32 v77, v82, v86
	v_pk_add_f32 v[78:79], v[78:79], v[86:87] neg_lo:[0,1] neg_hi:[0,1]
	v_sub_f32_e32 v77, v88, v77
	v_add_f32_e32 v77, v78, v77
	v_add_f32_e32 v77, v77, v79
	v_add_f32_e32 v77, v80, v77
	v_cndmask_b32_e32 v77, v224, v77, vcc
	v_cmp_ngt_f32_e32 vcc, -1.0, v76
	s_nop 1
	v_cndmask_b32_e32 v77, v225, v77, vcc
	v_cmp_neq_f32_e32 vcc, -1.0, v76
	s_nop 1
	v_cndmask_b32_e32 v77, v226, v77, vcc
	v_cmp_lt_f32_e64 vcc, |v76|, s56
	s_nop 1
	v_cndmask_b32_e32 v76, v77, v76, vcc
	v_add_f32_e32 v75, v75, v76

.LBB0_1159:
	s_and_b64 vcc, exec, s[4:5]
	v_or_b32_e32 v69, 3, v74
	s_cbranch_vccnz .LBB0_1688
	s_andn2_b64 vcc, exec, s[36:37]
	v_mov_b32_e32 v75, v53
	s_cbranch_vccnz .LBB0_1162
	s_nop 0
	v_lshl_add_u64 v[76:77], v[66:67], 0, s[80:81]
	s_waitcnt lgkmcnt(0)
	v_lshl_add_u64 v[76:77], v[76:77], 2, vcc
	v_mov_b32_e32 v75, v251
	s_nop 0
	v_add_f32_e32 v76, v53, v75
	v_max_f32_e32 v75, 0, v76
	v_mul_f32_e64 v76, |v76|, s73
	v_exp_f32_e32 v76, v76
	s_nop 0
	v_add_f32_e32 v77, 1.0, v76
	v_add_f32_e32 v78, -1.0, v77
	v_sub_f32_e32 v79, v78, v77
	v_add_f32_e32 v79, 1.0, v79
	v_sub_f32_e32 v78, v76, v78
	v_add_f32_e32 v80, v78, v79
	v_frexp_mant_f32_e32 v78, v77
	v_cmp_gt_f32_e32 vcc, s46, v78
	v_cvt_f64_f32_e32 v[78:79], v77
	v_frexp_exp_i32_f64_e32 v78, v[78:79]
	v_subbrev_co_u32_e32 v86, vcc, 0, v78, vcc
	v_sub_u32_e32 v78, 0, v86
	v_ldexp_f32 v77, v77, v78
	v_ldexp_f32 v78, v80, v78
	v_add_f32_e32 v80, -1.0, v77
	v_add_f32_e32 v79, 1.0, v80
	v_sub_f32_e32 v79, v77, v79
	v_add_f32_e32 v81, v78, v79
	v_add_f32_e32 v79, 1.0, v77
	v_add_f32_e32 v82, -1.0, v79
	v_sub_f32_e32 v77, v77, v82
	v_add_f32_e32 v77, v78, v77
	v_add_f32_e32 v87, v79, v77
	v_rcp_f32_e32 v88, v87
	v_sub_f32_e32 v78, v87, v79
	v_add_f32_e32 v79, v80, v81
	v_sub_f32_e32 v77, v77, v78
	v_mul_f32_e32 v90, v79, v88
	v_sub_f32_e32 v78, v79, v80
	v_mul_f32_e32 v80, v87, v90
	v_fma_f32 v82, v90, v87, -v80
	v_fmac_f32_e32 v82, v90, v77
	v_sub_f32_e32 v89, v81, v78
	v_add_f32_e32 v78, v80, v82
	v_sub_f32_e32 v81, v79, v78
	v_pk_add_f32 v[84:85], v[78:79], v[80:81] neg_lo:[0,1] neg_hi:[0,1]
	v_mov_b32_e32 v83, v78
	v_pk_add_f32 v[78:79], v[84:85], v[82:83] neg_lo:[0,1] neg_hi:[0,1]
	v_cmp_neq_f32_e32 vcc, s0, v76
	v_add_f32_e32 v79, v89, v79
	v_add_f32_e32 v78, v78, v79
	v_add_f32_e32 v79, v81, v78
	v_mul_f32_e32 v89, v88, v79
	v_mul_f32_e32 v80, v87, v89
	v_fma_f32 v82, v89, v87, -v80
	v_fmac_f32_e32 v82, v89, v77
	v_sub_f32_e32 v77, v81, v79
	v_add_f32_e32 v77, v78, v77
	v_add_f32_e32 v78, v80, v82
	v_sub_f32_e32 v81, v79, v78
	v_pk_add_f32 v[84:85], v[78:79], v[80:81] neg_lo:[0,1] neg_hi:[0,1]
	v_mov_b32_e32 v83, v78
	v_pk_add_f32 v[78:79], v[84:85], v[82:83] neg_lo:[0,1] neg_hi:[0,1]
	s_nop 0
	v_add_f32_e32 v77, v77, v79
	v_add_f32_e32 v77, v78, v77
	v_add_f32_e32 v79, v90, v89
	v_add_f32_e32 v77, v81, v77
	v_sub_f32_e32 v78, v79, v90
	v_mul_f32_e32 v77, v88, v77
	v_sub_f32_e32 v78, v89, v78
	v_add_f32_e32 v77, v78, v77
	v_add_f32_e32 v80, v79, v77
	v_mul_f32_e32 v82, v80, v80
	v_fmamk_f32 v78, v82, 0x3e9b6dac, v210
	v_fmaak_f32 v121, v82, v78, 0x3f2aaada
	v_cvt_f32_i32_e32 v78, v86
	v_sub_f32_e32 v79, v80, v79
	v_sub_f32_e32 v77, v77, v79
	v_mul_f32_e32 v79, v80, v82
	v_pk_mul_f32 v[82:83], v[78:79], v[120:121]
	v_ldexp_f32 v81, v80, 1
	v_fma_f32 v80, v78, s1, -v82
	v_fmac_f32_e32 v80, 0xb102e308, v78
	v_pk_add_f32 v[78:79], v[82:83], v[80:81]
	v_ldexp_f32 v77, v77, 1
	v_sub_f32_e32 v81, v79, v81
	v_sub_f32_e32 v81, v83, v81
	v_add_f32_e32 v85, v77, v81
	v_mov_b32_e32 v84, v82
	v_pk_add_f32 v[82:83], v[78:79], v[82:83] neg_lo:[0,1] neg_hi:[0,1]
	v_pk_add_f32 v[86:87], v[78:79], v[84:85]
	v_mov_b32_e32 v81, v78
	v_mov_b32_e32 v83, v87
	v_pk_add_f32 v[88:89], v[80:81], v[82:83] neg_lo:[0,1] neg_hi:[0,1]
	v_pk_add_f32 v[80:81], v[80:81], v[82:83]
	v_mov_b32_e32 v84, v85
	v_pk_add_f32 v[82:83], v[80:81], v[78:79] op_sel:[1,0] op_sel_hi:[0,1] neg_lo:[0,1] neg_hi:[0,1]
	v_pk_add_f32 v[90:91], v[86:87], v[82:83] op_sel_hi:[1,0] neg_lo:[0,1] neg_hi:[0,1]
	v_mov_b32_e32 v86, v87
	v_mov_b32_e32 v87, v81
	v_pk_mov_b32 v[82:83], v[78:79], v[82:83] op_sel:[1,0]
	v_mov_b32_e32 v85, v78
	v_pk_add_f32 v[82:83], v[86:87], v[82:83] neg_lo:[0,1] neg_hi:[0,1]
	v_mov_b32_e32 v90, v88
	v_pk_add_f32 v[78:79], v[84:85], v[82:83] neg_lo:[0,1] neg_hi:[0,1]
	v_mov_b32_e32 v89, v81
	v_pk_add_f32 v[82:83], v[90:91], v[78:79]
	s_nop 0
	v_pk_add_f32 v[84:85], v[82:83], v[82:83] op_sel:[0,1] op_sel_hi:[1,0]
	s_nop 0
	v_pk_add_f32 v[80:81], v[80:81], v[84:85] op_sel:[1,0] op_sel_hi:[0,1]
	v_mov_b32_e32 v83, v80
	v_pk_add_f32 v[86:87], v[82:83], v[88:89] neg_lo:[0,1] neg_hi:[0,1]
	v_mov_b32_e32 v79, v84
	v_sub_f32_e32 v77, v82, v86
	v_pk_add_f32 v[78:79], v[78:79], v[86:87] neg_lo:[0,1] neg_hi:[0,1]
	v_sub_f32_e32 v77, v88, v77
	v_add_f32_e32 v77, v78, v77
	v_add_f32_e32 v77, v77, v79
	v_add_f32_e32 v77, v80, v77
	v_cndmask_b32_e32 v77, v224, v77, vcc
	v_cmp_ngt_f32_e32 vcc, -1.0, v76
	s_nop 1
	v_cndmask_b32_e32 v77, v225, v77, vcc
	v_cmp_neq_f32_e32 vcc, -1.0, v76
	s_nop 1
	v_cndmask_b32_e32 v77, v226, v77, vcc
	v_cmp_lt_f32_e64 vcc, |v76|, s56
	s_nop 1
	v_cndmask_b32_e32 v76, v77, v76, vcc
	v_add_f32_e32 v75, v75, v76

.LBB0_1164:
	s_or_b64 exec, exec, s[58:59]
	v_or_b32_e32 v75, 16, v74
	s_and_saveexec_b64 s[58:59], s[6:7]
	s_cbranch_execz .LBB0_1185
	v_ashrrev_i32_e32 v69, 31, v68
	s_and_b64 vcc, exec, s[4:5]
	v_lshl_add_u64 v[70:71], v[66:67], 2, s[34:35]
	s_cbranch_vccnz .LBB0_1689
	s_andn2_b64 vcc, exec, s[36:37]
	v_mov_b32_e32 v72, v46
	s_cbranch_vccnz .LBB0_1168
	s_nop 0
	s_waitcnt lgkmcnt(0)
	v_lshl_add_u64 v[72:73], v[68:69], 2, vcc
	v_mov_b32_e32 v72, v248
	s_nop 0
	v_add_f32_e32 v73, v46, v72
	v_max_f32_e32 v72, 0, v73
	v_mul_f32_e64 v73, |v73|, s73
	v_exp_f32_e32 v73, v73
	s_nop 0
	v_add_f32_e32 v78, 1.0, v73
	v_add_f32_e32 v76, -1.0, v78
	v_sub_f32_e32 v77, v76, v78
	v_add_f32_e32 v77, 1.0, v77
	v_sub_f32_e32 v76, v73, v76
	v_add_f32_e32 v79, v76, v77
	v_frexp_mant_f32_e32 v76, v78
	v_cmp_gt_f32_e32 vcc, s46, v76
	v_cvt_f64_f32_e32 v[76:77], v78
	v_frexp_exp_i32_f64_e32 v76, v[76:77]
	v_subbrev_co_u32_e32 v84, vcc, 0, v76, vcc
	v_sub_u32_e32 v76, 0, v84
	v_ldexp_f32 v77, v78, v76
	v_add_f32_e32 v78, -1.0, v77
	v_add_f32_e32 v80, 1.0, v77
	v_ldexp_f32 v76, v79, v76
	v_add_f32_e32 v79, 1.0, v78
	v_add_f32_e32 v81, -1.0, v80
	v_sub_f32_e32 v79, v77, v79
	v_sub_f32_e32 v77, v77, v81
	v_add_f32_e32 v79, v76, v79
	v_add_f32_e32 v76, v76, v77
	v_add_f32_e32 v85, v80, v76
	v_rcp_f32_e32 v87, v85
	v_sub_f32_e32 v77, v85, v80
	v_sub_f32_e32 v86, v76, v77
	v_add_f32_e32 v77, v78, v79
	v_mul_f32_e32 v89, v77, v87
	v_sub_f32_e32 v76, v77, v78
	v_mul_f32_e32 v78, v85, v89
	v_fma_f32 v80, v89, v85, -v78
	v_fmac_f32_e32 v80, v89, v86
	v_sub_f32_e32 v88, v79, v76
	v_add_f32_e32 v76, v78, v80
	v_sub_f32_e32 v79, v77, v76
	v_pk_add_f32 v[82:83], v[76:77], v[78:79] neg_lo:[0,1] neg_hi:[0,1]
	v_mov_b32_e32 v81, v76
	v_pk_add_f32 v[76:77], v[82:83], v[80:81] neg_lo:[0,1] neg_hi:[0,1]
	v_cmp_neq_f32_e32 vcc, s0, v73
	v_add_f32_e32 v77, v88, v77
	v_add_f32_e32 v76, v76, v77
	v_add_f32_e32 v77, v79, v76
	v_mul_f32_e32 v88, v87, v77
	v_mul_f32_e32 v78, v85, v88
	v_fma_f32 v80, v88, v85, -v78
	v_fmac_f32_e32 v80, v88, v86
	v_sub_f32_e32 v79, v79, v77
	v_add_f32_e32 v85, v76, v79
	v_add_f32_e32 v76, v78, v80
	v_sub_f32_e32 v79, v77, v76
	v_pk_add_f32 v[82:83], v[76:77], v[78:79] neg_lo:[0,1] neg_hi:[0,1]
	v_mov_b32_e32 v81, v76
	v_pk_add_f32 v[76:77], v[82:83], v[80:81] neg_lo:[0,1] neg_hi:[0,1]
	s_nop 0
	v_add_f32_e32 v77, v85, v77
	v_add_f32_e32 v76, v76, v77
	v_add_f32_e32 v77, v89, v88
	v_add_f32_e32 v76, v79, v76
	v_sub_f32_e32 v78, v77, v89
	v_mul_f32_e32 v76, v87, v76
	v_sub_f32_e32 v78, v88, v78
	v_add_f32_e32 v78, v78, v76
	v_add_f32_e32 v80, v77, v78
	v_mul_f32_e32 v81, v80, v80
	v_fmamk_f32 v76, v81, 0x3e9b6dac, v210
	v_fmaak_f32 v121, v81, v76, 0x3f2aaada
	v_cvt_f32_i32_e32 v76, v84
	v_sub_f32_e32 v77, v80, v77
	v_sub_f32_e32 v77, v78, v77
	v_ldexp_f32 v82, v77, 1
	v_mul_f32_e32 v77, v80, v81
	v_ldexp_f32 v79, v80, 1
	v_pk_mul_f32 v[80:81], v[76:77], v[120:121]
	s_nop 0
	v_fma_f32 v78, v76, s1, -v80
	v_fmac_f32_e32 v78, 0xb102e308, v76
	v_pk_add_f32 v[76:77], v[80:81], v[78:79]
	s_nop 0
	v_sub_f32_e32 v79, v77, v79
	v_sub_f32_e32 v79, v81, v79
	v_add_f32_e32 v83, v82, v79
	v_mov_b32_e32 v82, v80
	v_pk_add_f32 v[80:81], v[76:77], v[80:81] neg_lo:[0,1] neg_hi:[0,1]
	v_pk_add_f32 v[84:85], v[76:77], v[82:83]
	v_mov_b32_e32 v79, v76
	v_mov_b32_e32 v81, v85
	v_pk_add_f32 v[86:87], v[78:79], v[80:81] neg_lo:[0,1] neg_hi:[0,1]
	v_pk_add_f32 v[78:79], v[78:79], v[80:81]
	v_mov_b32_e32 v82, v83
	v_pk_add_f32 v[80:81], v[78:79], v[76:77] op_sel:[1,0] op_sel_hi:[0,1] neg_lo:[0,1] neg_hi:[0,1]
	v_pk_add_f32 v[88:89], v[84:85], v[80:81] op_sel_hi:[1,0] neg_lo:[0,1] neg_hi:[0,1]
	v_mov_b32_e32 v84, v85
	v_mov_b32_e32 v85, v79
	v_pk_mov_b32 v[80:81], v[76:77], v[80:81] op_sel:[1,0]
	v_mov_b32_e32 v83, v76
	v_pk_add_f32 v[80:81], v[84:85], v[80:81] neg_lo:[0,1] neg_hi:[0,1]
	v_mov_b32_e32 v88, v86
	v_pk_add_f32 v[76:77], v[82:83], v[80:81] neg_lo:[0,1] neg_hi:[0,1]
	v_mov_b32_e32 v87, v79
	v_pk_add_f32 v[80:81], v[88:89], v[76:77]
	s_nop 0
	v_pk_add_f32 v[82:83], v[80:81], v[80:81] op_sel:[0,1] op_sel_hi:[1,0]
	s_nop 0
	v_pk_add_f32 v[78:79], v[78:79], v[82:83] op_sel:[1,0] op_sel_hi:[0,1]
	v_mov_b32_e32 v81, v78
	v_pk_add_f32 v[84:85], v[80:81], v[86:87] neg_lo:[0,1] neg_hi:[0,1]
	v_mov_b32_e32 v77, v82
	v_sub_f32_e32 v79, v80, v84
	v_pk_add_f32 v[76:77], v[76:77], v[84:85] neg_lo:[0,1] neg_hi:[0,1]
	v_sub_f32_e32 v79, v86, v79
	v_add_f32_e32 v76, v76, v79
	v_add_f32_e32 v76, v76, v77
	v_add_f32_e32 v76, v78, v76
	v_cndmask_b32_e32 v76, v224, v76, vcc
	v_cmp_ngt_f32_e32 vcc, -1.0, v73
	s_nop 1
	v_cndmask_b32_e32 v76, v225, v76, vcc
	v_cmp_neq_f32_e32 vcc, -1.0, v73
	s_nop 1
	v_cndmask_b32_e32 v76, v226, v76, vcc
	v_cmp_lt_f32_e64 vcc, |v73|, s56
	s_nop 1
	v_cndmask_b32_e32 v73, v76, v73, vcc
	v_add_f32_e32 v72, v72, v73

.LBB0_1170:
	s_and_b64 vcc, exec, s[4:5]
	v_or_b32_e32 v76, 17, v74
	s_cbranch_vccnz .LBB0_1690
	s_andn2_b64 vcc, exec, s[36:37]
	v_mov_b32_e32 v77, v47
	s_cbranch_vccnz .LBB0_1173
	s_nop 0
	s_waitcnt vmcnt(4) lgkmcnt(0)
	v_lshl_add_u64 v[78:79], v[68:69], 2, vcc
	v_mov_b32_e32 v77, v248
	s_nop 0
	v_add_f32_e32 v78, v47, v77
	v_max_f32_e32 v77, 0, v78
	v_mul_f32_e64 v78, |v78|, s73
	v_exp_f32_e32 v78, v78
	s_nop 0
	v_add_f32_e32 v79, 1.0, v78
	v_add_f32_e32 v80, -1.0, v79
	v_sub_f32_e32 v81, v80, v79
	v_add_f32_e32 v81, 1.0, v81
	v_sub_f32_e32 v80, v78, v80
	v_add_f32_e32 v82, v80, v81
	v_frexp_mant_f32_e32 v80, v79
	v_cmp_gt_f32_e32 vcc, s46, v80
	v_cvt_f64_f32_e32 v[80:81], v79
	v_frexp_exp_i32_f64_e32 v80, v[80:81]
	v_subbrev_co_u32_e32 v88, vcc, 0, v80, vcc
	v_sub_u32_e32 v80, 0, v88
	v_ldexp_f32 v79, v79, v80
	v_ldexp_f32 v80, v82, v80
	v_add_f32_e32 v82, -1.0, v79
	v_add_f32_e32 v81, 1.0, v82
	v_sub_f32_e32 v81, v79, v81
	v_add_f32_e32 v83, v80, v81
	v_add_f32_e32 v81, 1.0, v79
	v_add_f32_e32 v84, -1.0, v81
	v_sub_f32_e32 v79, v79, v84
	v_add_f32_e32 v79, v80, v79
	v_add_f32_e32 v89, v81, v79
	v_rcp_f32_e32 v90, v89
	v_sub_f32_e32 v80, v89, v81
	v_add_f32_e32 v81, v82, v83
	v_sub_f32_e32 v79, v79, v80
	v_mul_f32_e32 v92, v81, v90
	v_sub_f32_e32 v80, v81, v82
	v_mul_f32_e32 v82, v89, v92
	v_fma_f32 v84, v92, v89, -v82
	v_fmac_f32_e32 v84, v92, v79
	v_sub_f32_e32 v91, v83, v80
	v_add_f32_e32 v80, v82, v84
	v_sub_f32_e32 v83, v81, v80
	v_pk_add_f32 v[86:87], v[80:81], v[82:83] neg_lo:[0,1] neg_hi:[0,1]
	v_mov_b32_e32 v85, v80
	v_pk_add_f32 v[80:81], v[86:87], v[84:85] neg_lo:[0,1] neg_hi:[0,1]
	v_cmp_neq_f32_e32 vcc, s0, v78
	v_add_f32_e32 v81, v91, v81
	v_add_f32_e32 v80, v80, v81
	v_add_f32_e32 v81, v83, v80
	v_mul_f32_e32 v91, v90, v81
	v_mul_f32_e32 v82, v89, v91
	v_fma_f32 v84, v91, v89, -v82
	v_fmac_f32_e32 v84, v91, v79
	v_sub_f32_e32 v79, v83, v81
	v_add_f32_e32 v79, v80, v79
	v_add_f32_e32 v80, v82, v84
	v_sub_f32_e32 v83, v81, v80
	v_pk_add_f32 v[86:87], v[80:81], v[82:83] neg_lo:[0,1] neg_hi:[0,1]
	v_mov_b32_e32 v85, v80
	v_pk_add_f32 v[80:81], v[86:87], v[84:85] neg_lo:[0,1] neg_hi:[0,1]
	s_nop 0
	v_add_f32_e32 v79, v79, v81
	v_add_f32_e32 v79, v80, v79
	v_add_f32_e32 v81, v92, v91
	v_add_f32_e32 v79, v83, v79
	v_sub_f32_e32 v80, v81, v92
	v_mul_f32_e32 v79, v90, v79
	v_sub_f32_e32 v80, v91, v80
	v_add_f32_e32 v79, v80, v79
	v_add_f32_e32 v82, v81, v79
	v_mul_f32_e32 v84, v82, v82
	v_fmamk_f32 v80, v84, 0x3e9b6dac, v210
	v_fmaak_f32 v121, v84, v80, 0x3f2aaada
	v_cvt_f32_i32_e32 v80, v88
	v_sub_f32_e32 v81, v82, v81
	v_sub_f32_e32 v79, v79, v81
	v_mul_f32_e32 v81, v82, v84
	v_pk_mul_f32 v[84:85], v[80:81], v[120:121]
	v_ldexp_f32 v83, v82, 1
	v_fma_f32 v82, v80, s1, -v84
	v_fmac_f32_e32 v82, 0xb102e308, v80
	v_pk_add_f32 v[80:81], v[84:85], v[82:83]
	v_ldexp_f32 v79, v79, 1
	v_sub_f32_e32 v83, v81, v83
	v_sub_f32_e32 v83, v85, v83
	v_add_f32_e32 v87, v79, v83
	v_mov_b32_e32 v86, v84
	v_pk_add_f32 v[84:85], v[80:81], v[84:85] neg_lo:[0,1] neg_hi:[0,1]
	v_pk_add_f32 v[88:89], v[80:81], v[86:87]
	v_mov_b32_e32 v83, v80
	v_mov_b32_e32 v85, v89
	v_pk_add_f32 v[90:91], v[82:83], v[84:85] neg_lo:[0,1] neg_hi:[0,1]
	v_pk_add_f32 v[82:83], v[82:83], v[84:85]
	v_mov_b32_e32 v86, v87
	v_pk_add_f32 v[84:85], v[82:83], v[80:81] op_sel:[1,0] op_sel_hi:[0,1] neg_lo:[0,1] neg_hi:[0,1]
	v_pk_add_f32 v[92:93], v[88:89], v[84:85] op_sel_hi:[1,0] neg_lo:[0,1] neg_hi:[0,1]
	v_mov_b32_e32 v88, v89
	v_mov_b32_e32 v89, v83
	v_pk_mov_b32 v[84:85], v[80:81], v[84:85] op_sel:[1,0]
	v_mov_b32_e32 v87, v80
	v_pk_add_f32 v[84:85], v[88:89], v[84:85] neg_lo:[0,1] neg_hi:[0,1]
	v_mov_b32_e32 v92, v90
	v_pk_add_f32 v[80:81], v[86:87], v[84:85] neg_lo:[0,1] neg_hi:[0,1]
	v_mov_b32_e32 v91, v83
	v_pk_add_f32 v[84:85], v[92:93], v[80:81]
	s_nop 0
	v_pk_add_f32 v[86:87], v[84:85], v[84:85] op_sel:[0,1] op_sel_hi:[1,0]
	s_nop 0
	v_pk_add_f32 v[82:83], v[82:83], v[86:87] op_sel:[1,0] op_sel_hi:[0,1]
	v_mov_b32_e32 v85, v82
	v_pk_add_f32 v[88:89], v[84:85], v[90:91] neg_lo:[0,1] neg_hi:[0,1]
	v_mov_b32_e32 v81, v86
	v_sub_f32_e32 v79, v84, v88
	v_pk_add_f32 v[80:81], v[80:81], v[88:89] neg_lo:[0,1] neg_hi:[0,1]
	v_sub_f32_e32 v79, v90, v79
	v_add_f32_e32 v79, v80, v79
	v_add_f32_e32 v79, v79, v81
	v_add_f32_e32 v79, v82, v79
	v_cndmask_b32_e32 v79, v224, v79, vcc
	v_cmp_ngt_f32_e32 vcc, -1.0, v78
	s_nop 1
	v_cndmask_b32_e32 v79, v225, v79, vcc
	v_cmp_neq_f32_e32 vcc, -1.0, v78
	s_nop 1
	v_cndmask_b32_e32 v79, v226, v79, vcc
	v_cmp_lt_f32_e64 vcc, |v78|, s56
	s_nop 1
	v_cndmask_b32_e32 v78, v79, v78, vcc
	v_add_f32_e32 v77, v77, v78

.LBB0_1175:
	s_and_b64 vcc, exec, s[4:5]
	v_or_b32_e32 v76, 18, v74
	s_cbranch_vccnz .LBB0_1691
	s_andn2_b64 vcc, exec, s[36:37]
	v_mov_b32_e32 v77, v48
	s_cbranch_vccnz .LBB0_1178
	s_nop 0
	s_waitcnt vmcnt(4) lgkmcnt(0)
	v_lshl_add_u64 v[78:79], v[68:69], 2, vcc
	v_mov_b32_e32 v77, v248
	s_nop 0
	v_add_f32_e32 v78, v48, v77
	v_max_f32_e32 v77, 0, v78
	v_mul_f32_e64 v78, |v78|, s73
	v_exp_f32_e32 v78, v78
	s_nop 0
	v_add_f32_e32 v79, 1.0, v78
	v_add_f32_e32 v80, -1.0, v79
	v_sub_f32_e32 v81, v80, v79
	v_add_f32_e32 v81, 1.0, v81
	v_sub_f32_e32 v80, v78, v80
	v_add_f32_e32 v82, v80, v81
	v_frexp_mant_f32_e32 v80, v79
	v_cmp_gt_f32_e32 vcc, s46, v80
	v_cvt_f64_f32_e32 v[80:81], v79
	v_frexp_exp_i32_f64_e32 v80, v[80:81]
	v_subbrev_co_u32_e32 v88, vcc, 0, v80, vcc
	v_sub_u32_e32 v80, 0, v88
	v_ldexp_f32 v79, v79, v80
	v_ldexp_f32 v80, v82, v80
	v_add_f32_e32 v82, -1.0, v79
	v_add_f32_e32 v81, 1.0, v82
	v_sub_f32_e32 v81, v79, v81
	v_add_f32_e32 v83, v80, v81
	v_add_f32_e32 v81, 1.0, v79
	v_add_f32_e32 v84, -1.0, v81
	v_sub_f32_e32 v79, v79, v84
	v_add_f32_e32 v79, v80, v79
	v_add_f32_e32 v89, v81, v79
	v_rcp_f32_e32 v90, v89
	v_sub_f32_e32 v80, v89, v81
	v_add_f32_e32 v81, v82, v83
	v_sub_f32_e32 v79, v79, v80
	v_mul_f32_e32 v92, v81, v90
	v_sub_f32_e32 v80, v81, v82
	v_mul_f32_e32 v82, v89, v92
	v_fma_f32 v84, v92, v89, -v82
	v_fmac_f32_e32 v84, v92, v79
	v_sub_f32_e32 v91, v83, v80
	v_add_f32_e32 v80, v82, v84
	v_sub_f32_e32 v83, v81, v80
	v_pk_add_f32 v[86:87], v[80:81], v[82:83] neg_lo:[0,1] neg_hi:[0,1]
	v_mov_b32_e32 v85, v80
	v_pk_add_f32 v[80:81], v[86:87], v[84:85] neg_lo:[0,1] neg_hi:[0,1]
	v_cmp_neq_f32_e32 vcc, s0, v78
	v_add_f32_e32 v81, v91, v81
	v_add_f32_e32 v80, v80, v81
	v_add_f32_e32 v81, v83, v80
	v_mul_f32_e32 v91, v90, v81
	v_mul_f32_e32 v82, v89, v91
	v_fma_f32 v84, v91, v89, -v82
	v_fmac_f32_e32 v84, v91, v79
	v_sub_f32_e32 v79, v83, v81
	v_add_f32_e32 v79, v80, v79
	v_add_f32_e32 v80, v82, v84
	v_sub_f32_e32 v83, v81, v80
	v_pk_add_f32 v[86:87], v[80:81], v[82:83] neg_lo:[0,1] neg_hi:[0,1]
	v_mov_b32_e32 v85, v80
	v_pk_add_f32 v[80:81], v[86:87], v[84:85] neg_lo:[0,1] neg_hi:[0,1]
	s_nop 0
	v_add_f32_e32 v79, v79, v81
	v_add_f32_e32 v79, v80, v79
	v_add_f32_e32 v81, v92, v91
	v_add_f32_e32 v79, v83, v79
	v_sub_f32_e32 v80, v81, v92
	v_mul_f32_e32 v79, v90, v79
	v_sub_f32_e32 v80, v91, v80
	v_add_f32_e32 v79, v80, v79
	v_add_f32_e32 v82, v81, v79
	v_mul_f32_e32 v84, v82, v82
	v_fmamk_f32 v80, v84, 0x3e9b6dac, v210
	v_fmaak_f32 v121, v84, v80, 0x3f2aaada
	v_cvt_f32_i32_e32 v80, v88
	v_sub_f32_e32 v81, v82, v81
	v_sub_f32_e32 v79, v79, v81
	v_mul_f32_e32 v81, v82, v84
	v_pk_mul_f32 v[84:85], v[80:81], v[120:121]
	v_ldexp_f32 v83, v82, 1
	v_fma_f32 v82, v80, s1, -v84
	v_fmac_f32_e32 v82, 0xb102e308, v80
	v_pk_add_f32 v[80:81], v[84:85], v[82:83]
	v_ldexp_f32 v79, v79, 1
	v_sub_f32_e32 v83, v81, v83
	v_sub_f32_e32 v83, v85, v83
	v_add_f32_e32 v87, v79, v83
	v_mov_b32_e32 v86, v84
	v_pk_add_f32 v[84:85], v[80:81], v[84:85] neg_lo:[0,1] neg_hi:[0,1]
	v_pk_add_f32 v[88:89], v[80:81], v[86:87]
	v_mov_b32_e32 v83, v80
	v_mov_b32_e32 v85, v89
	v_pk_add_f32 v[90:91], v[82:83], v[84:85] neg_lo:[0,1] neg_hi:[0,1]
	v_pk_add_f32 v[82:83], v[82:83], v[84:85]
	v_mov_b32_e32 v86, v87
	v_pk_add_f32 v[84:85], v[82:83], v[80:81] op_sel:[1,0] op_sel_hi:[0,1] neg_lo:[0,1] neg_hi:[0,1]
	v_pk_add_f32 v[92:93], v[88:89], v[84:85] op_sel_hi:[1,0] neg_lo:[0,1] neg_hi:[0,1]
	v_mov_b32_e32 v88, v89
	v_mov_b32_e32 v89, v83
	v_pk_mov_b32 v[84:85], v[80:81], v[84:85] op_sel:[1,0]
	v_mov_b32_e32 v87, v80
	v_pk_add_f32 v[84:85], v[88:89], v[84:85] neg_lo:[0,1] neg_hi:[0,1]
	v_mov_b32_e32 v92, v90
	v_pk_add_f32 v[80:81], v[86:87], v[84:85] neg_lo:[0,1] neg_hi:[0,1]
	v_mov_b32_e32 v91, v83
	v_pk_add_f32 v[84:85], v[92:93], v[80:81]
	s_nop 0
	v_pk_add_f32 v[86:87], v[84:85], v[84:85] op_sel:[0,1] op_sel_hi:[1,0]
	s_nop 0
	v_pk_add_f32 v[82:83], v[82:83], v[86:87] op_sel:[1,0] op_sel_hi:[0,1]
	v_mov_b32_e32 v85, v82
	v_pk_add_f32 v[88:89], v[84:85], v[90:91] neg_lo:[0,1] neg_hi:[0,1]
	v_mov_b32_e32 v81, v86
	v_sub_f32_e32 v79, v84, v88
	v_pk_add_f32 v[80:81], v[80:81], v[88:89] neg_lo:[0,1] neg_hi:[0,1]
	v_sub_f32_e32 v79, v90, v79
	v_add_f32_e32 v79, v80, v79
	v_add_f32_e32 v79, v79, v81
	v_add_f32_e32 v79, v82, v79
	v_cndmask_b32_e32 v79, v224, v79, vcc
	v_cmp_ngt_f32_e32 vcc, -1.0, v78
	s_nop 1
	v_cndmask_b32_e32 v79, v225, v79, vcc
	v_cmp_neq_f32_e32 vcc, -1.0, v78
	s_nop 1
	v_cndmask_b32_e32 v79, v226, v79, vcc
	v_cmp_lt_f32_e64 vcc, |v78|, s56
	s_nop 1
	v_cndmask_b32_e32 v78, v79, v78, vcc
	v_add_f32_e32 v77, v77, v78

.LBB0_1180:
	s_and_b64 vcc, exec, s[4:5]
	v_or_b32_e32 v76, 19, v74
	s_cbranch_vccnz .LBB0_1692
	s_andn2_b64 vcc, exec, s[36:37]
	v_mov_b32_e32 v77, v49
	s_cbranch_vccnz .LBB0_1183
	s_nop 0
	s_waitcnt vmcnt(4) lgkmcnt(0)
	v_lshl_add_u64 v[78:79], v[68:69], 2, vcc
	v_mov_b32_e32 v69, v248
	s_nop 0
	v_add_f32_e32 v77, v49, v69
	v_max_f32_e32 v69, 0, v77
	v_mul_f32_e64 v77, |v77|, s73
	v_exp_f32_e32 v77, v77
	s_nop 0
	v_add_f32_e32 v80, 1.0, v77
	v_add_f32_e32 v78, -1.0, v80
	v_sub_f32_e32 v79, v78, v80
	v_add_f32_e32 v79, 1.0, v79
	v_sub_f32_e32 v78, v77, v78
	v_add_f32_e32 v81, v78, v79
	v_frexp_mant_f32_e32 v78, v80
	v_cmp_gt_f32_e32 vcc, s46, v78
	v_cvt_f64_f32_e32 v[78:79], v80
	v_frexp_exp_i32_f64_e32 v78, v[78:79]
	v_subbrev_co_u32_e32 v86, vcc, 0, v78, vcc
	v_sub_u32_e32 v78, 0, v86
	v_ldexp_f32 v79, v80, v78
	v_add_f32_e32 v80, -1.0, v79
	v_add_f32_e32 v82, 1.0, v79
	v_ldexp_f32 v78, v81, v78
	v_add_f32_e32 v81, 1.0, v80
	v_add_f32_e32 v83, -1.0, v82
	v_sub_f32_e32 v81, v79, v81
	v_sub_f32_e32 v79, v79, v83
	v_add_f32_e32 v81, v78, v81
	v_add_f32_e32 v78, v78, v79
	v_add_f32_e32 v87, v82, v78
	v_rcp_f32_e32 v89, v87
	v_sub_f32_e32 v79, v87, v82
	v_sub_f32_e32 v88, v78, v79
	v_add_f32_e32 v79, v80, v81
	v_mul_f32_e32 v91, v79, v89
	v_sub_f32_e32 v78, v79, v80
	v_mul_f32_e32 v80, v87, v91
	v_fma_f32 v82, v91, v87, -v80
	v_fmac_f32_e32 v82, v91, v88
	v_sub_f32_e32 v90, v81, v78
	v_add_f32_e32 v78, v80, v82
	v_sub_f32_e32 v81, v79, v78
	v_pk_add_f32 v[84:85], v[78:79], v[80:81] neg_lo:[0,1] neg_hi:[0,1]
	v_mov_b32_e32 v83, v78
	v_pk_add_f32 v[78:79], v[84:85], v[82:83] neg_lo:[0,1] neg_hi:[0,1]
	v_cmp_neq_f32_e32 vcc, s0, v77
	v_add_f32_e32 v79, v90, v79
	v_add_f32_e32 v78, v78, v79
	v_add_f32_e32 v79, v81, v78
	v_mul_f32_e32 v90, v89, v79
	v_mul_f32_e32 v80, v87, v90
	v_fma_f32 v82, v90, v87, -v80
	v_fmac_f32_e32 v82, v90, v88
	v_sub_f32_e32 v81, v81, v79
	v_add_f32_e32 v87, v78, v81
	v_add_f32_e32 v78, v80, v82
	v_sub_f32_e32 v81, v79, v78
	v_pk_add_f32 v[84:85], v[78:79], v[80:81] neg_lo:[0,1] neg_hi:[0,1]
	v_mov_b32_e32 v83, v78
	v_pk_add_f32 v[78:79], v[84:85], v[82:83] neg_lo:[0,1] neg_hi:[0,1]
	s_nop 0
	v_add_f32_e32 v79, v87, v79
	v_add_f32_e32 v78, v78, v79
	v_add_f32_e32 v79, v91, v90
	v_add_f32_e32 v78, v81, v78
	v_sub_f32_e32 v80, v79, v91
	v_mul_f32_e32 v78, v89, v78
	v_sub_f32_e32 v80, v90, v80
	v_add_f32_e32 v80, v80, v78
	v_add_f32_e32 v82, v79, v80
	v_mul_f32_e32 v83, v82, v82
	v_fmamk_f32 v78, v83, 0x3e9b6dac, v210
	v_fmaak_f32 v121, v83, v78, 0x3f2aaada
	v_cvt_f32_i32_e32 v78, v86
	v_sub_f32_e32 v79, v82, v79
	v_sub_f32_e32 v79, v80, v79
	v_ldexp_f32 v84, v79, 1
	v_mul_f32_e32 v79, v82, v83
	v_ldexp_f32 v81, v82, 1
	v_pk_mul_f32 v[82:83], v[78:79], v[120:121]
	s_nop 0
	v_fma_f32 v80, v78, s1, -v82
	v_fmac_f32_e32 v80, 0xb102e308, v78
	v_pk_add_f32 v[78:79], v[82:83], v[80:81]
	s_nop 0
	v_sub_f32_e32 v81, v79, v81
	v_sub_f32_e32 v81, v83, v81
	v_add_f32_e32 v85, v84, v81
	v_mov_b32_e32 v84, v82
	v_pk_add_f32 v[82:83], v[78:79], v[82:83] neg_lo:[0,1] neg_hi:[0,1]
	v_pk_add_f32 v[86:87], v[78:79], v[84:85]
	v_mov_b32_e32 v81, v78
	v_mov_b32_e32 v83, v87
	v_pk_add_f32 v[88:89], v[80:81], v[82:83] neg_lo:[0,1] neg_hi:[0,1]
	v_pk_add_f32 v[80:81], v[80:81], v[82:83]
	v_mov_b32_e32 v84, v85
	v_pk_add_f32 v[82:83], v[80:81], v[78:79] op_sel:[1,0] op_sel_hi:[0,1] neg_lo:[0,1] neg_hi:[0,1]
	v_pk_add_f32 v[90:91], v[86:87], v[82:83] op_sel_hi:[1,0] neg_lo:[0,1] neg_hi:[0,1]
	v_mov_b32_e32 v86, v87
	v_mov_b32_e32 v87, v81
	v_pk_mov_b32 v[82:83], v[78:79], v[82:83] op_sel:[1,0]
	v_mov_b32_e32 v85, v78
	v_pk_add_f32 v[82:83], v[86:87], v[82:83] neg_lo:[0,1] neg_hi:[0,1]
	v_mov_b32_e32 v90, v88
	v_pk_add_f32 v[78:79], v[84:85], v[82:83] neg_lo:[0,1] neg_hi:[0,1]
	v_mov_b32_e32 v89, v81
	v_pk_add_f32 v[82:83], v[90:91], v[78:79]
	s_nop 0
	v_pk_add_f32 v[84:85], v[82:83], v[82:83] op_sel:[0,1] op_sel_hi:[1,0]
	s_nop 0
	v_pk_add_f32 v[80:81], v[80:81], v[84:85] op_sel:[1,0] op_sel_hi:[0,1]
	v_mov_b32_e32 v83, v80
	v_pk_add_f32 v[86:87], v[82:83], v[88:89] neg_lo:[0,1] neg_hi:[0,1]
	v_mov_b32_e32 v79, v84
	v_sub_f32_e32 v81, v82, v86
	v_pk_add_f32 v[78:79], v[78:79], v[86:87] neg_lo:[0,1] neg_hi:[0,1]
	v_sub_f32_e32 v81, v88, v81
	v_add_f32_e32 v78, v78, v81
	v_add_f32_e32 v78, v78, v79
	v_add_f32_e32 v78, v80, v78
	v_cndmask_b32_e32 v78, v224, v78, vcc
	v_cmp_ngt_f32_e32 vcc, -1.0, v77
	s_nop 1
	v_cndmask_b32_e32 v78, v225, v78, vcc
	v_cmp_neq_f32_e32 vcc, -1.0, v77
	s_nop 1
	v_cndmask_b32_e32 v78, v226, v78, vcc
	v_cmp_lt_f32_e64 vcc, |v77|, s56
	s_nop 1
	v_cndmask_b32_e32 v77, v78, v77, vcc
	v_add_f32_e32 v77, v69, v77

.LBB0_1185:
	s_or_b64 exec, exec, s[58:59]
	s_and_saveexec_b64 s[58:59], s[8:9]
	s_cbranch_execz .LBB0_1206
	s_and_b64 vcc, exec, s[4:5]
	v_lshl_add_u64 v[70:71], v[66:67], 2, s[34:35]
	s_cbranch_vccnz .LBB0_1693
	s_andn2_b64 vcc, exec, s[36:37]
	v_mov_b32_e32 v69, v42
	s_cbranch_vccnz .LBB0_1189
	s_nop 0
	v_lshl_add_u64 v[72:73], v[66:67], 0, s[80:81]
	s_waitcnt lgkmcnt(0)
	v_lshl_add_u64 v[72:73], v[72:73], 2, vcc
	v_mov_b32_e32 v69, v249
	s_nop 0
	v_add_f32_e32 v72, v42, v69
	v_max_f32_e32 v69, 0, v72
	v_mul_f32_e64 v72, |v72|, s73
	v_exp_f32_e32 v72, v72
	s_nop 0
	v_add_f32_e32 v73, 1.0, v72
	v_add_f32_e32 v76, -1.0, v73
	v_sub_f32_e32 v77, v76, v73
	v_add_f32_e32 v77, 1.0, v77
	v_sub_f32_e32 v76, v72, v76
	v_add_f32_e32 v78, v76, v77
	v_frexp_mant_f32_e32 v76, v73
	v_cmp_gt_f32_e32 vcc, s46, v76
	v_cvt_f64_f32_e32 v[76:77], v73
	v_frexp_exp_i32_f64_e32 v76, v[76:77]
	v_subbrev_co_u32_e32 v84, vcc, 0, v76, vcc
	v_sub_u32_e32 v76, 0, v84
	v_ldexp_f32 v73, v73, v76
	v_ldexp_f32 v76, v78, v76
	v_add_f32_e32 v78, -1.0, v73
	v_add_f32_e32 v77, 1.0, v78
	v_sub_f32_e32 v77, v73, v77
	v_add_f32_e32 v79, v76, v77
	v_add_f32_e32 v77, 1.0, v73
	v_add_f32_e32 v80, -1.0, v77
	v_sub_f32_e32 v73, v73, v80
	v_add_f32_e32 v73, v76, v73
	v_add_f32_e32 v85, v77, v73
	v_rcp_f32_e32 v86, v85
	v_sub_f32_e32 v76, v85, v77
	v_add_f32_e32 v77, v78, v79
	v_sub_f32_e32 v73, v73, v76
	v_mul_f32_e32 v88, v77, v86
	v_sub_f32_e32 v76, v77, v78
	v_mul_f32_e32 v78, v85, v88
	v_fma_f32 v80, v88, v85, -v78
	v_fmac_f32_e32 v80, v88, v73
	v_sub_f32_e32 v87, v79, v76
	v_add_f32_e32 v76, v78, v80
	v_sub_f32_e32 v79, v77, v76
	v_pk_add_f32 v[82:83], v[76:77], v[78:79] neg_lo:[0,1] neg_hi:[0,1]
	v_mov_b32_e32 v81, v76
	v_pk_add_f32 v[76:77], v[82:83], v[80:81] neg_lo:[0,1] neg_hi:[0,1]
	v_cmp_neq_f32_e32 vcc, s0, v72
	v_add_f32_e32 v77, v87, v77
	v_add_f32_e32 v76, v76, v77
	v_add_f32_e32 v77, v79, v76
	v_mul_f32_e32 v87, v86, v77
	v_mul_f32_e32 v78, v85, v87
	v_fma_f32 v80, v87, v85, -v78
	v_fmac_f32_e32 v80, v87, v73
	v_sub_f32_e32 v73, v79, v77
	v_add_f32_e32 v73, v76, v73
	v_add_f32_e32 v76, v78, v80
	v_sub_f32_e32 v79, v77, v76
	v_pk_add_f32 v[82:83], v[76:77], v[78:79] neg_lo:[0,1] neg_hi:[0,1]
	v_mov_b32_e32 v81, v76
	v_pk_add_f32 v[76:77], v[82:83], v[80:81] neg_lo:[0,1] neg_hi:[0,1]
	s_nop 0
	v_add_f32_e32 v73, v73, v77
	v_add_f32_e32 v73, v76, v73
	v_add_f32_e32 v77, v88, v87
	v_add_f32_e32 v73, v79, v73
	v_sub_f32_e32 v76, v77, v88
	v_mul_f32_e32 v73, v86, v73
	v_sub_f32_e32 v76, v87, v76
	v_add_f32_e32 v73, v76, v73
	v_add_f32_e32 v78, v77, v73
	v_mul_f32_e32 v80, v78, v78
	v_fmamk_f32 v76, v80, 0x3e9b6dac, v210
	v_fmaak_f32 v121, v80, v76, 0x3f2aaada
	v_cvt_f32_i32_e32 v76, v84
	v_sub_f32_e32 v77, v78, v77
	v_sub_f32_e32 v73, v73, v77
	v_mul_f32_e32 v77, v78, v80
	v_pk_mul_f32 v[80:81], v[76:77], v[120:121]
	v_ldexp_f32 v79, v78, 1
	v_fma_f32 v78, v76, s1, -v80
	v_fmac_f32_e32 v78, 0xb102e308, v76
	v_pk_add_f32 v[76:77], v[80:81], v[78:79]
	v_ldexp_f32 v73, v73, 1
	v_sub_f32_e32 v79, v77, v79
	v_sub_f32_e32 v79, v81, v79
	v_add_f32_e32 v83, v73, v79
	v_mov_b32_e32 v82, v80
	v_pk_add_f32 v[80:81], v[76:77], v[80:81] neg_lo:[0,1] neg_hi:[0,1]
	v_pk_add_f32 v[84:85], v[76:77], v[82:83]
	v_mov_b32_e32 v79, v76
	v_mov_b32_e32 v81, v85
	v_pk_add_f32 v[86:87], v[78:79], v[80:81] neg_lo:[0,1] neg_hi:[0,1]
	v_pk_add_f32 v[78:79], v[78:79], v[80:81]
	v_mov_b32_e32 v82, v83
	v_pk_add_f32 v[80:81], v[78:79], v[76:77] op_sel:[1,0] op_sel_hi:[0,1] neg_lo:[0,1] neg_hi:[0,1]
	v_pk_add_f32 v[88:89], v[84:85], v[80:81] op_sel_hi:[1,0] neg_lo:[0,1] neg_hi:[0,1]
	v_mov_b32_e32 v84, v85
	v_mov_b32_e32 v85, v79
	v_pk_mov_b32 v[80:81], v[76:77], v[80:81] op_sel:[1,0]
	v_mov_b32_e32 v83, v76
	v_pk_add_f32 v[80:81], v[84:85], v[80:81] neg_lo:[0,1] neg_hi:[0,1]
	v_mov_b32_e32 v88, v86
	v_pk_add_f32 v[76:77], v[82:83], v[80:81] neg_lo:[0,1] neg_hi:[0,1]
	v_mov_b32_e32 v87, v79
	v_pk_add_f32 v[80:81], v[88:89], v[76:77]
	s_nop 0
	v_pk_add_f32 v[82:83], v[80:81], v[80:81] op_sel:[0,1] op_sel_hi:[1,0]
	s_nop 0
	v_pk_add_f32 v[78:79], v[78:79], v[82:83] op_sel:[1,0] op_sel_hi:[0,1]
	v_mov_b32_e32 v81, v78
	v_pk_add_f32 v[84:85], v[80:81], v[86:87] neg_lo:[0,1] neg_hi:[0,1]
	v_mov_b32_e32 v77, v82
	v_sub_f32_e32 v73, v80, v84
	v_pk_add_f32 v[76:77], v[76:77], v[84:85] neg_lo:[0,1] neg_hi:[0,1]
	v_sub_f32_e32 v73, v86, v73
	v_add_f32_e32 v73, v76, v73
	v_add_f32_e32 v73, v73, v77
	v_add_f32_e32 v73, v78, v73
	v_cndmask_b32_e32 v73, v224, v73, vcc
	v_cmp_ngt_f32_e32 vcc, -1.0, v72
	s_nop 1
	v_cndmask_b32_e32 v73, v225, v73, vcc
	v_cmp_neq_f32_e32 vcc, -1.0, v72
	s_nop 1
	v_cndmask_b32_e32 v73, v226, v73, vcc
	v_cmp_lt_f32_e64 vcc, |v72|, s56
	s_nop 1
	v_cndmask_b32_e32 v72, v73, v72, vcc
	v_add_f32_e32 v69, v69, v72

.LBB0_1191:
	s_and_b64 vcc, exec, s[4:5]
	v_or_b32_e32 v69, 17, v74
	s_cbranch_vccnz .LBB0_1694
	s_andn2_b64 vcc, exec, s[36:37]
	v_mov_b32_e32 v76, v43
	s_cbranch_vccnz .LBB0_1194
	s_nop 0
	v_lshl_add_u64 v[76:77], v[66:67], 0, s[80:81]
	s_waitcnt lgkmcnt(0)
	v_lshl_add_u64 v[76:77], v[76:77], 2, vcc
	v_mov_b32_e32 v76, v249
	s_nop 0
	v_add_f32_e32 v77, v43, v76
	v_max_f32_e32 v76, 0, v77
	v_mul_f32_e64 v77, |v77|, s73
	v_exp_f32_e32 v77, v77
	s_nop 0
	v_add_f32_e32 v80, 1.0, v77
	v_add_f32_e32 v78, -1.0, v80
	v_sub_f32_e32 v79, v78, v80
	v_add_f32_e32 v79, 1.0, v79
	v_sub_f32_e32 v78, v77, v78
	v_add_f32_e32 v81, v78, v79
	v_frexp_mant_f32_e32 v78, v80
	v_cmp_gt_f32_e32 vcc, s46, v78
	v_cvt_f64_f32_e32 v[78:79], v80
	v_frexp_exp_i32_f64_e32 v78, v[78:79]
	v_subbrev_co_u32_e32 v86, vcc, 0, v78, vcc
	v_sub_u32_e32 v78, 0, v86
	v_ldexp_f32 v79, v80, v78
	v_add_f32_e32 v80, -1.0, v79
	v_add_f32_e32 v82, 1.0, v79
	v_ldexp_f32 v78, v81, v78
	v_add_f32_e32 v81, 1.0, v80
	v_add_f32_e32 v83, -1.0, v82
	v_sub_f32_e32 v81, v79, v81
	v_sub_f32_e32 v79, v79, v83
	v_add_f32_e32 v81, v78, v81
	v_add_f32_e32 v78, v78, v79
	v_add_f32_e32 v87, v82, v78
	v_rcp_f32_e32 v89, v87
	v_sub_f32_e32 v79, v87, v82
	v_sub_f32_e32 v88, v78, v79
	v_add_f32_e32 v79, v80, v81
	v_mul_f32_e32 v91, v79, v89
	v_sub_f32_e32 v78, v79, v80
	v_mul_f32_e32 v80, v87, v91
	v_fma_f32 v82, v91, v87, -v80
	v_fmac_f32_e32 v82, v91, v88
	v_sub_f32_e32 v90, v81, v78
	v_add_f32_e32 v78, v80, v82
	v_sub_f32_e32 v81, v79, v78
	v_pk_add_f32 v[84:85], v[78:79], v[80:81] neg_lo:[0,1] neg_hi:[0,1]
	v_mov_b32_e32 v83, v78
	v_pk_add_f32 v[78:79], v[84:85], v[82:83] neg_lo:[0,1] neg_hi:[0,1]
	v_cmp_neq_f32_e32 vcc, s0, v77
	v_add_f32_e32 v79, v90, v79
	v_add_f32_e32 v78, v78, v79
	v_add_f32_e32 v79, v81, v78
	v_mul_f32_e32 v90, v89, v79
	v_mul_f32_e32 v80, v87, v90
	v_fma_f32 v82, v90, v87, -v80
	v_fmac_f32_e32 v82, v90, v88
	v_sub_f32_e32 v81, v81, v79
	v_add_f32_e32 v87, v78, v81
	v_add_f32_e32 v78, v80, v82
	v_sub_f32_e32 v81, v79, v78
	v_pk_add_f32 v[84:85], v[78:79], v[80:81] neg_lo:[0,1] neg_hi:[0,1]
	v_mov_b32_e32 v83, v78
	v_pk_add_f32 v[78:79], v[84:85], v[82:83] neg_lo:[0,1] neg_hi:[0,1]
	s_nop 0
	v_add_f32_e32 v79, v87, v79
	v_add_f32_e32 v78, v78, v79
	v_add_f32_e32 v79, v91, v90
	v_add_f32_e32 v78, v81, v78
	v_sub_f32_e32 v80, v79, v91
	v_mul_f32_e32 v78, v89, v78
	v_sub_f32_e32 v80, v90, v80
	v_add_f32_e32 v80, v80, v78
	v_add_f32_e32 v82, v79, v80
	v_mul_f32_e32 v83, v82, v82
	v_fmamk_f32 v78, v83, 0x3e9b6dac, v210
	v_fmaak_f32 v121, v83, v78, 0x3f2aaada
	v_cvt_f32_i32_e32 v78, v86
	v_sub_f32_e32 v79, v82, v79
	v_sub_f32_e32 v79, v80, v79
	v_ldexp_f32 v84, v79, 1
	v_mul_f32_e32 v79, v82, v83
	v_ldexp_f32 v81, v82, 1
	v_pk_mul_f32 v[82:83], v[78:79], v[120:121]
	s_nop 0
	v_fma_f32 v80, v78, s1, -v82
	v_fmac_f32_e32 v80, 0xb102e308, v78
	v_pk_add_f32 v[78:79], v[82:83], v[80:81]
	s_nop 0
	v_sub_f32_e32 v81, v79, v81
	v_sub_f32_e32 v81, v83, v81
	v_add_f32_e32 v85, v84, v81
	v_mov_b32_e32 v84, v82
	v_pk_add_f32 v[82:83], v[78:79], v[82:83] neg_lo:[0,1] neg_hi:[0,1]
	v_pk_add_f32 v[86:87], v[78:79], v[84:85]
	v_mov_b32_e32 v81, v78
	v_mov_b32_e32 v83, v87
	v_pk_add_f32 v[88:89], v[80:81], v[82:83] neg_lo:[0,1] neg_hi:[0,1]
	v_pk_add_f32 v[80:81], v[80:81], v[82:83]
	v_mov_b32_e32 v84, v85
	v_pk_add_f32 v[82:83], v[80:81], v[78:79] op_sel:[1,0] op_sel_hi:[0,1] neg_lo:[0,1] neg_hi:[0,1]
	v_pk_add_f32 v[90:91], v[86:87], v[82:83] op_sel_hi:[1,0] neg_lo:[0,1] neg_hi:[0,1]
	v_mov_b32_e32 v86, v87
	v_mov_b32_e32 v87, v81
	v_pk_mov_b32 v[82:83], v[78:79], v[82:83] op_sel:[1,0]
	v_mov_b32_e32 v85, v78
	v_pk_add_f32 v[82:83], v[86:87], v[82:83] neg_lo:[0,1] neg_hi:[0,1]
	v_mov_b32_e32 v90, v88
	v_pk_add_f32 v[78:79], v[84:85], v[82:83] neg_lo:[0,1] neg_hi:[0,1]
	v_mov_b32_e32 v89, v81
	v_pk_add_f32 v[82:83], v[90:91], v[78:79]
	s_nop 0
	v_pk_add_f32 v[84:85], v[82:83], v[82:83] op_sel:[0,1] op_sel_hi:[1,0]
	s_nop 0
	v_pk_add_f32 v[80:81], v[80:81], v[84:85] op_sel:[1,0] op_sel_hi:[0,1]
	v_mov_b32_e32 v83, v80
	v_pk_add_f32 v[86:87], v[82:83], v[88:89] neg_lo:[0,1] neg_hi:[0,1]
	v_mov_b32_e32 v79, v84
	v_sub_f32_e32 v81, v82, v86
	v_pk_add_f32 v[78:79], v[78:79], v[86:87] neg_lo:[0,1] neg_hi:[0,1]
	v_sub_f32_e32 v81, v88, v81
	v_add_f32_e32 v78, v78, v81
	v_add_f32_e32 v78, v78, v79
	v_add_f32_e32 v78, v80, v78
	v_cndmask_b32_e32 v78, v224, v78, vcc
	v_cmp_ngt_f32_e32 vcc, -1.0, v77
	s_nop 1
	v_cndmask_b32_e32 v78, v225, v78, vcc
	v_cmp_neq_f32_e32 vcc, -1.0, v77
	s_nop 1
	v_cndmask_b32_e32 v78, v226, v78, vcc
	v_cmp_lt_f32_e64 vcc, |v77|, s56
	s_nop 1
	v_cndmask_b32_e32 v77, v78, v77, vcc
	v_add_f32_e32 v76, v76, v77

.LBB0_1196:
	s_and_b64 vcc, exec, s[4:5]
	v_or_b32_e32 v69, 18, v74
	s_cbranch_vccnz .LBB0_1695
	s_andn2_b64 vcc, exec, s[36:37]
	v_mov_b32_e32 v76, v44
	s_cbranch_vccnz .LBB0_1199
	s_nop 0
	v_lshl_add_u64 v[76:77], v[66:67], 0, s[80:81]
	s_waitcnt lgkmcnt(0)
	v_lshl_add_u64 v[76:77], v[76:77], 2, vcc
	v_mov_b32_e32 v76, v249
	s_nop 0
	v_add_f32_e32 v77, v44, v76
	v_max_f32_e32 v76, 0, v77
	v_mul_f32_e64 v77, |v77|, s73
	v_exp_f32_e32 v77, v77
	s_nop 0
	v_add_f32_e32 v80, 1.0, v77
	v_add_f32_e32 v78, -1.0, v80
	v_sub_f32_e32 v79, v78, v80
	v_add_f32_e32 v79, 1.0, v79
	v_sub_f32_e32 v78, v77, v78
	v_add_f32_e32 v81, v78, v79
	v_frexp_mant_f32_e32 v78, v80
	v_cmp_gt_f32_e32 vcc, s46, v78
	v_cvt_f64_f32_e32 v[78:79], v80
	v_frexp_exp_i32_f64_e32 v78, v[78:79]
	v_subbrev_co_u32_e32 v86, vcc, 0, v78, vcc
	v_sub_u32_e32 v78, 0, v86
	v_ldexp_f32 v79, v80, v78
	v_add_f32_e32 v80, -1.0, v79
	v_add_f32_e32 v82, 1.0, v79
	v_ldexp_f32 v78, v81, v78
	v_add_f32_e32 v81, 1.0, v80
	v_add_f32_e32 v83, -1.0, v82
	v_sub_f32_e32 v81, v79, v81
	v_sub_f32_e32 v79, v79, v83
	v_add_f32_e32 v81, v78, v81
	v_add_f32_e32 v78, v78, v79
	v_add_f32_e32 v87, v82, v78
	v_rcp_f32_e32 v89, v87
	v_sub_f32_e32 v79, v87, v82
	v_sub_f32_e32 v88, v78, v79
	v_add_f32_e32 v79, v80, v81
	v_mul_f32_e32 v91, v79, v89
	v_sub_f32_e32 v78, v79, v80
	v_mul_f32_e32 v80, v87, v91
	v_fma_f32 v82, v91, v87, -v80
	v_fmac_f32_e32 v82, v91, v88
	v_sub_f32_e32 v90, v81, v78
	v_add_f32_e32 v78, v80, v82
	v_sub_f32_e32 v81, v79, v78
	v_pk_add_f32 v[84:85], v[78:79], v[80:81] neg_lo:[0,1] neg_hi:[0,1]
	v_mov_b32_e32 v83, v78
	v_pk_add_f32 v[78:79], v[84:85], v[82:83] neg_lo:[0,1] neg_hi:[0,1]
	v_cmp_neq_f32_e32 vcc, s0, v77
	v_add_f32_e32 v79, v90, v79
	v_add_f32_e32 v78, v78, v79
	v_add_f32_e32 v79, v81, v78
	v_mul_f32_e32 v90, v89, v79
	v_mul_f32_e32 v80, v87, v90
	v_fma_f32 v82, v90, v87, -v80
	v_fmac_f32_e32 v82, v90, v88
	v_sub_f32_e32 v81, v81, v79
	v_add_f32_e32 v87, v78, v81
	v_add_f32_e32 v78, v80, v82
	v_sub_f32_e32 v81, v79, v78
	v_pk_add_f32 v[84:85], v[78:79], v[80:81] neg_lo:[0,1] neg_hi:[0,1]
	v_mov_b32_e32 v83, v78
	v_pk_add_f32 v[78:79], v[84:85], v[82:83] neg_lo:[0,1] neg_hi:[0,1]
	s_nop 0
	v_add_f32_e32 v79, v87, v79
	v_add_f32_e32 v78, v78, v79
	v_add_f32_e32 v79, v91, v90
	v_add_f32_e32 v78, v81, v78
	v_sub_f32_e32 v80, v79, v91
	v_mul_f32_e32 v78, v89, v78
	v_sub_f32_e32 v80, v90, v80
	v_add_f32_e32 v80, v80, v78
	v_add_f32_e32 v82, v79, v80
	v_mul_f32_e32 v83, v82, v82
	v_fmamk_f32 v78, v83, 0x3e9b6dac, v210
	v_fmaak_f32 v121, v83, v78, 0x3f2aaada
	v_cvt_f32_i32_e32 v78, v86
	v_sub_f32_e32 v79, v82, v79
	v_sub_f32_e32 v79, v80, v79
	v_ldexp_f32 v84, v79, 1
	v_mul_f32_e32 v79, v82, v83
	v_ldexp_f32 v81, v82, 1
	v_pk_mul_f32 v[82:83], v[78:79], v[120:121]
	s_nop 0
	v_fma_f32 v80, v78, s1, -v82
	v_fmac_f32_e32 v80, 0xb102e308, v78
	v_pk_add_f32 v[78:79], v[82:83], v[80:81]
	s_nop 0
	v_sub_f32_e32 v81, v79, v81
	v_sub_f32_e32 v81, v83, v81
	v_add_f32_e32 v85, v84, v81
	v_mov_b32_e32 v84, v82
	v_pk_add_f32 v[82:83], v[78:79], v[82:83] neg_lo:[0,1] neg_hi:[0,1]
	v_pk_add_f32 v[86:87], v[78:79], v[84:85]
	v_mov_b32_e32 v81, v78
	v_mov_b32_e32 v83, v87
	v_pk_add_f32 v[88:89], v[80:81], v[82:83] neg_lo:[0,1] neg_hi:[0,1]
	v_pk_add_f32 v[80:81], v[80:81], v[82:83]
	v_mov_b32_e32 v84, v85
	v_pk_add_f32 v[82:83], v[80:81], v[78:79] op_sel:[1,0] op_sel_hi:[0,1] neg_lo:[0,1] neg_hi:[0,1]
	v_pk_add_f32 v[90:91], v[86:87], v[82:83] op_sel_hi:[1,0] neg_lo:[0,1] neg_hi:[0,1]
	v_mov_b32_e32 v86, v87
	v_mov_b32_e32 v87, v81
	v_pk_mov_b32 v[82:83], v[78:79], v[82:83] op_sel:[1,0]
	v_mov_b32_e32 v85, v78
	v_pk_add_f32 v[82:83], v[86:87], v[82:83] neg_lo:[0,1] neg_hi:[0,1]
	v_mov_b32_e32 v90, v88
	v_pk_add_f32 v[78:79], v[84:85], v[82:83] neg_lo:[0,1] neg_hi:[0,1]
	v_mov_b32_e32 v89, v81
	v_pk_add_f32 v[82:83], v[90:91], v[78:79]
	s_nop 0
	v_pk_add_f32 v[84:85], v[82:83], v[82:83] op_sel:[0,1] op_sel_hi:[1,0]
	s_nop 0
	v_pk_add_f32 v[80:81], v[80:81], v[84:85] op_sel:[1,0] op_sel_hi:[0,1]
	v_mov_b32_e32 v83, v80
	v_pk_add_f32 v[86:87], v[82:83], v[88:89] neg_lo:[0,1] neg_hi:[0,1]
	v_mov_b32_e32 v79, v84
	v_sub_f32_e32 v81, v82, v86
	v_pk_add_f32 v[78:79], v[78:79], v[86:87] neg_lo:[0,1] neg_hi:[0,1]
	v_sub_f32_e32 v81, v88, v81
	v_add_f32_e32 v78, v78, v81
	v_add_f32_e32 v78, v78, v79
	v_add_f32_e32 v78, v80, v78
	v_cndmask_b32_e32 v78, v224, v78, vcc
	v_cmp_ngt_f32_e32 vcc, -1.0, v77
	s_nop 1
	v_cndmask_b32_e32 v78, v225, v78, vcc
	v_cmp_neq_f32_e32 vcc, -1.0, v77
	s_nop 1
	v_cndmask_b32_e32 v78, v226, v78, vcc
	v_cmp_lt_f32_e64 vcc, |v77|, s56
	s_nop 1
	v_cndmask_b32_e32 v77, v78, v77, vcc
	v_add_f32_e32 v76, v76, v77

.LBB0_1201:
	s_and_b64 vcc, exec, s[4:5]
	v_or_b32_e32 v69, 19, v74
	s_cbranch_vccnz .LBB0_1696
	s_andn2_b64 vcc, exec, s[36:37]
	v_mov_b32_e32 v76, v45
	s_cbranch_vccnz .LBB0_1204
	s_nop 0
	v_lshl_add_u64 v[76:77], v[66:67], 0, s[80:81]
	s_waitcnt lgkmcnt(0)
	v_lshl_add_u64 v[76:77], v[76:77], 2, vcc
	v_mov_b32_e32 v76, v249
	s_nop 0
	v_add_f32_e32 v77, v45, v76
	v_max_f32_e32 v76, 0, v77
	v_mul_f32_e64 v77, |v77|, s73
	v_exp_f32_e32 v77, v77
	s_nop 0
	v_add_f32_e32 v80, 1.0, v77
	v_add_f32_e32 v78, -1.0, v80
	v_sub_f32_e32 v79, v78, v80
	v_add_f32_e32 v79, 1.0, v79
	v_sub_f32_e32 v78, v77, v78
	v_add_f32_e32 v81, v78, v79
	v_frexp_mant_f32_e32 v78, v80
	v_cmp_gt_f32_e32 vcc, s46, v78
	v_cvt_f64_f32_e32 v[78:79], v80
	v_frexp_exp_i32_f64_e32 v78, v[78:79]
	v_subbrev_co_u32_e32 v86, vcc, 0, v78, vcc
	v_sub_u32_e32 v78, 0, v86
	v_ldexp_f32 v79, v80, v78
	v_add_f32_e32 v80, -1.0, v79
	v_add_f32_e32 v82, 1.0, v79
	v_ldexp_f32 v78, v81, v78
	v_add_f32_e32 v81, 1.0, v80
	v_add_f32_e32 v83, -1.0, v82
	v_sub_f32_e32 v81, v79, v81
	v_sub_f32_e32 v79, v79, v83
	v_add_f32_e32 v81, v78, v81
	v_add_f32_e32 v78, v78, v79
	v_add_f32_e32 v87, v82, v78
	v_rcp_f32_e32 v89, v87
	v_sub_f32_e32 v79, v87, v82
	v_sub_f32_e32 v88, v78, v79
	v_add_f32_e32 v79, v80, v81
	v_mul_f32_e32 v91, v79, v89
	v_sub_f32_e32 v78, v79, v80
	v_mul_f32_e32 v80, v87, v91
	v_fma_f32 v82, v91, v87, -v80
	v_fmac_f32_e32 v82, v91, v88
	v_sub_f32_e32 v90, v81, v78
	v_add_f32_e32 v78, v80, v82
	v_sub_f32_e32 v81, v79, v78
	v_pk_add_f32 v[84:85], v[78:79], v[80:81] neg_lo:[0,1] neg_hi:[0,1]
	v_mov_b32_e32 v83, v78
	v_pk_add_f32 v[78:79], v[84:85], v[82:83] neg_lo:[0,1] neg_hi:[0,1]
	v_cmp_neq_f32_e32 vcc, s0, v77
	v_add_f32_e32 v79, v90, v79
	v_add_f32_e32 v78, v78, v79
	v_add_f32_e32 v79, v81, v78
	v_mul_f32_e32 v90, v89, v79
	v_mul_f32_e32 v80, v87, v90
	v_fma_f32 v82, v90, v87, -v80
	v_fmac_f32_e32 v82, v90, v88
	v_sub_f32_e32 v81, v81, v79
	v_add_f32_e32 v87, v78, v81
	v_add_f32_e32 v78, v80, v82
	v_sub_f32_e32 v81, v79, v78
	v_pk_add_f32 v[84:85], v[78:79], v[80:81] neg_lo:[0,1] neg_hi:[0,1]
	v_mov_b32_e32 v83, v78
	v_pk_add_f32 v[78:79], v[84:85], v[82:83] neg_lo:[0,1] neg_hi:[0,1]
	s_nop 0
	v_add_f32_e32 v79, v87, v79
	v_add_f32_e32 v78, v78, v79
	v_add_f32_e32 v79, v91, v90
	v_add_f32_e32 v78, v81, v78
	v_sub_f32_e32 v80, v79, v91
	v_mul_f32_e32 v78, v89, v78
	v_sub_f32_e32 v80, v90, v80
	v_add_f32_e32 v80, v80, v78
	v_add_f32_e32 v82, v79, v80
	v_mul_f32_e32 v83, v82, v82
	v_fmamk_f32 v78, v83, 0x3e9b6dac, v210
	v_fmaak_f32 v121, v83, v78, 0x3f2aaada
	v_cvt_f32_i32_e32 v78, v86
	v_sub_f32_e32 v79, v82, v79
	v_sub_f32_e32 v79, v80, v79
	v_ldexp_f32 v84, v79, 1
	v_mul_f32_e32 v79, v82, v83
	v_ldexp_f32 v81, v82, 1
	v_pk_mul_f32 v[82:83], v[78:79], v[120:121]
	s_nop 0
	v_fma_f32 v80, v78, s1, -v82
	v_fmac_f32_e32 v80, 0xb102e308, v78
	v_pk_add_f32 v[78:79], v[82:83], v[80:81]
	s_nop 0
	v_sub_f32_e32 v81, v79, v81
	v_sub_f32_e32 v81, v83, v81
	v_add_f32_e32 v85, v84, v81
	v_mov_b32_e32 v84, v82
	v_pk_add_f32 v[82:83], v[78:79], v[82:83] neg_lo:[0,1] neg_hi:[0,1]
	v_pk_add_f32 v[86:87], v[78:79], v[84:85]
	v_mov_b32_e32 v81, v78
	v_mov_b32_e32 v83, v87
	v_pk_add_f32 v[88:89], v[80:81], v[82:83] neg_lo:[0,1] neg_hi:[0,1]
	v_pk_add_f32 v[80:81], v[80:81], v[82:83]
	v_mov_b32_e32 v84, v85
	v_pk_add_f32 v[82:83], v[80:81], v[78:79] op_sel:[1,0] op_sel_hi:[0,1] neg_lo:[0,1] neg_hi:[0,1]
	v_pk_add_f32 v[90:91], v[86:87], v[82:83] op_sel_hi:[1,0] neg_lo:[0,1] neg_hi:[0,1]
	v_mov_b32_e32 v86, v87
	v_mov_b32_e32 v87, v81
	v_pk_mov_b32 v[82:83], v[78:79], v[82:83] op_sel:[1,0]
	v_mov_b32_e32 v85, v78
	v_pk_add_f32 v[82:83], v[86:87], v[82:83] neg_lo:[0,1] neg_hi:[0,1]
	v_mov_b32_e32 v90, v88
	v_pk_add_f32 v[78:79], v[84:85], v[82:83] neg_lo:[0,1] neg_hi:[0,1]
	v_mov_b32_e32 v89, v81
	v_pk_add_f32 v[82:83], v[90:91], v[78:79]
	s_nop 0
	v_pk_add_f32 v[84:85], v[82:83], v[82:83] op_sel:[0,1] op_sel_hi:[1,0]
	s_nop 0
	v_pk_add_f32 v[80:81], v[80:81], v[84:85] op_sel:[1,0] op_sel_hi:[0,1]
	v_mov_b32_e32 v83, v80
	v_pk_add_f32 v[86:87], v[82:83], v[88:89] neg_lo:[0,1] neg_hi:[0,1]
	v_mov_b32_e32 v79, v84
	v_sub_f32_e32 v81, v82, v86
	v_pk_add_f32 v[78:79], v[78:79], v[86:87] neg_lo:[0,1] neg_hi:[0,1]
	v_sub_f32_e32 v81, v88, v81
	v_add_f32_e32 v78, v78, v81
	v_add_f32_e32 v78, v78, v79
	v_add_f32_e32 v78, v80, v78
	v_cndmask_b32_e32 v78, v224, v78, vcc
	v_cmp_ngt_f32_e32 vcc, -1.0, v77
	s_nop 1
	v_cndmask_b32_e32 v78, v225, v78, vcc
	v_cmp_neq_f32_e32 vcc, -1.0, v77
	s_nop 1
	v_cndmask_b32_e32 v78, v226, v78, vcc
	v_cmp_lt_f32_e64 vcc, |v77|, s56
	s_nop 1
	v_cndmask_b32_e32 v77, v78, v77, vcc
	v_add_f32_e32 v76, v76, v77

.LBB0_1206:
	s_or_b64 exec, exec, s[58:59]
	s_and_saveexec_b64 s[58:59], s[10:11]
	s_cbranch_execz .LBB0_1227
	s_and_b64 vcc, exec, s[4:5]
	v_lshl_add_u64 v[70:71], v[66:67], 2, s[34:35]
	s_cbranch_vccnz .LBB0_1697
	s_andn2_b64 vcc, exec, s[36:37]
	v_mov_b32_e32 v69, v38
	s_cbranch_vccnz .LBB0_1210
	s_nop 0
	v_lshl_add_u64 v[72:73], v[66:67], 0, s[80:81]
	s_waitcnt lgkmcnt(0)
	v_lshl_add_u64 v[72:73], v[72:73], 2, vcc
	v_mov_b32_e32 v69, v250
	s_nop 0
	v_add_f32_e32 v72, v38, v69
	v_max_f32_e32 v69, 0, v72
	v_mul_f32_e64 v72, |v72|, s73
	v_exp_f32_e32 v72, v72
	s_nop 0
	v_add_f32_e32 v73, 1.0, v72
	v_add_f32_e32 v76, -1.0, v73
	v_sub_f32_e32 v77, v76, v73
	v_add_f32_e32 v77, 1.0, v77
	v_sub_f32_e32 v76, v72, v76
	v_add_f32_e32 v78, v76, v77
	v_frexp_mant_f32_e32 v76, v73
	v_cmp_gt_f32_e32 vcc, s46, v76
	v_cvt_f64_f32_e32 v[76:77], v73
	v_frexp_exp_i32_f64_e32 v76, v[76:77]
	v_subbrev_co_u32_e32 v84, vcc, 0, v76, vcc
	v_sub_u32_e32 v76, 0, v84
	v_ldexp_f32 v73, v73, v76
	v_ldexp_f32 v76, v78, v76
	v_add_f32_e32 v78, -1.0, v73
	v_add_f32_e32 v77, 1.0, v78
	v_sub_f32_e32 v77, v73, v77
	v_add_f32_e32 v79, v76, v77
	v_add_f32_e32 v77, 1.0, v73
	v_add_f32_e32 v80, -1.0, v77
	v_sub_f32_e32 v73, v73, v80
	v_add_f32_e32 v73, v76, v73
	v_add_f32_e32 v85, v77, v73
	v_rcp_f32_e32 v86, v85
	v_sub_f32_e32 v76, v85, v77
	v_add_f32_e32 v77, v78, v79
	v_sub_f32_e32 v73, v73, v76
	v_mul_f32_e32 v88, v77, v86
	v_sub_f32_e32 v76, v77, v78
	v_mul_f32_e32 v78, v85, v88
	v_fma_f32 v80, v88, v85, -v78
	v_fmac_f32_e32 v80, v88, v73
	v_sub_f32_e32 v87, v79, v76
	v_add_f32_e32 v76, v78, v80
	v_sub_f32_e32 v79, v77, v76
	v_pk_add_f32 v[82:83], v[76:77], v[78:79] neg_lo:[0,1] neg_hi:[0,1]
	v_mov_b32_e32 v81, v76
	v_pk_add_f32 v[76:77], v[82:83], v[80:81] neg_lo:[0,1] neg_hi:[0,1]
	v_cmp_neq_f32_e32 vcc, s0, v72
	v_add_f32_e32 v77, v87, v77
	v_add_f32_e32 v76, v76, v77
	v_add_f32_e32 v77, v79, v76
	v_mul_f32_e32 v87, v86, v77
	v_mul_f32_e32 v78, v85, v87
	v_fma_f32 v80, v87, v85, -v78
	v_fmac_f32_e32 v80, v87, v73
	v_sub_f32_e32 v73, v79, v77
	v_add_f32_e32 v73, v76, v73
	v_add_f32_e32 v76, v78, v80
	v_sub_f32_e32 v79, v77, v76
	v_pk_add_f32 v[82:83], v[76:77], v[78:79] neg_lo:[0,1] neg_hi:[0,1]
	v_mov_b32_e32 v81, v76
	v_pk_add_f32 v[76:77], v[82:83], v[80:81] neg_lo:[0,1] neg_hi:[0,1]
	s_nop 0
	v_add_f32_e32 v73, v73, v77
	v_add_f32_e32 v73, v76, v73
	v_add_f32_e32 v77, v88, v87
	v_add_f32_e32 v73, v79, v73
	v_sub_f32_e32 v76, v77, v88
	v_mul_f32_e32 v73, v86, v73
	v_sub_f32_e32 v76, v87, v76
	v_add_f32_e32 v73, v76, v73
	v_add_f32_e32 v78, v77, v73
	v_mul_f32_e32 v80, v78, v78
	v_fmamk_f32 v76, v80, 0x3e9b6dac, v210
	v_fmaak_f32 v121, v80, v76, 0x3f2aaada
	v_cvt_f32_i32_e32 v76, v84
	v_sub_f32_e32 v77, v78, v77
	v_sub_f32_e32 v73, v73, v77
	v_mul_f32_e32 v77, v78, v80
	v_pk_mul_f32 v[80:81], v[76:77], v[120:121]
	v_ldexp_f32 v79, v78, 1
	v_fma_f32 v78, v76, s1, -v80
	v_fmac_f32_e32 v78, 0xb102e308, v76
	v_pk_add_f32 v[76:77], v[80:81], v[78:79]
	v_ldexp_f32 v73, v73, 1
	v_sub_f32_e32 v79, v77, v79
	v_sub_f32_e32 v79, v81, v79
	v_add_f32_e32 v83, v73, v79
	v_mov_b32_e32 v82, v80
	v_pk_add_f32 v[80:81], v[76:77], v[80:81] neg_lo:[0,1] neg_hi:[0,1]
	v_pk_add_f32 v[84:85], v[76:77], v[82:83]
	v_mov_b32_e32 v79, v76
	v_mov_b32_e32 v81, v85
	v_pk_add_f32 v[86:87], v[78:79], v[80:81] neg_lo:[0,1] neg_hi:[0,1]
	v_pk_add_f32 v[78:79], v[78:79], v[80:81]
	v_mov_b32_e32 v82, v83
	v_pk_add_f32 v[80:81], v[78:79], v[76:77] op_sel:[1,0] op_sel_hi:[0,1] neg_lo:[0,1] neg_hi:[0,1]
	v_pk_add_f32 v[88:89], v[84:85], v[80:81] op_sel_hi:[1,0] neg_lo:[0,1] neg_hi:[0,1]
	v_mov_b32_e32 v84, v85
	v_mov_b32_e32 v85, v79
	v_pk_mov_b32 v[80:81], v[76:77], v[80:81] op_sel:[1,0]
	v_mov_b32_e32 v83, v76
	v_pk_add_f32 v[80:81], v[84:85], v[80:81] neg_lo:[0,1] neg_hi:[0,1]
	v_mov_b32_e32 v88, v86
	v_pk_add_f32 v[76:77], v[82:83], v[80:81] neg_lo:[0,1] neg_hi:[0,1]
	v_mov_b32_e32 v87, v79
	v_pk_add_f32 v[80:81], v[88:89], v[76:77]
	s_nop 0
	v_pk_add_f32 v[82:83], v[80:81], v[80:81] op_sel:[0,1] op_sel_hi:[1,0]
	s_nop 0
	v_pk_add_f32 v[78:79], v[78:79], v[82:83] op_sel:[1,0] op_sel_hi:[0,1]
	v_mov_b32_e32 v81, v78
	v_pk_add_f32 v[84:85], v[80:81], v[86:87] neg_lo:[0,1] neg_hi:[0,1]
	v_mov_b32_e32 v77, v82
	v_sub_f32_e32 v73, v80, v84
	v_pk_add_f32 v[76:77], v[76:77], v[84:85] neg_lo:[0,1] neg_hi:[0,1]
	v_sub_f32_e32 v73, v86, v73
	v_add_f32_e32 v73, v76, v73
	v_add_f32_e32 v73, v73, v77
	v_add_f32_e32 v73, v78, v73
	v_cndmask_b32_e32 v73, v224, v73, vcc
	v_cmp_ngt_f32_e32 vcc, -1.0, v72
	s_nop 1
	v_cndmask_b32_e32 v73, v225, v73, vcc
	v_cmp_neq_f32_e32 vcc, -1.0, v72
	s_nop 1
	v_cndmask_b32_e32 v73, v226, v73, vcc
	v_cmp_lt_f32_e64 vcc, |v72|, s56
	s_nop 1
	v_cndmask_b32_e32 v72, v73, v72, vcc
	v_add_f32_e32 v69, v69, v72

.LBB0_1212:
	s_and_b64 vcc, exec, s[4:5]
	v_or_b32_e32 v69, 17, v74
	s_cbranch_vccnz .LBB0_1698
	s_andn2_b64 vcc, exec, s[36:37]
	v_mov_b32_e32 v76, v39
	s_cbranch_vccnz .LBB0_1215
	s_nop 0
	v_lshl_add_u64 v[76:77], v[66:67], 0, s[80:81]
	s_waitcnt lgkmcnt(0)
	v_lshl_add_u64 v[76:77], v[76:77], 2, vcc
	v_mov_b32_e32 v76, v250
	s_nop 0
	v_add_f32_e32 v77, v39, v76
	v_max_f32_e32 v76, 0, v77
	v_mul_f32_e64 v77, |v77|, s73
	v_exp_f32_e32 v77, v77
	s_nop 0
	v_add_f32_e32 v80, 1.0, v77
	v_add_f32_e32 v78, -1.0, v80
	v_sub_f32_e32 v79, v78, v80
	v_add_f32_e32 v79, 1.0, v79
	v_sub_f32_e32 v78, v77, v78
	v_add_f32_e32 v81, v78, v79
	v_frexp_mant_f32_e32 v78, v80
	v_cmp_gt_f32_e32 vcc, s46, v78
	v_cvt_f64_f32_e32 v[78:79], v80
	v_frexp_exp_i32_f64_e32 v78, v[78:79]
	v_subbrev_co_u32_e32 v86, vcc, 0, v78, vcc
	v_sub_u32_e32 v78, 0, v86
	v_ldexp_f32 v79, v80, v78
	v_add_f32_e32 v80, -1.0, v79
	v_add_f32_e32 v82, 1.0, v79
	v_ldexp_f32 v78, v81, v78
	v_add_f32_e32 v81, 1.0, v80
	v_add_f32_e32 v83, -1.0, v82
	v_sub_f32_e32 v81, v79, v81
	v_sub_f32_e32 v79, v79, v83
	v_add_f32_e32 v81, v78, v81
	v_add_f32_e32 v78, v78, v79
	v_add_f32_e32 v87, v82, v78
	v_rcp_f32_e32 v89, v87
	v_sub_f32_e32 v79, v87, v82
	v_sub_f32_e32 v88, v78, v79
	v_add_f32_e32 v79, v80, v81
	v_mul_f32_e32 v91, v79, v89
	v_sub_f32_e32 v78, v79, v80
	v_mul_f32_e32 v80, v87, v91
	v_fma_f32 v82, v91, v87, -v80
	v_fmac_f32_e32 v82, v91, v88
	v_sub_f32_e32 v90, v81, v78
	v_add_f32_e32 v78, v80, v82
	v_sub_f32_e32 v81, v79, v78
	v_pk_add_f32 v[84:85], v[78:79], v[80:81] neg_lo:[0,1] neg_hi:[0,1]
	v_mov_b32_e32 v83, v78
	v_pk_add_f32 v[78:79], v[84:85], v[82:83] neg_lo:[0,1] neg_hi:[0,1]
	v_cmp_neq_f32_e32 vcc, s0, v77
	v_add_f32_e32 v79, v90, v79
	v_add_f32_e32 v78, v78, v79
	v_add_f32_e32 v79, v81, v78
	v_mul_f32_e32 v90, v89, v79
	v_mul_f32_e32 v80, v87, v90
	v_fma_f32 v82, v90, v87, -v80
	v_fmac_f32_e32 v82, v90, v88
	v_sub_f32_e32 v81, v81, v79
	v_add_f32_e32 v87, v78, v81
	v_add_f32_e32 v78, v80, v82
	v_sub_f32_e32 v81, v79, v78
	v_pk_add_f32 v[84:85], v[78:79], v[80:81] neg_lo:[0,1] neg_hi:[0,1]
	v_mov_b32_e32 v83, v78
	v_pk_add_f32 v[78:79], v[84:85], v[82:83] neg_lo:[0,1] neg_hi:[0,1]
	s_nop 0
	v_add_f32_e32 v79, v87, v79
	v_add_f32_e32 v78, v78, v79
	v_add_f32_e32 v79, v91, v90
	v_add_f32_e32 v78, v81, v78
	v_sub_f32_e32 v80, v79, v91
	v_mul_f32_e32 v78, v89, v78
	v_sub_f32_e32 v80, v90, v80
	v_add_f32_e32 v80, v80, v78
	v_add_f32_e32 v82, v79, v80
	v_mul_f32_e32 v83, v82, v82
	v_fmamk_f32 v78, v83, 0x3e9b6dac, v210
	v_fmaak_f32 v121, v83, v78, 0x3f2aaada
	v_cvt_f32_i32_e32 v78, v86
	v_sub_f32_e32 v79, v82, v79
	v_sub_f32_e32 v79, v80, v79
	v_ldexp_f32 v84, v79, 1
	v_mul_f32_e32 v79, v82, v83
	v_ldexp_f32 v81, v82, 1
	v_pk_mul_f32 v[82:83], v[78:79], v[120:121]
	s_nop 0
	v_fma_f32 v80, v78, s1, -v82
	v_fmac_f32_e32 v80, 0xb102e308, v78
	v_pk_add_f32 v[78:79], v[82:83], v[80:81]
	s_nop 0
	v_sub_f32_e32 v81, v79, v81
	v_sub_f32_e32 v81, v83, v81
	v_add_f32_e32 v85, v84, v81
	v_mov_b32_e32 v84, v82
	v_pk_add_f32 v[82:83], v[78:79], v[82:83] neg_lo:[0,1] neg_hi:[0,1]
	v_pk_add_f32 v[86:87], v[78:79], v[84:85]
	v_mov_b32_e32 v81, v78
	v_mov_b32_e32 v83, v87
	v_pk_add_f32 v[88:89], v[80:81], v[82:83] neg_lo:[0,1] neg_hi:[0,1]
	v_pk_add_f32 v[80:81], v[80:81], v[82:83]
	v_mov_b32_e32 v84, v85
	v_pk_add_f32 v[82:83], v[80:81], v[78:79] op_sel:[1,0] op_sel_hi:[0,1] neg_lo:[0,1] neg_hi:[0,1]
	v_pk_add_f32 v[90:91], v[86:87], v[82:83] op_sel_hi:[1,0] neg_lo:[0,1] neg_hi:[0,1]
	v_mov_b32_e32 v86, v87
	v_mov_b32_e32 v87, v81
	v_pk_mov_b32 v[82:83], v[78:79], v[82:83] op_sel:[1,0]
	v_mov_b32_e32 v85, v78
	v_pk_add_f32 v[82:83], v[86:87], v[82:83] neg_lo:[0,1] neg_hi:[0,1]
	v_mov_b32_e32 v90, v88
	v_pk_add_f32 v[78:79], v[84:85], v[82:83] neg_lo:[0,1] neg_hi:[0,1]
	v_mov_b32_e32 v89, v81
	v_pk_add_f32 v[82:83], v[90:91], v[78:79]
	s_nop 0
	v_pk_add_f32 v[84:85], v[82:83], v[82:83] op_sel:[0,1] op_sel_hi:[1,0]
	s_nop 0
	v_pk_add_f32 v[80:81], v[80:81], v[84:85] op_sel:[1,0] op_sel_hi:[0,1]
	v_mov_b32_e32 v83, v80
	v_pk_add_f32 v[86:87], v[82:83], v[88:89] neg_lo:[0,1] neg_hi:[0,1]
	v_mov_b32_e32 v79, v84
	v_sub_f32_e32 v81, v82, v86
	v_pk_add_f32 v[78:79], v[78:79], v[86:87] neg_lo:[0,1] neg_hi:[0,1]
	v_sub_f32_e32 v81, v88, v81
	v_add_f32_e32 v78, v78, v81
	v_add_f32_e32 v78, v78, v79
	v_add_f32_e32 v78, v80, v78
	v_cndmask_b32_e32 v78, v224, v78, vcc
	v_cmp_ngt_f32_e32 vcc, -1.0, v77
	s_nop 1
	v_cndmask_b32_e32 v78, v225, v78, vcc
	v_cmp_neq_f32_e32 vcc, -1.0, v77
	s_nop 1
	v_cndmask_b32_e32 v78, v226, v78, vcc
	v_cmp_lt_f32_e64 vcc, |v77|, s56
	s_nop 1
	v_cndmask_b32_e32 v77, v78, v77, vcc
	v_add_f32_e32 v76, v76, v77

.LBB0_1217:
	s_and_b64 vcc, exec, s[4:5]
	v_or_b32_e32 v69, 18, v74
	s_cbranch_vccnz .LBB0_1699
	s_andn2_b64 vcc, exec, s[36:37]
	v_mov_b32_e32 v76, v40
	s_cbranch_vccnz .LBB0_1220
	s_nop 0
	v_lshl_add_u64 v[76:77], v[66:67], 0, s[80:81]
	s_waitcnt lgkmcnt(0)
	v_lshl_add_u64 v[76:77], v[76:77], 2, vcc
	v_mov_b32_e32 v76, v250
	s_nop 0
	v_add_f32_e32 v77, v40, v76
	v_max_f32_e32 v76, 0, v77
	v_mul_f32_e64 v77, |v77|, s73
	v_exp_f32_e32 v77, v77
	s_nop 0
	v_add_f32_e32 v80, 1.0, v77
	v_add_f32_e32 v78, -1.0, v80
	v_sub_f32_e32 v79, v78, v80
	v_add_f32_e32 v79, 1.0, v79
	v_sub_f32_e32 v78, v77, v78
	v_add_f32_e32 v81, v78, v79
	v_frexp_mant_f32_e32 v78, v80
	v_cmp_gt_f32_e32 vcc, s46, v78
	v_cvt_f64_f32_e32 v[78:79], v80
	v_frexp_exp_i32_f64_e32 v78, v[78:79]
	v_subbrev_co_u32_e32 v86, vcc, 0, v78, vcc
	v_sub_u32_e32 v78, 0, v86
	v_ldexp_f32 v79, v80, v78
	v_add_f32_e32 v80, -1.0, v79
	v_add_f32_e32 v82, 1.0, v79
	v_ldexp_f32 v78, v81, v78
	v_add_f32_e32 v81, 1.0, v80
	v_add_f32_e32 v83, -1.0, v82
	v_sub_f32_e32 v81, v79, v81
	v_sub_f32_e32 v79, v79, v83
	v_add_f32_e32 v81, v78, v81
	v_add_f32_e32 v78, v78, v79
	v_add_f32_e32 v87, v82, v78
	v_rcp_f32_e32 v89, v87
	v_sub_f32_e32 v79, v87, v82
	v_sub_f32_e32 v88, v78, v79
	v_add_f32_e32 v79, v80, v81
	v_mul_f32_e32 v91, v79, v89
	v_sub_f32_e32 v78, v79, v80
	v_mul_f32_e32 v80, v87, v91
	v_fma_f32 v82, v91, v87, -v80
	v_fmac_f32_e32 v82, v91, v88
	v_sub_f32_e32 v90, v81, v78
	v_add_f32_e32 v78, v80, v82
	v_sub_f32_e32 v81, v79, v78
	v_pk_add_f32 v[84:85], v[78:79], v[80:81] neg_lo:[0,1] neg_hi:[0,1]
	v_mov_b32_e32 v83, v78
	v_pk_add_f32 v[78:79], v[84:85], v[82:83] neg_lo:[0,1] neg_hi:[0,1]
	v_cmp_neq_f32_e32 vcc, s0, v77
	v_add_f32_e32 v79, v90, v79
	v_add_f32_e32 v78, v78, v79
	v_add_f32_e32 v79, v81, v78
	v_mul_f32_e32 v90, v89, v79
	v_mul_f32_e32 v80, v87, v90
	v_fma_f32 v82, v90, v87, -v80
	v_fmac_f32_e32 v82, v90, v88
	v_sub_f32_e32 v81, v81, v79
	v_add_f32_e32 v87, v78, v81
	v_add_f32_e32 v78, v80, v82
	v_sub_f32_e32 v81, v79, v78
	v_pk_add_f32 v[84:85], v[78:79], v[80:81] neg_lo:[0,1] neg_hi:[0,1]
	v_mov_b32_e32 v83, v78
	v_pk_add_f32 v[78:79], v[84:85], v[82:83] neg_lo:[0,1] neg_hi:[0,1]
	s_nop 0
	v_add_f32_e32 v79, v87, v79
	v_add_f32_e32 v78, v78, v79
	v_add_f32_e32 v79, v91, v90
	v_add_f32_e32 v78, v81, v78
	v_sub_f32_e32 v80, v79, v91
	v_mul_f32_e32 v78, v89, v78
	v_sub_f32_e32 v80, v90, v80
	v_add_f32_e32 v80, v80, v78
	v_add_f32_e32 v82, v79, v80
	v_mul_f32_e32 v83, v82, v82
	v_fmamk_f32 v78, v83, 0x3e9b6dac, v210
	v_fmaak_f32 v121, v83, v78, 0x3f2aaada
	v_cvt_f32_i32_e32 v78, v86
	v_sub_f32_e32 v79, v82, v79
	v_sub_f32_e32 v79, v80, v79
	v_ldexp_f32 v84, v79, 1
	v_mul_f32_e32 v79, v82, v83
	v_ldexp_f32 v81, v82, 1
	v_pk_mul_f32 v[82:83], v[78:79], v[120:121]
	s_nop 0
	v_fma_f32 v80, v78, s1, -v82
	v_fmac_f32_e32 v80, 0xb102e308, v78
	v_pk_add_f32 v[78:79], v[82:83], v[80:81]
	s_nop 0
	v_sub_f32_e32 v81, v79, v81
	v_sub_f32_e32 v81, v83, v81
	v_add_f32_e32 v85, v84, v81
	v_mov_b32_e32 v84, v82
	v_pk_add_f32 v[82:83], v[78:79], v[82:83] neg_lo:[0,1] neg_hi:[0,1]
	v_pk_add_f32 v[86:87], v[78:79], v[84:85]
	v_mov_b32_e32 v81, v78
	v_mov_b32_e32 v83, v87
	v_pk_add_f32 v[88:89], v[80:81], v[82:83] neg_lo:[0,1] neg_hi:[0,1]
	v_pk_add_f32 v[80:81], v[80:81], v[82:83]
	v_mov_b32_e32 v84, v85
	v_pk_add_f32 v[82:83], v[80:81], v[78:79] op_sel:[1,0] op_sel_hi:[0,1] neg_lo:[0,1] neg_hi:[0,1]
	v_pk_add_f32 v[90:91], v[86:87], v[82:83] op_sel_hi:[1,0] neg_lo:[0,1] neg_hi:[0,1]
	v_mov_b32_e32 v86, v87
	v_mov_b32_e32 v87, v81
	v_pk_mov_b32 v[82:83], v[78:79], v[82:83] op_sel:[1,0]
	v_mov_b32_e32 v85, v78
	v_pk_add_f32 v[82:83], v[86:87], v[82:83] neg_lo:[0,1] neg_hi:[0,1]
	v_mov_b32_e32 v90, v88
	v_pk_add_f32 v[78:79], v[84:85], v[82:83] neg_lo:[0,1] neg_hi:[0,1]
	v_mov_b32_e32 v89, v81
	v_pk_add_f32 v[82:83], v[90:91], v[78:79]
	s_nop 0
	v_pk_add_f32 v[84:85], v[82:83], v[82:83] op_sel:[0,1] op_sel_hi:[1,0]
	s_nop 0
	v_pk_add_f32 v[80:81], v[80:81], v[84:85] op_sel:[1,0] op_sel_hi:[0,1]
	v_mov_b32_e32 v83, v80
	v_pk_add_f32 v[86:87], v[82:83], v[88:89] neg_lo:[0,1] neg_hi:[0,1]
	v_mov_b32_e32 v79, v84
	v_sub_f32_e32 v81, v82, v86
	v_pk_add_f32 v[78:79], v[78:79], v[86:87] neg_lo:[0,1] neg_hi:[0,1]
	v_sub_f32_e32 v81, v88, v81
	v_add_f32_e32 v78, v78, v81
	v_add_f32_e32 v78, v78, v79
	v_add_f32_e32 v78, v80, v78
	v_cndmask_b32_e32 v78, v224, v78, vcc
	v_cmp_ngt_f32_e32 vcc, -1.0, v77
	s_nop 1
	v_cndmask_b32_e32 v78, v225, v78, vcc
	v_cmp_neq_f32_e32 vcc, -1.0, v77
	s_nop 1
	v_cndmask_b32_e32 v78, v226, v78, vcc
	v_cmp_lt_f32_e64 vcc, |v77|, s56
	s_nop 1
	v_cndmask_b32_e32 v77, v78, v77, vcc
	v_add_f32_e32 v76, v76, v77

.LBB0_1222:
	s_and_b64 vcc, exec, s[4:5]
	v_or_b32_e32 v69, 19, v74
	s_cbranch_vccnz .LBB0_1700
	s_andn2_b64 vcc, exec, s[36:37]
	v_mov_b32_e32 v76, v41
	s_cbranch_vccnz .LBB0_1225
	s_nop 0
	v_lshl_add_u64 v[76:77], v[66:67], 0, s[80:81]
	s_waitcnt lgkmcnt(0)
	v_lshl_add_u64 v[76:77], v[76:77], 2, vcc
	v_mov_b32_e32 v76, v250
	s_nop 0
	v_add_f32_e32 v77, v41, v76
	v_max_f32_e32 v76, 0, v77
	v_mul_f32_e64 v77, |v77|, s73
	v_exp_f32_e32 v77, v77
	s_nop 0
	v_add_f32_e32 v80, 1.0, v77
	v_add_f32_e32 v78, -1.0, v80
	v_sub_f32_e32 v79, v78, v80
	v_add_f32_e32 v79, 1.0, v79
	v_sub_f32_e32 v78, v77, v78
	v_add_f32_e32 v81, v78, v79
	v_frexp_mant_f32_e32 v78, v80
	v_cmp_gt_f32_e32 vcc, s46, v78
	v_cvt_f64_f32_e32 v[78:79], v80
	v_frexp_exp_i32_f64_e32 v78, v[78:79]
	v_subbrev_co_u32_e32 v86, vcc, 0, v78, vcc
	v_sub_u32_e32 v78, 0, v86
	v_ldexp_f32 v79, v80, v78
	v_add_f32_e32 v80, -1.0, v79
	v_add_f32_e32 v82, 1.0, v79
	v_ldexp_f32 v78, v81, v78
	v_add_f32_e32 v81, 1.0, v80
	v_add_f32_e32 v83, -1.0, v82
	v_sub_f32_e32 v81, v79, v81
	v_sub_f32_e32 v79, v79, v83
	v_add_f32_e32 v81, v78, v81
	v_add_f32_e32 v78, v78, v79
	v_add_f32_e32 v87, v82, v78
	v_rcp_f32_e32 v89, v87
	v_sub_f32_e32 v79, v87, v82
	v_sub_f32_e32 v88, v78, v79
	v_add_f32_e32 v79, v80, v81
	v_mul_f32_e32 v91, v79, v89
	v_sub_f32_e32 v78, v79, v80
	v_mul_f32_e32 v80, v87, v91
	v_fma_f32 v82, v91, v87, -v80
	v_fmac_f32_e32 v82, v91, v88
	v_sub_f32_e32 v90, v81, v78
	v_add_f32_e32 v78, v80, v82
	v_sub_f32_e32 v81, v79, v78
	v_pk_add_f32 v[84:85], v[78:79], v[80:81] neg_lo:[0,1] neg_hi:[0,1]
	v_mov_b32_e32 v83, v78
	v_pk_add_f32 v[78:79], v[84:85], v[82:83] neg_lo:[0,1] neg_hi:[0,1]
	v_cmp_neq_f32_e32 vcc, s0, v77
	v_add_f32_e32 v79, v90, v79
	v_add_f32_e32 v78, v78, v79
	v_add_f32_e32 v79, v81, v78
	v_mul_f32_e32 v90, v89, v79
	v_mul_f32_e32 v80, v87, v90
	v_fma_f32 v82, v90, v87, -v80
	v_fmac_f32_e32 v82, v90, v88
	v_sub_f32_e32 v81, v81, v79
	v_add_f32_e32 v87, v78, v81
	v_add_f32_e32 v78, v80, v82
	v_sub_f32_e32 v81, v79, v78
	v_pk_add_f32 v[84:85], v[78:79], v[80:81] neg_lo:[0,1] neg_hi:[0,1]
	v_mov_b32_e32 v83, v78
	v_pk_add_f32 v[78:79], v[84:85], v[82:83] neg_lo:[0,1] neg_hi:[0,1]
	s_nop 0
	v_add_f32_e32 v79, v87, v79
	v_add_f32_e32 v78, v78, v79
	v_add_f32_e32 v79, v91, v90
	v_add_f32_e32 v78, v81, v78
	v_sub_f32_e32 v80, v79, v91
	v_mul_f32_e32 v78, v89, v78
	v_sub_f32_e32 v80, v90, v80
	v_add_f32_e32 v80, v80, v78
	v_add_f32_e32 v82, v79, v80
	v_mul_f32_e32 v83, v82, v82
	v_fmamk_f32 v78, v83, 0x3e9b6dac, v210
	v_fmaak_f32 v121, v83, v78, 0x3f2aaada
	v_cvt_f32_i32_e32 v78, v86
	v_sub_f32_e32 v79, v82, v79
	v_sub_f32_e32 v79, v80, v79
	v_ldexp_f32 v84, v79, 1
	v_mul_f32_e32 v79, v82, v83
	v_ldexp_f32 v81, v82, 1
	v_pk_mul_f32 v[82:83], v[78:79], v[120:121]
	s_nop 0
	v_fma_f32 v80, v78, s1, -v82
	v_fmac_f32_e32 v80, 0xb102e308, v78
	v_pk_add_f32 v[78:79], v[82:83], v[80:81]
	s_nop 0
	v_sub_f32_e32 v81, v79, v81
	v_sub_f32_e32 v81, v83, v81
	v_add_f32_e32 v85, v84, v81
	v_mov_b32_e32 v84, v82
	v_pk_add_f32 v[82:83], v[78:79], v[82:83] neg_lo:[0,1] neg_hi:[0,1]
	v_pk_add_f32 v[86:87], v[78:79], v[84:85]
	v_mov_b32_e32 v81, v78
	v_mov_b32_e32 v83, v87
	v_pk_add_f32 v[88:89], v[80:81], v[82:83] neg_lo:[0,1] neg_hi:[0,1]
	v_pk_add_f32 v[80:81], v[80:81], v[82:83]
	v_mov_b32_e32 v84, v85
	v_pk_add_f32 v[82:83], v[80:81], v[78:79] op_sel:[1,0] op_sel_hi:[0,1] neg_lo:[0,1] neg_hi:[0,1]
	v_pk_add_f32 v[90:91], v[86:87], v[82:83] op_sel_hi:[1,0] neg_lo:[0,1] neg_hi:[0,1]
	v_mov_b32_e32 v86, v87
	v_mov_b32_e32 v87, v81
	v_pk_mov_b32 v[82:83], v[78:79], v[82:83] op_sel:[1,0]
	v_mov_b32_e32 v85, v78
	v_pk_add_f32 v[82:83], v[86:87], v[82:83] neg_lo:[0,1] neg_hi:[0,1]
	v_mov_b32_e32 v90, v88
	v_pk_add_f32 v[78:79], v[84:85], v[82:83] neg_lo:[0,1] neg_hi:[0,1]
	v_mov_b32_e32 v89, v81
	v_pk_add_f32 v[82:83], v[90:91], v[78:79]
	s_nop 0
	v_pk_add_f32 v[84:85], v[82:83], v[82:83] op_sel:[0,1] op_sel_hi:[1,0]
	s_nop 0
	v_pk_add_f32 v[80:81], v[80:81], v[84:85] op_sel:[1,0] op_sel_hi:[0,1]
	v_mov_b32_e32 v83, v80
	v_pk_add_f32 v[86:87], v[82:83], v[88:89] neg_lo:[0,1] neg_hi:[0,1]
	v_mov_b32_e32 v79, v84
	v_sub_f32_e32 v81, v82, v86
	v_pk_add_f32 v[78:79], v[78:79], v[86:87] neg_lo:[0,1] neg_hi:[0,1]
	v_sub_f32_e32 v81, v88, v81
	v_add_f32_e32 v78, v78, v81
	v_add_f32_e32 v78, v78, v79
	v_add_f32_e32 v78, v80, v78
	v_cndmask_b32_e32 v78, v224, v78, vcc
	v_cmp_ngt_f32_e32 vcc, -1.0, v77
	s_nop 1
	v_cndmask_b32_e32 v78, v225, v78, vcc
	v_cmp_neq_f32_e32 vcc, -1.0, v77
	s_nop 1
	v_cndmask_b32_e32 v78, v226, v78, vcc
	v_cmp_lt_f32_e64 vcc, |v77|, s56
	s_nop 1
	v_cndmask_b32_e32 v77, v78, v77, vcc
	v_add_f32_e32 v76, v76, v77

.LBB0_1227:
	s_or_b64 exec, exec, s[58:59]
	s_and_saveexec_b64 s[58:59], s[12:13]
	s_cbranch_execz .LBB0_1248
	s_and_b64 vcc, exec, s[4:5]
	v_lshl_add_u64 v[70:71], v[66:67], 2, s[34:35]
	s_cbranch_vccnz .LBB0_1701
	s_andn2_b64 vcc, exec, s[36:37]
	v_mov_b32_e32 v69, v34
	s_cbranch_vccnz .LBB0_1231
	s_nop 0
	v_lshl_add_u64 v[72:73], v[66:67], 0, s[80:81]
	s_waitcnt lgkmcnt(0)
	v_lshl_add_u64 v[72:73], v[72:73], 2, vcc
	v_mov_b32_e32 v69, v251
	s_nop 0
	v_add_f32_e32 v72, v34, v69
	v_max_f32_e32 v69, 0, v72
	v_mul_f32_e64 v72, |v72|, s73
	v_exp_f32_e32 v72, v72
	s_nop 0
	v_add_f32_e32 v73, 1.0, v72
	v_add_f32_e32 v76, -1.0, v73
	v_sub_f32_e32 v77, v76, v73
	v_add_f32_e32 v77, 1.0, v77
	v_sub_f32_e32 v76, v72, v76
	v_add_f32_e32 v78, v76, v77
	v_frexp_mant_f32_e32 v76, v73
	v_cmp_gt_f32_e32 vcc, s46, v76
	v_cvt_f64_f32_e32 v[76:77], v73
	v_frexp_exp_i32_f64_e32 v76, v[76:77]
	v_subbrev_co_u32_e32 v84, vcc, 0, v76, vcc
	v_sub_u32_e32 v76, 0, v84
	v_ldexp_f32 v73, v73, v76
	v_ldexp_f32 v76, v78, v76
	v_add_f32_e32 v78, -1.0, v73
	v_add_f32_e32 v77, 1.0, v78
	v_sub_f32_e32 v77, v73, v77
	v_add_f32_e32 v79, v76, v77
	v_add_f32_e32 v77, 1.0, v73
	v_add_f32_e32 v80, -1.0, v77
	v_sub_f32_e32 v73, v73, v80
	v_add_f32_e32 v73, v76, v73
	v_add_f32_e32 v85, v77, v73
	v_rcp_f32_e32 v86, v85
	v_sub_f32_e32 v76, v85, v77
	v_add_f32_e32 v77, v78, v79
	v_sub_f32_e32 v73, v73, v76
	v_mul_f32_e32 v88, v77, v86
	v_sub_f32_e32 v76, v77, v78
	v_mul_f32_e32 v78, v85, v88
	v_fma_f32 v80, v88, v85, -v78
	v_fmac_f32_e32 v80, v88, v73
	v_sub_f32_e32 v87, v79, v76
	v_add_f32_e32 v76, v78, v80
	v_sub_f32_e32 v79, v77, v76
	v_pk_add_f32 v[82:83], v[76:77], v[78:79] neg_lo:[0,1] neg_hi:[0,1]
	v_mov_b32_e32 v81, v76
	v_pk_add_f32 v[76:77], v[82:83], v[80:81] neg_lo:[0,1] neg_hi:[0,1]
	v_cmp_neq_f32_e32 vcc, s0, v72
	v_add_f32_e32 v77, v87, v77
	v_add_f32_e32 v76, v76, v77
	v_add_f32_e32 v77, v79, v76
	v_mul_f32_e32 v87, v86, v77
	v_mul_f32_e32 v78, v85, v87
	v_fma_f32 v80, v87, v85, -v78
	v_fmac_f32_e32 v80, v87, v73
	v_sub_f32_e32 v73, v79, v77
	v_add_f32_e32 v73, v76, v73
	v_add_f32_e32 v76, v78, v80
	v_sub_f32_e32 v79, v77, v76
	v_pk_add_f32 v[82:83], v[76:77], v[78:79] neg_lo:[0,1] neg_hi:[0,1]
	v_mov_b32_e32 v81, v76
	v_pk_add_f32 v[76:77], v[82:83], v[80:81] neg_lo:[0,1] neg_hi:[0,1]
	s_nop 0
	v_add_f32_e32 v73, v73, v77
	v_add_f32_e32 v73, v76, v73
	v_add_f32_e32 v77, v88, v87
	v_add_f32_e32 v73, v79, v73
	v_sub_f32_e32 v76, v77, v88
	v_mul_f32_e32 v73, v86, v73
	v_sub_f32_e32 v76, v87, v76
	v_add_f32_e32 v73, v76, v73
	v_add_f32_e32 v78, v77, v73
	v_mul_f32_e32 v80, v78, v78
	v_fmamk_f32 v76, v80, 0x3e9b6dac, v210
	v_fmaak_f32 v121, v80, v76, 0x3f2aaada
	v_cvt_f32_i32_e32 v76, v84
	v_sub_f32_e32 v77, v78, v77
	v_sub_f32_e32 v73, v73, v77
	v_mul_f32_e32 v77, v78, v80
	v_pk_mul_f32 v[80:81], v[76:77], v[120:121]
	v_ldexp_f32 v79, v78, 1
	v_fma_f32 v78, v76, s1, -v80
	v_fmac_f32_e32 v78, 0xb102e308, v76
	v_pk_add_f32 v[76:77], v[80:81], v[78:79]
	v_ldexp_f32 v73, v73, 1
	v_sub_f32_e32 v79, v77, v79
	v_sub_f32_e32 v79, v81, v79
	v_add_f32_e32 v83, v73, v79
	v_mov_b32_e32 v82, v80
	v_pk_add_f32 v[80:81], v[76:77], v[80:81] neg_lo:[0,1] neg_hi:[0,1]
	v_pk_add_f32 v[84:85], v[76:77], v[82:83]
	v_mov_b32_e32 v79, v76
	v_mov_b32_e32 v81, v85
	v_pk_add_f32 v[86:87], v[78:79], v[80:81] neg_lo:[0,1] neg_hi:[0,1]
	v_pk_add_f32 v[78:79], v[78:79], v[80:81]
	v_mov_b32_e32 v82, v83
	v_pk_add_f32 v[80:81], v[78:79], v[76:77] op_sel:[1,0] op_sel_hi:[0,1] neg_lo:[0,1] neg_hi:[0,1]
	v_pk_add_f32 v[88:89], v[84:85], v[80:81] op_sel_hi:[1,0] neg_lo:[0,1] neg_hi:[0,1]
	v_mov_b32_e32 v84, v85
	v_mov_b32_e32 v85, v79
	v_pk_mov_b32 v[80:81], v[76:77], v[80:81] op_sel:[1,0]
	v_mov_b32_e32 v83, v76
	v_pk_add_f32 v[80:81], v[84:85], v[80:81] neg_lo:[0,1] neg_hi:[0,1]
	v_mov_b32_e32 v88, v86
	v_pk_add_f32 v[76:77], v[82:83], v[80:81] neg_lo:[0,1] neg_hi:[0,1]
	v_mov_b32_e32 v87, v79
	v_pk_add_f32 v[80:81], v[88:89], v[76:77]
	s_nop 0
	v_pk_add_f32 v[82:83], v[80:81], v[80:81] op_sel:[0,1] op_sel_hi:[1,0]
	s_nop 0
	v_pk_add_f32 v[78:79], v[78:79], v[82:83] op_sel:[1,0] op_sel_hi:[0,1]
	v_mov_b32_e32 v81, v78
	v_pk_add_f32 v[84:85], v[80:81], v[86:87] neg_lo:[0,1] neg_hi:[0,1]
	v_mov_b32_e32 v77, v82
	v_sub_f32_e32 v73, v80, v84
	v_pk_add_f32 v[76:77], v[76:77], v[84:85] neg_lo:[0,1] neg_hi:[0,1]
	v_sub_f32_e32 v73, v86, v73
	v_add_f32_e32 v73, v76, v73
	v_add_f32_e32 v73, v73, v77
	v_add_f32_e32 v73, v78, v73
	v_cndmask_b32_e32 v73, v224, v73, vcc
	v_cmp_ngt_f32_e32 vcc, -1.0, v72
	s_nop 1
	v_cndmask_b32_e32 v73, v225, v73, vcc
	v_cmp_neq_f32_e32 vcc, -1.0, v72
	s_nop 1
	v_cndmask_b32_e32 v73, v226, v73, vcc
	v_cmp_lt_f32_e64 vcc, |v72|, s56
	s_nop 1
	v_cndmask_b32_e32 v72, v73, v72, vcc
	v_add_f32_e32 v69, v69, v72

.LBB0_1233:
	s_and_b64 vcc, exec, s[4:5]
	v_or_b32_e32 v69, 17, v74
	s_cbranch_vccnz .LBB0_1702
	s_andn2_b64 vcc, exec, s[36:37]
	v_mov_b32_e32 v75, v35
	s_cbranch_vccnz .LBB0_1236
	s_nop 0
	v_lshl_add_u64 v[76:77], v[66:67], 0, s[80:81]
	s_waitcnt lgkmcnt(0)
	v_lshl_add_u64 v[76:77], v[76:77], 2, vcc
	v_mov_b32_e32 v75, v251
	s_nop 0
	v_add_f32_e32 v76, v35, v75
	v_max_f32_e32 v75, 0, v76
	v_mul_f32_e64 v76, |v76|, s73
	v_exp_f32_e32 v76, v76
	s_nop 0
	v_add_f32_e32 v77, 1.0, v76
	v_add_f32_e32 v78, -1.0, v77
	v_sub_f32_e32 v79, v78, v77
	v_add_f32_e32 v79, 1.0, v79
	v_sub_f32_e32 v78, v76, v78
	v_add_f32_e32 v80, v78, v79
	v_frexp_mant_f32_e32 v78, v77
	v_cmp_gt_f32_e32 vcc, s46, v78
	v_cvt_f64_f32_e32 v[78:79], v77
	v_frexp_exp_i32_f64_e32 v78, v[78:79]
	v_subbrev_co_u32_e32 v86, vcc, 0, v78, vcc
	v_sub_u32_e32 v78, 0, v86
	v_ldexp_f32 v77, v77, v78
	v_ldexp_f32 v78, v80, v78
	v_add_f32_e32 v80, -1.0, v77
	v_add_f32_e32 v79, 1.0, v80
	v_sub_f32_e32 v79, v77, v79
	v_add_f32_e32 v81, v78, v79
	v_add_f32_e32 v79, 1.0, v77
	v_add_f32_e32 v82, -1.0, v79
	v_sub_f32_e32 v77, v77, v82
	v_add_f32_e32 v77, v78, v77
	v_add_f32_e32 v87, v79, v77
	v_rcp_f32_e32 v88, v87
	v_sub_f32_e32 v78, v87, v79
	v_add_f32_e32 v79, v80, v81
	v_sub_f32_e32 v77, v77, v78
	v_mul_f32_e32 v90, v79, v88
	v_sub_f32_e32 v78, v79, v80
	v_mul_f32_e32 v80, v87, v90
	v_fma_f32 v82, v90, v87, -v80
	v_fmac_f32_e32 v82, v90, v77
	v_sub_f32_e32 v89, v81, v78
	v_add_f32_e32 v78, v80, v82
	v_sub_f32_e32 v81, v79, v78
	v_pk_add_f32 v[84:85], v[78:79], v[80:81] neg_lo:[0,1] neg_hi:[0,1]
	v_mov_b32_e32 v83, v78
	v_pk_add_f32 v[78:79], v[84:85], v[82:83] neg_lo:[0,1] neg_hi:[0,1]
	v_cmp_neq_f32_e32 vcc, s0, v76
	v_add_f32_e32 v79, v89, v79
	v_add_f32_e32 v78, v78, v79
	v_add_f32_e32 v79, v81, v78
	v_mul_f32_e32 v89, v88, v79
	v_mul_f32_e32 v80, v87, v89
	v_fma_f32 v82, v89, v87, -v80
	v_fmac_f32_e32 v82, v89, v77
	v_sub_f32_e32 v77, v81, v79
	v_add_f32_e32 v77, v78, v77
	v_add_f32_e32 v78, v80, v82
	v_sub_f32_e32 v81, v79, v78
	v_pk_add_f32 v[84:85], v[78:79], v[80:81] neg_lo:[0,1] neg_hi:[0,1]
	v_mov_b32_e32 v83, v78
	v_pk_add_f32 v[78:79], v[84:85], v[82:83] neg_lo:[0,1] neg_hi:[0,1]
	s_nop 0
	v_add_f32_e32 v77, v77, v79
	v_add_f32_e32 v77, v78, v77
	v_add_f32_e32 v79, v90, v89
	v_add_f32_e32 v77, v81, v77
	v_sub_f32_e32 v78, v79, v90
	v_mul_f32_e32 v77, v88, v77
	v_sub_f32_e32 v78, v89, v78
	v_add_f32_e32 v77, v78, v77
	v_add_f32_e32 v80, v79, v77
	v_mul_f32_e32 v82, v80, v80
	v_fmamk_f32 v78, v82, 0x3e9b6dac, v210
	v_fmaak_f32 v121, v82, v78, 0x3f2aaada
	v_cvt_f32_i32_e32 v78, v86
	v_sub_f32_e32 v79, v80, v79
	v_sub_f32_e32 v77, v77, v79
	v_mul_f32_e32 v79, v80, v82
	v_pk_mul_f32 v[82:83], v[78:79], v[120:121]
	v_ldexp_f32 v81, v80, 1
	v_fma_f32 v80, v78, s1, -v82
	v_fmac_f32_e32 v80, 0xb102e308, v78
	v_pk_add_f32 v[78:79], v[82:83], v[80:81]
	v_ldexp_f32 v77, v77, 1
	v_sub_f32_e32 v81, v79, v81
	v_sub_f32_e32 v81, v83, v81
	v_add_f32_e32 v85, v77, v81
	v_mov_b32_e32 v84, v82
	v_pk_add_f32 v[82:83], v[78:79], v[82:83] neg_lo:[0,1] neg_hi:[0,1]
	v_pk_add_f32 v[86:87], v[78:79], v[84:85]
	v_mov_b32_e32 v81, v78
	v_mov_b32_e32 v83, v87
	v_pk_add_f32 v[88:89], v[80:81], v[82:83] neg_lo:[0,1] neg_hi:[0,1]
	v_pk_add_f32 v[80:81], v[80:81], v[82:83]
	v_mov_b32_e32 v84, v85
	v_pk_add_f32 v[82:83], v[80:81], v[78:79] op_sel:[1,0] op_sel_hi:[0,1] neg_lo:[0,1] neg_hi:[0,1]
	v_pk_add_f32 v[90:91], v[86:87], v[82:83] op_sel_hi:[1,0] neg_lo:[0,1] neg_hi:[0,1]
	v_mov_b32_e32 v86, v87
	v_mov_b32_e32 v87, v81
	v_pk_mov_b32 v[82:83], v[78:79], v[82:83] op_sel:[1,0]
	v_mov_b32_e32 v85, v78
	v_pk_add_f32 v[82:83], v[86:87], v[82:83] neg_lo:[0,1] neg_hi:[0,1]
	v_mov_b32_e32 v90, v88
	v_pk_add_f32 v[78:79], v[84:85], v[82:83] neg_lo:[0,1] neg_hi:[0,1]
	v_mov_b32_e32 v89, v81
	v_pk_add_f32 v[82:83], v[90:91], v[78:79]
	s_nop 0
	v_pk_add_f32 v[84:85], v[82:83], v[82:83] op_sel:[0,1] op_sel_hi:[1,0]
	s_nop 0
	v_pk_add_f32 v[80:81], v[80:81], v[84:85] op_sel:[1,0] op_sel_hi:[0,1]
	v_mov_b32_e32 v83, v80
	v_pk_add_f32 v[86:87], v[82:83], v[88:89] neg_lo:[0,1] neg_hi:[0,1]
	v_mov_b32_e32 v79, v84
	v_sub_f32_e32 v77, v82, v86
	v_pk_add_f32 v[78:79], v[78:79], v[86:87] neg_lo:[0,1] neg_hi:[0,1]
	v_sub_f32_e32 v77, v88, v77
	v_add_f32_e32 v77, v78, v77
	v_add_f32_e32 v77, v77, v79
	v_add_f32_e32 v77, v80, v77
	v_cndmask_b32_e32 v77, v224, v77, vcc
	v_cmp_ngt_f32_e32 vcc, -1.0, v76
	s_nop 1
	v_cndmask_b32_e32 v77, v225, v77, vcc
	v_cmp_neq_f32_e32 vcc, -1.0, v76
	s_nop 1
	v_cndmask_b32_e32 v77, v226, v77, vcc
	v_cmp_lt_f32_e64 vcc, |v76|, s56
	s_nop 1
	v_cndmask_b32_e32 v76, v77, v76, vcc
	v_add_f32_e32 v75, v75, v76

.LBB0_1238:
	s_and_b64 vcc, exec, s[4:5]
	v_or_b32_e32 v69, 18, v74
	s_cbranch_vccnz .LBB0_1703
	s_andn2_b64 vcc, exec, s[36:37]
	v_mov_b32_e32 v75, v36
	s_cbranch_vccnz .LBB0_1241
	s_nop 0
	v_lshl_add_u64 v[76:77], v[66:67], 0, s[80:81]
	s_waitcnt lgkmcnt(0)
	v_lshl_add_u64 v[76:77], v[76:77], 2, vcc
	v_mov_b32_e32 v75, v251
	s_nop 0
	v_add_f32_e32 v76, v36, v75
	v_max_f32_e32 v75, 0, v76
	v_mul_f32_e64 v76, |v76|, s73
	v_exp_f32_e32 v76, v76
	s_nop 0
	v_add_f32_e32 v77, 1.0, v76
	v_add_f32_e32 v78, -1.0, v77
	v_sub_f32_e32 v79, v78, v77
	v_add_f32_e32 v79, 1.0, v79
	v_sub_f32_e32 v78, v76, v78
	v_add_f32_e32 v80, v78, v79
	v_frexp_mant_f32_e32 v78, v77
	v_cmp_gt_f32_e32 vcc, s46, v78
	v_cvt_f64_f32_e32 v[78:79], v77
	v_frexp_exp_i32_f64_e32 v78, v[78:79]
	v_subbrev_co_u32_e32 v86, vcc, 0, v78, vcc
	v_sub_u32_e32 v78, 0, v86
	v_ldexp_f32 v77, v77, v78
	v_ldexp_f32 v78, v80, v78
	v_add_f32_e32 v80, -1.0, v77
	v_add_f32_e32 v79, 1.0, v80
	v_sub_f32_e32 v79, v77, v79
	v_add_f32_e32 v81, v78, v79
	v_add_f32_e32 v79, 1.0, v77
	v_add_f32_e32 v82, -1.0, v79
	v_sub_f32_e32 v77, v77, v82
	v_add_f32_e32 v77, v78, v77
	v_add_f32_e32 v87, v79, v77
	v_rcp_f32_e32 v88, v87
	v_sub_f32_e32 v78, v87, v79
	v_add_f32_e32 v79, v80, v81
	v_sub_f32_e32 v77, v77, v78
	v_mul_f32_e32 v90, v79, v88
	v_sub_f32_e32 v78, v79, v80
	v_mul_f32_e32 v80, v87, v90
	v_fma_f32 v82, v90, v87, -v80
	v_fmac_f32_e32 v82, v90, v77
	v_sub_f32_e32 v89, v81, v78
	v_add_f32_e32 v78, v80, v82
	v_sub_f32_e32 v81, v79, v78
	v_pk_add_f32 v[84:85], v[78:79], v[80:81] neg_lo:[0,1] neg_hi:[0,1]
	v_mov_b32_e32 v83, v78
	v_pk_add_f32 v[78:79], v[84:85], v[82:83] neg_lo:[0,1] neg_hi:[0,1]
	v_cmp_neq_f32_e32 vcc, s0, v76
	v_add_f32_e32 v79, v89, v79
	v_add_f32_e32 v78, v78, v79
	v_add_f32_e32 v79, v81, v78
	v_mul_f32_e32 v89, v88, v79
	v_mul_f32_e32 v80, v87, v89
	v_fma_f32 v82, v89, v87, -v80
	v_fmac_f32_e32 v82, v89, v77
	v_sub_f32_e32 v77, v81, v79
	v_add_f32_e32 v77, v78, v77
	v_add_f32_e32 v78, v80, v82
	v_sub_f32_e32 v81, v79, v78
	v_pk_add_f32 v[84:85], v[78:79], v[80:81] neg_lo:[0,1] neg_hi:[0,1]
	v_mov_b32_e32 v83, v78
	v_pk_add_f32 v[78:79], v[84:85], v[82:83] neg_lo:[0,1] neg_hi:[0,1]
	s_nop 0
	v_add_f32_e32 v77, v77, v79
	v_add_f32_e32 v77, v78, v77
	v_add_f32_e32 v79, v90, v89
	v_add_f32_e32 v77, v81, v77
	v_sub_f32_e32 v78, v79, v90
	v_mul_f32_e32 v77, v88, v77
	v_sub_f32_e32 v78, v89, v78
	v_add_f32_e32 v77, v78, v77
	v_add_f32_e32 v80, v79, v77
	v_mul_f32_e32 v82, v80, v80
	v_fmamk_f32 v78, v82, 0x3e9b6dac, v210
	v_fmaak_f32 v121, v82, v78, 0x3f2aaada
	v_cvt_f32_i32_e32 v78, v86
	v_sub_f32_e32 v79, v80, v79
	v_sub_f32_e32 v77, v77, v79
	v_mul_f32_e32 v79, v80, v82
	v_pk_mul_f32 v[82:83], v[78:79], v[120:121]
	v_ldexp_f32 v81, v80, 1
	v_fma_f32 v80, v78, s1, -v82
	v_fmac_f32_e32 v80, 0xb102e308, v78
	v_pk_add_f32 v[78:79], v[82:83], v[80:81]
	v_ldexp_f32 v77, v77, 1
	v_sub_f32_e32 v81, v79, v81
	v_sub_f32_e32 v81, v83, v81
	v_add_f32_e32 v85, v77, v81
	v_mov_b32_e32 v84, v82
	v_pk_add_f32 v[82:83], v[78:79], v[82:83] neg_lo:[0,1] neg_hi:[0,1]
	v_pk_add_f32 v[86:87], v[78:79], v[84:85]
	v_mov_b32_e32 v81, v78
	v_mov_b32_e32 v83, v87
	v_pk_add_f32 v[88:89], v[80:81], v[82:83] neg_lo:[0,1] neg_hi:[0,1]
	v_pk_add_f32 v[80:81], v[80:81], v[82:83]
	v_mov_b32_e32 v84, v85
	v_pk_add_f32 v[82:83], v[80:81], v[78:79] op_sel:[1,0] op_sel_hi:[0,1] neg_lo:[0,1] neg_hi:[0,1]
	v_pk_add_f32 v[90:91], v[86:87], v[82:83] op_sel_hi:[1,0] neg_lo:[0,1] neg_hi:[0,1]
	v_mov_b32_e32 v86, v87
	v_mov_b32_e32 v87, v81
	v_pk_mov_b32 v[82:83], v[78:79], v[82:83] op_sel:[1,0]
	v_mov_b32_e32 v85, v78
	v_pk_add_f32 v[82:83], v[86:87], v[82:83] neg_lo:[0,1] neg_hi:[0,1]
	v_mov_b32_e32 v90, v88
	v_pk_add_f32 v[78:79], v[84:85], v[82:83] neg_lo:[0,1] neg_hi:[0,1]
	v_mov_b32_e32 v89, v81
	v_pk_add_f32 v[82:83], v[90:91], v[78:79]
	s_nop 0
	v_pk_add_f32 v[84:85], v[82:83], v[82:83] op_sel:[0,1] op_sel_hi:[1,0]
	s_nop 0
	v_pk_add_f32 v[80:81], v[80:81], v[84:85] op_sel:[1,0] op_sel_hi:[0,1]
	v_mov_b32_e32 v83, v80
	v_pk_add_f32 v[86:87], v[82:83], v[88:89] neg_lo:[0,1] neg_hi:[0,1]
	v_mov_b32_e32 v79, v84
	v_sub_f32_e32 v77, v82, v86
	v_pk_add_f32 v[78:79], v[78:79], v[86:87] neg_lo:[0,1] neg_hi:[0,1]
	v_sub_f32_e32 v77, v88, v77
	v_add_f32_e32 v77, v78, v77
	v_add_f32_e32 v77, v77, v79
	v_add_f32_e32 v77, v80, v77
	v_cndmask_b32_e32 v77, v224, v77, vcc
	v_cmp_ngt_f32_e32 vcc, -1.0, v76
	s_nop 1
	v_cndmask_b32_e32 v77, v225, v77, vcc
	v_cmp_neq_f32_e32 vcc, -1.0, v76
	s_nop 1
	v_cndmask_b32_e32 v77, v226, v77, vcc
	v_cmp_lt_f32_e64 vcc, |v76|, s56
	s_nop 1
	v_cndmask_b32_e32 v76, v77, v76, vcc
	v_add_f32_e32 v75, v75, v76

.LBB0_1243:
	s_and_b64 vcc, exec, s[4:5]
	v_or_b32_e32 v69, 19, v74
	s_cbranch_vccnz .LBB0_1704
	s_andn2_b64 vcc, exec, s[36:37]
	v_mov_b32_e32 v75, v37
	s_cbranch_vccnz .LBB0_1246
	s_nop 0
	v_lshl_add_u64 v[76:77], v[66:67], 0, s[80:81]
	s_waitcnt lgkmcnt(0)
	v_lshl_add_u64 v[76:77], v[76:77], 2, vcc
	v_mov_b32_e32 v75, v251
	s_nop 0
	v_add_f32_e32 v76, v37, v75
	v_max_f32_e32 v75, 0, v76
	v_mul_f32_e64 v76, |v76|, s73
	v_exp_f32_e32 v76, v76
	s_nop 0
	v_add_f32_e32 v77, 1.0, v76
	v_add_f32_e32 v78, -1.0, v77
	v_sub_f32_e32 v79, v78, v77
	v_add_f32_e32 v79, 1.0, v79
	v_sub_f32_e32 v78, v76, v78
	v_add_f32_e32 v80, v78, v79
	v_frexp_mant_f32_e32 v78, v77
	v_cmp_gt_f32_e32 vcc, s46, v78
	v_cvt_f64_f32_e32 v[78:79], v77
	v_frexp_exp_i32_f64_e32 v78, v[78:79]
	v_subbrev_co_u32_e32 v86, vcc, 0, v78, vcc
	v_sub_u32_e32 v78, 0, v86
	v_ldexp_f32 v77, v77, v78
	v_ldexp_f32 v78, v80, v78
	v_add_f32_e32 v80, -1.0, v77
	v_add_f32_e32 v79, 1.0, v80
	v_sub_f32_e32 v79, v77, v79
	v_add_f32_e32 v81, v78, v79
	v_add_f32_e32 v79, 1.0, v77
	v_add_f32_e32 v82, -1.0, v79
	v_sub_f32_e32 v77, v77, v82
	v_add_f32_e32 v77, v78, v77
	v_add_f32_e32 v87, v79, v77
	v_rcp_f32_e32 v88, v87
	v_sub_f32_e32 v78, v87, v79
	v_add_f32_e32 v79, v80, v81
	v_sub_f32_e32 v77, v77, v78
	v_mul_f32_e32 v90, v79, v88
	v_sub_f32_e32 v78, v79, v80
	v_mul_f32_e32 v80, v87, v90
	v_fma_f32 v82, v90, v87, -v80
	v_fmac_f32_e32 v82, v90, v77
	v_sub_f32_e32 v89, v81, v78
	v_add_f32_e32 v78, v80, v82
	v_sub_f32_e32 v81, v79, v78
	v_pk_add_f32 v[84:85], v[78:79], v[80:81] neg_lo:[0,1] neg_hi:[0,1]
	v_mov_b32_e32 v83, v78
	v_pk_add_f32 v[78:79], v[84:85], v[82:83] neg_lo:[0,1] neg_hi:[0,1]
	v_cmp_neq_f32_e32 vcc, s0, v76
	v_add_f32_e32 v79, v89, v79
	v_add_f32_e32 v78, v78, v79
	v_add_f32_e32 v79, v81, v78
	v_mul_f32_e32 v89, v88, v79
	v_mul_f32_e32 v80, v87, v89
	v_fma_f32 v82, v89, v87, -v80
	v_fmac_f32_e32 v82, v89, v77
	v_sub_f32_e32 v77, v81, v79
	v_add_f32_e32 v77, v78, v77
	v_add_f32_e32 v78, v80, v82
	v_sub_f32_e32 v81, v79, v78
	v_pk_add_f32 v[84:85], v[78:79], v[80:81] neg_lo:[0,1] neg_hi:[0,1]
	v_mov_b32_e32 v83, v78
	v_pk_add_f32 v[78:79], v[84:85], v[82:83] neg_lo:[0,1] neg_hi:[0,1]
	s_nop 0
	v_add_f32_e32 v77, v77, v79
	v_add_f32_e32 v77, v78, v77
	v_add_f32_e32 v79, v90, v89
	v_add_f32_e32 v77, v81, v77
	v_sub_f32_e32 v78, v79, v90
	v_mul_f32_e32 v77, v88, v77
	v_sub_f32_e32 v78, v89, v78
	v_add_f32_e32 v77, v78, v77
	v_add_f32_e32 v80, v79, v77
	v_mul_f32_e32 v82, v80, v80
	v_fmamk_f32 v78, v82, 0x3e9b6dac, v210
	v_fmaak_f32 v121, v82, v78, 0x3f2aaada
	v_cvt_f32_i32_e32 v78, v86
	v_sub_f32_e32 v79, v80, v79
	v_sub_f32_e32 v77, v77, v79
	v_mul_f32_e32 v79, v80, v82
	v_pk_mul_f32 v[82:83], v[78:79], v[120:121]
	v_ldexp_f32 v81, v80, 1
	v_fma_f32 v80, v78, s1, -v82
	v_fmac_f32_e32 v80, 0xb102e308, v78
	v_pk_add_f32 v[78:79], v[82:83], v[80:81]
	v_ldexp_f32 v77, v77, 1
	v_sub_f32_e32 v81, v79, v81
	v_sub_f32_e32 v81, v83, v81
	v_add_f32_e32 v85, v77, v81
	v_mov_b32_e32 v84, v82
	v_pk_add_f32 v[82:83], v[78:79], v[82:83] neg_lo:[0,1] neg_hi:[0,1]
	v_pk_add_f32 v[86:87], v[78:79], v[84:85]
	v_mov_b32_e32 v81, v78
	v_mov_b32_e32 v83, v87
	v_pk_add_f32 v[88:89], v[80:81], v[82:83] neg_lo:[0,1] neg_hi:[0,1]
	v_pk_add_f32 v[80:81], v[80:81], v[82:83]
	v_mov_b32_e32 v84, v85
	v_pk_add_f32 v[82:83], v[80:81], v[78:79] op_sel:[1,0] op_sel_hi:[0,1] neg_lo:[0,1] neg_hi:[0,1]
	v_pk_add_f32 v[90:91], v[86:87], v[82:83] op_sel_hi:[1,0] neg_lo:[0,1] neg_hi:[0,1]
	v_mov_b32_e32 v86, v87
	v_mov_b32_e32 v87, v81
	v_pk_mov_b32 v[82:83], v[78:79], v[82:83] op_sel:[1,0]
	v_mov_b32_e32 v85, v78
	v_pk_add_f32 v[82:83], v[86:87], v[82:83] neg_lo:[0,1] neg_hi:[0,1]
	v_mov_b32_e32 v90, v88
	v_pk_add_f32 v[78:79], v[84:85], v[82:83] neg_lo:[0,1] neg_hi:[0,1]
	v_mov_b32_e32 v89, v81
	v_pk_add_f32 v[82:83], v[90:91], v[78:79]
	s_nop 0
	v_pk_add_f32 v[84:85], v[82:83], v[82:83] op_sel:[0,1] op_sel_hi:[1,0]
	s_nop 0
	v_pk_add_f32 v[80:81], v[80:81], v[84:85] op_sel:[1,0] op_sel_hi:[0,1]
	v_mov_b32_e32 v83, v80
	v_pk_add_f32 v[86:87], v[82:83], v[88:89] neg_lo:[0,1] neg_hi:[0,1]
	v_mov_b32_e32 v79, v84
	v_sub_f32_e32 v77, v82, v86
	v_pk_add_f32 v[78:79], v[78:79], v[86:87] neg_lo:[0,1] neg_hi:[0,1]
	v_sub_f32_e32 v77, v88, v77
	v_add_f32_e32 v77, v78, v77
	v_add_f32_e32 v77, v77, v79
	v_add_f32_e32 v77, v80, v77
	v_cndmask_b32_e32 v77, v224, v77, vcc
	v_cmp_ngt_f32_e32 vcc, -1.0, v76
	s_nop 1
	v_cndmask_b32_e32 v77, v225, v77, vcc
	v_cmp_neq_f32_e32 vcc, -1.0, v76
	s_nop 1
	v_cndmask_b32_e32 v77, v226, v77, vcc
	v_cmp_lt_f32_e64 vcc, |v76|, s56
	s_nop 1
	v_cndmask_b32_e32 v76, v77, v76, vcc
	v_add_f32_e32 v75, v75, v76

.LBB0_1248:
	s_or_b64 exec, exec, s[58:59]
	v_or_b32_e32 v75, 32, v74
	s_and_saveexec_b64 s[58:59], s[6:7]
	s_cbranch_execz .LBB0_1269
	v_ashrrev_i32_e32 v69, 31, v68
	s_and_b64 vcc, exec, s[4:5]
	v_lshl_add_u64 v[70:71], v[66:67], 2, s[34:35]
	s_cbranch_vccnz .LBB0_1705
	s_andn2_b64 vcc, exec, s[36:37]
	v_mov_b32_e32 v72, v30
	s_cbranch_vccnz .LBB0_1252
	s_nop 0
	s_waitcnt lgkmcnt(0)
	v_lshl_add_u64 v[72:73], v[68:69], 2, vcc
	v_mov_b32_e32 v72, v248
	s_nop 0
	v_add_f32_e32 v73, v30, v72
	v_max_f32_e32 v72, 0, v73
	v_mul_f32_e64 v73, |v73|, s73
	v_exp_f32_e32 v73, v73
	s_nop 0
	v_add_f32_e32 v78, 1.0, v73
	v_add_f32_e32 v76, -1.0, v78
	v_sub_f32_e32 v77, v76, v78
	v_add_f32_e32 v77, 1.0, v77
	v_sub_f32_e32 v76, v73, v76
	v_add_f32_e32 v79, v76, v77
	v_frexp_mant_f32_e32 v76, v78
	v_cmp_gt_f32_e32 vcc, s46, v76
	v_cvt_f64_f32_e32 v[76:77], v78
	v_frexp_exp_i32_f64_e32 v76, v[76:77]
	v_subbrev_co_u32_e32 v84, vcc, 0, v76, vcc
	v_sub_u32_e32 v76, 0, v84
	v_ldexp_f32 v77, v78, v76
	v_add_f32_e32 v78, -1.0, v77
	v_add_f32_e32 v80, 1.0, v77
	v_ldexp_f32 v76, v79, v76
	v_add_f32_e32 v79, 1.0, v78
	v_add_f32_e32 v81, -1.0, v80
	v_sub_f32_e32 v79, v77, v79
	v_sub_f32_e32 v77, v77, v81
	v_add_f32_e32 v79, v76, v79
	v_add_f32_e32 v76, v76, v77
	v_add_f32_e32 v85, v80, v76
	v_rcp_f32_e32 v87, v85
	v_sub_f32_e32 v77, v85, v80
	v_sub_f32_e32 v86, v76, v77
	v_add_f32_e32 v77, v78, v79
	v_mul_f32_e32 v89, v77, v87
	v_sub_f32_e32 v76, v77, v78
	v_mul_f32_e32 v78, v85, v89
	v_fma_f32 v80, v89, v85, -v78
	v_fmac_f32_e32 v80, v89, v86
	v_sub_f32_e32 v88, v79, v76
	v_add_f32_e32 v76, v78, v80
	v_sub_f32_e32 v79, v77, v76
	v_pk_add_f32 v[82:83], v[76:77], v[78:79] neg_lo:[0,1] neg_hi:[0,1]
	v_mov_b32_e32 v81, v76
	v_pk_add_f32 v[76:77], v[82:83], v[80:81] neg_lo:[0,1] neg_hi:[0,1]
	v_cmp_neq_f32_e32 vcc, s0, v73
	v_add_f32_e32 v77, v88, v77
	v_add_f32_e32 v76, v76, v77
	v_add_f32_e32 v77, v79, v76
	v_mul_f32_e32 v88, v87, v77
	v_mul_f32_e32 v78, v85, v88
	v_fma_f32 v80, v88, v85, -v78
	v_fmac_f32_e32 v80, v88, v86
	v_sub_f32_e32 v79, v79, v77
	v_add_f32_e32 v85, v76, v79
	v_add_f32_e32 v76, v78, v80
	v_sub_f32_e32 v79, v77, v76
	v_pk_add_f32 v[82:83], v[76:77], v[78:79] neg_lo:[0,1] neg_hi:[0,1]
	v_mov_b32_e32 v81, v76
	v_pk_add_f32 v[76:77], v[82:83], v[80:81] neg_lo:[0,1] neg_hi:[0,1]
	s_nop 0
	v_add_f32_e32 v77, v85, v77
	v_add_f32_e32 v76, v76, v77
	v_add_f32_e32 v77, v89, v88
	v_add_f32_e32 v76, v79, v76
	v_sub_f32_e32 v78, v77, v89
	v_mul_f32_e32 v76, v87, v76
	v_sub_f32_e32 v78, v88, v78
	v_add_f32_e32 v78, v78, v76
	v_add_f32_e32 v80, v77, v78
	v_mul_f32_e32 v81, v80, v80
	v_fmamk_f32 v76, v81, 0x3e9b6dac, v210
	v_fmaak_f32 v121, v81, v76, 0x3f2aaada
	v_cvt_f32_i32_e32 v76, v84
	v_sub_f32_e32 v77, v80, v77
	v_sub_f32_e32 v77, v78, v77
	v_ldexp_f32 v82, v77, 1
	v_mul_f32_e32 v77, v80, v81
	v_ldexp_f32 v79, v80, 1
	v_pk_mul_f32 v[80:81], v[76:77], v[120:121]
	s_nop 0
	v_fma_f32 v78, v76, s1, -v80
	v_fmac_f32_e32 v78, 0xb102e308, v76
	v_pk_add_f32 v[76:77], v[80:81], v[78:79]
	s_nop 0
	v_sub_f32_e32 v79, v77, v79
	v_sub_f32_e32 v79, v81, v79
	v_add_f32_e32 v83, v82, v79
	v_mov_b32_e32 v82, v80
	v_pk_add_f32 v[80:81], v[76:77], v[80:81] neg_lo:[0,1] neg_hi:[0,1]
	v_pk_add_f32 v[84:85], v[76:77], v[82:83]
	v_mov_b32_e32 v79, v76
	v_mov_b32_e32 v81, v85
	v_pk_add_f32 v[86:87], v[78:79], v[80:81] neg_lo:[0,1] neg_hi:[0,1]
	v_pk_add_f32 v[78:79], v[78:79], v[80:81]
	v_mov_b32_e32 v82, v83
	v_pk_add_f32 v[80:81], v[78:79], v[76:77] op_sel:[1,0] op_sel_hi:[0,1] neg_lo:[0,1] neg_hi:[0,1]
	v_pk_add_f32 v[88:89], v[84:85], v[80:81] op_sel_hi:[1,0] neg_lo:[0,1] neg_hi:[0,1]
	v_mov_b32_e32 v84, v85
	v_mov_b32_e32 v85, v79
	v_pk_mov_b32 v[80:81], v[76:77], v[80:81] op_sel:[1,0]
	v_mov_b32_e32 v83, v76
	v_pk_add_f32 v[80:81], v[84:85], v[80:81] neg_lo:[0,1] neg_hi:[0,1]
	v_mov_b32_e32 v88, v86
	v_pk_add_f32 v[76:77], v[82:83], v[80:81] neg_lo:[0,1] neg_hi:[0,1]
	v_mov_b32_e32 v87, v79
	v_pk_add_f32 v[80:81], v[88:89], v[76:77]
	s_nop 0
	v_pk_add_f32 v[82:83], v[80:81], v[80:81] op_sel:[0,1] op_sel_hi:[1,0]
	s_nop 0
	v_pk_add_f32 v[78:79], v[78:79], v[82:83] op_sel:[1,0] op_sel_hi:[0,1]
	v_mov_b32_e32 v81, v78
	v_pk_add_f32 v[84:85], v[80:81], v[86:87] neg_lo:[0,1] neg_hi:[0,1]
	v_mov_b32_e32 v77, v82
	v_sub_f32_e32 v79, v80, v84
	v_pk_add_f32 v[76:77], v[76:77], v[84:85] neg_lo:[0,1] neg_hi:[0,1]
	v_sub_f32_e32 v79, v86, v79
	v_add_f32_e32 v76, v76, v79
	v_add_f32_e32 v76, v76, v77
	v_add_f32_e32 v76, v78, v76
	v_cndmask_b32_e32 v76, v224, v76, vcc
	v_cmp_ngt_f32_e32 vcc, -1.0, v73
	s_nop 1
	v_cndmask_b32_e32 v76, v225, v76, vcc
	v_cmp_neq_f32_e32 vcc, -1.0, v73
	s_nop 1
	v_cndmask_b32_e32 v76, v226, v76, vcc
	v_cmp_lt_f32_e64 vcc, |v73|, s56
	s_nop 1
	v_cndmask_b32_e32 v73, v76, v73, vcc
	v_add_f32_e32 v72, v72, v73

.LBB0_1254:
	s_and_b64 vcc, exec, s[4:5]
	v_or_b32_e32 v76, 33, v74
	s_cbranch_vccnz .LBB0_1706
	s_andn2_b64 vcc, exec, s[36:37]
	v_mov_b32_e32 v77, v31
	s_cbranch_vccnz .LBB0_1257
	s_nop 0
	s_waitcnt vmcnt(4) lgkmcnt(0)
	v_lshl_add_u64 v[78:79], v[68:69], 2, vcc
	v_mov_b32_e32 v77, v248
	s_nop 0
	v_add_f32_e32 v78, v31, v77
	v_max_f32_e32 v77, 0, v78
	v_mul_f32_e64 v78, |v78|, s73
	v_exp_f32_e32 v78, v78
	s_nop 0
	v_add_f32_e32 v79, 1.0, v78
	v_add_f32_e32 v80, -1.0, v79
	v_sub_f32_e32 v81, v80, v79
	v_add_f32_e32 v81, 1.0, v81
	v_sub_f32_e32 v80, v78, v80
	v_add_f32_e32 v82, v80, v81
	v_frexp_mant_f32_e32 v80, v79
	v_cmp_gt_f32_e32 vcc, s46, v80
	v_cvt_f64_f32_e32 v[80:81], v79
	v_frexp_exp_i32_f64_e32 v80, v[80:81]
	v_subbrev_co_u32_e32 v88, vcc, 0, v80, vcc
	v_sub_u32_e32 v80, 0, v88
	v_ldexp_f32 v79, v79, v80
	v_ldexp_f32 v80, v82, v80
	v_add_f32_e32 v82, -1.0, v79
	v_add_f32_e32 v81, 1.0, v82
	v_sub_f32_e32 v81, v79, v81
	v_add_f32_e32 v83, v80, v81
	v_add_f32_e32 v81, 1.0, v79
	v_add_f32_e32 v84, -1.0, v81
	v_sub_f32_e32 v79, v79, v84
	v_add_f32_e32 v79, v80, v79
	v_add_f32_e32 v89, v81, v79
	v_rcp_f32_e32 v90, v89
	v_sub_f32_e32 v80, v89, v81
	v_add_f32_e32 v81, v82, v83
	v_sub_f32_e32 v79, v79, v80
	v_mul_f32_e32 v92, v81, v90
	v_sub_f32_e32 v80, v81, v82
	v_mul_f32_e32 v82, v89, v92
	v_fma_f32 v84, v92, v89, -v82
	v_fmac_f32_e32 v84, v92, v79
	v_sub_f32_e32 v91, v83, v80
	v_add_f32_e32 v80, v82, v84
	v_sub_f32_e32 v83, v81, v80
	v_pk_add_f32 v[86:87], v[80:81], v[82:83] neg_lo:[0,1] neg_hi:[0,1]
	v_mov_b32_e32 v85, v80
	v_pk_add_f32 v[80:81], v[86:87], v[84:85] neg_lo:[0,1] neg_hi:[0,1]
	v_cmp_neq_f32_e32 vcc, s0, v78
	v_add_f32_e32 v81, v91, v81
	v_add_f32_e32 v80, v80, v81
	v_add_f32_e32 v81, v83, v80
	v_mul_f32_e32 v91, v90, v81
	v_mul_f32_e32 v82, v89, v91
	v_fma_f32 v84, v91, v89, -v82
	v_fmac_f32_e32 v84, v91, v79
	v_sub_f32_e32 v79, v83, v81
	v_add_f32_e32 v79, v80, v79
	v_add_f32_e32 v80, v82, v84
	v_sub_f32_e32 v83, v81, v80
	v_pk_add_f32 v[86:87], v[80:81], v[82:83] neg_lo:[0,1] neg_hi:[0,1]
	v_mov_b32_e32 v85, v80
	v_pk_add_f32 v[80:81], v[86:87], v[84:85] neg_lo:[0,1] neg_hi:[0,1]
	s_nop 0
	v_add_f32_e32 v79, v79, v81
	v_add_f32_e32 v79, v80, v79
	v_add_f32_e32 v81, v92, v91
	v_add_f32_e32 v79, v83, v79
	v_sub_f32_e32 v80, v81, v92
	v_mul_f32_e32 v79, v90, v79
	v_sub_f32_e32 v80, v91, v80
	v_add_f32_e32 v79, v80, v79
	v_add_f32_e32 v82, v81, v79
	v_mul_f32_e32 v84, v82, v82
	v_fmamk_f32 v80, v84, 0x3e9b6dac, v210
	v_fmaak_f32 v121, v84, v80, 0x3f2aaada
	v_cvt_f32_i32_e32 v80, v88
	v_sub_f32_e32 v81, v82, v81
	v_sub_f32_e32 v79, v79, v81
	v_mul_f32_e32 v81, v82, v84
	v_pk_mul_f32 v[84:85], v[80:81], v[120:121]
	v_ldexp_f32 v83, v82, 1
	v_fma_f32 v82, v80, s1, -v84
	v_fmac_f32_e32 v82, 0xb102e308, v80
	v_pk_add_f32 v[80:81], v[84:85], v[82:83]
	v_ldexp_f32 v79, v79, 1
	v_sub_f32_e32 v83, v81, v83
	v_sub_f32_e32 v83, v85, v83
	v_add_f32_e32 v87, v79, v83
	v_mov_b32_e32 v86, v84
	v_pk_add_f32 v[84:85], v[80:81], v[84:85] neg_lo:[0,1] neg_hi:[0,1]
	v_pk_add_f32 v[88:89], v[80:81], v[86:87]
	v_mov_b32_e32 v83, v80
	v_mov_b32_e32 v85, v89
	v_pk_add_f32 v[90:91], v[82:83], v[84:85] neg_lo:[0,1] neg_hi:[0,1]
	v_pk_add_f32 v[82:83], v[82:83], v[84:85]
	v_mov_b32_e32 v86, v87
	v_pk_add_f32 v[84:85], v[82:83], v[80:81] op_sel:[1,0] op_sel_hi:[0,1] neg_lo:[0,1] neg_hi:[0,1]
	v_pk_add_f32 v[92:93], v[88:89], v[84:85] op_sel_hi:[1,0] neg_lo:[0,1] neg_hi:[0,1]
	v_mov_b32_e32 v88, v89
	v_mov_b32_e32 v89, v83
	v_pk_mov_b32 v[84:85], v[80:81], v[84:85] op_sel:[1,0]
	v_mov_b32_e32 v87, v80
	v_pk_add_f32 v[84:85], v[88:89], v[84:85] neg_lo:[0,1] neg_hi:[0,1]
	v_mov_b32_e32 v92, v90
	v_pk_add_f32 v[80:81], v[86:87], v[84:85] neg_lo:[0,1] neg_hi:[0,1]
	v_mov_b32_e32 v91, v83
	v_pk_add_f32 v[84:85], v[92:93], v[80:81]
	s_nop 0
	v_pk_add_f32 v[86:87], v[84:85], v[84:85] op_sel:[0,1] op_sel_hi:[1,0]
	s_nop 0
	v_pk_add_f32 v[82:83], v[82:83], v[86:87] op_sel:[1,0] op_sel_hi:[0,1]
	v_mov_b32_e32 v85, v82
	v_pk_add_f32 v[88:89], v[84:85], v[90:91] neg_lo:[0,1] neg_hi:[0,1]
	v_mov_b32_e32 v81, v86
	v_sub_f32_e32 v79, v84, v88
	v_pk_add_f32 v[80:81], v[80:81], v[88:89] neg_lo:[0,1] neg_hi:[0,1]
	v_sub_f32_e32 v79, v90, v79
	v_add_f32_e32 v79, v80, v79
	v_add_f32_e32 v79, v79, v81
	v_add_f32_e32 v79, v82, v79
	v_cndmask_b32_e32 v79, v224, v79, vcc
	v_cmp_ngt_f32_e32 vcc, -1.0, v78
	s_nop 1
	v_cndmask_b32_e32 v79, v225, v79, vcc
	v_cmp_neq_f32_e32 vcc, -1.0, v78
	s_nop 1
	v_cndmask_b32_e32 v79, v226, v79, vcc
	v_cmp_lt_f32_e64 vcc, |v78|, s56
	s_nop 1
	v_cndmask_b32_e32 v78, v79, v78, vcc
	v_add_f32_e32 v77, v77, v78

.LBB0_1259:
	s_and_b64 vcc, exec, s[4:5]
	v_or_b32_e32 v76, 34, v74
	s_cbranch_vccnz .LBB0_1707
	s_andn2_b64 vcc, exec, s[36:37]
	v_mov_b32_e32 v77, v32
	s_cbranch_vccnz .LBB0_1262
	s_nop 0
	s_waitcnt vmcnt(4) lgkmcnt(0)
	v_lshl_add_u64 v[78:79], v[68:69], 2, vcc
	v_mov_b32_e32 v77, v248
	s_nop 0
	v_add_f32_e32 v78, v32, v77
	v_max_f32_e32 v77, 0, v78
	v_mul_f32_e64 v78, |v78|, s73
	v_exp_f32_e32 v78, v78
	s_nop 0
	v_add_f32_e32 v79, 1.0, v78
	v_add_f32_e32 v80, -1.0, v79
	v_sub_f32_e32 v81, v80, v79
	v_add_f32_e32 v81, 1.0, v81
	v_sub_f32_e32 v80, v78, v80
	v_add_f32_e32 v82, v80, v81
	v_frexp_mant_f32_e32 v80, v79
	v_cmp_gt_f32_e32 vcc, s46, v80
	v_cvt_f64_f32_e32 v[80:81], v79
	v_frexp_exp_i32_f64_e32 v80, v[80:81]
	v_subbrev_co_u32_e32 v88, vcc, 0, v80, vcc
	v_sub_u32_e32 v80, 0, v88
	v_ldexp_f32 v79, v79, v80
	v_ldexp_f32 v80, v82, v80
	v_add_f32_e32 v82, -1.0, v79
	v_add_f32_e32 v81, 1.0, v82
	v_sub_f32_e32 v81, v79, v81
	v_add_f32_e32 v83, v80, v81
	v_add_f32_e32 v81, 1.0, v79
	v_add_f32_e32 v84, -1.0, v81
	v_sub_f32_e32 v79, v79, v84
	v_add_f32_e32 v79, v80, v79
	v_add_f32_e32 v89, v81, v79
	v_rcp_f32_e32 v90, v89
	v_sub_f32_e32 v80, v89, v81
	v_add_f32_e32 v81, v82, v83
	v_sub_f32_e32 v79, v79, v80
	v_mul_f32_e32 v92, v81, v90
	v_sub_f32_e32 v80, v81, v82
	v_mul_f32_e32 v82, v89, v92
	v_fma_f32 v84, v92, v89, -v82
	v_fmac_f32_e32 v84, v92, v79
	v_sub_f32_e32 v91, v83, v80
	v_add_f32_e32 v80, v82, v84
	v_sub_f32_e32 v83, v81, v80
	v_pk_add_f32 v[86:87], v[80:81], v[82:83] neg_lo:[0,1] neg_hi:[0,1]
	v_mov_b32_e32 v85, v80
	v_pk_add_f32 v[80:81], v[86:87], v[84:85] neg_lo:[0,1] neg_hi:[0,1]
	v_cmp_neq_f32_e32 vcc, s0, v78
	v_add_f32_e32 v81, v91, v81
	v_add_f32_e32 v80, v80, v81
	v_add_f32_e32 v81, v83, v80
	v_mul_f32_e32 v91, v90, v81
	v_mul_f32_e32 v82, v89, v91
	v_fma_f32 v84, v91, v89, -v82
	v_fmac_f32_e32 v84, v91, v79
	v_sub_f32_e32 v79, v83, v81
	v_add_f32_e32 v79, v80, v79
	v_add_f32_e32 v80, v82, v84
	v_sub_f32_e32 v83, v81, v80
	v_pk_add_f32 v[86:87], v[80:81], v[82:83] neg_lo:[0,1] neg_hi:[0,1]
	v_mov_b32_e32 v85, v80
	v_pk_add_f32 v[80:81], v[86:87], v[84:85] neg_lo:[0,1] neg_hi:[0,1]
	s_nop 0
	v_add_f32_e32 v79, v79, v81
	v_add_f32_e32 v79, v80, v79
	v_add_f32_e32 v81, v92, v91
	v_add_f32_e32 v79, v83, v79
	v_sub_f32_e32 v80, v81, v92
	v_mul_f32_e32 v79, v90, v79
	v_sub_f32_e32 v80, v91, v80
	v_add_f32_e32 v79, v80, v79
	v_add_f32_e32 v82, v81, v79
	v_mul_f32_e32 v84, v82, v82
	v_fmamk_f32 v80, v84, 0x3e9b6dac, v210
	v_fmaak_f32 v121, v84, v80, 0x3f2aaada
	v_cvt_f32_i32_e32 v80, v88
	v_sub_f32_e32 v81, v82, v81
	v_sub_f32_e32 v79, v79, v81
	v_mul_f32_e32 v81, v82, v84
	v_pk_mul_f32 v[84:85], v[80:81], v[120:121]
	v_ldexp_f32 v83, v82, 1
	v_fma_f32 v82, v80, s1, -v84
	v_fmac_f32_e32 v82, 0xb102e308, v80
	v_pk_add_f32 v[80:81], v[84:85], v[82:83]
	v_ldexp_f32 v79, v79, 1
	v_sub_f32_e32 v83, v81, v83
	v_sub_f32_e32 v83, v85, v83
	v_add_f32_e32 v87, v79, v83
	v_mov_b32_e32 v86, v84
	v_pk_add_f32 v[84:85], v[80:81], v[84:85] neg_lo:[0,1] neg_hi:[0,1]
	v_pk_add_f32 v[88:89], v[80:81], v[86:87]
	v_mov_b32_e32 v83, v80
	v_mov_b32_e32 v85, v89
	v_pk_add_f32 v[90:91], v[82:83], v[84:85] neg_lo:[0,1] neg_hi:[0,1]
	v_pk_add_f32 v[82:83], v[82:83], v[84:85]
	v_mov_b32_e32 v86, v87
	v_pk_add_f32 v[84:85], v[82:83], v[80:81] op_sel:[1,0] op_sel_hi:[0,1] neg_lo:[0,1] neg_hi:[0,1]
	v_pk_add_f32 v[92:93], v[88:89], v[84:85] op_sel_hi:[1,0] neg_lo:[0,1] neg_hi:[0,1]
	v_mov_b32_e32 v88, v89
	v_mov_b32_e32 v89, v83
	v_pk_mov_b32 v[84:85], v[80:81], v[84:85] op_sel:[1,0]
	v_mov_b32_e32 v87, v80
	v_pk_add_f32 v[84:85], v[88:89], v[84:85] neg_lo:[0,1] neg_hi:[0,1]
	v_mov_b32_e32 v92, v90
	v_pk_add_f32 v[80:81], v[86:87], v[84:85] neg_lo:[0,1] neg_hi:[0,1]
	v_mov_b32_e32 v91, v83
	v_pk_add_f32 v[84:85], v[92:93], v[80:81]
	s_nop 0
	v_pk_add_f32 v[86:87], v[84:85], v[84:85] op_sel:[0,1] op_sel_hi:[1,0]
	s_nop 0
	v_pk_add_f32 v[82:83], v[82:83], v[86:87] op_sel:[1,0] op_sel_hi:[0,1]
	v_mov_b32_e32 v85, v82
	v_pk_add_f32 v[88:89], v[84:85], v[90:91] neg_lo:[0,1] neg_hi:[0,1]
	v_mov_b32_e32 v81, v86
	v_sub_f32_e32 v79, v84, v88
	v_pk_add_f32 v[80:81], v[80:81], v[88:89] neg_lo:[0,1] neg_hi:[0,1]
	v_sub_f32_e32 v79, v90, v79
	v_add_f32_e32 v79, v80, v79
	v_add_f32_e32 v79, v79, v81
	v_add_f32_e32 v79, v82, v79
	v_cndmask_b32_e32 v79, v224, v79, vcc
	v_cmp_ngt_f32_e32 vcc, -1.0, v78
	s_nop 1
	v_cndmask_b32_e32 v79, v225, v79, vcc
	v_cmp_neq_f32_e32 vcc, -1.0, v78
	s_nop 1
	v_cndmask_b32_e32 v79, v226, v79, vcc
	v_cmp_lt_f32_e64 vcc, |v78|, s56
	s_nop 1
	v_cndmask_b32_e32 v78, v79, v78, vcc
	v_add_f32_e32 v77, v77, v78

.LBB0_1264:
	s_and_b64 vcc, exec, s[4:5]
	v_or_b32_e32 v76, 35, v74
	s_cbranch_vccnz .LBB0_1708
	s_andn2_b64 vcc, exec, s[36:37]
	v_mov_b32_e32 v77, v33
	s_cbranch_vccnz .LBB0_1267
	s_nop 0
	s_waitcnt vmcnt(4) lgkmcnt(0)
	v_lshl_add_u64 v[78:79], v[68:69], 2, vcc
	v_mov_b32_e32 v69, v248
	s_nop 0
	v_add_f32_e32 v77, v33, v69
	v_max_f32_e32 v69, 0, v77
	v_mul_f32_e64 v77, |v77|, s73
	v_exp_f32_e32 v77, v77
	s_nop 0
	v_add_f32_e32 v80, 1.0, v77
	v_add_f32_e32 v78, -1.0, v80
	v_sub_f32_e32 v79, v78, v80
	v_add_f32_e32 v79, 1.0, v79
	v_sub_f32_e32 v78, v77, v78
	v_add_f32_e32 v81, v78, v79
	v_frexp_mant_f32_e32 v78, v80
	v_cmp_gt_f32_e32 vcc, s46, v78
	v_cvt_f64_f32_e32 v[78:79], v80
	v_frexp_exp_i32_f64_e32 v78, v[78:79]
	v_subbrev_co_u32_e32 v86, vcc, 0, v78, vcc
	v_sub_u32_e32 v78, 0, v86
	v_ldexp_f32 v79, v80, v78
	v_add_f32_e32 v80, -1.0, v79
	v_add_f32_e32 v82, 1.0, v79
	v_ldexp_f32 v78, v81, v78
	v_add_f32_e32 v81, 1.0, v80
	v_add_f32_e32 v83, -1.0, v82
	v_sub_f32_e32 v81, v79, v81
	v_sub_f32_e32 v79, v79, v83
	v_add_f32_e32 v81, v78, v81
	v_add_f32_e32 v78, v78, v79
	v_add_f32_e32 v87, v82, v78
	v_rcp_f32_e32 v89, v87
	v_sub_f32_e32 v79, v87, v82
	v_sub_f32_e32 v88, v78, v79
	v_add_f32_e32 v79, v80, v81
	v_mul_f32_e32 v91, v79, v89
	v_sub_f32_e32 v78, v79, v80
	v_mul_f32_e32 v80, v87, v91
	v_fma_f32 v82, v91, v87, -v80
	v_fmac_f32_e32 v82, v91, v88
	v_sub_f32_e32 v90, v81, v78
	v_add_f32_e32 v78, v80, v82
	v_sub_f32_e32 v81, v79, v78
	v_pk_add_f32 v[84:85], v[78:79], v[80:81] neg_lo:[0,1] neg_hi:[0,1]
	v_mov_b32_e32 v83, v78
	v_pk_add_f32 v[78:79], v[84:85], v[82:83] neg_lo:[0,1] neg_hi:[0,1]
	v_cmp_neq_f32_e32 vcc, s0, v77
	v_add_f32_e32 v79, v90, v79
	v_add_f32_e32 v78, v78, v79
	v_add_f32_e32 v79, v81, v78
	v_mul_f32_e32 v90, v89, v79
	v_mul_f32_e32 v80, v87, v90
	v_fma_f32 v82, v90, v87, -v80
	v_fmac_f32_e32 v82, v90, v88
	v_sub_f32_e32 v81, v81, v79
	v_add_f32_e32 v87, v78, v81
	v_add_f32_e32 v78, v80, v82
	v_sub_f32_e32 v81, v79, v78
	v_pk_add_f32 v[84:85], v[78:79], v[80:81] neg_lo:[0,1] neg_hi:[0,1]
	v_mov_b32_e32 v83, v78
	v_pk_add_f32 v[78:79], v[84:85], v[82:83] neg_lo:[0,1] neg_hi:[0,1]
	s_nop 0
	v_add_f32_e32 v79, v87, v79
	v_add_f32_e32 v78, v78, v79
	v_add_f32_e32 v79, v91, v90
	v_add_f32_e32 v78, v81, v78
	v_sub_f32_e32 v80, v79, v91
	v_mul_f32_e32 v78, v89, v78
	v_sub_f32_e32 v80, v90, v80
	v_add_f32_e32 v80, v80, v78
	v_add_f32_e32 v82, v79, v80
	v_mul_f32_e32 v83, v82, v82
	v_fmamk_f32 v78, v83, 0x3e9b6dac, v210
	v_fmaak_f32 v121, v83, v78, 0x3f2aaada
	v_cvt_f32_i32_e32 v78, v86
	v_sub_f32_e32 v79, v82, v79
	v_sub_f32_e32 v79, v80, v79
	v_ldexp_f32 v84, v79, 1
	v_mul_f32_e32 v79, v82, v83
	v_ldexp_f32 v81, v82, 1
	v_pk_mul_f32 v[82:83], v[78:79], v[120:121]
	s_nop 0
	v_fma_f32 v80, v78, s1, -v82
	v_fmac_f32_e32 v80, 0xb102e308, v78
	v_pk_add_f32 v[78:79], v[82:83], v[80:81]
	s_nop 0
	v_sub_f32_e32 v81, v79, v81
	v_sub_f32_e32 v81, v83, v81
	v_add_f32_e32 v85, v84, v81
	v_mov_b32_e32 v84, v82
	v_pk_add_f32 v[82:83], v[78:79], v[82:83] neg_lo:[0,1] neg_hi:[0,1]
	v_pk_add_f32 v[86:87], v[78:79], v[84:85]
	v_mov_b32_e32 v81, v78
	v_mov_b32_e32 v83, v87
	v_pk_add_f32 v[88:89], v[80:81], v[82:83] neg_lo:[0,1] neg_hi:[0,1]
	v_pk_add_f32 v[80:81], v[80:81], v[82:83]
	v_mov_b32_e32 v84, v85
	v_pk_add_f32 v[82:83], v[80:81], v[78:79] op_sel:[1,0] op_sel_hi:[0,1] neg_lo:[0,1] neg_hi:[0,1]
	v_pk_add_f32 v[90:91], v[86:87], v[82:83] op_sel_hi:[1,0] neg_lo:[0,1] neg_hi:[0,1]
	v_mov_b32_e32 v86, v87
	v_mov_b32_e32 v87, v81
	v_pk_mov_b32 v[82:83], v[78:79], v[82:83] op_sel:[1,0]
	v_mov_b32_e32 v85, v78
	v_pk_add_f32 v[82:83], v[86:87], v[82:83] neg_lo:[0,1] neg_hi:[0,1]
	v_mov_b32_e32 v90, v88
	v_pk_add_f32 v[78:79], v[84:85], v[82:83] neg_lo:[0,1] neg_hi:[0,1]
	v_mov_b32_e32 v89, v81
	v_pk_add_f32 v[82:83], v[90:91], v[78:79]
	s_nop 0
	v_pk_add_f32 v[84:85], v[82:83], v[82:83] op_sel:[0,1] op_sel_hi:[1,0]
	s_nop 0
	v_pk_add_f32 v[80:81], v[80:81], v[84:85] op_sel:[1,0] op_sel_hi:[0,1]
	v_mov_b32_e32 v83, v80
	v_pk_add_f32 v[86:87], v[82:83], v[88:89] neg_lo:[0,1] neg_hi:[0,1]
	v_mov_b32_e32 v79, v84
	v_sub_f32_e32 v81, v82, v86
	v_pk_add_f32 v[78:79], v[78:79], v[86:87] neg_lo:[0,1] neg_hi:[0,1]
	v_sub_f32_e32 v81, v88, v81
	v_add_f32_e32 v78, v78, v81
	v_add_f32_e32 v78, v78, v79
	v_add_f32_e32 v78, v80, v78
	v_cndmask_b32_e32 v78, v224, v78, vcc
	v_cmp_ngt_f32_e32 vcc, -1.0, v77
	s_nop 1
	v_cndmask_b32_e32 v78, v225, v78, vcc
	v_cmp_neq_f32_e32 vcc, -1.0, v77
	s_nop 1
	v_cndmask_b32_e32 v78, v226, v78, vcc
	v_cmp_lt_f32_e64 vcc, |v77|, s56
	s_nop 1
	v_cndmask_b32_e32 v77, v78, v77, vcc
	v_add_f32_e32 v77, v69, v77

.LBB0_1269:
	s_or_b64 exec, exec, s[58:59]
	s_and_saveexec_b64 s[58:59], s[8:9]
	s_cbranch_execz .LBB0_1290
	s_and_b64 vcc, exec, s[4:5]
	v_lshl_add_u64 v[70:71], v[66:67], 2, s[34:35]
	s_cbranch_vccnz .LBB0_1709
	s_andn2_b64 vcc, exec, s[36:37]
	v_mov_b32_e32 v69, v26
	s_cbranch_vccnz .LBB0_1273
	s_nop 0
	v_lshl_add_u64 v[72:73], v[66:67], 0, s[80:81]
	s_waitcnt lgkmcnt(0)
	v_lshl_add_u64 v[72:73], v[72:73], 2, vcc
	v_mov_b32_e32 v69, v249
	s_nop 0
	v_add_f32_e32 v72, v26, v69
	v_max_f32_e32 v69, 0, v72
	v_mul_f32_e64 v72, |v72|, s73
	v_exp_f32_e32 v72, v72
	s_nop 0
	v_add_f32_e32 v73, 1.0, v72
	v_add_f32_e32 v76, -1.0, v73
	v_sub_f32_e32 v77, v76, v73
	v_add_f32_e32 v77, 1.0, v77
	v_sub_f32_e32 v76, v72, v76
	v_add_f32_e32 v78, v76, v77
	v_frexp_mant_f32_e32 v76, v73
	v_cmp_gt_f32_e32 vcc, s46, v76
	v_cvt_f64_f32_e32 v[76:77], v73
	v_frexp_exp_i32_f64_e32 v76, v[76:77]
	v_subbrev_co_u32_e32 v84, vcc, 0, v76, vcc
	v_sub_u32_e32 v76, 0, v84
	v_ldexp_f32 v73, v73, v76
	v_ldexp_f32 v76, v78, v76
	v_add_f32_e32 v78, -1.0, v73
	v_add_f32_e32 v77, 1.0, v78
	v_sub_f32_e32 v77, v73, v77
	v_add_f32_e32 v79, v76, v77
	v_add_f32_e32 v77, 1.0, v73
	v_add_f32_e32 v80, -1.0, v77
	v_sub_f32_e32 v73, v73, v80
	v_add_f32_e32 v73, v76, v73
	v_add_f32_e32 v85, v77, v73
	v_rcp_f32_e32 v86, v85
	v_sub_f32_e32 v76, v85, v77
	v_add_f32_e32 v77, v78, v79
	v_sub_f32_e32 v73, v73, v76
	v_mul_f32_e32 v88, v77, v86
	v_sub_f32_e32 v76, v77, v78
	v_mul_f32_e32 v78, v85, v88
	v_fma_f32 v80, v88, v85, -v78
	v_fmac_f32_e32 v80, v88, v73
	v_sub_f32_e32 v87, v79, v76
	v_add_f32_e32 v76, v78, v80
	v_sub_f32_e32 v79, v77, v76
	v_pk_add_f32 v[82:83], v[76:77], v[78:79] neg_lo:[0,1] neg_hi:[0,1]
	v_mov_b32_e32 v81, v76
	v_pk_add_f32 v[76:77], v[82:83], v[80:81] neg_lo:[0,1] neg_hi:[0,1]
	v_cmp_neq_f32_e32 vcc, s0, v72
	v_add_f32_e32 v77, v87, v77
	v_add_f32_e32 v76, v76, v77
	v_add_f32_e32 v77, v79, v76
	v_mul_f32_e32 v87, v86, v77
	v_mul_f32_e32 v78, v85, v87
	v_fma_f32 v80, v87, v85, -v78
	v_fmac_f32_e32 v80, v87, v73
	v_sub_f32_e32 v73, v79, v77
	v_add_f32_e32 v73, v76, v73
	v_add_f32_e32 v76, v78, v80
	v_sub_f32_e32 v79, v77, v76
	v_pk_add_f32 v[82:83], v[76:77], v[78:79] neg_lo:[0,1] neg_hi:[0,1]
	v_mov_b32_e32 v81, v76
	v_pk_add_f32 v[76:77], v[82:83], v[80:81] neg_lo:[0,1] neg_hi:[0,1]
	s_nop 0
	v_add_f32_e32 v73, v73, v77
	v_add_f32_e32 v73, v76, v73
	v_add_f32_e32 v77, v88, v87
	v_add_f32_e32 v73, v79, v73
	v_sub_f32_e32 v76, v77, v88
	v_mul_f32_e32 v73, v86, v73
	v_sub_f32_e32 v76, v87, v76
	v_add_f32_e32 v73, v76, v73
	v_add_f32_e32 v78, v77, v73
	v_mul_f32_e32 v80, v78, v78
	v_fmamk_f32 v76, v80, 0x3e9b6dac, v210
	v_fmaak_f32 v121, v80, v76, 0x3f2aaada
	v_cvt_f32_i32_e32 v76, v84
	v_sub_f32_e32 v77, v78, v77
	v_sub_f32_e32 v73, v73, v77
	v_mul_f32_e32 v77, v78, v80
	v_pk_mul_f32 v[80:81], v[76:77], v[120:121]
	v_ldexp_f32 v79, v78, 1
	v_fma_f32 v78, v76, s1, -v80
	v_fmac_f32_e32 v78, 0xb102e308, v76
	v_pk_add_f32 v[76:77], v[80:81], v[78:79]
	v_ldexp_f32 v73, v73, 1
	v_sub_f32_e32 v79, v77, v79
	v_sub_f32_e32 v79, v81, v79
	v_add_f32_e32 v83, v73, v79
	v_mov_b32_e32 v82, v80
	v_pk_add_f32 v[80:81], v[76:77], v[80:81] neg_lo:[0,1] neg_hi:[0,1]
	v_pk_add_f32 v[84:85], v[76:77], v[82:83]
	v_mov_b32_e32 v79, v76
	v_mov_b32_e32 v81, v85
	v_pk_add_f32 v[86:87], v[78:79], v[80:81] neg_lo:[0,1] neg_hi:[0,1]
	v_pk_add_f32 v[78:79], v[78:79], v[80:81]
	v_mov_b32_e32 v82, v83
	v_pk_add_f32 v[80:81], v[78:79], v[76:77] op_sel:[1,0] op_sel_hi:[0,1] neg_lo:[0,1] neg_hi:[0,1]
	v_pk_add_f32 v[88:89], v[84:85], v[80:81] op_sel_hi:[1,0] neg_lo:[0,1] neg_hi:[0,1]
	v_mov_b32_e32 v84, v85
	v_mov_b32_e32 v85, v79
	v_pk_mov_b32 v[80:81], v[76:77], v[80:81] op_sel:[1,0]
	v_mov_b32_e32 v83, v76
	v_pk_add_f32 v[80:81], v[84:85], v[80:81] neg_lo:[0,1] neg_hi:[0,1]
	v_mov_b32_e32 v88, v86
	v_pk_add_f32 v[76:77], v[82:83], v[80:81] neg_lo:[0,1] neg_hi:[0,1]
	v_mov_b32_e32 v87, v79
	v_pk_add_f32 v[80:81], v[88:89], v[76:77]
	s_nop 0
	v_pk_add_f32 v[82:83], v[80:81], v[80:81] op_sel:[0,1] op_sel_hi:[1,0]
	s_nop 0
	v_pk_add_f32 v[78:79], v[78:79], v[82:83] op_sel:[1,0] op_sel_hi:[0,1]
	v_mov_b32_e32 v81, v78
	v_pk_add_f32 v[84:85], v[80:81], v[86:87] neg_lo:[0,1] neg_hi:[0,1]
	v_mov_b32_e32 v77, v82
	v_sub_f32_e32 v73, v80, v84
	v_pk_add_f32 v[76:77], v[76:77], v[84:85] neg_lo:[0,1] neg_hi:[0,1]
	v_sub_f32_e32 v73, v86, v73
	v_add_f32_e32 v73, v76, v73
	v_add_f32_e32 v73, v73, v77
	v_add_f32_e32 v73, v78, v73
	v_cndmask_b32_e32 v73, v224, v73, vcc
	v_cmp_ngt_f32_e32 vcc, -1.0, v72
	s_nop 1
	v_cndmask_b32_e32 v73, v225, v73, vcc
	v_cmp_neq_f32_e32 vcc, -1.0, v72
	s_nop 1
	v_cndmask_b32_e32 v73, v226, v73, vcc
	v_cmp_lt_f32_e64 vcc, |v72|, s56
	s_nop 1
	v_cndmask_b32_e32 v72, v73, v72, vcc
	v_add_f32_e32 v69, v69, v72

.LBB0_1275:
	s_and_b64 vcc, exec, s[4:5]
	v_or_b32_e32 v69, 33, v74
	s_cbranch_vccnz .LBB0_1710
	s_andn2_b64 vcc, exec, s[36:37]
	v_mov_b32_e32 v76, v27
	s_cbranch_vccnz .LBB0_1278
	s_nop 0
	v_lshl_add_u64 v[76:77], v[66:67], 0, s[80:81]
	s_waitcnt lgkmcnt(0)
	v_lshl_add_u64 v[76:77], v[76:77], 2, vcc
	v_mov_b32_e32 v76, v249
	s_nop 0
	v_add_f32_e32 v77, v27, v76
	v_max_f32_e32 v76, 0, v77
	v_mul_f32_e64 v77, |v77|, s73
	v_exp_f32_e32 v77, v77
	s_nop 0
	v_add_f32_e32 v80, 1.0, v77
	v_add_f32_e32 v78, -1.0, v80
	v_sub_f32_e32 v79, v78, v80
	v_add_f32_e32 v79, 1.0, v79
	v_sub_f32_e32 v78, v77, v78
	v_add_f32_e32 v81, v78, v79
	v_frexp_mant_f32_e32 v78, v80
	v_cmp_gt_f32_e32 vcc, s46, v78
	v_cvt_f64_f32_e32 v[78:79], v80
	v_frexp_exp_i32_f64_e32 v78, v[78:79]
	v_subbrev_co_u32_e32 v86, vcc, 0, v78, vcc
	v_sub_u32_e32 v78, 0, v86
	v_ldexp_f32 v79, v80, v78
	v_add_f32_e32 v80, -1.0, v79
	v_add_f32_e32 v82, 1.0, v79
	v_ldexp_f32 v78, v81, v78
	v_add_f32_e32 v81, 1.0, v80
	v_add_f32_e32 v83, -1.0, v82
	v_sub_f32_e32 v81, v79, v81
	v_sub_f32_e32 v79, v79, v83
	v_add_f32_e32 v81, v78, v81
	v_add_f32_e32 v78, v78, v79
	v_add_f32_e32 v87, v82, v78
	v_rcp_f32_e32 v89, v87
	v_sub_f32_e32 v79, v87, v82
	v_sub_f32_e32 v88, v78, v79
	v_add_f32_e32 v79, v80, v81
	v_mul_f32_e32 v91, v79, v89
	v_sub_f32_e32 v78, v79, v80
	v_mul_f32_e32 v80, v87, v91
	v_fma_f32 v82, v91, v87, -v80
	v_fmac_f32_e32 v82, v91, v88
	v_sub_f32_e32 v90, v81, v78
	v_add_f32_e32 v78, v80, v82
	v_sub_f32_e32 v81, v79, v78
	v_pk_add_f32 v[84:85], v[78:79], v[80:81] neg_lo:[0,1] neg_hi:[0,1]
	v_mov_b32_e32 v83, v78
	v_pk_add_f32 v[78:79], v[84:85], v[82:83] neg_lo:[0,1] neg_hi:[0,1]
	v_cmp_neq_f32_e32 vcc, s0, v77
	v_add_f32_e32 v79, v90, v79
	v_add_f32_e32 v78, v78, v79
	v_add_f32_e32 v79, v81, v78
	v_mul_f32_e32 v90, v89, v79
	v_mul_f32_e32 v80, v87, v90
	v_fma_f32 v82, v90, v87, -v80
	v_fmac_f32_e32 v82, v90, v88
	v_sub_f32_e32 v81, v81, v79
	v_add_f32_e32 v87, v78, v81
	v_add_f32_e32 v78, v80, v82
	v_sub_f32_e32 v81, v79, v78
	v_pk_add_f32 v[84:85], v[78:79], v[80:81] neg_lo:[0,1] neg_hi:[0,1]
	v_mov_b32_e32 v83, v78
	v_pk_add_f32 v[78:79], v[84:85], v[82:83] neg_lo:[0,1] neg_hi:[0,1]
	s_nop 0
	v_add_f32_e32 v79, v87, v79
	v_add_f32_e32 v78, v78, v79
	v_add_f32_e32 v79, v91, v90
	v_add_f32_e32 v78, v81, v78
	v_sub_f32_e32 v80, v79, v91
	v_mul_f32_e32 v78, v89, v78
	v_sub_f32_e32 v80, v90, v80
	v_add_f32_e32 v80, v80, v78
	v_add_f32_e32 v82, v79, v80
	v_mul_f32_e32 v83, v82, v82
	v_fmamk_f32 v78, v83, 0x3e9b6dac, v210
	v_fmaak_f32 v121, v83, v78, 0x3f2aaada
	v_cvt_f32_i32_e32 v78, v86
	v_sub_f32_e32 v79, v82, v79
	v_sub_f32_e32 v79, v80, v79
	v_ldexp_f32 v84, v79, 1
	v_mul_f32_e32 v79, v82, v83
	v_ldexp_f32 v81, v82, 1
	v_pk_mul_f32 v[82:83], v[78:79], v[120:121]
	s_nop 0
	v_fma_f32 v80, v78, s1, -v82
	v_fmac_f32_e32 v80, 0xb102e308, v78
	v_pk_add_f32 v[78:79], v[82:83], v[80:81]
	s_nop 0
	v_sub_f32_e32 v81, v79, v81
	v_sub_f32_e32 v81, v83, v81
	v_add_f32_e32 v85, v84, v81
	v_mov_b32_e32 v84, v82
	v_pk_add_f32 v[82:83], v[78:79], v[82:83] neg_lo:[0,1] neg_hi:[0,1]
	v_pk_add_f32 v[86:87], v[78:79], v[84:85]
	v_mov_b32_e32 v81, v78
	v_mov_b32_e32 v83, v87
	v_pk_add_f32 v[88:89], v[80:81], v[82:83] neg_lo:[0,1] neg_hi:[0,1]
	v_pk_add_f32 v[80:81], v[80:81], v[82:83]
	v_mov_b32_e32 v84, v85
	v_pk_add_f32 v[82:83], v[80:81], v[78:79] op_sel:[1,0] op_sel_hi:[0,1] neg_lo:[0,1] neg_hi:[0,1]
	v_pk_add_f32 v[90:91], v[86:87], v[82:83] op_sel_hi:[1,0] neg_lo:[0,1] neg_hi:[0,1]
	v_mov_b32_e32 v86, v87
	v_mov_b32_e32 v87, v81
	v_pk_mov_b32 v[82:83], v[78:79], v[82:83] op_sel:[1,0]
	v_mov_b32_e32 v85, v78
	v_pk_add_f32 v[82:83], v[86:87], v[82:83] neg_lo:[0,1] neg_hi:[0,1]
	v_mov_b32_e32 v90, v88
	v_pk_add_f32 v[78:79], v[84:85], v[82:83] neg_lo:[0,1] neg_hi:[0,1]
	v_mov_b32_e32 v89, v81
	v_pk_add_f32 v[82:83], v[90:91], v[78:79]
	s_nop 0
	v_pk_add_f32 v[84:85], v[82:83], v[82:83] op_sel:[0,1] op_sel_hi:[1,0]
	s_nop 0
	v_pk_add_f32 v[80:81], v[80:81], v[84:85] op_sel:[1,0] op_sel_hi:[0,1]
	v_mov_b32_e32 v83, v80
	v_pk_add_f32 v[86:87], v[82:83], v[88:89] neg_lo:[0,1] neg_hi:[0,1]
	v_mov_b32_e32 v79, v84
	v_sub_f32_e32 v81, v82, v86
	v_pk_add_f32 v[78:79], v[78:79], v[86:87] neg_lo:[0,1] neg_hi:[0,1]
	v_sub_f32_e32 v81, v88, v81
	v_add_f32_e32 v78, v78, v81
	v_add_f32_e32 v78, v78, v79
	v_add_f32_e32 v78, v80, v78
	v_cndmask_b32_e32 v78, v224, v78, vcc
	v_cmp_ngt_f32_e32 vcc, -1.0, v77
	s_nop 1
	v_cndmask_b32_e32 v78, v225, v78, vcc
	v_cmp_neq_f32_e32 vcc, -1.0, v77
	s_nop 1
	v_cndmask_b32_e32 v78, v226, v78, vcc
	v_cmp_lt_f32_e64 vcc, |v77|, s56
	s_nop 1
	v_cndmask_b32_e32 v77, v78, v77, vcc
	v_add_f32_e32 v76, v76, v77

.LBB0_1280:
	s_and_b64 vcc, exec, s[4:5]
	v_or_b32_e32 v69, 34, v74
	s_cbranch_vccnz .LBB0_1711
	s_andn2_b64 vcc, exec, s[36:37]
	v_mov_b32_e32 v76, v28
	s_cbranch_vccnz .LBB0_1283
	s_nop 0
	v_lshl_add_u64 v[76:77], v[66:67], 0, s[80:81]
	s_waitcnt lgkmcnt(0)
	v_lshl_add_u64 v[76:77], v[76:77], 2, vcc
	v_mov_b32_e32 v76, v249
	s_nop 0
	v_add_f32_e32 v77, v28, v76
	v_max_f32_e32 v76, 0, v77
	v_mul_f32_e64 v77, |v77|, s73
	v_exp_f32_e32 v77, v77
	s_nop 0
	v_add_f32_e32 v80, 1.0, v77
	v_add_f32_e32 v78, -1.0, v80
	v_sub_f32_e32 v79, v78, v80
	v_add_f32_e32 v79, 1.0, v79
	v_sub_f32_e32 v78, v77, v78
	v_add_f32_e32 v81, v78, v79
	v_frexp_mant_f32_e32 v78, v80
	v_cmp_gt_f32_e32 vcc, s46, v78
	v_cvt_f64_f32_e32 v[78:79], v80
	v_frexp_exp_i32_f64_e32 v78, v[78:79]
	v_subbrev_co_u32_e32 v86, vcc, 0, v78, vcc
	v_sub_u32_e32 v78, 0, v86
	v_ldexp_f32 v79, v80, v78
	v_add_f32_e32 v80, -1.0, v79
	v_add_f32_e32 v82, 1.0, v79
	v_ldexp_f32 v78, v81, v78
	v_add_f32_e32 v81, 1.0, v80
	v_add_f32_e32 v83, -1.0, v82
	v_sub_f32_e32 v81, v79, v81
	v_sub_f32_e32 v79, v79, v83
	v_add_f32_e32 v81, v78, v81
	v_add_f32_e32 v78, v78, v79
	v_add_f32_e32 v87, v82, v78
	v_rcp_f32_e32 v89, v87
	v_sub_f32_e32 v79, v87, v82
	v_sub_f32_e32 v88, v78, v79
	v_add_f32_e32 v79, v80, v81
	v_mul_f32_e32 v91, v79, v89
	v_sub_f32_e32 v78, v79, v80
	v_mul_f32_e32 v80, v87, v91
	v_fma_f32 v82, v91, v87, -v80
	v_fmac_f32_e32 v82, v91, v88
	v_sub_f32_e32 v90, v81, v78
	v_add_f32_e32 v78, v80, v82
	v_sub_f32_e32 v81, v79, v78
	v_pk_add_f32 v[84:85], v[78:79], v[80:81] neg_lo:[0,1] neg_hi:[0,1]
	v_mov_b32_e32 v83, v78
	v_pk_add_f32 v[78:79], v[84:85], v[82:83] neg_lo:[0,1] neg_hi:[0,1]
	v_cmp_neq_f32_e32 vcc, s0, v77
	v_add_f32_e32 v79, v90, v79
	v_add_f32_e32 v78, v78, v79
	v_add_f32_e32 v79, v81, v78
	v_mul_f32_e32 v90, v89, v79
	v_mul_f32_e32 v80, v87, v90
	v_fma_f32 v82, v90, v87, -v80
	v_fmac_f32_e32 v82, v90, v88
	v_sub_f32_e32 v81, v81, v79
	v_add_f32_e32 v87, v78, v81
	v_add_f32_e32 v78, v80, v82
	v_sub_f32_e32 v81, v79, v78
	v_pk_add_f32 v[84:85], v[78:79], v[80:81] neg_lo:[0,1] neg_hi:[0,1]
	v_mov_b32_e32 v83, v78
	v_pk_add_f32 v[78:79], v[84:85], v[82:83] neg_lo:[0,1] neg_hi:[0,1]
	s_nop 0
	v_add_f32_e32 v79, v87, v79
	v_add_f32_e32 v78, v78, v79
	v_add_f32_e32 v79, v91, v90
	v_add_f32_e32 v78, v81, v78
	v_sub_f32_e32 v80, v79, v91
	v_mul_f32_e32 v78, v89, v78
	v_sub_f32_e32 v80, v90, v80
	v_add_f32_e32 v80, v80, v78
	v_add_f32_e32 v82, v79, v80
	v_mul_f32_e32 v83, v82, v82
	v_fmamk_f32 v78, v83, 0x3e9b6dac, v210
	v_fmaak_f32 v121, v83, v78, 0x3f2aaada
	v_cvt_f32_i32_e32 v78, v86
	v_sub_f32_e32 v79, v82, v79
	v_sub_f32_e32 v79, v80, v79
	v_ldexp_f32 v84, v79, 1
	v_mul_f32_e32 v79, v82, v83
	v_ldexp_f32 v81, v82, 1
	v_pk_mul_f32 v[82:83], v[78:79], v[120:121]
	s_nop 0
	v_fma_f32 v80, v78, s1, -v82
	v_fmac_f32_e32 v80, 0xb102e308, v78
	v_pk_add_f32 v[78:79], v[82:83], v[80:81]
	s_nop 0
	v_sub_f32_e32 v81, v79, v81
	v_sub_f32_e32 v81, v83, v81
	v_add_f32_e32 v85, v84, v81
	v_mov_b32_e32 v84, v82
	v_pk_add_f32 v[82:83], v[78:79], v[82:83] neg_lo:[0,1] neg_hi:[0,1]
	v_pk_add_f32 v[86:87], v[78:79], v[84:85]
	v_mov_b32_e32 v81, v78
	v_mov_b32_e32 v83, v87
	v_pk_add_f32 v[88:89], v[80:81], v[82:83] neg_lo:[0,1] neg_hi:[0,1]
	v_pk_add_f32 v[80:81], v[80:81], v[82:83]
	v_mov_b32_e32 v84, v85
	v_pk_add_f32 v[82:83], v[80:81], v[78:79] op_sel:[1,0] op_sel_hi:[0,1] neg_lo:[0,1] neg_hi:[0,1]
	v_pk_add_f32 v[90:91], v[86:87], v[82:83] op_sel_hi:[1,0] neg_lo:[0,1] neg_hi:[0,1]
	v_mov_b32_e32 v86, v87
	v_mov_b32_e32 v87, v81
	v_pk_mov_b32 v[82:83], v[78:79], v[82:83] op_sel:[1,0]
	v_mov_b32_e32 v85, v78
	v_pk_add_f32 v[82:83], v[86:87], v[82:83] neg_lo:[0,1] neg_hi:[0,1]
	v_mov_b32_e32 v90, v88
	v_pk_add_f32 v[78:79], v[84:85], v[82:83] neg_lo:[0,1] neg_hi:[0,1]
	v_mov_b32_e32 v89, v81
	v_pk_add_f32 v[82:83], v[90:91], v[78:79]
	s_nop 0
	v_pk_add_f32 v[84:85], v[82:83], v[82:83] op_sel:[0,1] op_sel_hi:[1,0]
	s_nop 0
	v_pk_add_f32 v[80:81], v[80:81], v[84:85] op_sel:[1,0] op_sel_hi:[0,1]
	v_mov_b32_e32 v83, v80
	v_pk_add_f32 v[86:87], v[82:83], v[88:89] neg_lo:[0,1] neg_hi:[0,1]
	v_mov_b32_e32 v79, v84
	v_sub_f32_e32 v81, v82, v86
	v_pk_add_f32 v[78:79], v[78:79], v[86:87] neg_lo:[0,1] neg_hi:[0,1]
	v_sub_f32_e32 v81, v88, v81
	v_add_f32_e32 v78, v78, v81
	v_add_f32_e32 v78, v78, v79
	v_add_f32_e32 v78, v80, v78
	v_cndmask_b32_e32 v78, v224, v78, vcc
	v_cmp_ngt_f32_e32 vcc, -1.0, v77
	s_nop 1
	v_cndmask_b32_e32 v78, v225, v78, vcc
	v_cmp_neq_f32_e32 vcc, -1.0, v77
	s_nop 1
	v_cndmask_b32_e32 v78, v226, v78, vcc
	v_cmp_lt_f32_e64 vcc, |v77|, s56
	s_nop 1
	v_cndmask_b32_e32 v77, v78, v77, vcc
	v_add_f32_e32 v76, v76, v77

.LBB0_1285:
	s_and_b64 vcc, exec, s[4:5]
	v_or_b32_e32 v69, 35, v74
	s_cbranch_vccnz .LBB0_1712
	s_andn2_b64 vcc, exec, s[36:37]
	v_mov_b32_e32 v76, v29
	s_cbranch_vccnz .LBB0_1288
	s_nop 0
	v_lshl_add_u64 v[76:77], v[66:67], 0, s[80:81]
	s_waitcnt lgkmcnt(0)
	v_lshl_add_u64 v[76:77], v[76:77], 2, vcc
	v_mov_b32_e32 v76, v249
	s_nop 0
	v_add_f32_e32 v77, v29, v76
	v_max_f32_e32 v76, 0, v77
	v_mul_f32_e64 v77, |v77|, s73
	v_exp_f32_e32 v77, v77
	s_nop 0
	v_add_f32_e32 v80, 1.0, v77
	v_add_f32_e32 v78, -1.0, v80
	v_sub_f32_e32 v79, v78, v80
	v_add_f32_e32 v79, 1.0, v79
	v_sub_f32_e32 v78, v77, v78
	v_add_f32_e32 v81, v78, v79
	v_frexp_mant_f32_e32 v78, v80
	v_cmp_gt_f32_e32 vcc, s46, v78
	v_cvt_f64_f32_e32 v[78:79], v80
	v_frexp_exp_i32_f64_e32 v78, v[78:79]
	v_subbrev_co_u32_e32 v86, vcc, 0, v78, vcc
	v_sub_u32_e32 v78, 0, v86
	v_ldexp_f32 v79, v80, v78
	v_add_f32_e32 v80, -1.0, v79
	v_add_f32_e32 v82, 1.0, v79
	v_ldexp_f32 v78, v81, v78
	v_add_f32_e32 v81, 1.0, v80
	v_add_f32_e32 v83, -1.0, v82
	v_sub_f32_e32 v81, v79, v81
	v_sub_f32_e32 v79, v79, v83
	v_add_f32_e32 v81, v78, v81
	v_add_f32_e32 v78, v78, v79
	v_add_f32_e32 v87, v82, v78
	v_rcp_f32_e32 v89, v87
	v_sub_f32_e32 v79, v87, v82
	v_sub_f32_e32 v88, v78, v79
	v_add_f32_e32 v79, v80, v81
	v_mul_f32_e32 v91, v79, v89
	v_sub_f32_e32 v78, v79, v80
	v_mul_f32_e32 v80, v87, v91
	v_fma_f32 v82, v91, v87, -v80
	v_fmac_f32_e32 v82, v91, v88
	v_sub_f32_e32 v90, v81, v78
	v_add_f32_e32 v78, v80, v82
	v_sub_f32_e32 v81, v79, v78
	v_pk_add_f32 v[84:85], v[78:79], v[80:81] neg_lo:[0,1] neg_hi:[0,1]
	v_mov_b32_e32 v83, v78
	v_pk_add_f32 v[78:79], v[84:85], v[82:83] neg_lo:[0,1] neg_hi:[0,1]
	v_cmp_neq_f32_e32 vcc, s0, v77
	v_add_f32_e32 v79, v90, v79
	v_add_f32_e32 v78, v78, v79
	v_add_f32_e32 v79, v81, v78
	v_mul_f32_e32 v90, v89, v79
	v_mul_f32_e32 v80, v87, v90
	v_fma_f32 v82, v90, v87, -v80
	v_fmac_f32_e32 v82, v90, v88
	v_sub_f32_e32 v81, v81, v79
	v_add_f32_e32 v87, v78, v81
	v_add_f32_e32 v78, v80, v82
	v_sub_f32_e32 v81, v79, v78
	v_pk_add_f32 v[84:85], v[78:79], v[80:81] neg_lo:[0,1] neg_hi:[0,1]
	v_mov_b32_e32 v83, v78
	v_pk_add_f32 v[78:79], v[84:85], v[82:83] neg_lo:[0,1] neg_hi:[0,1]
	s_nop 0
	v_add_f32_e32 v79, v87, v79
	v_add_f32_e32 v78, v78, v79
	v_add_f32_e32 v79, v91, v90
	v_add_f32_e32 v78, v81, v78
	v_sub_f32_e32 v80, v79, v91
	v_mul_f32_e32 v78, v89, v78
	v_sub_f32_e32 v80, v90, v80
	v_add_f32_e32 v80, v80, v78
	v_add_f32_e32 v82, v79, v80
	v_mul_f32_e32 v83, v82, v82
	v_fmamk_f32 v78, v83, 0x3e9b6dac, v210
	v_fmaak_f32 v121, v83, v78, 0x3f2aaada
	v_cvt_f32_i32_e32 v78, v86
	v_sub_f32_e32 v79, v82, v79
	v_sub_f32_e32 v79, v80, v79
	v_ldexp_f32 v84, v79, 1
	v_mul_f32_e32 v79, v82, v83
	v_ldexp_f32 v81, v82, 1
	v_pk_mul_f32 v[82:83], v[78:79], v[120:121]
	s_nop 0
	v_fma_f32 v80, v78, s1, -v82
	v_fmac_f32_e32 v80, 0xb102e308, v78
	v_pk_add_f32 v[78:79], v[82:83], v[80:81]
	s_nop 0
	v_sub_f32_e32 v81, v79, v81
	v_sub_f32_e32 v81, v83, v81
	v_add_f32_e32 v85, v84, v81
	v_mov_b32_e32 v84, v82
	v_pk_add_f32 v[82:83], v[78:79], v[82:83] neg_lo:[0,1] neg_hi:[0,1]
	v_pk_add_f32 v[86:87], v[78:79], v[84:85]
	v_mov_b32_e32 v81, v78
	v_mov_b32_e32 v83, v87
	v_pk_add_f32 v[88:89], v[80:81], v[82:83] neg_lo:[0,1] neg_hi:[0,1]
	v_pk_add_f32 v[80:81], v[80:81], v[82:83]
	v_mov_b32_e32 v84, v85
	v_pk_add_f32 v[82:83], v[80:81], v[78:79] op_sel:[1,0] op_sel_hi:[0,1] neg_lo:[0,1] neg_hi:[0,1]
	v_pk_add_f32 v[90:91], v[86:87], v[82:83] op_sel_hi:[1,0] neg_lo:[0,1] neg_hi:[0,1]
	v_mov_b32_e32 v86, v87
	v_mov_b32_e32 v87, v81
	v_pk_mov_b32 v[82:83], v[78:79], v[82:83] op_sel:[1,0]
	v_mov_b32_e32 v85, v78
	v_pk_add_f32 v[82:83], v[86:87], v[82:83] neg_lo:[0,1] neg_hi:[0,1]
	v_mov_b32_e32 v90, v88
	v_pk_add_f32 v[78:79], v[84:85], v[82:83] neg_lo:[0,1] neg_hi:[0,1]
	v_mov_b32_e32 v89, v81
	v_pk_add_f32 v[82:83], v[90:91], v[78:79]
	s_nop 0
	v_pk_add_f32 v[84:85], v[82:83], v[82:83] op_sel:[0,1] op_sel_hi:[1,0]
	s_nop 0
	v_pk_add_f32 v[80:81], v[80:81], v[84:85] op_sel:[1,0] op_sel_hi:[0,1]
	v_mov_b32_e32 v83, v80
	v_pk_add_f32 v[86:87], v[82:83], v[88:89] neg_lo:[0,1] neg_hi:[0,1]
	v_mov_b32_e32 v79, v84
	v_sub_f32_e32 v81, v82, v86
	v_pk_add_f32 v[78:79], v[78:79], v[86:87] neg_lo:[0,1] neg_hi:[0,1]
	v_sub_f32_e32 v81, v88, v81
	v_add_f32_e32 v78, v78, v81
	v_add_f32_e32 v78, v78, v79
	v_add_f32_e32 v78, v80, v78
	v_cndmask_b32_e32 v78, v224, v78, vcc
	v_cmp_ngt_f32_e32 vcc, -1.0, v77
	s_nop 1
	v_cndmask_b32_e32 v78, v225, v78, vcc
	v_cmp_neq_f32_e32 vcc, -1.0, v77
	s_nop 1
	v_cndmask_b32_e32 v78, v226, v78, vcc
	v_cmp_lt_f32_e64 vcc, |v77|, s56
	s_nop 1
	v_cndmask_b32_e32 v77, v78, v77, vcc
	v_add_f32_e32 v76, v76, v77

.LBB0_1290:
	s_or_b64 exec, exec, s[58:59]
	s_and_saveexec_b64 s[58:59], s[10:11]
	s_cbranch_execz .LBB0_1311
	s_and_b64 vcc, exec, s[4:5]
	v_lshl_add_u64 v[70:71], v[66:67], 2, s[34:35]
	s_cbranch_vccnz .LBB0_1713
	s_andn2_b64 vcc, exec, s[36:37]
	v_mov_b32_e32 v69, v22
	s_cbranch_vccnz .LBB0_1294
	s_nop 0
	v_lshl_add_u64 v[72:73], v[66:67], 0, s[80:81]
	s_waitcnt lgkmcnt(0)
	v_lshl_add_u64 v[72:73], v[72:73], 2, vcc
	v_mov_b32_e32 v69, v250
	s_nop 0
	v_add_f32_e32 v72, v22, v69
	v_max_f32_e32 v69, 0, v72
	v_mul_f32_e64 v72, |v72|, s73
	v_exp_f32_e32 v72, v72
	s_nop 0
	v_add_f32_e32 v73, 1.0, v72
	v_add_f32_e32 v76, -1.0, v73
	v_sub_f32_e32 v77, v76, v73
	v_add_f32_e32 v77, 1.0, v77
	v_sub_f32_e32 v76, v72, v76
	v_add_f32_e32 v78, v76, v77
	v_frexp_mant_f32_e32 v76, v73
	v_cmp_gt_f32_e32 vcc, s46, v76
	v_cvt_f64_f32_e32 v[76:77], v73
	v_frexp_exp_i32_f64_e32 v76, v[76:77]
	v_subbrev_co_u32_e32 v84, vcc, 0, v76, vcc
	v_sub_u32_e32 v76, 0, v84
	v_ldexp_f32 v73, v73, v76
	v_ldexp_f32 v76, v78, v76
	v_add_f32_e32 v78, -1.0, v73
	v_add_f32_e32 v77, 1.0, v78
	v_sub_f32_e32 v77, v73, v77
	v_add_f32_e32 v79, v76, v77
	v_add_f32_e32 v77, 1.0, v73
	v_add_f32_e32 v80, -1.0, v77
	v_sub_f32_e32 v73, v73, v80
	v_add_f32_e32 v73, v76, v73
	v_add_f32_e32 v85, v77, v73
	v_rcp_f32_e32 v86, v85
	v_sub_f32_e32 v76, v85, v77
	v_add_f32_e32 v77, v78, v79
	v_sub_f32_e32 v73, v73, v76
	v_mul_f32_e32 v88, v77, v86
	v_sub_f32_e32 v76, v77, v78
	v_mul_f32_e32 v78, v85, v88
	v_fma_f32 v80, v88, v85, -v78
	v_fmac_f32_e32 v80, v88, v73
	v_sub_f32_e32 v87, v79, v76
	v_add_f32_e32 v76, v78, v80
	v_sub_f32_e32 v79, v77, v76
	v_pk_add_f32 v[82:83], v[76:77], v[78:79] neg_lo:[0,1] neg_hi:[0,1]
	v_mov_b32_e32 v81, v76
	v_pk_add_f32 v[76:77], v[82:83], v[80:81] neg_lo:[0,1] neg_hi:[0,1]
	v_cmp_neq_f32_e32 vcc, s0, v72
	v_add_f32_e32 v77, v87, v77
	v_add_f32_e32 v76, v76, v77
	v_add_f32_e32 v77, v79, v76
	v_mul_f32_e32 v87, v86, v77
	v_mul_f32_e32 v78, v85, v87
	v_fma_f32 v80, v87, v85, -v78
	v_fmac_f32_e32 v80, v87, v73
	v_sub_f32_e32 v73, v79, v77
	v_add_f32_e32 v73, v76, v73
	v_add_f32_e32 v76, v78, v80
	v_sub_f32_e32 v79, v77, v76
	v_pk_add_f32 v[82:83], v[76:77], v[78:79] neg_lo:[0,1] neg_hi:[0,1]
	v_mov_b32_e32 v81, v76
	v_pk_add_f32 v[76:77], v[82:83], v[80:81] neg_lo:[0,1] neg_hi:[0,1]
	s_nop 0
	v_add_f32_e32 v73, v73, v77
	v_add_f32_e32 v73, v76, v73
	v_add_f32_e32 v77, v88, v87
	v_add_f32_e32 v73, v79, v73
	v_sub_f32_e32 v76, v77, v88
	v_mul_f32_e32 v73, v86, v73
	v_sub_f32_e32 v76, v87, v76
	v_add_f32_e32 v73, v76, v73
	v_add_f32_e32 v78, v77, v73
	v_mul_f32_e32 v80, v78, v78
	v_fmamk_f32 v76, v80, 0x3e9b6dac, v210
	v_fmaak_f32 v121, v80, v76, 0x3f2aaada
	v_cvt_f32_i32_e32 v76, v84
	v_sub_f32_e32 v77, v78, v77
	v_sub_f32_e32 v73, v73, v77
	v_mul_f32_e32 v77, v78, v80
	v_pk_mul_f32 v[80:81], v[76:77], v[120:121]
	v_ldexp_f32 v79, v78, 1
	v_fma_f32 v78, v76, s1, -v80
	v_fmac_f32_e32 v78, 0xb102e308, v76
	v_pk_add_f32 v[76:77], v[80:81], v[78:79]
	v_ldexp_f32 v73, v73, 1
	v_sub_f32_e32 v79, v77, v79
	v_sub_f32_e32 v79, v81, v79
	v_add_f32_e32 v83, v73, v79
	v_mov_b32_e32 v82, v80
	v_pk_add_f32 v[80:81], v[76:77], v[80:81] neg_lo:[0,1] neg_hi:[0,1]
	v_pk_add_f32 v[84:85], v[76:77], v[82:83]
	v_mov_b32_e32 v79, v76
	v_mov_b32_e32 v81, v85
	v_pk_add_f32 v[86:87], v[78:79], v[80:81] neg_lo:[0,1] neg_hi:[0,1]
	v_pk_add_f32 v[78:79], v[78:79], v[80:81]
	v_mov_b32_e32 v82, v83
	v_pk_add_f32 v[80:81], v[78:79], v[76:77] op_sel:[1,0] op_sel_hi:[0,1] neg_lo:[0,1] neg_hi:[0,1]
	v_pk_add_f32 v[88:89], v[84:85], v[80:81] op_sel_hi:[1,0] neg_lo:[0,1] neg_hi:[0,1]
	v_mov_b32_e32 v84, v85
	v_mov_b32_e32 v85, v79
	v_pk_mov_b32 v[80:81], v[76:77], v[80:81] op_sel:[1,0]
	v_mov_b32_e32 v83, v76
	v_pk_add_f32 v[80:81], v[84:85], v[80:81] neg_lo:[0,1] neg_hi:[0,1]
	v_mov_b32_e32 v88, v86
	v_pk_add_f32 v[76:77], v[82:83], v[80:81] neg_lo:[0,1] neg_hi:[0,1]
	v_mov_b32_e32 v87, v79
	v_pk_add_f32 v[80:81], v[88:89], v[76:77]
	s_nop 0
	v_pk_add_f32 v[82:83], v[80:81], v[80:81] op_sel:[0,1] op_sel_hi:[1,0]
	s_nop 0
	v_pk_add_f32 v[78:79], v[78:79], v[82:83] op_sel:[1,0] op_sel_hi:[0,1]
	v_mov_b32_e32 v81, v78
	v_pk_add_f32 v[84:85], v[80:81], v[86:87] neg_lo:[0,1] neg_hi:[0,1]
	v_mov_b32_e32 v77, v82
	v_sub_f32_e32 v73, v80, v84
	v_pk_add_f32 v[76:77], v[76:77], v[84:85] neg_lo:[0,1] neg_hi:[0,1]
	v_sub_f32_e32 v73, v86, v73
	v_add_f32_e32 v73, v76, v73
	v_add_f32_e32 v73, v73, v77
	v_add_f32_e32 v73, v78, v73
	v_cndmask_b32_e32 v73, v224, v73, vcc
	v_cmp_ngt_f32_e32 vcc, -1.0, v72
	s_nop 1
	v_cndmask_b32_e32 v73, v225, v73, vcc
	v_cmp_neq_f32_e32 vcc, -1.0, v72
	s_nop 1
	v_cndmask_b32_e32 v73, v226, v73, vcc
	v_cmp_lt_f32_e64 vcc, |v72|, s56
	s_nop 1
	v_cndmask_b32_e32 v72, v73, v72, vcc
	v_add_f32_e32 v69, v69, v72

.LBB0_1296:
	s_and_b64 vcc, exec, s[4:5]
	v_or_b32_e32 v69, 33, v74
	s_cbranch_vccnz .LBB0_1714
	s_andn2_b64 vcc, exec, s[36:37]
	v_mov_b32_e32 v76, v23
	s_cbranch_vccnz .LBB0_1299
	s_nop 0
	v_lshl_add_u64 v[76:77], v[66:67], 0, s[80:81]
	s_waitcnt lgkmcnt(0)
	v_lshl_add_u64 v[76:77], v[76:77], 2, vcc
	v_mov_b32_e32 v76, v250
	s_nop 0
	v_add_f32_e32 v77, v23, v76
	v_max_f32_e32 v76, 0, v77
	v_mul_f32_e64 v77, |v77|, s73
	v_exp_f32_e32 v77, v77
	s_nop 0
	v_add_f32_e32 v80, 1.0, v77
	v_add_f32_e32 v78, -1.0, v80
	v_sub_f32_e32 v79, v78, v80
	v_add_f32_e32 v79, 1.0, v79
	v_sub_f32_e32 v78, v77, v78
	v_add_f32_e32 v81, v78, v79
	v_frexp_mant_f32_e32 v78, v80
	v_cmp_gt_f32_e32 vcc, s46, v78
	v_cvt_f64_f32_e32 v[78:79], v80
	v_frexp_exp_i32_f64_e32 v78, v[78:79]
	v_subbrev_co_u32_e32 v86, vcc, 0, v78, vcc
	v_sub_u32_e32 v78, 0, v86
	v_ldexp_f32 v79, v80, v78
	v_add_f32_e32 v80, -1.0, v79
	v_add_f32_e32 v82, 1.0, v79
	v_ldexp_f32 v78, v81, v78
	v_add_f32_e32 v81, 1.0, v80
	v_add_f32_e32 v83, -1.0, v82
	v_sub_f32_e32 v81, v79, v81
	v_sub_f32_e32 v79, v79, v83
	v_add_f32_e32 v81, v78, v81
	v_add_f32_e32 v78, v78, v79
	v_add_f32_e32 v87, v82, v78
	v_rcp_f32_e32 v89, v87
	v_sub_f32_e32 v79, v87, v82
	v_sub_f32_e32 v88, v78, v79
	v_add_f32_e32 v79, v80, v81
	v_mul_f32_e32 v91, v79, v89
	v_sub_f32_e32 v78, v79, v80
	v_mul_f32_e32 v80, v87, v91
	v_fma_f32 v82, v91, v87, -v80
	v_fmac_f32_e32 v82, v91, v88
	v_sub_f32_e32 v90, v81, v78
	v_add_f32_e32 v78, v80, v82
	v_sub_f32_e32 v81, v79, v78
	v_pk_add_f32 v[84:85], v[78:79], v[80:81] neg_lo:[0,1] neg_hi:[0,1]
	v_mov_b32_e32 v83, v78
	v_pk_add_f32 v[78:79], v[84:85], v[82:83] neg_lo:[0,1] neg_hi:[0,1]
	v_cmp_neq_f32_e32 vcc, s0, v77
	v_add_f32_e32 v79, v90, v79
	v_add_f32_e32 v78, v78, v79
	v_add_f32_e32 v79, v81, v78
	v_mul_f32_e32 v90, v89, v79
	v_mul_f32_e32 v80, v87, v90
	v_fma_f32 v82, v90, v87, -v80
	v_fmac_f32_e32 v82, v90, v88
	v_sub_f32_e32 v81, v81, v79
	v_add_f32_e32 v87, v78, v81
	v_add_f32_e32 v78, v80, v82
	v_sub_f32_e32 v81, v79, v78
	v_pk_add_f32 v[84:85], v[78:79], v[80:81] neg_lo:[0,1] neg_hi:[0,1]
	v_mov_b32_e32 v83, v78
	v_pk_add_f32 v[78:79], v[84:85], v[82:83] neg_lo:[0,1] neg_hi:[0,1]
	s_nop 0
	v_add_f32_e32 v79, v87, v79
	v_add_f32_e32 v78, v78, v79
	v_add_f32_e32 v79, v91, v90
	v_add_f32_e32 v78, v81, v78
	v_sub_f32_e32 v80, v79, v91
	v_mul_f32_e32 v78, v89, v78
	v_sub_f32_e32 v80, v90, v80
	v_add_f32_e32 v80, v80, v78
	v_add_f32_e32 v82, v79, v80
	v_mul_f32_e32 v83, v82, v82
	v_fmamk_f32 v78, v83, 0x3e9b6dac, v210
	v_fmaak_f32 v121, v83, v78, 0x3f2aaada
	v_cvt_f32_i32_e32 v78, v86
	v_sub_f32_e32 v79, v82, v79
	v_sub_f32_e32 v79, v80, v79
	v_ldexp_f32 v84, v79, 1
	v_mul_f32_e32 v79, v82, v83
	v_ldexp_f32 v81, v82, 1
	v_pk_mul_f32 v[82:83], v[78:79], v[120:121]
	s_nop 0
	v_fma_f32 v80, v78, s1, -v82
	v_fmac_f32_e32 v80, 0xb102e308, v78
	v_pk_add_f32 v[78:79], v[82:83], v[80:81]
	s_nop 0
	v_sub_f32_e32 v81, v79, v81
	v_sub_f32_e32 v81, v83, v81
	v_add_f32_e32 v85, v84, v81
	v_mov_b32_e32 v84, v82
	v_pk_add_f32 v[82:83], v[78:79], v[82:83] neg_lo:[0,1] neg_hi:[0,1]
	v_pk_add_f32 v[86:87], v[78:79], v[84:85]
	v_mov_b32_e32 v81, v78
	v_mov_b32_e32 v83, v87
	v_pk_add_f32 v[88:89], v[80:81], v[82:83] neg_lo:[0,1] neg_hi:[0,1]
	v_pk_add_f32 v[80:81], v[80:81], v[82:83]
	v_mov_b32_e32 v84, v85
	v_pk_add_f32 v[82:83], v[80:81], v[78:79] op_sel:[1,0] op_sel_hi:[0,1] neg_lo:[0,1] neg_hi:[0,1]
	v_pk_add_f32 v[90:91], v[86:87], v[82:83] op_sel_hi:[1,0] neg_lo:[0,1] neg_hi:[0,1]
	v_mov_b32_e32 v86, v87
	v_mov_b32_e32 v87, v81
	v_pk_mov_b32 v[82:83], v[78:79], v[82:83] op_sel:[1,0]
	v_mov_b32_e32 v85, v78
	v_pk_add_f32 v[82:83], v[86:87], v[82:83] neg_lo:[0,1] neg_hi:[0,1]
	v_mov_b32_e32 v90, v88
	v_pk_add_f32 v[78:79], v[84:85], v[82:83] neg_lo:[0,1] neg_hi:[0,1]
	v_mov_b32_e32 v89, v81
	v_pk_add_f32 v[82:83], v[90:91], v[78:79]
	s_nop 0
	v_pk_add_f32 v[84:85], v[82:83], v[82:83] op_sel:[0,1] op_sel_hi:[1,0]
	s_nop 0
	v_pk_add_f32 v[80:81], v[80:81], v[84:85] op_sel:[1,0] op_sel_hi:[0,1]
	v_mov_b32_e32 v83, v80
	v_pk_add_f32 v[86:87], v[82:83], v[88:89] neg_lo:[0,1] neg_hi:[0,1]
	v_mov_b32_e32 v79, v84
	v_sub_f32_e32 v81, v82, v86
	v_pk_add_f32 v[78:79], v[78:79], v[86:87] neg_lo:[0,1] neg_hi:[0,1]
	v_sub_f32_e32 v81, v88, v81
	v_add_f32_e32 v78, v78, v81
	v_add_f32_e32 v78, v78, v79
	v_add_f32_e32 v78, v80, v78
	v_cndmask_b32_e32 v78, v224, v78, vcc
	v_cmp_ngt_f32_e32 vcc, -1.0, v77
	s_nop 1
	v_cndmask_b32_e32 v78, v225, v78, vcc
	v_cmp_neq_f32_e32 vcc, -1.0, v77
	s_nop 1
	v_cndmask_b32_e32 v78, v226, v78, vcc
	v_cmp_lt_f32_e64 vcc, |v77|, s56
	s_nop 1
	v_cndmask_b32_e32 v77, v78, v77, vcc
	v_add_f32_e32 v76, v76, v77

.LBB0_1301:
	s_and_b64 vcc, exec, s[4:5]
	v_or_b32_e32 v69, 34, v74
	s_cbranch_vccnz .LBB0_1715
	s_andn2_b64 vcc, exec, s[36:37]
	v_mov_b32_e32 v76, v24
	s_cbranch_vccnz .LBB0_1304
	s_nop 0
	v_lshl_add_u64 v[76:77], v[66:67], 0, s[80:81]
	s_waitcnt lgkmcnt(0)
	v_lshl_add_u64 v[76:77], v[76:77], 2, vcc
	v_mov_b32_e32 v76, v250
	s_nop 0
	v_add_f32_e32 v77, v24, v76
	v_max_f32_e32 v76, 0, v77
	v_mul_f32_e64 v77, |v77|, s73
	v_exp_f32_e32 v77, v77
	s_nop 0
	v_add_f32_e32 v80, 1.0, v77
	v_add_f32_e32 v78, -1.0, v80
	v_sub_f32_e32 v79, v78, v80
	v_add_f32_e32 v79, 1.0, v79
	v_sub_f32_e32 v78, v77, v78
	v_add_f32_e32 v81, v78, v79
	v_frexp_mant_f32_e32 v78, v80
	v_cmp_gt_f32_e32 vcc, s46, v78
	v_cvt_f64_f32_e32 v[78:79], v80
	v_frexp_exp_i32_f64_e32 v78, v[78:79]
	v_subbrev_co_u32_e32 v86, vcc, 0, v78, vcc
	v_sub_u32_e32 v78, 0, v86
	v_ldexp_f32 v79, v80, v78
	v_add_f32_e32 v80, -1.0, v79
	v_add_f32_e32 v82, 1.0, v79
	v_ldexp_f32 v78, v81, v78
	v_add_f32_e32 v81, 1.0, v80
	v_add_f32_e32 v83, -1.0, v82
	v_sub_f32_e32 v81, v79, v81
	v_sub_f32_e32 v79, v79, v83
	v_add_f32_e32 v81, v78, v81
	v_add_f32_e32 v78, v78, v79
	v_add_f32_e32 v87, v82, v78
	v_rcp_f32_e32 v89, v87
	v_sub_f32_e32 v79, v87, v82
	v_sub_f32_e32 v88, v78, v79
	v_add_f32_e32 v79, v80, v81
	v_mul_f32_e32 v91, v79, v89
	v_sub_f32_e32 v78, v79, v80
	v_mul_f32_e32 v80, v87, v91
	v_fma_f32 v82, v91, v87, -v80
	v_fmac_f32_e32 v82, v91, v88
	v_sub_f32_e32 v90, v81, v78
	v_add_f32_e32 v78, v80, v82
	v_sub_f32_e32 v81, v79, v78
	v_pk_add_f32 v[84:85], v[78:79], v[80:81] neg_lo:[0,1] neg_hi:[0,1]
	v_mov_b32_e32 v83, v78
	v_pk_add_f32 v[78:79], v[84:85], v[82:83] neg_lo:[0,1] neg_hi:[0,1]
	v_cmp_neq_f32_e32 vcc, s0, v77
	v_add_f32_e32 v79, v90, v79
	v_add_f32_e32 v78, v78, v79
	v_add_f32_e32 v79, v81, v78
	v_mul_f32_e32 v90, v89, v79
	v_mul_f32_e32 v80, v87, v90
	v_fma_f32 v82, v90, v87, -v80
	v_fmac_f32_e32 v82, v90, v88
	v_sub_f32_e32 v81, v81, v79
	v_add_f32_e32 v87, v78, v81
	v_add_f32_e32 v78, v80, v82
	v_sub_f32_e32 v81, v79, v78
	v_pk_add_f32 v[84:85], v[78:79], v[80:81] neg_lo:[0,1] neg_hi:[0,1]
	v_mov_b32_e32 v83, v78
	v_pk_add_f32 v[78:79], v[84:85], v[82:83] neg_lo:[0,1] neg_hi:[0,1]
	s_nop 0
	v_add_f32_e32 v79, v87, v79
	v_add_f32_e32 v78, v78, v79
	v_add_f32_e32 v79, v91, v90
	v_add_f32_e32 v78, v81, v78
	v_sub_f32_e32 v80, v79, v91
	v_mul_f32_e32 v78, v89, v78
	v_sub_f32_e32 v80, v90, v80
	v_add_f32_e32 v80, v80, v78
	v_add_f32_e32 v82, v79, v80
	v_mul_f32_e32 v83, v82, v82
	v_fmamk_f32 v78, v83, 0x3e9b6dac, v210
	v_fmaak_f32 v121, v83, v78, 0x3f2aaada
	v_cvt_f32_i32_e32 v78, v86
	v_sub_f32_e32 v79, v82, v79
	v_sub_f32_e32 v79, v80, v79
	v_ldexp_f32 v84, v79, 1
	v_mul_f32_e32 v79, v82, v83
	v_ldexp_f32 v81, v82, 1
	v_pk_mul_f32 v[82:83], v[78:79], v[120:121]
	s_nop 0
	v_fma_f32 v80, v78, s1, -v82
	v_fmac_f32_e32 v80, 0xb102e308, v78
	v_pk_add_f32 v[78:79], v[82:83], v[80:81]
	s_nop 0
	v_sub_f32_e32 v81, v79, v81
	v_sub_f32_e32 v81, v83, v81
	v_add_f32_e32 v85, v84, v81
	v_mov_b32_e32 v84, v82
	v_pk_add_f32 v[82:83], v[78:79], v[82:83] neg_lo:[0,1] neg_hi:[0,1]
	v_pk_add_f32 v[86:87], v[78:79], v[84:85]
	v_mov_b32_e32 v81, v78
	v_mov_b32_e32 v83, v87
	v_pk_add_f32 v[88:89], v[80:81], v[82:83] neg_lo:[0,1] neg_hi:[0,1]
	v_pk_add_f32 v[80:81], v[80:81], v[82:83]
	v_mov_b32_e32 v84, v85
	v_pk_add_f32 v[82:83], v[80:81], v[78:79] op_sel:[1,0] op_sel_hi:[0,1] neg_lo:[0,1] neg_hi:[0,1]
	v_pk_add_f32 v[90:91], v[86:87], v[82:83] op_sel_hi:[1,0] neg_lo:[0,1] neg_hi:[0,1]
	v_mov_b32_e32 v86, v87
	v_mov_b32_e32 v87, v81
	v_pk_mov_b32 v[82:83], v[78:79], v[82:83] op_sel:[1,0]
	v_mov_b32_e32 v85, v78
	v_pk_add_f32 v[82:83], v[86:87], v[82:83] neg_lo:[0,1] neg_hi:[0,1]
	v_mov_b32_e32 v90, v88
	v_pk_add_f32 v[78:79], v[84:85], v[82:83] neg_lo:[0,1] neg_hi:[0,1]
	v_mov_b32_e32 v89, v81
	v_pk_add_f32 v[82:83], v[90:91], v[78:79]
	s_nop 0
	v_pk_add_f32 v[84:85], v[82:83], v[82:83] op_sel:[0,1] op_sel_hi:[1,0]
	s_nop 0
	v_pk_add_f32 v[80:81], v[80:81], v[84:85] op_sel:[1,0] op_sel_hi:[0,1]
	v_mov_b32_e32 v83, v80
	v_pk_add_f32 v[86:87], v[82:83], v[88:89] neg_lo:[0,1] neg_hi:[0,1]
	v_mov_b32_e32 v79, v84
	v_sub_f32_e32 v81, v82, v86
	v_pk_add_f32 v[78:79], v[78:79], v[86:87] neg_lo:[0,1] neg_hi:[0,1]
	v_sub_f32_e32 v81, v88, v81
	v_add_f32_e32 v78, v78, v81
	v_add_f32_e32 v78, v78, v79
	v_add_f32_e32 v78, v80, v78
	v_cndmask_b32_e32 v78, v224, v78, vcc
	v_cmp_ngt_f32_e32 vcc, -1.0, v77
	s_nop 1
	v_cndmask_b32_e32 v78, v225, v78, vcc
	v_cmp_neq_f32_e32 vcc, -1.0, v77
	s_nop 1
	v_cndmask_b32_e32 v78, v226, v78, vcc
	v_cmp_lt_f32_e64 vcc, |v77|, s56
	s_nop 1
	v_cndmask_b32_e32 v77, v78, v77, vcc
	v_add_f32_e32 v76, v76, v77

.LBB0_1306:
	s_and_b64 vcc, exec, s[4:5]
	v_or_b32_e32 v69, 35, v74
	s_cbranch_vccnz .LBB0_1716
	s_andn2_b64 vcc, exec, s[36:37]
	v_mov_b32_e32 v76, v25
	s_cbranch_vccnz .LBB0_1309
	s_nop 0
	v_lshl_add_u64 v[76:77], v[66:67], 0, s[80:81]
	s_waitcnt lgkmcnt(0)
	v_lshl_add_u64 v[76:77], v[76:77], 2, vcc
	v_mov_b32_e32 v76, v250
	s_nop 0
	v_add_f32_e32 v77, v25, v76
	v_max_f32_e32 v76, 0, v77
	v_mul_f32_e64 v77, |v77|, s73
	v_exp_f32_e32 v77, v77
	s_nop 0
	v_add_f32_e32 v80, 1.0, v77
	v_add_f32_e32 v78, -1.0, v80
	v_sub_f32_e32 v79, v78, v80
	v_add_f32_e32 v79, 1.0, v79
	v_sub_f32_e32 v78, v77, v78
	v_add_f32_e32 v81, v78, v79
	v_frexp_mant_f32_e32 v78, v80
	v_cmp_gt_f32_e32 vcc, s46, v78
	v_cvt_f64_f32_e32 v[78:79], v80
	v_frexp_exp_i32_f64_e32 v78, v[78:79]
	v_subbrev_co_u32_e32 v86, vcc, 0, v78, vcc
	v_sub_u32_e32 v78, 0, v86
	v_ldexp_f32 v79, v80, v78
	v_add_f32_e32 v80, -1.0, v79
	v_add_f32_e32 v82, 1.0, v79
	v_ldexp_f32 v78, v81, v78
	v_add_f32_e32 v81, 1.0, v80
	v_add_f32_e32 v83, -1.0, v82
	v_sub_f32_e32 v81, v79, v81
	v_sub_f32_e32 v79, v79, v83
	v_add_f32_e32 v81, v78, v81
	v_add_f32_e32 v78, v78, v79
	v_add_f32_e32 v87, v82, v78
	v_rcp_f32_e32 v89, v87
	v_sub_f32_e32 v79, v87, v82
	v_sub_f32_e32 v88, v78, v79
	v_add_f32_e32 v79, v80, v81
	v_mul_f32_e32 v91, v79, v89
	v_sub_f32_e32 v78, v79, v80
	v_mul_f32_e32 v80, v87, v91
	v_fma_f32 v82, v91, v87, -v80
	v_fmac_f32_e32 v82, v91, v88
	v_sub_f32_e32 v90, v81, v78
	v_add_f32_e32 v78, v80, v82
	v_sub_f32_e32 v81, v79, v78
	v_pk_add_f32 v[84:85], v[78:79], v[80:81] neg_lo:[0,1] neg_hi:[0,1]
	v_mov_b32_e32 v83, v78
	v_pk_add_f32 v[78:79], v[84:85], v[82:83] neg_lo:[0,1] neg_hi:[0,1]
	v_cmp_neq_f32_e32 vcc, s0, v77
	v_add_f32_e32 v79, v90, v79
	v_add_f32_e32 v78, v78, v79
	v_add_f32_e32 v79, v81, v78
	v_mul_f32_e32 v90, v89, v79
	v_mul_f32_e32 v80, v87, v90
	v_fma_f32 v82, v90, v87, -v80
	v_fmac_f32_e32 v82, v90, v88
	v_sub_f32_e32 v81, v81, v79
	v_add_f32_e32 v87, v78, v81
	v_add_f32_e32 v78, v80, v82
	v_sub_f32_e32 v81, v79, v78
	v_pk_add_f32 v[84:85], v[78:79], v[80:81] neg_lo:[0,1] neg_hi:[0,1]
	v_mov_b32_e32 v83, v78
	v_pk_add_f32 v[78:79], v[84:85], v[82:83] neg_lo:[0,1] neg_hi:[0,1]
	s_nop 0
	v_add_f32_e32 v79, v87, v79
	v_add_f32_e32 v78, v78, v79
	v_add_f32_e32 v79, v91, v90
	v_add_f32_e32 v78, v81, v78
	v_sub_f32_e32 v80, v79, v91
	v_mul_f32_e32 v78, v89, v78
	v_sub_f32_e32 v80, v90, v80
	v_add_f32_e32 v80, v80, v78
	v_add_f32_e32 v82, v79, v80
	v_mul_f32_e32 v83, v82, v82
	v_fmamk_f32 v78, v83, 0x3e9b6dac, v210
	v_fmaak_f32 v121, v83, v78, 0x3f2aaada
	v_cvt_f32_i32_e32 v78, v86
	v_sub_f32_e32 v79, v82, v79
	v_sub_f32_e32 v79, v80, v79
	v_ldexp_f32 v84, v79, 1
	v_mul_f32_e32 v79, v82, v83
	v_ldexp_f32 v81, v82, 1
	v_pk_mul_f32 v[82:83], v[78:79], v[120:121]
	s_nop 0
	v_fma_f32 v80, v78, s1, -v82
	v_fmac_f32_e32 v80, 0xb102e308, v78
	v_pk_add_f32 v[78:79], v[82:83], v[80:81]
	s_nop 0
	v_sub_f32_e32 v81, v79, v81
	v_sub_f32_e32 v81, v83, v81
	v_add_f32_e32 v85, v84, v81
	v_mov_b32_e32 v84, v82
	v_pk_add_f32 v[82:83], v[78:79], v[82:83] neg_lo:[0,1] neg_hi:[0,1]
	v_pk_add_f32 v[86:87], v[78:79], v[84:85]
	v_mov_b32_e32 v81, v78
	v_mov_b32_e32 v83, v87
	v_pk_add_f32 v[88:89], v[80:81], v[82:83] neg_lo:[0,1] neg_hi:[0,1]
	v_pk_add_f32 v[80:81], v[80:81], v[82:83]
	v_mov_b32_e32 v84, v85
	v_pk_add_f32 v[82:83], v[80:81], v[78:79] op_sel:[1,0] op_sel_hi:[0,1] neg_lo:[0,1] neg_hi:[0,1]
	v_pk_add_f32 v[90:91], v[86:87], v[82:83] op_sel_hi:[1,0] neg_lo:[0,1] neg_hi:[0,1]
	v_mov_b32_e32 v86, v87
	v_mov_b32_e32 v87, v81
	v_pk_mov_b32 v[82:83], v[78:79], v[82:83] op_sel:[1,0]
	v_mov_b32_e32 v85, v78
	v_pk_add_f32 v[82:83], v[86:87], v[82:83] neg_lo:[0,1] neg_hi:[0,1]
	v_mov_b32_e32 v90, v88
	v_pk_add_f32 v[78:79], v[84:85], v[82:83] neg_lo:[0,1] neg_hi:[0,1]
	v_mov_b32_e32 v89, v81
	v_pk_add_f32 v[82:83], v[90:91], v[78:79]
	s_nop 0
	v_pk_add_f32 v[84:85], v[82:83], v[82:83] op_sel:[0,1] op_sel_hi:[1,0]
	s_nop 0
	v_pk_add_f32 v[80:81], v[80:81], v[84:85] op_sel:[1,0] op_sel_hi:[0,1]
	v_mov_b32_e32 v83, v80
	v_pk_add_f32 v[86:87], v[82:83], v[88:89] neg_lo:[0,1] neg_hi:[0,1]
	v_mov_b32_e32 v79, v84
	v_sub_f32_e32 v81, v82, v86
	v_pk_add_f32 v[78:79], v[78:79], v[86:87] neg_lo:[0,1] neg_hi:[0,1]
	v_sub_f32_e32 v81, v88, v81
	v_add_f32_e32 v78, v78, v81
	v_add_f32_e32 v78, v78, v79
	v_add_f32_e32 v78, v80, v78
	v_cndmask_b32_e32 v78, v224, v78, vcc
	v_cmp_ngt_f32_e32 vcc, -1.0, v77
	s_nop 1
	v_cndmask_b32_e32 v78, v225, v78, vcc
	v_cmp_neq_f32_e32 vcc, -1.0, v77
	s_nop 1
	v_cndmask_b32_e32 v78, v226, v78, vcc
	v_cmp_lt_f32_e64 vcc, |v77|, s56
	s_nop 1
	v_cndmask_b32_e32 v77, v78, v77, vcc
	v_add_f32_e32 v76, v76, v77

.LBB0_1311:
	s_or_b64 exec, exec, s[58:59]
	s_and_saveexec_b64 s[58:59], s[12:13]
	s_cbranch_execz .LBB0_1332
	s_and_b64 vcc, exec, s[4:5]
	v_lshl_add_u64 v[70:71], v[66:67], 2, s[34:35]
	s_cbranch_vccnz .LBB0_1717
	s_andn2_b64 vcc, exec, s[36:37]
	v_mov_b32_e32 v69, v18
	s_cbranch_vccnz .LBB0_1315
	s_nop 0
	v_lshl_add_u64 v[72:73], v[66:67], 0, s[80:81]
	s_waitcnt lgkmcnt(0)
	v_lshl_add_u64 v[72:73], v[72:73], 2, vcc
	v_mov_b32_e32 v69, v251
	s_nop 0
	v_add_f32_e32 v72, v18, v69
	v_max_f32_e32 v69, 0, v72
	v_mul_f32_e64 v72, |v72|, s73
	v_exp_f32_e32 v72, v72
	s_nop 0
	v_add_f32_e32 v73, 1.0, v72
	v_add_f32_e32 v76, -1.0, v73
	v_sub_f32_e32 v77, v76, v73
	v_add_f32_e32 v77, 1.0, v77
	v_sub_f32_e32 v76, v72, v76
	v_add_f32_e32 v78, v76, v77
	v_frexp_mant_f32_e32 v76, v73
	v_cmp_gt_f32_e32 vcc, s46, v76
	v_cvt_f64_f32_e32 v[76:77], v73
	v_frexp_exp_i32_f64_e32 v76, v[76:77]
	v_subbrev_co_u32_e32 v84, vcc, 0, v76, vcc
	v_sub_u32_e32 v76, 0, v84
	v_ldexp_f32 v73, v73, v76
	v_ldexp_f32 v76, v78, v76
	v_add_f32_e32 v78, -1.0, v73
	v_add_f32_e32 v77, 1.0, v78
	v_sub_f32_e32 v77, v73, v77
	v_add_f32_e32 v79, v76, v77
	v_add_f32_e32 v77, 1.0, v73
	v_add_f32_e32 v80, -1.0, v77
	v_sub_f32_e32 v73, v73, v80
	v_add_f32_e32 v73, v76, v73
	v_add_f32_e32 v85, v77, v73
	v_rcp_f32_e32 v86, v85
	v_sub_f32_e32 v76, v85, v77
	v_add_f32_e32 v77, v78, v79
	v_sub_f32_e32 v73, v73, v76
	v_mul_f32_e32 v88, v77, v86
	v_sub_f32_e32 v76, v77, v78
	v_mul_f32_e32 v78, v85, v88
	v_fma_f32 v80, v88, v85, -v78
	v_fmac_f32_e32 v80, v88, v73
	v_sub_f32_e32 v87, v79, v76
	v_add_f32_e32 v76, v78, v80
	v_sub_f32_e32 v79, v77, v76
	v_pk_add_f32 v[82:83], v[76:77], v[78:79] neg_lo:[0,1] neg_hi:[0,1]
	v_mov_b32_e32 v81, v76
	v_pk_add_f32 v[76:77], v[82:83], v[80:81] neg_lo:[0,1] neg_hi:[0,1]
	v_cmp_neq_f32_e32 vcc, s0, v72
	v_add_f32_e32 v77, v87, v77
	v_add_f32_e32 v76, v76, v77
	v_add_f32_e32 v77, v79, v76
	v_mul_f32_e32 v87, v86, v77
	v_mul_f32_e32 v78, v85, v87
	v_fma_f32 v80, v87, v85, -v78
	v_fmac_f32_e32 v80, v87, v73
	v_sub_f32_e32 v73, v79, v77
	v_add_f32_e32 v73, v76, v73
	v_add_f32_e32 v76, v78, v80
	v_sub_f32_e32 v79, v77, v76
	v_pk_add_f32 v[82:83], v[76:77], v[78:79] neg_lo:[0,1] neg_hi:[0,1]
	v_mov_b32_e32 v81, v76
	v_pk_add_f32 v[76:77], v[82:83], v[80:81] neg_lo:[0,1] neg_hi:[0,1]
	s_nop 0
	v_add_f32_e32 v73, v73, v77
	v_add_f32_e32 v73, v76, v73
	v_add_f32_e32 v77, v88, v87
	v_add_f32_e32 v73, v79, v73
	v_sub_f32_e32 v76, v77, v88
	v_mul_f32_e32 v73, v86, v73
	v_sub_f32_e32 v76, v87, v76
	v_add_f32_e32 v73, v76, v73
	v_add_f32_e32 v78, v77, v73
	v_mul_f32_e32 v80, v78, v78
	v_fmamk_f32 v76, v80, 0x3e9b6dac, v210
	v_fmaak_f32 v121, v80, v76, 0x3f2aaada
	v_cvt_f32_i32_e32 v76, v84
	v_sub_f32_e32 v77, v78, v77
	v_sub_f32_e32 v73, v73, v77
	v_mul_f32_e32 v77, v78, v80
	v_pk_mul_f32 v[80:81], v[76:77], v[120:121]
	v_ldexp_f32 v79, v78, 1
	v_fma_f32 v78, v76, s1, -v80
	v_fmac_f32_e32 v78, 0xb102e308, v76
	v_pk_add_f32 v[76:77], v[80:81], v[78:79]
	v_ldexp_f32 v73, v73, 1
	v_sub_f32_e32 v79, v77, v79
	v_sub_f32_e32 v79, v81, v79
	v_add_f32_e32 v83, v73, v79
	v_mov_b32_e32 v82, v80
	v_pk_add_f32 v[80:81], v[76:77], v[80:81] neg_lo:[0,1] neg_hi:[0,1]
	v_pk_add_f32 v[84:85], v[76:77], v[82:83]
	v_mov_b32_e32 v79, v76
	v_mov_b32_e32 v81, v85
	v_pk_add_f32 v[86:87], v[78:79], v[80:81] neg_lo:[0,1] neg_hi:[0,1]
	v_pk_add_f32 v[78:79], v[78:79], v[80:81]
	v_mov_b32_e32 v82, v83
	v_pk_add_f32 v[80:81], v[78:79], v[76:77] op_sel:[1,0] op_sel_hi:[0,1] neg_lo:[0,1] neg_hi:[0,1]
	v_pk_add_f32 v[88:89], v[84:85], v[80:81] op_sel_hi:[1,0] neg_lo:[0,1] neg_hi:[0,1]
	v_mov_b32_e32 v84, v85
	v_mov_b32_e32 v85, v79
	v_pk_mov_b32 v[80:81], v[76:77], v[80:81] op_sel:[1,0]
	v_mov_b32_e32 v83, v76
	v_pk_add_f32 v[80:81], v[84:85], v[80:81] neg_lo:[0,1] neg_hi:[0,1]
	v_mov_b32_e32 v88, v86
	v_pk_add_f32 v[76:77], v[82:83], v[80:81] neg_lo:[0,1] neg_hi:[0,1]
	v_mov_b32_e32 v87, v79
	v_pk_add_f32 v[80:81], v[88:89], v[76:77]
	s_nop 0
	v_pk_add_f32 v[82:83], v[80:81], v[80:81] op_sel:[0,1] op_sel_hi:[1,0]
	s_nop 0
	v_pk_add_f32 v[78:79], v[78:79], v[82:83] op_sel:[1,0] op_sel_hi:[0,1]
	v_mov_b32_e32 v81, v78
	v_pk_add_f32 v[84:85], v[80:81], v[86:87] neg_lo:[0,1] neg_hi:[0,1]
	v_mov_b32_e32 v77, v82
	v_sub_f32_e32 v73, v80, v84
	v_pk_add_f32 v[76:77], v[76:77], v[84:85] neg_lo:[0,1] neg_hi:[0,1]
	v_sub_f32_e32 v73, v86, v73
	v_add_f32_e32 v73, v76, v73
	v_add_f32_e32 v73, v73, v77
	v_add_f32_e32 v73, v78, v73
	v_cndmask_b32_e32 v73, v224, v73, vcc
	v_cmp_ngt_f32_e32 vcc, -1.0, v72
	s_nop 1
	v_cndmask_b32_e32 v73, v225, v73, vcc
	v_cmp_neq_f32_e32 vcc, -1.0, v72
	s_nop 1
	v_cndmask_b32_e32 v73, v226, v73, vcc
	v_cmp_lt_f32_e64 vcc, |v72|, s56
	s_nop 1
	v_cndmask_b32_e32 v72, v73, v72, vcc
	v_add_f32_e32 v69, v69, v72

.LBB0_1317:
	s_and_b64 vcc, exec, s[4:5]
	v_or_b32_e32 v69, 33, v74
	s_cbranch_vccnz .LBB0_1718
	s_andn2_b64 vcc, exec, s[36:37]
	v_mov_b32_e32 v75, v19
	s_cbranch_vccnz .LBB0_1320
	s_nop 0
	v_lshl_add_u64 v[76:77], v[66:67], 0, s[80:81]
	s_waitcnt lgkmcnt(0)
	v_lshl_add_u64 v[76:77], v[76:77], 2, vcc
	v_mov_b32_e32 v75, v251
	s_nop 0
	v_add_f32_e32 v76, v19, v75
	v_max_f32_e32 v75, 0, v76
	v_mul_f32_e64 v76, |v76|, s73
	v_exp_f32_e32 v76, v76
	s_nop 0
	v_add_f32_e32 v77, 1.0, v76
	v_add_f32_e32 v78, -1.0, v77
	v_sub_f32_e32 v79, v78, v77
	v_add_f32_e32 v79, 1.0, v79
	v_sub_f32_e32 v78, v76, v78
	v_add_f32_e32 v80, v78, v79
	v_frexp_mant_f32_e32 v78, v77
	v_cmp_gt_f32_e32 vcc, s46, v78
	v_cvt_f64_f32_e32 v[78:79], v77
	v_frexp_exp_i32_f64_e32 v78, v[78:79]
	v_subbrev_co_u32_e32 v86, vcc, 0, v78, vcc
	v_sub_u32_e32 v78, 0, v86
	v_ldexp_f32 v77, v77, v78
	v_ldexp_f32 v78, v80, v78
	v_add_f32_e32 v80, -1.0, v77
	v_add_f32_e32 v79, 1.0, v80
	v_sub_f32_e32 v79, v77, v79
	v_add_f32_e32 v81, v78, v79
	v_add_f32_e32 v79, 1.0, v77
	v_add_f32_e32 v82, -1.0, v79
	v_sub_f32_e32 v77, v77, v82
	v_add_f32_e32 v77, v78, v77
	v_add_f32_e32 v87, v79, v77
	v_rcp_f32_e32 v88, v87
	v_sub_f32_e32 v78, v87, v79
	v_add_f32_e32 v79, v80, v81
	v_sub_f32_e32 v77, v77, v78
	v_mul_f32_e32 v90, v79, v88
	v_sub_f32_e32 v78, v79, v80
	v_mul_f32_e32 v80, v87, v90
	v_fma_f32 v82, v90, v87, -v80
	v_fmac_f32_e32 v82, v90, v77
	v_sub_f32_e32 v89, v81, v78
	v_add_f32_e32 v78, v80, v82
	v_sub_f32_e32 v81, v79, v78
	v_pk_add_f32 v[84:85], v[78:79], v[80:81] neg_lo:[0,1] neg_hi:[0,1]
	v_mov_b32_e32 v83, v78
	v_pk_add_f32 v[78:79], v[84:85], v[82:83] neg_lo:[0,1] neg_hi:[0,1]
	v_cmp_neq_f32_e32 vcc, s0, v76
	v_add_f32_e32 v79, v89, v79
	v_add_f32_e32 v78, v78, v79
	v_add_f32_e32 v79, v81, v78
	v_mul_f32_e32 v89, v88, v79
	v_mul_f32_e32 v80, v87, v89
	v_fma_f32 v82, v89, v87, -v80
	v_fmac_f32_e32 v82, v89, v77
	v_sub_f32_e32 v77, v81, v79
	v_add_f32_e32 v77, v78, v77
	v_add_f32_e32 v78, v80, v82
	v_sub_f32_e32 v81, v79, v78
	v_pk_add_f32 v[84:85], v[78:79], v[80:81] neg_lo:[0,1] neg_hi:[0,1]
	v_mov_b32_e32 v83, v78
	v_pk_add_f32 v[78:79], v[84:85], v[82:83] neg_lo:[0,1] neg_hi:[0,1]
	s_nop 0
	v_add_f32_e32 v77, v77, v79
	v_add_f32_e32 v77, v78, v77
	v_add_f32_e32 v79, v90, v89
	v_add_f32_e32 v77, v81, v77
	v_sub_f32_e32 v78, v79, v90
	v_mul_f32_e32 v77, v88, v77
	v_sub_f32_e32 v78, v89, v78
	v_add_f32_e32 v77, v78, v77
	v_add_f32_e32 v80, v79, v77
	v_mul_f32_e32 v82, v80, v80
	v_fmamk_f32 v78, v82, 0x3e9b6dac, v210
	v_fmaak_f32 v121, v82, v78, 0x3f2aaada
	v_cvt_f32_i32_e32 v78, v86
	v_sub_f32_e32 v79, v80, v79
	v_sub_f32_e32 v77, v77, v79
	v_mul_f32_e32 v79, v80, v82
	v_pk_mul_f32 v[82:83], v[78:79], v[120:121]
	v_ldexp_f32 v81, v80, 1
	v_fma_f32 v80, v78, s1, -v82
	v_fmac_f32_e32 v80, 0xb102e308, v78
	v_pk_add_f32 v[78:79], v[82:83], v[80:81]
	v_ldexp_f32 v77, v77, 1
	v_sub_f32_e32 v81, v79, v81
	v_sub_f32_e32 v81, v83, v81
	v_add_f32_e32 v85, v77, v81
	v_mov_b32_e32 v84, v82
	v_pk_add_f32 v[82:83], v[78:79], v[82:83] neg_lo:[0,1] neg_hi:[0,1]
	v_pk_add_f32 v[86:87], v[78:79], v[84:85]
	v_mov_b32_e32 v81, v78
	v_mov_b32_e32 v83, v87
	v_pk_add_f32 v[88:89], v[80:81], v[82:83] neg_lo:[0,1] neg_hi:[0,1]
	v_pk_add_f32 v[80:81], v[80:81], v[82:83]
	v_mov_b32_e32 v84, v85
	v_pk_add_f32 v[82:83], v[80:81], v[78:79] op_sel:[1,0] op_sel_hi:[0,1] neg_lo:[0,1] neg_hi:[0,1]
	v_pk_add_f32 v[90:91], v[86:87], v[82:83] op_sel_hi:[1,0] neg_lo:[0,1] neg_hi:[0,1]
	v_mov_b32_e32 v86, v87
	v_mov_b32_e32 v87, v81
	v_pk_mov_b32 v[82:83], v[78:79], v[82:83] op_sel:[1,0]
	v_mov_b32_e32 v85, v78
	v_pk_add_f32 v[82:83], v[86:87], v[82:83] neg_lo:[0,1] neg_hi:[0,1]
	v_mov_b32_e32 v90, v88
	v_pk_add_f32 v[78:79], v[84:85], v[82:83] neg_lo:[0,1] neg_hi:[0,1]
	v_mov_b32_e32 v89, v81
	v_pk_add_f32 v[82:83], v[90:91], v[78:79]
	s_nop 0
	v_pk_add_f32 v[84:85], v[82:83], v[82:83] op_sel:[0,1] op_sel_hi:[1,0]
	s_nop 0
	v_pk_add_f32 v[80:81], v[80:81], v[84:85] op_sel:[1,0] op_sel_hi:[0,1]
	v_mov_b32_e32 v83, v80
	v_pk_add_f32 v[86:87], v[82:83], v[88:89] neg_lo:[0,1] neg_hi:[0,1]
	v_mov_b32_e32 v79, v84
	v_sub_f32_e32 v77, v82, v86
	v_pk_add_f32 v[78:79], v[78:79], v[86:87] neg_lo:[0,1] neg_hi:[0,1]
	v_sub_f32_e32 v77, v88, v77
	v_add_f32_e32 v77, v78, v77
	v_add_f32_e32 v77, v77, v79
	v_add_f32_e32 v77, v80, v77
	v_cndmask_b32_e32 v77, v224, v77, vcc
	v_cmp_ngt_f32_e32 vcc, -1.0, v76
	s_nop 1
	v_cndmask_b32_e32 v77, v225, v77, vcc
	v_cmp_neq_f32_e32 vcc, -1.0, v76
	s_nop 1
	v_cndmask_b32_e32 v77, v226, v77, vcc
	v_cmp_lt_f32_e64 vcc, |v76|, s56
	s_nop 1
	v_cndmask_b32_e32 v76, v77, v76, vcc
	v_add_f32_e32 v75, v75, v76

.LBB0_1322:
	s_and_b64 vcc, exec, s[4:5]
	v_or_b32_e32 v69, 34, v74
	s_cbranch_vccnz .LBB0_1719
	s_andn2_b64 vcc, exec, s[36:37]
	v_mov_b32_e32 v75, v20
	s_cbranch_vccnz .LBB0_1325
	s_nop 0
	v_lshl_add_u64 v[76:77], v[66:67], 0, s[80:81]
	s_waitcnt lgkmcnt(0)
	v_lshl_add_u64 v[76:77], v[76:77], 2, vcc
	v_mov_b32_e32 v75, v251
	s_nop 0
	v_add_f32_e32 v76, v20, v75
	v_max_f32_e32 v75, 0, v76
	v_mul_f32_e64 v76, |v76|, s73
	v_exp_f32_e32 v76, v76
	s_nop 0
	v_add_f32_e32 v77, 1.0, v76
	v_add_f32_e32 v78, -1.0, v77
	v_sub_f32_e32 v79, v78, v77
	v_add_f32_e32 v79, 1.0, v79
	v_sub_f32_e32 v78, v76, v78
	v_add_f32_e32 v80, v78, v79
	v_frexp_mant_f32_e32 v78, v77
	v_cmp_gt_f32_e32 vcc, s46, v78
	v_cvt_f64_f32_e32 v[78:79], v77
	v_frexp_exp_i32_f64_e32 v78, v[78:79]
	v_subbrev_co_u32_e32 v86, vcc, 0, v78, vcc
	v_sub_u32_e32 v78, 0, v86
	v_ldexp_f32 v77, v77, v78
	v_ldexp_f32 v78, v80, v78
	v_add_f32_e32 v80, -1.0, v77
	v_add_f32_e32 v79, 1.0, v80
	v_sub_f32_e32 v79, v77, v79
	v_add_f32_e32 v81, v78, v79
	v_add_f32_e32 v79, 1.0, v77
	v_add_f32_e32 v82, -1.0, v79
	v_sub_f32_e32 v77, v77, v82
	v_add_f32_e32 v77, v78, v77
	v_add_f32_e32 v87, v79, v77
	v_rcp_f32_e32 v88, v87
	v_sub_f32_e32 v78, v87, v79
	v_add_f32_e32 v79, v80, v81
	v_sub_f32_e32 v77, v77, v78
	v_mul_f32_e32 v90, v79, v88
	v_sub_f32_e32 v78, v79, v80
	v_mul_f32_e32 v80, v87, v90
	v_fma_f32 v82, v90, v87, -v80
	v_fmac_f32_e32 v82, v90, v77
	v_sub_f32_e32 v89, v81, v78
	v_add_f32_e32 v78, v80, v82
	v_sub_f32_e32 v81, v79, v78
	v_pk_add_f32 v[84:85], v[78:79], v[80:81] neg_lo:[0,1] neg_hi:[0,1]
	v_mov_b32_e32 v83, v78
	v_pk_add_f32 v[78:79], v[84:85], v[82:83] neg_lo:[0,1] neg_hi:[0,1]
	v_cmp_neq_f32_e32 vcc, s0, v76
	v_add_f32_e32 v79, v89, v79
	v_add_f32_e32 v78, v78, v79
	v_add_f32_e32 v79, v81, v78
	v_mul_f32_e32 v89, v88, v79
	v_mul_f32_e32 v80, v87, v89
	v_fma_f32 v82, v89, v87, -v80
	v_fmac_f32_e32 v82, v89, v77
	v_sub_f32_e32 v77, v81, v79
	v_add_f32_e32 v77, v78, v77
	v_add_f32_e32 v78, v80, v82
	v_sub_f32_e32 v81, v79, v78
	v_pk_add_f32 v[84:85], v[78:79], v[80:81] neg_lo:[0,1] neg_hi:[0,1]
	v_mov_b32_e32 v83, v78
	v_pk_add_f32 v[78:79], v[84:85], v[82:83] neg_lo:[0,1] neg_hi:[0,1]
	s_nop 0
	v_add_f32_e32 v77, v77, v79
	v_add_f32_e32 v77, v78, v77
	v_add_f32_e32 v79, v90, v89
	v_add_f32_e32 v77, v81, v77
	v_sub_f32_e32 v78, v79, v90
	v_mul_f32_e32 v77, v88, v77
	v_sub_f32_e32 v78, v89, v78
	v_add_f32_e32 v77, v78, v77
	v_add_f32_e32 v80, v79, v77
	v_mul_f32_e32 v82, v80, v80
	v_fmamk_f32 v78, v82, 0x3e9b6dac, v210
	v_fmaak_f32 v121, v82, v78, 0x3f2aaada
	v_cvt_f32_i32_e32 v78, v86
	v_sub_f32_e32 v79, v80, v79
	v_sub_f32_e32 v77, v77, v79
	v_mul_f32_e32 v79, v80, v82
	v_pk_mul_f32 v[82:83], v[78:79], v[120:121]
	v_ldexp_f32 v81, v80, 1
	v_fma_f32 v80, v78, s1, -v82
	v_fmac_f32_e32 v80, 0xb102e308, v78
	v_pk_add_f32 v[78:79], v[82:83], v[80:81]
	v_ldexp_f32 v77, v77, 1
	v_sub_f32_e32 v81, v79, v81
	v_sub_f32_e32 v81, v83, v81
	v_add_f32_e32 v85, v77, v81
	v_mov_b32_e32 v84, v82
	v_pk_add_f32 v[82:83], v[78:79], v[82:83] neg_lo:[0,1] neg_hi:[0,1]
	v_pk_add_f32 v[86:87], v[78:79], v[84:85]
	v_mov_b32_e32 v81, v78
	v_mov_b32_e32 v83, v87
	v_pk_add_f32 v[88:89], v[80:81], v[82:83] neg_lo:[0,1] neg_hi:[0,1]
	v_pk_add_f32 v[80:81], v[80:81], v[82:83]
	v_mov_b32_e32 v84, v85
	v_pk_add_f32 v[82:83], v[80:81], v[78:79] op_sel:[1,0] op_sel_hi:[0,1] neg_lo:[0,1] neg_hi:[0,1]
	v_pk_add_f32 v[90:91], v[86:87], v[82:83] op_sel_hi:[1,0] neg_lo:[0,1] neg_hi:[0,1]
	v_mov_b32_e32 v86, v87
	v_mov_b32_e32 v87, v81
	v_pk_mov_b32 v[82:83], v[78:79], v[82:83] op_sel:[1,0]
	v_mov_b32_e32 v85, v78
	v_pk_add_f32 v[82:83], v[86:87], v[82:83] neg_lo:[0,1] neg_hi:[0,1]
	v_mov_b32_e32 v90, v88
	v_pk_add_f32 v[78:79], v[84:85], v[82:83] neg_lo:[0,1] neg_hi:[0,1]
	v_mov_b32_e32 v89, v81
	v_pk_add_f32 v[82:83], v[90:91], v[78:79]
	s_nop 0
	v_pk_add_f32 v[84:85], v[82:83], v[82:83] op_sel:[0,1] op_sel_hi:[1,0]
	s_nop 0
	v_pk_add_f32 v[80:81], v[80:81], v[84:85] op_sel:[1,0] op_sel_hi:[0,1]
	v_mov_b32_e32 v83, v80
	v_pk_add_f32 v[86:87], v[82:83], v[88:89] neg_lo:[0,1] neg_hi:[0,1]
	v_mov_b32_e32 v79, v84
	v_sub_f32_e32 v77, v82, v86
	v_pk_add_f32 v[78:79], v[78:79], v[86:87] neg_lo:[0,1] neg_hi:[0,1]
	v_sub_f32_e32 v77, v88, v77
	v_add_f32_e32 v77, v78, v77
	v_add_f32_e32 v77, v77, v79
	v_add_f32_e32 v77, v80, v77
	v_cndmask_b32_e32 v77, v224, v77, vcc
	v_cmp_ngt_f32_e32 vcc, -1.0, v76
	s_nop 1
	v_cndmask_b32_e32 v77, v225, v77, vcc
	v_cmp_neq_f32_e32 vcc, -1.0, v76
	s_nop 1
	v_cndmask_b32_e32 v77, v226, v77, vcc
	v_cmp_lt_f32_e64 vcc, |v76|, s56
	s_nop 1
	v_cndmask_b32_e32 v76, v77, v76, vcc
	v_add_f32_e32 v75, v75, v76

.LBB0_1327:
	s_and_b64 vcc, exec, s[4:5]
	v_or_b32_e32 v69, 35, v74
	s_cbranch_vccnz .LBB0_1720
	s_andn2_b64 vcc, exec, s[36:37]
	v_mov_b32_e32 v75, v21
	s_cbranch_vccnz .LBB0_1330
	s_nop 0
	v_lshl_add_u64 v[76:77], v[66:67], 0, s[80:81]
	s_waitcnt lgkmcnt(0)
	v_lshl_add_u64 v[76:77], v[76:77], 2, vcc
	v_mov_b32_e32 v75, v251
	s_nop 0
	v_add_f32_e32 v76, v21, v75
	v_max_f32_e32 v75, 0, v76
	v_mul_f32_e64 v76, |v76|, s73
	v_exp_f32_e32 v76, v76
	s_nop 0
	v_add_f32_e32 v77, 1.0, v76
	v_add_f32_e32 v78, -1.0, v77
	v_sub_f32_e32 v79, v78, v77
	v_add_f32_e32 v79, 1.0, v79
	v_sub_f32_e32 v78, v76, v78
	v_add_f32_e32 v80, v78, v79
	v_frexp_mant_f32_e32 v78, v77
	v_cmp_gt_f32_e32 vcc, s46, v78
	v_cvt_f64_f32_e32 v[78:79], v77
	v_frexp_exp_i32_f64_e32 v78, v[78:79]
	v_subbrev_co_u32_e32 v86, vcc, 0, v78, vcc
	v_sub_u32_e32 v78, 0, v86
	v_ldexp_f32 v77, v77, v78
	v_ldexp_f32 v78, v80, v78
	v_add_f32_e32 v80, -1.0, v77
	v_add_f32_e32 v79, 1.0, v80
	v_sub_f32_e32 v79, v77, v79
	v_add_f32_e32 v81, v78, v79
	v_add_f32_e32 v79, 1.0, v77
	v_add_f32_e32 v82, -1.0, v79
	v_sub_f32_e32 v77, v77, v82
	v_add_f32_e32 v77, v78, v77
	v_add_f32_e32 v87, v79, v77
	v_rcp_f32_e32 v88, v87
	v_sub_f32_e32 v78, v87, v79
	v_add_f32_e32 v79, v80, v81
	v_sub_f32_e32 v77, v77, v78
	v_mul_f32_e32 v90, v79, v88
	v_sub_f32_e32 v78, v79, v80
	v_mul_f32_e32 v80, v87, v90
	v_fma_f32 v82, v90, v87, -v80
	v_fmac_f32_e32 v82, v90, v77
	v_sub_f32_e32 v89, v81, v78
	v_add_f32_e32 v78, v80, v82
	v_sub_f32_e32 v81, v79, v78
	v_pk_add_f32 v[84:85], v[78:79], v[80:81] neg_lo:[0,1] neg_hi:[0,1]
	v_mov_b32_e32 v83, v78
	v_pk_add_f32 v[78:79], v[84:85], v[82:83] neg_lo:[0,1] neg_hi:[0,1]
	v_cmp_neq_f32_e32 vcc, s0, v76
	v_add_f32_e32 v79, v89, v79
	v_add_f32_e32 v78, v78, v79
	v_add_f32_e32 v79, v81, v78
	v_mul_f32_e32 v89, v88, v79
	v_mul_f32_e32 v80, v87, v89
	v_fma_f32 v82, v89, v87, -v80
	v_fmac_f32_e32 v82, v89, v77
	v_sub_f32_e32 v77, v81, v79
	v_add_f32_e32 v77, v78, v77
	v_add_f32_e32 v78, v80, v82
	v_sub_f32_e32 v81, v79, v78
	v_pk_add_f32 v[84:85], v[78:79], v[80:81] neg_lo:[0,1] neg_hi:[0,1]
	v_mov_b32_e32 v83, v78
	v_pk_add_f32 v[78:79], v[84:85], v[82:83] neg_lo:[0,1] neg_hi:[0,1]
	s_nop 0
	v_add_f32_e32 v77, v77, v79
	v_add_f32_e32 v77, v78, v77
	v_add_f32_e32 v79, v90, v89
	v_add_f32_e32 v77, v81, v77
	v_sub_f32_e32 v78, v79, v90
	v_mul_f32_e32 v77, v88, v77
	v_sub_f32_e32 v78, v89, v78
	v_add_f32_e32 v77, v78, v77
	v_add_f32_e32 v80, v79, v77
	v_mul_f32_e32 v82, v80, v80
	v_fmamk_f32 v78, v82, 0x3e9b6dac, v210
	v_fmaak_f32 v121, v82, v78, 0x3f2aaada
	v_cvt_f32_i32_e32 v78, v86
	v_sub_f32_e32 v79, v80, v79
	v_sub_f32_e32 v77, v77, v79
	v_mul_f32_e32 v79, v80, v82
	v_pk_mul_f32 v[82:83], v[78:79], v[120:121]
	v_ldexp_f32 v81, v80, 1
	v_fma_f32 v80, v78, s1, -v82
	v_fmac_f32_e32 v80, 0xb102e308, v78
	v_pk_add_f32 v[78:79], v[82:83], v[80:81]
	v_ldexp_f32 v77, v77, 1
	v_sub_f32_e32 v81, v79, v81
	v_sub_f32_e32 v81, v83, v81
	v_add_f32_e32 v85, v77, v81
	v_mov_b32_e32 v84, v82
	v_pk_add_f32 v[82:83], v[78:79], v[82:83] neg_lo:[0,1] neg_hi:[0,1]
	v_pk_add_f32 v[86:87], v[78:79], v[84:85]
	v_mov_b32_e32 v81, v78
	v_mov_b32_e32 v83, v87
	v_pk_add_f32 v[88:89], v[80:81], v[82:83] neg_lo:[0,1] neg_hi:[0,1]
	v_pk_add_f32 v[80:81], v[80:81], v[82:83]
	v_mov_b32_e32 v84, v85
	v_pk_add_f32 v[82:83], v[80:81], v[78:79] op_sel:[1,0] op_sel_hi:[0,1] neg_lo:[0,1] neg_hi:[0,1]
	v_pk_add_f32 v[90:91], v[86:87], v[82:83] op_sel_hi:[1,0] neg_lo:[0,1] neg_hi:[0,1]
	v_mov_b32_e32 v86, v87
	v_mov_b32_e32 v87, v81
	v_pk_mov_b32 v[82:83], v[78:79], v[82:83] op_sel:[1,0]
	v_mov_b32_e32 v85, v78
	v_pk_add_f32 v[82:83], v[86:87], v[82:83] neg_lo:[0,1] neg_hi:[0,1]
	v_mov_b32_e32 v90, v88
	v_pk_add_f32 v[78:79], v[84:85], v[82:83] neg_lo:[0,1] neg_hi:[0,1]
	v_mov_b32_e32 v89, v81
	v_pk_add_f32 v[82:83], v[90:91], v[78:79]
	s_nop 0
	v_pk_add_f32 v[84:85], v[82:83], v[82:83] op_sel:[0,1] op_sel_hi:[1,0]
	s_nop 0
	v_pk_add_f32 v[80:81], v[80:81], v[84:85] op_sel:[1,0] op_sel_hi:[0,1]
	v_mov_b32_e32 v83, v80
	v_pk_add_f32 v[86:87], v[82:83], v[88:89] neg_lo:[0,1] neg_hi:[0,1]
	v_mov_b32_e32 v79, v84
	v_sub_f32_e32 v77, v82, v86
	v_pk_add_f32 v[78:79], v[78:79], v[86:87] neg_lo:[0,1] neg_hi:[0,1]
	v_sub_f32_e32 v77, v88, v77
	v_add_f32_e32 v77, v78, v77
	v_add_f32_e32 v77, v77, v79
	v_add_f32_e32 v77, v80, v77
	v_cndmask_b32_e32 v77, v224, v77, vcc
	v_cmp_ngt_f32_e32 vcc, -1.0, v76
	s_nop 1
	v_cndmask_b32_e32 v77, v225, v77, vcc
	v_cmp_neq_f32_e32 vcc, -1.0, v76
	s_nop 1
	v_cndmask_b32_e32 v77, v226, v77, vcc
	v_cmp_lt_f32_e64 vcc, |v76|, s56
	s_nop 1
	v_cndmask_b32_e32 v76, v77, v76, vcc
	v_add_f32_e32 v75, v75, v76

.LBB0_1332:
	s_or_b64 exec, exec, s[58:59]
	v_or_b32_e32 v75, 48, v74
	s_and_saveexec_b64 s[58:59], s[6:7]
	s_cbranch_execz .LBB0_1353
	v_ashrrev_i32_e32 v69, 31, v68
	s_and_b64 vcc, exec, s[4:5]
	v_lshl_add_u64 v[70:71], v[66:67], 2, s[34:35]
	s_cbranch_vccnz .LBB0_1721
	s_andn2_b64 vcc, exec, s[36:37]
	v_mov_b32_e32 v72, v12
	s_cbranch_vccnz .LBB0_1336
	s_nop 0
	s_waitcnt lgkmcnt(0)
	v_lshl_add_u64 v[72:73], v[68:69], 2, s[6:7]
	v_mov_b32_e32 v72, v248
	s_nop 0
	v_add_f32_e32 v73, v12, v72
	v_max_f32_e32 v72, 0, v73
	v_mul_f32_e64 v73, |v73|, s73
	v_exp_f32_e32 v73, v73
	s_nop 0
	v_add_f32_e32 v78, 1.0, v73
	v_add_f32_e32 v76, -1.0, v78
	v_sub_f32_e32 v77, v76, v78
	v_add_f32_e32 v77, 1.0, v77
	v_sub_f32_e32 v76, v73, v76
	v_add_f32_e32 v79, v76, v77
	v_frexp_mant_f32_e32 v76, v78
	v_cmp_gt_f32_e32 vcc, s46, v76
	v_cvt_f64_f32_e32 v[76:77], v78
	v_frexp_exp_i32_f64_e32 v76, v[76:77]
	v_subbrev_co_u32_e32 v84, vcc, 0, v76, vcc
	v_sub_u32_e32 v76, 0, v84
	v_ldexp_f32 v77, v78, v76
	v_add_f32_e32 v78, -1.0, v77
	v_add_f32_e32 v80, 1.0, v77
	v_ldexp_f32 v76, v79, v76
	v_add_f32_e32 v79, 1.0, v78
	v_add_f32_e32 v81, -1.0, v80
	v_sub_f32_e32 v79, v77, v79
	v_sub_f32_e32 v77, v77, v81
	v_add_f32_e32 v79, v76, v79
	v_add_f32_e32 v76, v76, v77
	v_add_f32_e32 v85, v80, v76
	v_rcp_f32_e32 v87, v85
	v_sub_f32_e32 v77, v85, v80
	v_sub_f32_e32 v86, v76, v77
	v_add_f32_e32 v77, v78, v79
	v_mul_f32_e32 v89, v77, v87
	v_sub_f32_e32 v76, v77, v78
	v_mul_f32_e32 v78, v85, v89
	v_fma_f32 v80, v89, v85, -v78
	v_fmac_f32_e32 v80, v89, v86
	v_sub_f32_e32 v88, v79, v76
	v_add_f32_e32 v76, v78, v80
	v_sub_f32_e32 v79, v77, v76
	v_pk_add_f32 v[82:83], v[76:77], v[78:79] neg_lo:[0,1] neg_hi:[0,1]
	v_mov_b32_e32 v81, v76
	v_pk_add_f32 v[76:77], v[82:83], v[80:81] neg_lo:[0,1] neg_hi:[0,1]
	v_cmp_neq_f32_e32 vcc, s0, v73
	v_add_f32_e32 v77, v88, v77
	v_add_f32_e32 v76, v76, v77
	v_add_f32_e32 v77, v79, v76
	v_mul_f32_e32 v88, v87, v77
	v_mul_f32_e32 v78, v85, v88
	v_fma_f32 v80, v88, v85, -v78
	v_fmac_f32_e32 v80, v88, v86
	v_sub_f32_e32 v79, v79, v77
	v_add_f32_e32 v85, v76, v79
	v_add_f32_e32 v76, v78, v80
	v_sub_f32_e32 v79, v77, v76
	v_pk_add_f32 v[82:83], v[76:77], v[78:79] neg_lo:[0,1] neg_hi:[0,1]
	v_mov_b32_e32 v81, v76
	v_pk_add_f32 v[76:77], v[82:83], v[80:81] neg_lo:[0,1] neg_hi:[0,1]
	s_nop 0
	v_add_f32_e32 v77, v85, v77
	v_add_f32_e32 v76, v76, v77
	v_add_f32_e32 v77, v89, v88
	v_add_f32_e32 v76, v79, v76
	v_sub_f32_e32 v78, v77, v89
	v_mul_f32_e32 v76, v87, v76
	v_sub_f32_e32 v78, v88, v78
	v_add_f32_e32 v78, v78, v76
	v_add_f32_e32 v80, v77, v78
	v_mul_f32_e32 v81, v80, v80
	v_fmamk_f32 v76, v81, 0x3e9b6dac, v210
	v_fmaak_f32 v121, v81, v76, 0x3f2aaada
	v_cvt_f32_i32_e32 v76, v84
	v_sub_f32_e32 v77, v80, v77
	v_sub_f32_e32 v77, v78, v77
	v_ldexp_f32 v82, v77, 1
	v_mul_f32_e32 v77, v80, v81
	v_ldexp_f32 v79, v80, 1
	v_pk_mul_f32 v[80:81], v[76:77], v[120:121]
	s_nop 0
	v_fma_f32 v78, v76, s1, -v80
	v_fmac_f32_e32 v78, 0xb102e308, v76
	v_pk_add_f32 v[76:77], v[80:81], v[78:79]
	s_nop 0
	v_sub_f32_e32 v79, v77, v79
	v_sub_f32_e32 v79, v81, v79
	v_add_f32_e32 v83, v82, v79
	v_mov_b32_e32 v82, v80
	v_pk_add_f32 v[80:81], v[76:77], v[80:81] neg_lo:[0,1] neg_hi:[0,1]
	v_pk_add_f32 v[84:85], v[76:77], v[82:83]
	v_mov_b32_e32 v79, v76
	v_mov_b32_e32 v81, v85
	v_pk_add_f32 v[86:87], v[78:79], v[80:81] neg_lo:[0,1] neg_hi:[0,1]
	v_pk_add_f32 v[78:79], v[78:79], v[80:81]
	v_mov_b32_e32 v82, v83
	v_pk_add_f32 v[80:81], v[78:79], v[76:77] op_sel:[1,0] op_sel_hi:[0,1] neg_lo:[0,1] neg_hi:[0,1]
	v_pk_add_f32 v[88:89], v[84:85], v[80:81] op_sel_hi:[1,0] neg_lo:[0,1] neg_hi:[0,1]
	v_mov_b32_e32 v84, v85
	v_mov_b32_e32 v85, v79
	v_pk_mov_b32 v[80:81], v[76:77], v[80:81] op_sel:[1,0]
	v_mov_b32_e32 v83, v76
	v_pk_add_f32 v[80:81], v[84:85], v[80:81] neg_lo:[0,1] neg_hi:[0,1]
	v_mov_b32_e32 v88, v86
	v_pk_add_f32 v[76:77], v[82:83], v[80:81] neg_lo:[0,1] neg_hi:[0,1]
	v_mov_b32_e32 v87, v79
	v_pk_add_f32 v[80:81], v[88:89], v[76:77]
	s_nop 0
	v_pk_add_f32 v[82:83], v[80:81], v[80:81] op_sel:[0,1] op_sel_hi:[1,0]
	s_nop 0
	v_pk_add_f32 v[78:79], v[78:79], v[82:83] op_sel:[1,0] op_sel_hi:[0,1]
	v_mov_b32_e32 v81, v78
	v_pk_add_f32 v[84:85], v[80:81], v[86:87] neg_lo:[0,1] neg_hi:[0,1]
	v_mov_b32_e32 v77, v82
	v_sub_f32_e32 v79, v80, v84
	v_pk_add_f32 v[76:77], v[76:77], v[84:85] neg_lo:[0,1] neg_hi:[0,1]
	v_sub_f32_e32 v79, v86, v79
	v_add_f32_e32 v76, v76, v79
	v_add_f32_e32 v76, v76, v77
	v_add_f32_e32 v76, v78, v76
	v_cndmask_b32_e32 v76, v224, v76, vcc
	v_cmp_ngt_f32_e32 vcc, -1.0, v73
	s_nop 1
	v_cndmask_b32_e32 v76, v225, v76, vcc
	v_cmp_neq_f32_e32 vcc, -1.0, v73
	s_nop 1
	v_cndmask_b32_e32 v76, v226, v76, vcc
	v_cmp_lt_f32_e64 vcc, |v73|, s56
	s_nop 1
	v_cndmask_b32_e32 v73, v76, v73, vcc
	v_add_f32_e32 v72, v72, v73

.LBB0_1338:
	s_and_b64 vcc, exec, s[4:5]
	v_or_b32_e32 v76, 49, v74
	s_cbranch_vccnz .LBB0_1722
	s_andn2_b64 vcc, exec, s[36:37]
	v_mov_b32_e32 v77, v13
	s_cbranch_vccnz .LBB0_1341
	s_nop 0
	s_waitcnt vmcnt(4) lgkmcnt(0)
	v_lshl_add_u64 v[78:79], v[68:69], 2, s[6:7]
	v_mov_b32_e32 v77, v248
	s_nop 0
	v_add_f32_e32 v78, v13, v77
	v_max_f32_e32 v77, 0, v78
	v_mul_f32_e64 v78, |v78|, s73
	v_exp_f32_e32 v78, v78
	s_nop 0
	v_add_f32_e32 v79, 1.0, v78
	v_add_f32_e32 v80, -1.0, v79
	v_sub_f32_e32 v81, v80, v79
	v_add_f32_e32 v81, 1.0, v81
	v_sub_f32_e32 v80, v78, v80
	v_add_f32_e32 v82, v80, v81
	v_frexp_mant_f32_e32 v80, v79
	v_cmp_gt_f32_e32 vcc, s46, v80
	v_cvt_f64_f32_e32 v[80:81], v79
	v_frexp_exp_i32_f64_e32 v80, v[80:81]
	v_subbrev_co_u32_e32 v88, vcc, 0, v80, vcc
	v_sub_u32_e32 v80, 0, v88
	v_ldexp_f32 v79, v79, v80
	v_ldexp_f32 v80, v82, v80
	v_add_f32_e32 v82, -1.0, v79
	v_add_f32_e32 v81, 1.0, v82
	v_sub_f32_e32 v81, v79, v81
	v_add_f32_e32 v83, v80, v81
	v_add_f32_e32 v81, 1.0, v79
	v_add_f32_e32 v84, -1.0, v81
	v_sub_f32_e32 v79, v79, v84
	v_add_f32_e32 v79, v80, v79
	v_add_f32_e32 v89, v81, v79
	v_rcp_f32_e32 v90, v89
	v_sub_f32_e32 v80, v89, v81
	v_add_f32_e32 v81, v82, v83
	v_sub_f32_e32 v79, v79, v80
	v_mul_f32_e32 v92, v81, v90
	v_sub_f32_e32 v80, v81, v82
	v_mul_f32_e32 v82, v89, v92
	v_fma_f32 v84, v92, v89, -v82
	v_fmac_f32_e32 v84, v92, v79
	v_sub_f32_e32 v91, v83, v80
	v_add_f32_e32 v80, v82, v84
	v_sub_f32_e32 v83, v81, v80
	v_pk_add_f32 v[86:87], v[80:81], v[82:83] neg_lo:[0,1] neg_hi:[0,1]
	v_mov_b32_e32 v85, v80
	v_pk_add_f32 v[80:81], v[86:87], v[84:85] neg_lo:[0,1] neg_hi:[0,1]
	v_cmp_neq_f32_e32 vcc, s0, v78
	v_add_f32_e32 v81, v91, v81
	v_add_f32_e32 v80, v80, v81
	v_add_f32_e32 v81, v83, v80
	v_mul_f32_e32 v91, v90, v81
	v_mul_f32_e32 v82, v89, v91
	v_fma_f32 v84, v91, v89, -v82
	v_fmac_f32_e32 v84, v91, v79
	v_sub_f32_e32 v79, v83, v81
	v_add_f32_e32 v79, v80, v79
	v_add_f32_e32 v80, v82, v84
	v_sub_f32_e32 v83, v81, v80
	v_pk_add_f32 v[86:87], v[80:81], v[82:83] neg_lo:[0,1] neg_hi:[0,1]
	v_mov_b32_e32 v85, v80
	v_pk_add_f32 v[80:81], v[86:87], v[84:85] neg_lo:[0,1] neg_hi:[0,1]
	s_nop 0
	v_add_f32_e32 v79, v79, v81
	v_add_f32_e32 v79, v80, v79
	v_add_f32_e32 v81, v92, v91
	v_add_f32_e32 v79, v83, v79
	v_sub_f32_e32 v80, v81, v92
	v_mul_f32_e32 v79, v90, v79
	v_sub_f32_e32 v80, v91, v80
	v_add_f32_e32 v79, v80, v79
	v_add_f32_e32 v82, v81, v79
	v_mul_f32_e32 v84, v82, v82
	v_fmamk_f32 v80, v84, 0x3e9b6dac, v210
	v_fmaak_f32 v121, v84, v80, 0x3f2aaada
	v_cvt_f32_i32_e32 v80, v88
	v_sub_f32_e32 v81, v82, v81
	v_sub_f32_e32 v79, v79, v81
	v_mul_f32_e32 v81, v82, v84
	v_pk_mul_f32 v[84:85], v[80:81], v[120:121]
	v_ldexp_f32 v83, v82, 1
	v_fma_f32 v82, v80, s1, -v84
	v_fmac_f32_e32 v82, 0xb102e308, v80
	v_pk_add_f32 v[80:81], v[84:85], v[82:83]
	v_ldexp_f32 v79, v79, 1
	v_sub_f32_e32 v83, v81, v83
	v_sub_f32_e32 v83, v85, v83
	v_add_f32_e32 v87, v79, v83
	v_mov_b32_e32 v86, v84
	v_pk_add_f32 v[84:85], v[80:81], v[84:85] neg_lo:[0,1] neg_hi:[0,1]
	v_pk_add_f32 v[88:89], v[80:81], v[86:87]
	v_mov_b32_e32 v83, v80
	v_mov_b32_e32 v85, v89
	v_pk_add_f32 v[90:91], v[82:83], v[84:85] neg_lo:[0,1] neg_hi:[0,1]
	v_pk_add_f32 v[82:83], v[82:83], v[84:85]
	v_mov_b32_e32 v86, v87
	v_pk_add_f32 v[84:85], v[82:83], v[80:81] op_sel:[1,0] op_sel_hi:[0,1] neg_lo:[0,1] neg_hi:[0,1]
	v_pk_add_f32 v[92:93], v[88:89], v[84:85] op_sel_hi:[1,0] neg_lo:[0,1] neg_hi:[0,1]
	v_mov_b32_e32 v88, v89
	v_mov_b32_e32 v89, v83
	v_pk_mov_b32 v[84:85], v[80:81], v[84:85] op_sel:[1,0]
	v_mov_b32_e32 v87, v80
	v_pk_add_f32 v[84:85], v[88:89], v[84:85] neg_lo:[0,1] neg_hi:[0,1]
	v_mov_b32_e32 v92, v90
	v_pk_add_f32 v[80:81], v[86:87], v[84:85] neg_lo:[0,1] neg_hi:[0,1]
	v_mov_b32_e32 v91, v83
	v_pk_add_f32 v[84:85], v[92:93], v[80:81]
	s_nop 0
	v_pk_add_f32 v[86:87], v[84:85], v[84:85] op_sel:[0,1] op_sel_hi:[1,0]
	s_nop 0
	v_pk_add_f32 v[82:83], v[82:83], v[86:87] op_sel:[1,0] op_sel_hi:[0,1]
	v_mov_b32_e32 v85, v82
	v_pk_add_f32 v[88:89], v[84:85], v[90:91] neg_lo:[0,1] neg_hi:[0,1]
	v_mov_b32_e32 v81, v86
	v_sub_f32_e32 v79, v84, v88
	v_pk_add_f32 v[80:81], v[80:81], v[88:89] neg_lo:[0,1] neg_hi:[0,1]
	v_sub_f32_e32 v79, v90, v79
	v_add_f32_e32 v79, v80, v79
	v_add_f32_e32 v79, v79, v81
	v_add_f32_e32 v79, v82, v79
	v_cndmask_b32_e32 v79, v224, v79, vcc
	v_cmp_ngt_f32_e32 vcc, -1.0, v78
	s_nop 1
	v_cndmask_b32_e32 v79, v225, v79, vcc
	v_cmp_neq_f32_e32 vcc, -1.0, v78
	s_nop 1
	v_cndmask_b32_e32 v79, v226, v79, vcc
	v_cmp_lt_f32_e64 vcc, |v78|, s56
	s_nop 1
	v_cndmask_b32_e32 v78, v79, v78, vcc
	v_add_f32_e32 v77, v77, v78

.LBB0_1343:
	s_and_b64 vcc, exec, s[4:5]
	v_or_b32_e32 v76, 50, v74
	s_cbranch_vccnz .LBB0_1723
	s_andn2_b64 vcc, exec, s[36:37]
	v_mov_b32_e32 v77, v14
	s_cbranch_vccnz .LBB0_1346
	s_nop 0
	s_waitcnt vmcnt(4) lgkmcnt(0)
	v_lshl_add_u64 v[78:79], v[68:69], 2, s[6:7]
	v_mov_b32_e32 v77, v248
	s_nop 0
	v_add_f32_e32 v78, v14, v77
	v_max_f32_e32 v77, 0, v78
	v_mul_f32_e64 v78, |v78|, s73
	v_exp_f32_e32 v78, v78
	s_nop 0
	v_add_f32_e32 v79, 1.0, v78
	v_add_f32_e32 v80, -1.0, v79
	v_sub_f32_e32 v81, v80, v79
	v_add_f32_e32 v81, 1.0, v81
	v_sub_f32_e32 v80, v78, v80
	v_add_f32_e32 v82, v80, v81
	v_frexp_mant_f32_e32 v80, v79
	v_cmp_gt_f32_e32 vcc, s46, v80
	v_cvt_f64_f32_e32 v[80:81], v79
	v_frexp_exp_i32_f64_e32 v80, v[80:81]
	v_subbrev_co_u32_e32 v88, vcc, 0, v80, vcc
	v_sub_u32_e32 v80, 0, v88
	v_ldexp_f32 v79, v79, v80
	v_ldexp_f32 v80, v82, v80
	v_add_f32_e32 v82, -1.0, v79
	v_add_f32_e32 v81, 1.0, v82
	v_sub_f32_e32 v81, v79, v81
	v_add_f32_e32 v83, v80, v81
	v_add_f32_e32 v81, 1.0, v79
	v_add_f32_e32 v84, -1.0, v81
	v_sub_f32_e32 v79, v79, v84
	v_add_f32_e32 v79, v80, v79
	v_add_f32_e32 v89, v81, v79
	v_rcp_f32_e32 v90, v89
	v_sub_f32_e32 v80, v89, v81
	v_add_f32_e32 v81, v82, v83
	v_sub_f32_e32 v79, v79, v80
	v_mul_f32_e32 v92, v81, v90
	v_sub_f32_e32 v80, v81, v82
	v_mul_f32_e32 v82, v89, v92
	v_fma_f32 v84, v92, v89, -v82
	v_fmac_f32_e32 v84, v92, v79
	v_sub_f32_e32 v91, v83, v80
	v_add_f32_e32 v80, v82, v84
	v_sub_f32_e32 v83, v81, v80
	v_pk_add_f32 v[86:87], v[80:81], v[82:83] neg_lo:[0,1] neg_hi:[0,1]
	v_mov_b32_e32 v85, v80
	v_pk_add_f32 v[80:81], v[86:87], v[84:85] neg_lo:[0,1] neg_hi:[0,1]
	v_cmp_neq_f32_e32 vcc, s0, v78
	v_add_f32_e32 v81, v91, v81
	v_add_f32_e32 v80, v80, v81
	v_add_f32_e32 v81, v83, v80
	v_mul_f32_e32 v91, v90, v81
	v_mul_f32_e32 v82, v89, v91
	v_fma_f32 v84, v91, v89, -v82
	v_fmac_f32_e32 v84, v91, v79
	v_sub_f32_e32 v79, v83, v81
	v_add_f32_e32 v79, v80, v79
	v_add_f32_e32 v80, v82, v84
	v_sub_f32_e32 v83, v81, v80
	v_pk_add_f32 v[86:87], v[80:81], v[82:83] neg_lo:[0,1] neg_hi:[0,1]
	v_mov_b32_e32 v85, v80
	v_pk_add_f32 v[80:81], v[86:87], v[84:85] neg_lo:[0,1] neg_hi:[0,1]
	s_nop 0
	v_add_f32_e32 v79, v79, v81
	v_add_f32_e32 v79, v80, v79
	v_add_f32_e32 v81, v92, v91
	v_add_f32_e32 v79, v83, v79
	v_sub_f32_e32 v80, v81, v92
	v_mul_f32_e32 v79, v90, v79
	v_sub_f32_e32 v80, v91, v80
	v_add_f32_e32 v79, v80, v79
	v_add_f32_e32 v82, v81, v79
	v_mul_f32_e32 v84, v82, v82
	v_fmamk_f32 v80, v84, 0x3e9b6dac, v210
	v_fmaak_f32 v121, v84, v80, 0x3f2aaada
	v_cvt_f32_i32_e32 v80, v88
	v_sub_f32_e32 v81, v82, v81
	v_sub_f32_e32 v79, v79, v81
	v_mul_f32_e32 v81, v82, v84
	v_pk_mul_f32 v[84:85], v[80:81], v[120:121]
	v_ldexp_f32 v83, v82, 1
	v_fma_f32 v82, v80, s1, -v84
	v_fmac_f32_e32 v82, 0xb102e308, v80
	v_pk_add_f32 v[80:81], v[84:85], v[82:83]
	v_ldexp_f32 v79, v79, 1
	v_sub_f32_e32 v83, v81, v83
	v_sub_f32_e32 v83, v85, v83
	v_add_f32_e32 v87, v79, v83
	v_mov_b32_e32 v86, v84
	v_pk_add_f32 v[84:85], v[80:81], v[84:85] neg_lo:[0,1] neg_hi:[0,1]
	v_pk_add_f32 v[88:89], v[80:81], v[86:87]
	v_mov_b32_e32 v83, v80
	v_mov_b32_e32 v85, v89
	v_pk_add_f32 v[90:91], v[82:83], v[84:85] neg_lo:[0,1] neg_hi:[0,1]
	v_pk_add_f32 v[82:83], v[82:83], v[84:85]
	v_mov_b32_e32 v86, v87
	v_pk_add_f32 v[84:85], v[82:83], v[80:81] op_sel:[1,0] op_sel_hi:[0,1] neg_lo:[0,1] neg_hi:[0,1]
	v_pk_add_f32 v[92:93], v[88:89], v[84:85] op_sel_hi:[1,0] neg_lo:[0,1] neg_hi:[0,1]
	v_mov_b32_e32 v88, v89
	v_mov_b32_e32 v89, v83
	v_pk_mov_b32 v[84:85], v[80:81], v[84:85] op_sel:[1,0]
	v_mov_b32_e32 v87, v80
	v_pk_add_f32 v[84:85], v[88:89], v[84:85] neg_lo:[0,1] neg_hi:[0,1]
	v_mov_b32_e32 v92, v90
	v_pk_add_f32 v[80:81], v[86:87], v[84:85] neg_lo:[0,1] neg_hi:[0,1]
	v_mov_b32_e32 v91, v83
	v_pk_add_f32 v[84:85], v[92:93], v[80:81]
	s_nop 0
	v_pk_add_f32 v[86:87], v[84:85], v[84:85] op_sel:[0,1] op_sel_hi:[1,0]
	s_nop 0
	v_pk_add_f32 v[82:83], v[82:83], v[86:87] op_sel:[1,0] op_sel_hi:[0,1]
	v_mov_b32_e32 v85, v82
	v_pk_add_f32 v[88:89], v[84:85], v[90:91] neg_lo:[0,1] neg_hi:[0,1]
	v_mov_b32_e32 v81, v86
	v_sub_f32_e32 v79, v84, v88
	v_pk_add_f32 v[80:81], v[80:81], v[88:89] neg_lo:[0,1] neg_hi:[0,1]
	v_sub_f32_e32 v79, v90, v79
	v_add_f32_e32 v79, v80, v79
	v_add_f32_e32 v79, v79, v81
	v_add_f32_e32 v79, v82, v79
	v_cndmask_b32_e32 v79, v224, v79, vcc
	v_cmp_ngt_f32_e32 vcc, -1.0, v78
	s_nop 1
	v_cndmask_b32_e32 v79, v225, v79, vcc
	v_cmp_neq_f32_e32 vcc, -1.0, v78
	s_nop 1
	v_cndmask_b32_e32 v79, v226, v79, vcc
	v_cmp_lt_f32_e64 vcc, |v78|, s56
	s_nop 1
	v_cndmask_b32_e32 v78, v79, v78, vcc
	v_add_f32_e32 v77, v77, v78

.LBB0_1348:
	s_and_b64 vcc, exec, s[4:5]
	v_or_b32_e32 v76, 51, v74
	s_cbranch_vccnz .LBB0_1724
	s_andn2_b64 vcc, exec, s[36:37]
	v_mov_b32_e32 v77, v15
	s_cbranch_vccnz .LBB0_1351
	s_nop 0
	s_waitcnt lgkmcnt(0)
	v_lshl_add_u64 v[68:69], v[68:69], 2, s[6:7]
	v_mov_b32_e32 v68, v248
	s_nop 0
	v_add_f32_e32 v69, v15, v68
	v_max_f32_e32 v68, 0, v69
	v_mul_f32_e64 v69, |v69|, s73
	v_exp_f32_e32 v69, v69
	s_nop 0
	v_add_f32_e32 v77, 1.0, v69
	v_add_f32_e32 v78, -1.0, v77
	v_sub_f32_e32 v79, v78, v77
	v_add_f32_e32 v79, 1.0, v79
	v_sub_f32_e32 v78, v69, v78
	v_add_f32_e32 v80, v78, v79
	v_frexp_mant_f32_e32 v78, v77
	v_cmp_gt_f32_e32 vcc, s46, v78
	v_cvt_f64_f32_e32 v[78:79], v77
	v_frexp_exp_i32_f64_e32 v78, v[78:79]
	v_subbrev_co_u32_e32 v86, vcc, 0, v78, vcc
	v_sub_u32_e32 v78, 0, v86
	v_ldexp_f32 v77, v77, v78
	v_ldexp_f32 v78, v80, v78
	v_add_f32_e32 v80, -1.0, v77
	v_add_f32_e32 v79, 1.0, v80
	v_sub_f32_e32 v79, v77, v79
	v_add_f32_e32 v81, v78, v79
	v_add_f32_e32 v79, 1.0, v77
	v_add_f32_e32 v82, -1.0, v79
	v_sub_f32_e32 v77, v77, v82
	v_add_f32_e32 v77, v78, v77
	v_add_f32_e32 v87, v79, v77
	v_rcp_f32_e32 v88, v87
	v_sub_f32_e32 v78, v87, v79
	v_add_f32_e32 v79, v80, v81
	v_sub_f32_e32 v77, v77, v78
	v_mul_f32_e32 v90, v79, v88
	v_sub_f32_e32 v78, v79, v80
	v_mul_f32_e32 v80, v87, v90
	v_fma_f32 v82, v90, v87, -v80
	v_fmac_f32_e32 v82, v90, v77
	v_sub_f32_e32 v89, v81, v78
	v_add_f32_e32 v78, v80, v82
	v_sub_f32_e32 v81, v79, v78
	v_pk_add_f32 v[84:85], v[78:79], v[80:81] neg_lo:[0,1] neg_hi:[0,1]
	v_mov_b32_e32 v83, v78
	v_pk_add_f32 v[78:79], v[84:85], v[82:83] neg_lo:[0,1] neg_hi:[0,1]
	v_cmp_neq_f32_e32 vcc, s0, v69
	v_add_f32_e32 v79, v89, v79
	v_add_f32_e32 v78, v78, v79
	v_add_f32_e32 v79, v81, v78
	v_mul_f32_e32 v89, v88, v79
	v_mul_f32_e32 v80, v87, v89
	v_fma_f32 v82, v89, v87, -v80
	v_fmac_f32_e32 v82, v89, v77
	v_sub_f32_e32 v77, v81, v79
	v_add_f32_e32 v77, v78, v77
	v_add_f32_e32 v78, v80, v82
	v_sub_f32_e32 v81, v79, v78
	v_pk_add_f32 v[84:85], v[78:79], v[80:81] neg_lo:[0,1] neg_hi:[0,1]
	v_mov_b32_e32 v83, v78
	v_pk_add_f32 v[78:79], v[84:85], v[82:83] neg_lo:[0,1] neg_hi:[0,1]
	s_nop 0
	v_add_f32_e32 v77, v77, v79
	v_add_f32_e32 v77, v78, v77
	v_add_f32_e32 v79, v90, v89
	v_add_f32_e32 v77, v81, v77
	v_sub_f32_e32 v78, v79, v90
	v_mul_f32_e32 v77, v88, v77
	v_sub_f32_e32 v78, v89, v78
	v_add_f32_e32 v77, v78, v77
	v_add_f32_e32 v80, v79, v77
	v_mul_f32_e32 v82, v80, v80
	v_fmamk_f32 v78, v82, 0x3e9b6dac, v210
	v_fmaak_f32 v121, v82, v78, 0x3f2aaada
	v_cvt_f32_i32_e32 v78, v86
	v_sub_f32_e32 v79, v80, v79
	v_sub_f32_e32 v77, v77, v79
	v_mul_f32_e32 v79, v80, v82
	v_pk_mul_f32 v[82:83], v[78:79], v[120:121]
	v_ldexp_f32 v81, v80, 1
	v_fma_f32 v80, v78, s1, -v82
	v_fmac_f32_e32 v80, 0xb102e308, v78
	v_pk_add_f32 v[78:79], v[82:83], v[80:81]
	v_ldexp_f32 v77, v77, 1
	v_sub_f32_e32 v81, v79, v81
	v_sub_f32_e32 v81, v83, v81
	v_add_f32_e32 v85, v77, v81
	v_mov_b32_e32 v84, v82
	v_pk_add_f32 v[82:83], v[78:79], v[82:83] neg_lo:[0,1] neg_hi:[0,1]
	v_pk_add_f32 v[86:87], v[78:79], v[84:85]
	v_mov_b32_e32 v81, v78
	v_mov_b32_e32 v83, v87
	v_pk_add_f32 v[88:89], v[80:81], v[82:83] neg_lo:[0,1] neg_hi:[0,1]
	v_pk_add_f32 v[80:81], v[80:81], v[82:83]
	v_mov_b32_e32 v84, v85
	v_pk_add_f32 v[82:83], v[80:81], v[78:79] op_sel:[1,0] op_sel_hi:[0,1] neg_lo:[0,1] neg_hi:[0,1]
	v_pk_add_f32 v[90:91], v[86:87], v[82:83] op_sel_hi:[1,0] neg_lo:[0,1] neg_hi:[0,1]
	v_mov_b32_e32 v86, v87
	v_mov_b32_e32 v87, v81
	v_pk_mov_b32 v[82:83], v[78:79], v[82:83] op_sel:[1,0]
	v_mov_b32_e32 v85, v78
	v_pk_add_f32 v[82:83], v[86:87], v[82:83] neg_lo:[0,1] neg_hi:[0,1]
	v_mov_b32_e32 v90, v88
	v_pk_add_f32 v[78:79], v[84:85], v[82:83] neg_lo:[0,1] neg_hi:[0,1]
	v_mov_b32_e32 v89, v81
	v_pk_add_f32 v[82:83], v[90:91], v[78:79]
	s_nop 0
	v_pk_add_f32 v[84:85], v[82:83], v[82:83] op_sel:[0,1] op_sel_hi:[1,0]
	s_nop 0
	v_pk_add_f32 v[80:81], v[80:81], v[84:85] op_sel:[1,0] op_sel_hi:[0,1]
	v_mov_b32_e32 v83, v80
	v_pk_add_f32 v[86:87], v[82:83], v[88:89] neg_lo:[0,1] neg_hi:[0,1]
	v_mov_b32_e32 v79, v84
	v_sub_f32_e32 v77, v82, v86
	v_pk_add_f32 v[78:79], v[78:79], v[86:87] neg_lo:[0,1] neg_hi:[0,1]
	v_sub_f32_e32 v77, v88, v77
	v_add_f32_e32 v77, v78, v77
	v_add_f32_e32 v77, v77, v79
	v_add_f32_e32 v77, v80, v77
	v_cndmask_b32_e32 v77, v224, v77, vcc
	v_cmp_ngt_f32_e32 vcc, -1.0, v69
	s_nop 1
	v_cndmask_b32_e32 v77, v225, v77, vcc
	v_cmp_neq_f32_e32 vcc, -1.0, v69
	s_nop 1
	v_cndmask_b32_e32 v77, v226, v77, vcc
	v_cmp_lt_f32_e64 vcc, |v69|, s56
	s_nop 1
	v_cndmask_b32_e32 v69, v77, v69, vcc
	v_add_f32_e32 v77, v68, v69

.LBB0_1353:
	s_or_b64 exec, exec, s[58:59]
	s_and_saveexec_b64 s[6:7], s[8:9]
	s_cbranch_execz .LBB0_1374
	s_and_b64 vcc, exec, s[4:5]
	v_lshl_add_u64 v[68:69], v[66:67], 2, s[34:35]
	s_cbranch_vccnz .LBB0_1725
	s_andn2_b64 vcc, exec, s[36:37]
	v_mov_b32_e32 v70, v8
	s_cbranch_vccnz .LBB0_1357
	s_nop 0
	v_lshl_add_u64 v[70:71], v[66:67], 0, s[80:81]
	s_waitcnt lgkmcnt(0)
	v_lshl_add_u64 v[70:71], v[70:71], 2, s[8:9]
	v_mov_b32_e32 v70, v249
	s_nop 0
	v_add_f32_e32 v71, v8, v70
	v_max_f32_e32 v70, 0, v71
	v_mul_f32_e64 v71, |v71|, s73
	v_exp_f32_e32 v71, v71
	s_nop 0
	v_add_f32_e32 v76, 1.0, v71
	v_add_f32_e32 v72, -1.0, v76
	v_sub_f32_e32 v73, v72, v76
	v_add_f32_e32 v73, 1.0, v73
	v_sub_f32_e32 v72, v71, v72
	v_add_f32_e32 v77, v72, v73
	v_frexp_mant_f32_e32 v72, v76
	v_cmp_gt_f32_e32 vcc, s46, v72
	v_cvt_f64_f32_e32 v[72:73], v76
	v_frexp_exp_i32_f64_e32 v72, v[72:73]
	v_subbrev_co_u32_e32 v82, vcc, 0, v72, vcc
	v_sub_u32_e32 v72, 0, v82
	v_ldexp_f32 v73, v76, v72
	v_add_f32_e32 v76, -1.0, v73
	v_add_f32_e32 v78, 1.0, v73
	v_ldexp_f32 v72, v77, v72
	v_add_f32_e32 v77, 1.0, v76
	v_add_f32_e32 v79, -1.0, v78
	v_sub_f32_e32 v77, v73, v77
	v_sub_f32_e32 v73, v73, v79
	v_add_f32_e32 v77, v72, v77
	v_add_f32_e32 v72, v72, v73
	v_add_f32_e32 v83, v78, v72
	v_rcp_f32_e32 v85, v83
	v_sub_f32_e32 v73, v83, v78
	v_sub_f32_e32 v84, v72, v73
	v_add_f32_e32 v73, v76, v77
	v_mul_f32_e32 v87, v73, v85
	v_sub_f32_e32 v72, v73, v76
	v_mul_f32_e32 v76, v83, v87
	v_fma_f32 v78, v87, v83, -v76
	v_fmac_f32_e32 v78, v87, v84
	v_sub_f32_e32 v86, v77, v72
	v_add_f32_e32 v72, v76, v78
	v_sub_f32_e32 v77, v73, v72
	v_pk_add_f32 v[80:81], v[72:73], v[76:77] neg_lo:[0,1] neg_hi:[0,1]
	v_mov_b32_e32 v79, v72
	v_pk_add_f32 v[72:73], v[80:81], v[78:79] neg_lo:[0,1] neg_hi:[0,1]
	v_cmp_neq_f32_e32 vcc, s0, v71
	v_add_f32_e32 v73, v86, v73
	v_add_f32_e32 v72, v72, v73
	v_add_f32_e32 v73, v77, v72
	v_mul_f32_e32 v86, v85, v73
	v_mul_f32_e32 v76, v83, v86
	v_fma_f32 v78, v86, v83, -v76
	v_fmac_f32_e32 v78, v86, v84
	v_sub_f32_e32 v77, v77, v73
	v_add_f32_e32 v83, v72, v77
	v_add_f32_e32 v72, v76, v78
	v_sub_f32_e32 v77, v73, v72
	v_pk_add_f32 v[80:81], v[72:73], v[76:77] neg_lo:[0,1] neg_hi:[0,1]
	v_mov_b32_e32 v79, v72
	v_pk_add_f32 v[72:73], v[80:81], v[78:79] neg_lo:[0,1] neg_hi:[0,1]
	s_nop 0
	v_add_f32_e32 v73, v83, v73
	v_add_f32_e32 v72, v72, v73
	v_add_f32_e32 v73, v87, v86
	v_add_f32_e32 v72, v77, v72
	v_sub_f32_e32 v76, v73, v87
	v_mul_f32_e32 v72, v85, v72
	v_sub_f32_e32 v76, v86, v76
	v_add_f32_e32 v76, v76, v72
	v_add_f32_e32 v78, v73, v76
	v_mul_f32_e32 v79, v78, v78
	v_fmamk_f32 v72, v79, 0x3e9b6dac, v210
	v_fmaak_f32 v121, v79, v72, 0x3f2aaada
	v_cvt_f32_i32_e32 v72, v82
	v_sub_f32_e32 v73, v78, v73
	v_sub_f32_e32 v73, v76, v73
	v_ldexp_f32 v80, v73, 1
	v_mul_f32_e32 v73, v78, v79
	v_ldexp_f32 v77, v78, 1
	v_pk_mul_f32 v[78:79], v[72:73], v[120:121]
	s_nop 0
	v_fma_f32 v76, v72, s1, -v78
	v_fmac_f32_e32 v76, 0xb102e308, v72
	v_pk_add_f32 v[72:73], v[78:79], v[76:77]
	s_nop 0
	v_sub_f32_e32 v77, v73, v77
	v_sub_f32_e32 v77, v79, v77
	v_add_f32_e32 v81, v80, v77
	v_mov_b32_e32 v80, v78
	v_pk_add_f32 v[78:79], v[72:73], v[78:79] neg_lo:[0,1] neg_hi:[0,1]
	v_pk_add_f32 v[82:83], v[72:73], v[80:81]
	v_mov_b32_e32 v77, v72
	v_mov_b32_e32 v79, v83
	v_pk_add_f32 v[84:85], v[76:77], v[78:79] neg_lo:[0,1] neg_hi:[0,1]
	v_pk_add_f32 v[76:77], v[76:77], v[78:79]
	v_mov_b32_e32 v80, v81
	v_pk_add_f32 v[78:79], v[76:77], v[72:73] op_sel:[1,0] op_sel_hi:[0,1] neg_lo:[0,1] neg_hi:[0,1]
	v_pk_add_f32 v[86:87], v[82:83], v[78:79] op_sel_hi:[1,0] neg_lo:[0,1] neg_hi:[0,1]
	v_mov_b32_e32 v82, v83
	v_mov_b32_e32 v83, v77
	v_pk_mov_b32 v[78:79], v[72:73], v[78:79] op_sel:[1,0]
	v_mov_b32_e32 v81, v72
	v_pk_add_f32 v[78:79], v[82:83], v[78:79] neg_lo:[0,1] neg_hi:[0,1]
	v_mov_b32_e32 v86, v84
	v_pk_add_f32 v[72:73], v[80:81], v[78:79] neg_lo:[0,1] neg_hi:[0,1]
	v_mov_b32_e32 v85, v77
	v_pk_add_f32 v[78:79], v[86:87], v[72:73]
	s_nop 0
	v_pk_add_f32 v[80:81], v[78:79], v[78:79] op_sel:[0,1] op_sel_hi:[1,0]
	s_nop 0
	v_pk_add_f32 v[76:77], v[76:77], v[80:81] op_sel:[1,0] op_sel_hi:[0,1]
	v_mov_b32_e32 v79, v76
	v_pk_add_f32 v[82:83], v[78:79], v[84:85] neg_lo:[0,1] neg_hi:[0,1]
	v_mov_b32_e32 v73, v80
	v_sub_f32_e32 v77, v78, v82
	v_pk_add_f32 v[72:73], v[72:73], v[82:83] neg_lo:[0,1] neg_hi:[0,1]
	v_sub_f32_e32 v77, v84, v77
	v_add_f32_e32 v72, v72, v77
	v_add_f32_e32 v72, v72, v73
	v_add_f32_e32 v72, v76, v72
	v_cndmask_b32_e32 v72, v224, v72, vcc
	v_cmp_ngt_f32_e32 vcc, -1.0, v71
	s_nop 1
	v_cndmask_b32_e32 v72, v225, v72, vcc
	v_cmp_neq_f32_e32 vcc, -1.0, v71
	s_nop 1
	v_cndmask_b32_e32 v72, v226, v72, vcc
	v_cmp_lt_f32_e64 vcc, |v71|, s56
	s_nop 1
	v_cndmask_b32_e32 v71, v72, v71, vcc
	v_add_f32_e32 v70, v70, v71

.LBB0_1359:
	s_and_b64 vcc, exec, s[4:5]
	v_or_b32_e32 v72, 49, v74
	s_cbranch_vccnz .LBB0_1726
	s_andn2_b64 vcc, exec, s[36:37]
	v_mov_b32_e32 v73, v9
	s_cbranch_vccnz .LBB0_1362
	s_nop 0
	v_lshl_add_u64 v[76:77], v[66:67], 0, s[80:81]
	s_waitcnt lgkmcnt(0)
	v_lshl_add_u64 v[76:77], v[76:77], 2, s[8:9]
	v_mov_b32_e32 v73, v249
	s_nop 0
	v_add_f32_e32 v76, v9, v73
	v_max_f32_e32 v73, 0, v76
	v_mul_f32_e64 v76, |v76|, s73
	v_exp_f32_e32 v76, v76
	s_nop 0
	v_add_f32_e32 v77, 1.0, v76
	v_add_f32_e32 v78, -1.0, v77
	v_sub_f32_e32 v79, v78, v77
	v_add_f32_e32 v79, 1.0, v79
	v_sub_f32_e32 v78, v76, v78
	v_add_f32_e32 v80, v78, v79
	v_frexp_mant_f32_e32 v78, v77
	v_cmp_gt_f32_e32 vcc, s46, v78
	v_cvt_f64_f32_e32 v[78:79], v77
	v_frexp_exp_i32_f64_e32 v78, v[78:79]
	v_subbrev_co_u32_e32 v86, vcc, 0, v78, vcc
	v_sub_u32_e32 v78, 0, v86
	v_ldexp_f32 v77, v77, v78
	v_ldexp_f32 v78, v80, v78
	v_add_f32_e32 v80, -1.0, v77
	v_add_f32_e32 v79, 1.0, v80
	v_sub_f32_e32 v79, v77, v79
	v_add_f32_e32 v81, v78, v79
	v_add_f32_e32 v79, 1.0, v77
	v_add_f32_e32 v82, -1.0, v79
	v_sub_f32_e32 v77, v77, v82
	v_add_f32_e32 v77, v78, v77
	v_add_f32_e32 v87, v79, v77
	v_rcp_f32_e32 v88, v87
	v_sub_f32_e32 v78, v87, v79
	v_add_f32_e32 v79, v80, v81
	v_sub_f32_e32 v77, v77, v78
	v_mul_f32_e32 v90, v79, v88
	v_sub_f32_e32 v78, v79, v80
	v_mul_f32_e32 v80, v87, v90
	v_fma_f32 v82, v90, v87, -v80
	v_fmac_f32_e32 v82, v90, v77
	v_sub_f32_e32 v89, v81, v78
	v_add_f32_e32 v78, v80, v82
	v_sub_f32_e32 v81, v79, v78
	v_pk_add_f32 v[84:85], v[78:79], v[80:81] neg_lo:[0,1] neg_hi:[0,1]
	v_mov_b32_e32 v83, v78
	v_pk_add_f32 v[78:79], v[84:85], v[82:83] neg_lo:[0,1] neg_hi:[0,1]
	v_cmp_neq_f32_e32 vcc, s0, v76
	v_add_f32_e32 v79, v89, v79
	v_add_f32_e32 v78, v78, v79
	v_add_f32_e32 v79, v81, v78
	v_mul_f32_e32 v89, v88, v79
	v_mul_f32_e32 v80, v87, v89
	v_fma_f32 v82, v89, v87, -v80
	v_fmac_f32_e32 v82, v89, v77
	v_sub_f32_e32 v77, v81, v79
	v_add_f32_e32 v77, v78, v77
	v_add_f32_e32 v78, v80, v82
	v_sub_f32_e32 v81, v79, v78
	v_pk_add_f32 v[84:85], v[78:79], v[80:81] neg_lo:[0,1] neg_hi:[0,1]
	v_mov_b32_e32 v83, v78
	v_pk_add_f32 v[78:79], v[84:85], v[82:83] neg_lo:[0,1] neg_hi:[0,1]
	s_nop 0
	v_add_f32_e32 v77, v77, v79
	v_add_f32_e32 v77, v78, v77
	v_add_f32_e32 v79, v90, v89
	v_add_f32_e32 v77, v81, v77
	v_sub_f32_e32 v78, v79, v90
	v_mul_f32_e32 v77, v88, v77
	v_sub_f32_e32 v78, v89, v78
	v_add_f32_e32 v77, v78, v77
	v_add_f32_e32 v80, v79, v77
	v_mul_f32_e32 v82, v80, v80
	v_fmamk_f32 v78, v82, 0x3e9b6dac, v210
	v_fmaak_f32 v121, v82, v78, 0x3f2aaada
	v_cvt_f32_i32_e32 v78, v86
	v_sub_f32_e32 v79, v80, v79
	v_sub_f32_e32 v77, v77, v79
	v_mul_f32_e32 v79, v80, v82
	v_pk_mul_f32 v[82:83], v[78:79], v[120:121]
	v_ldexp_f32 v81, v80, 1
	v_fma_f32 v80, v78, s1, -v82
	v_fmac_f32_e32 v80, 0xb102e308, v78
	v_pk_add_f32 v[78:79], v[82:83], v[80:81]
	v_ldexp_f32 v77, v77, 1
	v_sub_f32_e32 v81, v79, v81
	v_sub_f32_e32 v81, v83, v81
	v_add_f32_e32 v85, v77, v81
	v_mov_b32_e32 v84, v82
	v_pk_add_f32 v[82:83], v[78:79], v[82:83] neg_lo:[0,1] neg_hi:[0,1]
	v_pk_add_f32 v[86:87], v[78:79], v[84:85]
	v_mov_b32_e32 v81, v78
	v_mov_b32_e32 v83, v87
	v_pk_add_f32 v[88:89], v[80:81], v[82:83] neg_lo:[0,1] neg_hi:[0,1]
	v_pk_add_f32 v[80:81], v[80:81], v[82:83]
	v_mov_b32_e32 v84, v85
	v_pk_add_f32 v[82:83], v[80:81], v[78:79] op_sel:[1,0] op_sel_hi:[0,1] neg_lo:[0,1] neg_hi:[0,1]
	v_pk_add_f32 v[90:91], v[86:87], v[82:83] op_sel_hi:[1,0] neg_lo:[0,1] neg_hi:[0,1]
	v_mov_b32_e32 v86, v87
	v_mov_b32_e32 v87, v81
	v_pk_mov_b32 v[82:83], v[78:79], v[82:83] op_sel:[1,0]
	v_mov_b32_e32 v85, v78
	v_pk_add_f32 v[82:83], v[86:87], v[82:83] neg_lo:[0,1] neg_hi:[0,1]
	v_mov_b32_e32 v90, v88
	v_pk_add_f32 v[78:79], v[84:85], v[82:83] neg_lo:[0,1] neg_hi:[0,1]
	v_mov_b32_e32 v89, v81
	v_pk_add_f32 v[82:83], v[90:91], v[78:79]
	s_nop 0
	v_pk_add_f32 v[84:85], v[82:83], v[82:83] op_sel:[0,1] op_sel_hi:[1,0]
	s_nop 0
	v_pk_add_f32 v[80:81], v[80:81], v[84:85] op_sel:[1,0] op_sel_hi:[0,1]
	v_mov_b32_e32 v83, v80
	v_pk_add_f32 v[86:87], v[82:83], v[88:89] neg_lo:[0,1] neg_hi:[0,1]
	v_mov_b32_e32 v79, v84
	v_sub_f32_e32 v77, v82, v86
	v_pk_add_f32 v[78:79], v[78:79], v[86:87] neg_lo:[0,1] neg_hi:[0,1]
	v_sub_f32_e32 v77, v88, v77
	v_add_f32_e32 v77, v78, v77
	v_add_f32_e32 v77, v77, v79
	v_add_f32_e32 v77, v80, v77
	v_cndmask_b32_e32 v77, v224, v77, vcc
	v_cmp_ngt_f32_e32 vcc, -1.0, v76
	s_nop 1
	v_cndmask_b32_e32 v77, v225, v77, vcc
	v_cmp_neq_f32_e32 vcc, -1.0, v76
	s_nop 1
	v_cndmask_b32_e32 v77, v226, v77, vcc
	v_cmp_lt_f32_e64 vcc, |v76|, s56
	s_nop 1
	v_cndmask_b32_e32 v76, v77, v76, vcc
	v_add_f32_e32 v73, v73, v76

.LBB0_1364:
	s_and_b64 vcc, exec, s[4:5]
	v_or_b32_e32 v72, 50, v74
	s_cbranch_vccnz .LBB0_1727
	s_andn2_b64 vcc, exec, s[36:37]
	v_mov_b32_e32 v73, v10
	s_cbranch_vccnz .LBB0_1367
	s_nop 0
	v_lshl_add_u64 v[76:77], v[66:67], 0, s[80:81]
	s_waitcnt lgkmcnt(0)
	v_lshl_add_u64 v[76:77], v[76:77], 2, s[8:9]
	v_mov_b32_e32 v73, v249
	s_nop 0
	v_add_f32_e32 v76, v10, v73
	v_max_f32_e32 v73, 0, v76
	v_mul_f32_e64 v76, |v76|, s73
	v_exp_f32_e32 v76, v76
	s_nop 0
	v_add_f32_e32 v77, 1.0, v76
	v_add_f32_e32 v78, -1.0, v77
	v_sub_f32_e32 v79, v78, v77
	v_add_f32_e32 v79, 1.0, v79
	v_sub_f32_e32 v78, v76, v78
	v_add_f32_e32 v80, v78, v79
	v_frexp_mant_f32_e32 v78, v77
	v_cmp_gt_f32_e32 vcc, s46, v78
	v_cvt_f64_f32_e32 v[78:79], v77
	v_frexp_exp_i32_f64_e32 v78, v[78:79]
	v_subbrev_co_u32_e32 v86, vcc, 0, v78, vcc
	v_sub_u32_e32 v78, 0, v86
	v_ldexp_f32 v77, v77, v78
	v_ldexp_f32 v78, v80, v78
	v_add_f32_e32 v80, -1.0, v77
	v_add_f32_e32 v79, 1.0, v80
	v_sub_f32_e32 v79, v77, v79
	v_add_f32_e32 v81, v78, v79
	v_add_f32_e32 v79, 1.0, v77
	v_add_f32_e32 v82, -1.0, v79
	v_sub_f32_e32 v77, v77, v82
	v_add_f32_e32 v77, v78, v77
	v_add_f32_e32 v87, v79, v77
	v_rcp_f32_e32 v88, v87
	v_sub_f32_e32 v78, v87, v79
	v_add_f32_e32 v79, v80, v81
	v_sub_f32_e32 v77, v77, v78
	v_mul_f32_e32 v90, v79, v88
	v_sub_f32_e32 v78, v79, v80
	v_mul_f32_e32 v80, v87, v90
	v_fma_f32 v82, v90, v87, -v80
	v_fmac_f32_e32 v82, v90, v77
	v_sub_f32_e32 v89, v81, v78
	v_add_f32_e32 v78, v80, v82
	v_sub_f32_e32 v81, v79, v78
	v_pk_add_f32 v[84:85], v[78:79], v[80:81] neg_lo:[0,1] neg_hi:[0,1]
	v_mov_b32_e32 v83, v78
	v_pk_add_f32 v[78:79], v[84:85], v[82:83] neg_lo:[0,1] neg_hi:[0,1]
	v_cmp_neq_f32_e32 vcc, s0, v76
	v_add_f32_e32 v79, v89, v79
	v_add_f32_e32 v78, v78, v79
	v_add_f32_e32 v79, v81, v78
	v_mul_f32_e32 v89, v88, v79
	v_mul_f32_e32 v80, v87, v89
	v_fma_f32 v82, v89, v87, -v80
	v_fmac_f32_e32 v82, v89, v77
	v_sub_f32_e32 v77, v81, v79
	v_add_f32_e32 v77, v78, v77
	v_add_f32_e32 v78, v80, v82
	v_sub_f32_e32 v81, v79, v78
	v_pk_add_f32 v[84:85], v[78:79], v[80:81] neg_lo:[0,1] neg_hi:[0,1]
	v_mov_b32_e32 v83, v78
	v_pk_add_f32 v[78:79], v[84:85], v[82:83] neg_lo:[0,1] neg_hi:[0,1]
	s_nop 0
	v_add_f32_e32 v77, v77, v79
	v_add_f32_e32 v77, v78, v77
	v_add_f32_e32 v79, v90, v89
	v_add_f32_e32 v77, v81, v77
	v_sub_f32_e32 v78, v79, v90
	v_mul_f32_e32 v77, v88, v77
	v_sub_f32_e32 v78, v89, v78
	v_add_f32_e32 v77, v78, v77
	v_add_f32_e32 v80, v79, v77
	v_mul_f32_e32 v82, v80, v80
	v_fmamk_f32 v78, v82, 0x3e9b6dac, v210
	v_fmaak_f32 v121, v82, v78, 0x3f2aaada
	v_cvt_f32_i32_e32 v78, v86
	v_sub_f32_e32 v79, v80, v79
	v_sub_f32_e32 v77, v77, v79
	v_mul_f32_e32 v79, v80, v82
	v_pk_mul_f32 v[82:83], v[78:79], v[120:121]
	v_ldexp_f32 v81, v80, 1
	v_fma_f32 v80, v78, s1, -v82
	v_fmac_f32_e32 v80, 0xb102e308, v78
	v_pk_add_f32 v[78:79], v[82:83], v[80:81]
	v_ldexp_f32 v77, v77, 1
	v_sub_f32_e32 v81, v79, v81
	v_sub_f32_e32 v81, v83, v81
	v_add_f32_e32 v85, v77, v81
	v_mov_b32_e32 v84, v82
	v_pk_add_f32 v[82:83], v[78:79], v[82:83] neg_lo:[0,1] neg_hi:[0,1]
	v_pk_add_f32 v[86:87], v[78:79], v[84:85]
	v_mov_b32_e32 v81, v78
	v_mov_b32_e32 v83, v87
	v_pk_add_f32 v[88:89], v[80:81], v[82:83] neg_lo:[0,1] neg_hi:[0,1]
	v_pk_add_f32 v[80:81], v[80:81], v[82:83]
	v_mov_b32_e32 v84, v85
	v_pk_add_f32 v[82:83], v[80:81], v[78:79] op_sel:[1,0] op_sel_hi:[0,1] neg_lo:[0,1] neg_hi:[0,1]
	v_pk_add_f32 v[90:91], v[86:87], v[82:83] op_sel_hi:[1,0] neg_lo:[0,1] neg_hi:[0,1]
	v_mov_b32_e32 v86, v87
	v_mov_b32_e32 v87, v81
	v_pk_mov_b32 v[82:83], v[78:79], v[82:83] op_sel:[1,0]
	v_mov_b32_e32 v85, v78
	v_pk_add_f32 v[82:83], v[86:87], v[82:83] neg_lo:[0,1] neg_hi:[0,1]
	v_mov_b32_e32 v90, v88
	v_pk_add_f32 v[78:79], v[84:85], v[82:83] neg_lo:[0,1] neg_hi:[0,1]
	v_mov_b32_e32 v89, v81
	v_pk_add_f32 v[82:83], v[90:91], v[78:79]
	s_nop 0
	v_pk_add_f32 v[84:85], v[82:83], v[82:83] op_sel:[0,1] op_sel_hi:[1,0]
	s_nop 0
	v_pk_add_f32 v[80:81], v[80:81], v[84:85] op_sel:[1,0] op_sel_hi:[0,1]
	v_mov_b32_e32 v83, v80
	v_pk_add_f32 v[86:87], v[82:83], v[88:89] neg_lo:[0,1] neg_hi:[0,1]
	v_mov_b32_e32 v79, v84
	v_sub_f32_e32 v77, v82, v86
	v_pk_add_f32 v[78:79], v[78:79], v[86:87] neg_lo:[0,1] neg_hi:[0,1]
	v_sub_f32_e32 v77, v88, v77
	v_add_f32_e32 v77, v78, v77
	v_add_f32_e32 v77, v77, v79
	v_add_f32_e32 v77, v80, v77
	v_cndmask_b32_e32 v77, v224, v77, vcc
	v_cmp_ngt_f32_e32 vcc, -1.0, v76
	s_nop 1
	v_cndmask_b32_e32 v77, v225, v77, vcc
	v_cmp_neq_f32_e32 vcc, -1.0, v76
	s_nop 1
	v_cndmask_b32_e32 v77, v226, v77, vcc
	v_cmp_lt_f32_e64 vcc, |v76|, s56
	s_nop 1
	v_cndmask_b32_e32 v76, v77, v76, vcc
	v_add_f32_e32 v73, v73, v76

.LBB0_1369:
	s_and_b64 vcc, exec, s[4:5]
	v_or_b32_e32 v72, 51, v74
	s_cbranch_vccnz .LBB0_1728
	s_andn2_b64 vcc, exec, s[36:37]
	v_mov_b32_e32 v73, v11
	s_cbranch_vccnz .LBB0_1372
	s_nop 0
	v_lshl_add_u64 v[76:77], v[66:67], 0, s[80:81]
	s_waitcnt lgkmcnt(0)
	v_lshl_add_u64 v[76:77], v[76:77], 2, s[8:9]
	v_mov_b32_e32 v73, v249
	s_nop 0
	v_add_f32_e32 v76, v11, v73
	v_max_f32_e32 v73, 0, v76
	v_mul_f32_e64 v76, |v76|, s73
	v_exp_f32_e32 v76, v76
	s_nop 0
	v_add_f32_e32 v77, 1.0, v76
	v_add_f32_e32 v78, -1.0, v77
	v_sub_f32_e32 v79, v78, v77
	v_add_f32_e32 v79, 1.0, v79
	v_sub_f32_e32 v78, v76, v78
	v_add_f32_e32 v80, v78, v79
	v_frexp_mant_f32_e32 v78, v77
	v_cmp_gt_f32_e32 vcc, s46, v78
	v_cvt_f64_f32_e32 v[78:79], v77
	v_frexp_exp_i32_f64_e32 v78, v[78:79]
	v_subbrev_co_u32_e32 v86, vcc, 0, v78, vcc
	v_sub_u32_e32 v78, 0, v86
	v_ldexp_f32 v77, v77, v78
	v_ldexp_f32 v78, v80, v78
	v_add_f32_e32 v80, -1.0, v77
	v_add_f32_e32 v79, 1.0, v80
	v_sub_f32_e32 v79, v77, v79
	v_add_f32_e32 v81, v78, v79
	v_add_f32_e32 v79, 1.0, v77
	v_add_f32_e32 v82, -1.0, v79
	v_sub_f32_e32 v77, v77, v82
	v_add_f32_e32 v77, v78, v77
	v_add_f32_e32 v87, v79, v77
	v_rcp_f32_e32 v88, v87
	v_sub_f32_e32 v78, v87, v79
	v_add_f32_e32 v79, v80, v81
	v_sub_f32_e32 v77, v77, v78
	v_mul_f32_e32 v90, v79, v88
	v_sub_f32_e32 v78, v79, v80
	v_mul_f32_e32 v80, v87, v90
	v_fma_f32 v82, v90, v87, -v80
	v_fmac_f32_e32 v82, v90, v77
	v_sub_f32_e32 v89, v81, v78
	v_add_f32_e32 v78, v80, v82
	v_sub_f32_e32 v81, v79, v78
	v_pk_add_f32 v[84:85], v[78:79], v[80:81] neg_lo:[0,1] neg_hi:[0,1]
	v_mov_b32_e32 v83, v78
	v_pk_add_f32 v[78:79], v[84:85], v[82:83] neg_lo:[0,1] neg_hi:[0,1]
	v_cmp_neq_f32_e32 vcc, s0, v76
	v_add_f32_e32 v79, v89, v79
	v_add_f32_e32 v78, v78, v79
	v_add_f32_e32 v79, v81, v78
	v_mul_f32_e32 v89, v88, v79
	v_mul_f32_e32 v80, v87, v89
	v_fma_f32 v82, v89, v87, -v80
	v_fmac_f32_e32 v82, v89, v77
	v_sub_f32_e32 v77, v81, v79
	v_add_f32_e32 v77, v78, v77
	v_add_f32_e32 v78, v80, v82
	v_sub_f32_e32 v81, v79, v78
	v_pk_add_f32 v[84:85], v[78:79], v[80:81] neg_lo:[0,1] neg_hi:[0,1]
	v_mov_b32_e32 v83, v78
	v_pk_add_f32 v[78:79], v[84:85], v[82:83] neg_lo:[0,1] neg_hi:[0,1]
	s_nop 0
	v_add_f32_e32 v77, v77, v79
	v_add_f32_e32 v77, v78, v77
	v_add_f32_e32 v79, v90, v89
	v_add_f32_e32 v77, v81, v77
	v_sub_f32_e32 v78, v79, v90
	v_mul_f32_e32 v77, v88, v77
	v_sub_f32_e32 v78, v89, v78
	v_add_f32_e32 v77, v78, v77
	v_add_f32_e32 v80, v79, v77
	v_mul_f32_e32 v82, v80, v80
	v_fmamk_f32 v78, v82, 0x3e9b6dac, v210
	v_fmaak_f32 v121, v82, v78, 0x3f2aaada
	v_cvt_f32_i32_e32 v78, v86
	v_sub_f32_e32 v79, v80, v79
	v_sub_f32_e32 v77, v77, v79
	v_mul_f32_e32 v79, v80, v82
	v_pk_mul_f32 v[82:83], v[78:79], v[120:121]
	v_ldexp_f32 v81, v80, 1
	v_fma_f32 v80, v78, s1, -v82
	v_fmac_f32_e32 v80, 0xb102e308, v78
	v_pk_add_f32 v[78:79], v[82:83], v[80:81]
	v_ldexp_f32 v77, v77, 1
	v_sub_f32_e32 v81, v79, v81
	v_sub_f32_e32 v81, v83, v81
	v_add_f32_e32 v85, v77, v81
	v_mov_b32_e32 v84, v82
	v_pk_add_f32 v[82:83], v[78:79], v[82:83] neg_lo:[0,1] neg_hi:[0,1]
	v_pk_add_f32 v[86:87], v[78:79], v[84:85]
	v_mov_b32_e32 v81, v78
	v_mov_b32_e32 v83, v87
	v_pk_add_f32 v[88:89], v[80:81], v[82:83] neg_lo:[0,1] neg_hi:[0,1]
	v_pk_add_f32 v[80:81], v[80:81], v[82:83]
	v_mov_b32_e32 v84, v85
	v_pk_add_f32 v[82:83], v[80:81], v[78:79] op_sel:[1,0] op_sel_hi:[0,1] neg_lo:[0,1] neg_hi:[0,1]
	v_pk_add_f32 v[90:91], v[86:87], v[82:83] op_sel_hi:[1,0] neg_lo:[0,1] neg_hi:[0,1]
	v_mov_b32_e32 v86, v87
	v_mov_b32_e32 v87, v81
	v_pk_mov_b32 v[82:83], v[78:79], v[82:83] op_sel:[1,0]
	v_mov_b32_e32 v85, v78
	v_pk_add_f32 v[82:83], v[86:87], v[82:83] neg_lo:[0,1] neg_hi:[0,1]
	v_mov_b32_e32 v90, v88
	v_pk_add_f32 v[78:79], v[84:85], v[82:83] neg_lo:[0,1] neg_hi:[0,1]
	v_mov_b32_e32 v89, v81
	v_pk_add_f32 v[82:83], v[90:91], v[78:79]
	s_nop 0
	v_pk_add_f32 v[84:85], v[82:83], v[82:83] op_sel:[0,1] op_sel_hi:[1,0]
	s_nop 0
	v_pk_add_f32 v[80:81], v[80:81], v[84:85] op_sel:[1,0] op_sel_hi:[0,1]
	v_mov_b32_e32 v83, v80
	v_pk_add_f32 v[86:87], v[82:83], v[88:89] neg_lo:[0,1] neg_hi:[0,1]
	v_mov_b32_e32 v79, v84
	v_sub_f32_e32 v77, v82, v86
	v_pk_add_f32 v[78:79], v[78:79], v[86:87] neg_lo:[0,1] neg_hi:[0,1]
	v_sub_f32_e32 v77, v88, v77
	v_add_f32_e32 v77, v78, v77
	v_add_f32_e32 v77, v77, v79
	v_add_f32_e32 v77, v80, v77
	v_cndmask_b32_e32 v77, v224, v77, vcc
	v_cmp_ngt_f32_e32 vcc, -1.0, v76
	s_nop 1
	v_cndmask_b32_e32 v77, v225, v77, vcc
	v_cmp_neq_f32_e32 vcc, -1.0, v76
	s_nop 1
	v_cndmask_b32_e32 v77, v226, v77, vcc
	v_cmp_lt_f32_e64 vcc, |v76|, s56
	s_nop 1
	v_cndmask_b32_e32 v76, v77, v76, vcc
	v_add_f32_e32 v73, v73, v76

.LBB0_1374:
	s_or_b64 exec, exec, s[6:7]
	s_and_saveexec_b64 s[6:7], s[10:11]
	s_cbranch_execz .LBB0_1395
	s_and_b64 vcc, exec, s[4:5]
	v_lshl_add_u64 v[68:69], v[66:67], 2, s[34:35]
	s_cbranch_vccnz .LBB0_1729
	s_andn2_b64 vcc, exec, s[36:37]
	v_mov_b32_e32 v70, v4
	s_cbranch_vccnz .LBB0_1378
	s_nop 0
	v_lshl_add_u64 v[70:71], v[66:67], 0, s[80:81]
	s_waitcnt lgkmcnt(0)
	v_lshl_add_u64 v[70:71], v[70:71], 2, s[8:9]
	v_mov_b32_e32 v70, v250
	s_nop 0
	v_add_f32_e32 v71, v4, v70
	v_max_f32_e32 v70, 0, v71
	v_mul_f32_e64 v71, |v71|, s73
	v_exp_f32_e32 v71, v71
	s_nop 0
	v_add_f32_e32 v76, 1.0, v71
	v_add_f32_e32 v72, -1.0, v76
	v_sub_f32_e32 v73, v72, v76
	v_add_f32_e32 v73, 1.0, v73
	v_sub_f32_e32 v72, v71, v72
	v_add_f32_e32 v77, v72, v73
	v_frexp_mant_f32_e32 v72, v76
	v_cmp_gt_f32_e32 vcc, s46, v72
	v_cvt_f64_f32_e32 v[72:73], v76
	v_frexp_exp_i32_f64_e32 v72, v[72:73]
	v_subbrev_co_u32_e32 v82, vcc, 0, v72, vcc
	v_sub_u32_e32 v72, 0, v82
	v_ldexp_f32 v73, v76, v72
	v_add_f32_e32 v76, -1.0, v73
	v_add_f32_e32 v78, 1.0, v73
	v_ldexp_f32 v72, v77, v72
	v_add_f32_e32 v77, 1.0, v76
	v_add_f32_e32 v79, -1.0, v78
	v_sub_f32_e32 v77, v73, v77
	v_sub_f32_e32 v73, v73, v79
	v_add_f32_e32 v77, v72, v77
	v_add_f32_e32 v72, v72, v73
	v_add_f32_e32 v83, v78, v72
	v_rcp_f32_e32 v85, v83
	v_sub_f32_e32 v73, v83, v78
	v_sub_f32_e32 v84, v72, v73
	v_add_f32_e32 v73, v76, v77
	v_mul_f32_e32 v87, v73, v85
	v_sub_f32_e32 v72, v73, v76
	v_mul_f32_e32 v76, v83, v87
	v_fma_f32 v78, v87, v83, -v76
	v_fmac_f32_e32 v78, v87, v84
	v_sub_f32_e32 v86, v77, v72
	v_add_f32_e32 v72, v76, v78
	v_sub_f32_e32 v77, v73, v72
	v_pk_add_f32 v[80:81], v[72:73], v[76:77] neg_lo:[0,1] neg_hi:[0,1]
	v_mov_b32_e32 v79, v72
	v_pk_add_f32 v[72:73], v[80:81], v[78:79] neg_lo:[0,1] neg_hi:[0,1]
	v_cmp_neq_f32_e32 vcc, s0, v71
	v_add_f32_e32 v73, v86, v73
	v_add_f32_e32 v72, v72, v73
	v_add_f32_e32 v73, v77, v72
	v_mul_f32_e32 v86, v85, v73
	v_mul_f32_e32 v76, v83, v86
	v_fma_f32 v78, v86, v83, -v76
	v_fmac_f32_e32 v78, v86, v84
	v_sub_f32_e32 v77, v77, v73
	v_add_f32_e32 v83, v72, v77
	v_add_f32_e32 v72, v76, v78
	v_sub_f32_e32 v77, v73, v72
	v_pk_add_f32 v[80:81], v[72:73], v[76:77] neg_lo:[0,1] neg_hi:[0,1]
	v_mov_b32_e32 v79, v72
	v_pk_add_f32 v[72:73], v[80:81], v[78:79] neg_lo:[0,1] neg_hi:[0,1]
	s_nop 0
	v_add_f32_e32 v73, v83, v73
	v_add_f32_e32 v72, v72, v73
	v_add_f32_e32 v73, v87, v86
	v_add_f32_e32 v72, v77, v72
	v_sub_f32_e32 v76, v73, v87
	v_mul_f32_e32 v72, v85, v72
	v_sub_f32_e32 v76, v86, v76
	v_add_f32_e32 v76, v76, v72
	v_add_f32_e32 v78, v73, v76
	v_mul_f32_e32 v79, v78, v78
	v_fmamk_f32 v72, v79, 0x3e9b6dac, v210
	v_fmaak_f32 v121, v79, v72, 0x3f2aaada
	v_cvt_f32_i32_e32 v72, v82
	v_sub_f32_e32 v73, v78, v73
	v_sub_f32_e32 v73, v76, v73
	v_ldexp_f32 v80, v73, 1
	v_mul_f32_e32 v73, v78, v79
	v_ldexp_f32 v77, v78, 1
	v_pk_mul_f32 v[78:79], v[72:73], v[120:121]
	s_nop 0
	v_fma_f32 v76, v72, s1, -v78
	v_fmac_f32_e32 v76, 0xb102e308, v72
	v_pk_add_f32 v[72:73], v[78:79], v[76:77]
	s_nop 0
	v_sub_f32_e32 v77, v73, v77
	v_sub_f32_e32 v77, v79, v77
	v_add_f32_e32 v81, v80, v77
	v_mov_b32_e32 v80, v78
	v_pk_add_f32 v[78:79], v[72:73], v[78:79] neg_lo:[0,1] neg_hi:[0,1]
	v_pk_add_f32 v[82:83], v[72:73], v[80:81]
	v_mov_b32_e32 v77, v72
	v_mov_b32_e32 v79, v83
	v_pk_add_f32 v[84:85], v[76:77], v[78:79] neg_lo:[0,1] neg_hi:[0,1]
	v_pk_add_f32 v[76:77], v[76:77], v[78:79]
	v_mov_b32_e32 v80, v81
	v_pk_add_f32 v[78:79], v[76:77], v[72:73] op_sel:[1,0] op_sel_hi:[0,1] neg_lo:[0,1] neg_hi:[0,1]
	v_pk_add_f32 v[86:87], v[82:83], v[78:79] op_sel_hi:[1,0] neg_lo:[0,1] neg_hi:[0,1]
	v_mov_b32_e32 v82, v83
	v_mov_b32_e32 v83, v77
	v_pk_mov_b32 v[78:79], v[72:73], v[78:79] op_sel:[1,0]
	v_mov_b32_e32 v81, v72
	v_pk_add_f32 v[78:79], v[82:83], v[78:79] neg_lo:[0,1] neg_hi:[0,1]
	v_mov_b32_e32 v86, v84
	v_pk_add_f32 v[72:73], v[80:81], v[78:79] neg_lo:[0,1] neg_hi:[0,1]
	v_mov_b32_e32 v85, v77
	v_pk_add_f32 v[78:79], v[86:87], v[72:73]
	s_nop 0
	v_pk_add_f32 v[80:81], v[78:79], v[78:79] op_sel:[0,1] op_sel_hi:[1,0]
	s_nop 0
	v_pk_add_f32 v[76:77], v[76:77], v[80:81] op_sel:[1,0] op_sel_hi:[0,1]
	v_mov_b32_e32 v79, v76
	v_pk_add_f32 v[82:83], v[78:79], v[84:85] neg_lo:[0,1] neg_hi:[0,1]
	v_mov_b32_e32 v73, v80
	v_sub_f32_e32 v77, v78, v82
	v_pk_add_f32 v[72:73], v[72:73], v[82:83] neg_lo:[0,1] neg_hi:[0,1]
	v_sub_f32_e32 v77, v84, v77
	v_add_f32_e32 v72, v72, v77
	v_add_f32_e32 v72, v72, v73
	v_add_f32_e32 v72, v76, v72
	v_cndmask_b32_e32 v72, v224, v72, vcc
	v_cmp_ngt_f32_e32 vcc, -1.0, v71
	s_nop 1
	v_cndmask_b32_e32 v72, v225, v72, vcc
	v_cmp_neq_f32_e32 vcc, -1.0, v71
	s_nop 1
	v_cndmask_b32_e32 v72, v226, v72, vcc
	v_cmp_lt_f32_e64 vcc, |v71|, s56
	s_nop 1
	v_cndmask_b32_e32 v71, v72, v71, vcc
	v_add_f32_e32 v70, v70, v71

.LBB0_1380:
	s_and_b64 vcc, exec, s[4:5]
	v_or_b32_e32 v72, 49, v74
	s_cbranch_vccnz .LBB0_1730
	s_andn2_b64 vcc, exec, s[36:37]
	v_mov_b32_e32 v73, v5
	s_cbranch_vccnz .LBB0_1383
	s_nop 0
	v_lshl_add_u64 v[76:77], v[66:67], 0, s[80:81]
	s_waitcnt lgkmcnt(0)
	v_lshl_add_u64 v[76:77], v[76:77], 2, s[8:9]
	v_mov_b32_e32 v73, v250
	s_nop 0
	v_add_f32_e32 v76, v5, v73
	v_max_f32_e32 v73, 0, v76
	v_mul_f32_e64 v76, |v76|, s73
	v_exp_f32_e32 v76, v76
	s_nop 0
	v_add_f32_e32 v77, 1.0, v76
	v_add_f32_e32 v78, -1.0, v77
	v_sub_f32_e32 v79, v78, v77
	v_add_f32_e32 v79, 1.0, v79
	v_sub_f32_e32 v78, v76, v78
	v_add_f32_e32 v80, v78, v79
	v_frexp_mant_f32_e32 v78, v77
	v_cmp_gt_f32_e32 vcc, s46, v78
	v_cvt_f64_f32_e32 v[78:79], v77
	v_frexp_exp_i32_f64_e32 v78, v[78:79]
	v_subbrev_co_u32_e32 v86, vcc, 0, v78, vcc
	v_sub_u32_e32 v78, 0, v86
	v_ldexp_f32 v77, v77, v78
	v_ldexp_f32 v78, v80, v78
	v_add_f32_e32 v80, -1.0, v77
	v_add_f32_e32 v79, 1.0, v80
	v_sub_f32_e32 v79, v77, v79
	v_add_f32_e32 v81, v78, v79
	v_add_f32_e32 v79, 1.0, v77
	v_add_f32_e32 v82, -1.0, v79
	v_sub_f32_e32 v77, v77, v82
	v_add_f32_e32 v77, v78, v77
	v_add_f32_e32 v87, v79, v77
	v_rcp_f32_e32 v88, v87
	v_sub_f32_e32 v78, v87, v79
	v_add_f32_e32 v79, v80, v81
	v_sub_f32_e32 v77, v77, v78
	v_mul_f32_e32 v90, v79, v88
	v_sub_f32_e32 v78, v79, v80
	v_mul_f32_e32 v80, v87, v90
	v_fma_f32 v82, v90, v87, -v80
	v_fmac_f32_e32 v82, v90, v77
	v_sub_f32_e32 v89, v81, v78
	v_add_f32_e32 v78, v80, v82
	v_sub_f32_e32 v81, v79, v78
	v_pk_add_f32 v[84:85], v[78:79], v[80:81] neg_lo:[0,1] neg_hi:[0,1]
	v_mov_b32_e32 v83, v78
	v_pk_add_f32 v[78:79], v[84:85], v[82:83] neg_lo:[0,1] neg_hi:[0,1]
	v_cmp_neq_f32_e32 vcc, s0, v76
	v_add_f32_e32 v79, v89, v79
	v_add_f32_e32 v78, v78, v79
	v_add_f32_e32 v79, v81, v78
	v_mul_f32_e32 v89, v88, v79
	v_mul_f32_e32 v80, v87, v89
	v_fma_f32 v82, v89, v87, -v80
	v_fmac_f32_e32 v82, v89, v77
	v_sub_f32_e32 v77, v81, v79
	v_add_f32_e32 v77, v78, v77
	v_add_f32_e32 v78, v80, v82
	v_sub_f32_e32 v81, v79, v78
	v_pk_add_f32 v[84:85], v[78:79], v[80:81] neg_lo:[0,1] neg_hi:[0,1]
	v_mov_b32_e32 v83, v78
	v_pk_add_f32 v[78:79], v[84:85], v[82:83] neg_lo:[0,1] neg_hi:[0,1]
	s_nop 0
	v_add_f32_e32 v77, v77, v79
	v_add_f32_e32 v77, v78, v77
	v_add_f32_e32 v79, v90, v89
	v_add_f32_e32 v77, v81, v77
	v_sub_f32_e32 v78, v79, v90
	v_mul_f32_e32 v77, v88, v77
	v_sub_f32_e32 v78, v89, v78
	v_add_f32_e32 v77, v78, v77
	v_add_f32_e32 v80, v79, v77
	v_mul_f32_e32 v82, v80, v80
	v_fmamk_f32 v78, v82, 0x3e9b6dac, v210
	v_fmaak_f32 v121, v82, v78, 0x3f2aaada
	v_cvt_f32_i32_e32 v78, v86
	v_sub_f32_e32 v79, v80, v79
	v_sub_f32_e32 v77, v77, v79
	v_mul_f32_e32 v79, v80, v82
	v_pk_mul_f32 v[82:83], v[78:79], v[120:121]
	v_ldexp_f32 v81, v80, 1
	v_fma_f32 v80, v78, s1, -v82
	v_fmac_f32_e32 v80, 0xb102e308, v78
	v_pk_add_f32 v[78:79], v[82:83], v[80:81]
	v_ldexp_f32 v77, v77, 1
	v_sub_f32_e32 v81, v79, v81
	v_sub_f32_e32 v81, v83, v81
	v_add_f32_e32 v85, v77, v81
	v_mov_b32_e32 v84, v82
	v_pk_add_f32 v[82:83], v[78:79], v[82:83] neg_lo:[0,1] neg_hi:[0,1]
	v_pk_add_f32 v[86:87], v[78:79], v[84:85]
	v_mov_b32_e32 v81, v78
	v_mov_b32_e32 v83, v87
	v_pk_add_f32 v[88:89], v[80:81], v[82:83] neg_lo:[0,1] neg_hi:[0,1]
	v_pk_add_f32 v[80:81], v[80:81], v[82:83]
	v_mov_b32_e32 v84, v85
	v_pk_add_f32 v[82:83], v[80:81], v[78:79] op_sel:[1,0] op_sel_hi:[0,1] neg_lo:[0,1] neg_hi:[0,1]
	v_pk_add_f32 v[90:91], v[86:87], v[82:83] op_sel_hi:[1,0] neg_lo:[0,1] neg_hi:[0,1]
	v_mov_b32_e32 v86, v87
	v_mov_b32_e32 v87, v81
	v_pk_mov_b32 v[82:83], v[78:79], v[82:83] op_sel:[1,0]
	v_mov_b32_e32 v85, v78
	v_pk_add_f32 v[82:83], v[86:87], v[82:83] neg_lo:[0,1] neg_hi:[0,1]
	v_mov_b32_e32 v90, v88
	v_pk_add_f32 v[78:79], v[84:85], v[82:83] neg_lo:[0,1] neg_hi:[0,1]
	v_mov_b32_e32 v89, v81
	v_pk_add_f32 v[82:83], v[90:91], v[78:79]
	s_nop 0
	v_pk_add_f32 v[84:85], v[82:83], v[82:83] op_sel:[0,1] op_sel_hi:[1,0]
	s_nop 0
	v_pk_add_f32 v[80:81], v[80:81], v[84:85] op_sel:[1,0] op_sel_hi:[0,1]
	v_mov_b32_e32 v83, v80
	v_pk_add_f32 v[86:87], v[82:83], v[88:89] neg_lo:[0,1] neg_hi:[0,1]
	v_mov_b32_e32 v79, v84
	v_sub_f32_e32 v77, v82, v86
	v_pk_add_f32 v[78:79], v[78:79], v[86:87] neg_lo:[0,1] neg_hi:[0,1]
	v_sub_f32_e32 v77, v88, v77
	v_add_f32_e32 v77, v78, v77
	v_add_f32_e32 v77, v77, v79
	v_add_f32_e32 v77, v80, v77
	v_cndmask_b32_e32 v77, v224, v77, vcc
	v_cmp_ngt_f32_e32 vcc, -1.0, v76
	s_nop 1
	v_cndmask_b32_e32 v77, v225, v77, vcc
	v_cmp_neq_f32_e32 vcc, -1.0, v76
	s_nop 1
	v_cndmask_b32_e32 v77, v226, v77, vcc
	v_cmp_lt_f32_e64 vcc, |v76|, s56
	s_nop 1
	v_cndmask_b32_e32 v76, v77, v76, vcc
	v_add_f32_e32 v73, v73, v76

.LBB0_1385:
	s_and_b64 vcc, exec, s[4:5]
	v_or_b32_e32 v72, 50, v74
	s_cbranch_vccnz .LBB0_1731
	s_andn2_b64 vcc, exec, s[36:37]
	v_mov_b32_e32 v73, v6
	s_cbranch_vccnz .LBB0_1388
	s_nop 0
	v_lshl_add_u64 v[76:77], v[66:67], 0, s[80:81]
	s_waitcnt lgkmcnt(0)
	v_lshl_add_u64 v[76:77], v[76:77], 2, s[8:9]
	v_mov_b32_e32 v73, v250
	s_nop 0
	v_add_f32_e32 v76, v6, v73
	v_max_f32_e32 v73, 0, v76
	v_mul_f32_e64 v76, |v76|, s73
	v_exp_f32_e32 v76, v76
	s_nop 0
	v_add_f32_e32 v77, 1.0, v76
	v_add_f32_e32 v78, -1.0, v77
	v_sub_f32_e32 v79, v78, v77
	v_add_f32_e32 v79, 1.0, v79
	v_sub_f32_e32 v78, v76, v78
	v_add_f32_e32 v80, v78, v79
	v_frexp_mant_f32_e32 v78, v77
	v_cmp_gt_f32_e32 vcc, s46, v78
	v_cvt_f64_f32_e32 v[78:79], v77
	v_frexp_exp_i32_f64_e32 v78, v[78:79]
	v_subbrev_co_u32_e32 v86, vcc, 0, v78, vcc
	v_sub_u32_e32 v78, 0, v86
	v_ldexp_f32 v77, v77, v78
	v_ldexp_f32 v78, v80, v78
	v_add_f32_e32 v80, -1.0, v77
	v_add_f32_e32 v79, 1.0, v80
	v_sub_f32_e32 v79, v77, v79
	v_add_f32_e32 v81, v78, v79
	v_add_f32_e32 v79, 1.0, v77
	v_add_f32_e32 v82, -1.0, v79
	v_sub_f32_e32 v77, v77, v82
	v_add_f32_e32 v77, v78, v77
	v_add_f32_e32 v87, v79, v77
	v_rcp_f32_e32 v88, v87
	v_sub_f32_e32 v78, v87, v79
	v_add_f32_e32 v79, v80, v81
	v_sub_f32_e32 v77, v77, v78
	v_mul_f32_e32 v90, v79, v88
	v_sub_f32_e32 v78, v79, v80
	v_mul_f32_e32 v80, v87, v90
	v_fma_f32 v82, v90, v87, -v80
	v_fmac_f32_e32 v82, v90, v77
	v_sub_f32_e32 v89, v81, v78
	v_add_f32_e32 v78, v80, v82
	v_sub_f32_e32 v81, v79, v78
	v_pk_add_f32 v[84:85], v[78:79], v[80:81] neg_lo:[0,1] neg_hi:[0,1]
	v_mov_b32_e32 v83, v78
	v_pk_add_f32 v[78:79], v[84:85], v[82:83] neg_lo:[0,1] neg_hi:[0,1]
	v_cmp_neq_f32_e32 vcc, s0, v76
	v_add_f32_e32 v79, v89, v79
	v_add_f32_e32 v78, v78, v79
	v_add_f32_e32 v79, v81, v78
	v_mul_f32_e32 v89, v88, v79
	v_mul_f32_e32 v80, v87, v89
	v_fma_f32 v82, v89, v87, -v80
	v_fmac_f32_e32 v82, v89, v77
	v_sub_f32_e32 v77, v81, v79
	v_add_f32_e32 v77, v78, v77
	v_add_f32_e32 v78, v80, v82
	v_sub_f32_e32 v81, v79, v78
	v_pk_add_f32 v[84:85], v[78:79], v[80:81] neg_lo:[0,1] neg_hi:[0,1]
	v_mov_b32_e32 v83, v78
	v_pk_add_f32 v[78:79], v[84:85], v[82:83] neg_lo:[0,1] neg_hi:[0,1]
	s_nop 0
	v_add_f32_e32 v77, v77, v79
	v_add_f32_e32 v77, v78, v77
	v_add_f32_e32 v79, v90, v89
	v_add_f32_e32 v77, v81, v77
	v_sub_f32_e32 v78, v79, v90
	v_mul_f32_e32 v77, v88, v77
	v_sub_f32_e32 v78, v89, v78
	v_add_f32_e32 v77, v78, v77
	v_add_f32_e32 v80, v79, v77
	v_mul_f32_e32 v82, v80, v80
	v_fmamk_f32 v78, v82, 0x3e9b6dac, v210
	v_fmaak_f32 v121, v82, v78, 0x3f2aaada
	v_cvt_f32_i32_e32 v78, v86
	v_sub_f32_e32 v79, v80, v79
	v_sub_f32_e32 v77, v77, v79
	v_mul_f32_e32 v79, v80, v82
	v_pk_mul_f32 v[82:83], v[78:79], v[120:121]
	v_ldexp_f32 v81, v80, 1
	v_fma_f32 v80, v78, s1, -v82
	v_fmac_f32_e32 v80, 0xb102e308, v78
	v_pk_add_f32 v[78:79], v[82:83], v[80:81]
	v_ldexp_f32 v77, v77, 1
	v_sub_f32_e32 v81, v79, v81
	v_sub_f32_e32 v81, v83, v81
	v_add_f32_e32 v85, v77, v81
	v_mov_b32_e32 v84, v82
	v_pk_add_f32 v[82:83], v[78:79], v[82:83] neg_lo:[0,1] neg_hi:[0,1]
	v_pk_add_f32 v[86:87], v[78:79], v[84:85]
	v_mov_b32_e32 v81, v78
	v_mov_b32_e32 v83, v87
	v_pk_add_f32 v[88:89], v[80:81], v[82:83] neg_lo:[0,1] neg_hi:[0,1]
	v_pk_add_f32 v[80:81], v[80:81], v[82:83]
	v_mov_b32_e32 v84, v85
	v_pk_add_f32 v[82:83], v[80:81], v[78:79] op_sel:[1,0] op_sel_hi:[0,1] neg_lo:[0,1] neg_hi:[0,1]
	v_pk_add_f32 v[90:91], v[86:87], v[82:83] op_sel_hi:[1,0] neg_lo:[0,1] neg_hi:[0,1]
	v_mov_b32_e32 v86, v87
	v_mov_b32_e32 v87, v81
	v_pk_mov_b32 v[82:83], v[78:79], v[82:83] op_sel:[1,0]
	v_mov_b32_e32 v85, v78
	v_pk_add_f32 v[82:83], v[86:87], v[82:83] neg_lo:[0,1] neg_hi:[0,1]
	v_mov_b32_e32 v90, v88
	v_pk_add_f32 v[78:79], v[84:85], v[82:83] neg_lo:[0,1] neg_hi:[0,1]
	v_mov_b32_e32 v89, v81
	v_pk_add_f32 v[82:83], v[90:91], v[78:79]
	s_nop 0
	v_pk_add_f32 v[84:85], v[82:83], v[82:83] op_sel:[0,1] op_sel_hi:[1,0]
	s_nop 0
	v_pk_add_f32 v[80:81], v[80:81], v[84:85] op_sel:[1,0] op_sel_hi:[0,1]
	v_mov_b32_e32 v83, v80
	v_pk_add_f32 v[86:87], v[82:83], v[88:89] neg_lo:[0,1] neg_hi:[0,1]
	v_mov_b32_e32 v79, v84
	v_sub_f32_e32 v77, v82, v86
	v_pk_add_f32 v[78:79], v[78:79], v[86:87] neg_lo:[0,1] neg_hi:[0,1]
	v_sub_f32_e32 v77, v88, v77
	v_add_f32_e32 v77, v78, v77
	v_add_f32_e32 v77, v77, v79
	v_add_f32_e32 v77, v80, v77
	v_cndmask_b32_e32 v77, v224, v77, vcc
	v_cmp_ngt_f32_e32 vcc, -1.0, v76
	s_nop 1
	v_cndmask_b32_e32 v77, v225, v77, vcc
	v_cmp_neq_f32_e32 vcc, -1.0, v76
	s_nop 1
	v_cndmask_b32_e32 v77, v226, v77, vcc
	v_cmp_lt_f32_e64 vcc, |v76|, s56
	s_nop 1
	v_cndmask_b32_e32 v76, v77, v76, vcc
	v_add_f32_e32 v73, v73, v76

.LBB0_1390:
	s_and_b64 vcc, exec, s[4:5]
	v_or_b32_e32 v72, 51, v74
	s_cbranch_vccnz .LBB0_1732
	s_andn2_b64 vcc, exec, s[36:37]
	v_mov_b32_e32 v73, v7
	s_cbranch_vccnz .LBB0_1393
	s_nop 0
	v_lshl_add_u64 v[76:77], v[66:67], 0, s[80:81]
	s_waitcnt lgkmcnt(0)
	v_lshl_add_u64 v[76:77], v[76:77], 2, s[8:9]
	v_mov_b32_e32 v73, v250
	s_nop 0
	v_add_f32_e32 v76, v7, v73
	v_max_f32_e32 v73, 0, v76
	v_mul_f32_e64 v76, |v76|, s73
	v_exp_f32_e32 v76, v76
	s_nop 0
	v_add_f32_e32 v77, 1.0, v76
	v_add_f32_e32 v78, -1.0, v77
	v_sub_f32_e32 v79, v78, v77
	v_add_f32_e32 v79, 1.0, v79
	v_sub_f32_e32 v78, v76, v78
	v_add_f32_e32 v80, v78, v79
	v_frexp_mant_f32_e32 v78, v77
	v_cmp_gt_f32_e32 vcc, s46, v78
	v_cvt_f64_f32_e32 v[78:79], v77
	v_frexp_exp_i32_f64_e32 v78, v[78:79]
	v_subbrev_co_u32_e32 v86, vcc, 0, v78, vcc
	v_sub_u32_e32 v78, 0, v86
	v_ldexp_f32 v77, v77, v78
	v_ldexp_f32 v78, v80, v78
	v_add_f32_e32 v80, -1.0, v77
	v_add_f32_e32 v79, 1.0, v80
	v_sub_f32_e32 v79, v77, v79
	v_add_f32_e32 v81, v78, v79
	v_add_f32_e32 v79, 1.0, v77
	v_add_f32_e32 v82, -1.0, v79
	v_sub_f32_e32 v77, v77, v82
	v_add_f32_e32 v77, v78, v77
	v_add_f32_e32 v87, v79, v77
	v_rcp_f32_e32 v88, v87
	v_sub_f32_e32 v78, v87, v79
	v_add_f32_e32 v79, v80, v81
	v_sub_f32_e32 v77, v77, v78
	v_mul_f32_e32 v90, v79, v88
	v_sub_f32_e32 v78, v79, v80
	v_mul_f32_e32 v80, v87, v90
	v_fma_f32 v82, v90, v87, -v80
	v_fmac_f32_e32 v82, v90, v77
	v_sub_f32_e32 v89, v81, v78
	v_add_f32_e32 v78, v80, v82
	v_sub_f32_e32 v81, v79, v78
	v_pk_add_f32 v[84:85], v[78:79], v[80:81] neg_lo:[0,1] neg_hi:[0,1]
	v_mov_b32_e32 v83, v78
	v_pk_add_f32 v[78:79], v[84:85], v[82:83] neg_lo:[0,1] neg_hi:[0,1]
	v_cmp_neq_f32_e32 vcc, s0, v76
	v_add_f32_e32 v79, v89, v79
	v_add_f32_e32 v78, v78, v79
	v_add_f32_e32 v79, v81, v78
	v_mul_f32_e32 v89, v88, v79
	v_mul_f32_e32 v80, v87, v89
	v_fma_f32 v82, v89, v87, -v80
	v_fmac_f32_e32 v82, v89, v77
	v_sub_f32_e32 v77, v81, v79
	v_add_f32_e32 v77, v78, v77
	v_add_f32_e32 v78, v80, v82
	v_sub_f32_e32 v81, v79, v78
	v_pk_add_f32 v[84:85], v[78:79], v[80:81] neg_lo:[0,1] neg_hi:[0,1]
	v_mov_b32_e32 v83, v78
	v_pk_add_f32 v[78:79], v[84:85], v[82:83] neg_lo:[0,1] neg_hi:[0,1]
	s_nop 0
	v_add_f32_e32 v77, v77, v79
	v_add_f32_e32 v77, v78, v77
	v_add_f32_e32 v79, v90, v89
	v_add_f32_e32 v77, v81, v77
	v_sub_f32_e32 v78, v79, v90
	v_mul_f32_e32 v77, v88, v77
	v_sub_f32_e32 v78, v89, v78
	v_add_f32_e32 v77, v78, v77
	v_add_f32_e32 v80, v79, v77
	v_mul_f32_e32 v82, v80, v80
	v_fmamk_f32 v78, v82, 0x3e9b6dac, v210
	v_fmaak_f32 v121, v82, v78, 0x3f2aaada
	v_cvt_f32_i32_e32 v78, v86
	v_sub_f32_e32 v79, v80, v79
	v_sub_f32_e32 v77, v77, v79
	v_mul_f32_e32 v79, v80, v82
	v_pk_mul_f32 v[82:83], v[78:79], v[120:121]
	v_ldexp_f32 v81, v80, 1
	v_fma_f32 v80, v78, s1, -v82
	v_fmac_f32_e32 v80, 0xb102e308, v78
	v_pk_add_f32 v[78:79], v[82:83], v[80:81]
	v_ldexp_f32 v77, v77, 1
	v_sub_f32_e32 v81, v79, v81
	v_sub_f32_e32 v81, v83, v81
	v_add_f32_e32 v85, v77, v81
	v_mov_b32_e32 v84, v82
	v_pk_add_f32 v[82:83], v[78:79], v[82:83] neg_lo:[0,1] neg_hi:[0,1]
	v_pk_add_f32 v[86:87], v[78:79], v[84:85]
	v_mov_b32_e32 v81, v78
	v_mov_b32_e32 v83, v87
	v_pk_add_f32 v[88:89], v[80:81], v[82:83] neg_lo:[0,1] neg_hi:[0,1]
	v_pk_add_f32 v[80:81], v[80:81], v[82:83]
	v_mov_b32_e32 v84, v85
	v_pk_add_f32 v[82:83], v[80:81], v[78:79] op_sel:[1,0] op_sel_hi:[0,1] neg_lo:[0,1] neg_hi:[0,1]
	v_pk_add_f32 v[90:91], v[86:87], v[82:83] op_sel_hi:[1,0] neg_lo:[0,1] neg_hi:[0,1]
	v_mov_b32_e32 v86, v87
	v_mov_b32_e32 v87, v81
	v_pk_mov_b32 v[82:83], v[78:79], v[82:83] op_sel:[1,0]
	v_mov_b32_e32 v85, v78
	v_pk_add_f32 v[82:83], v[86:87], v[82:83] neg_lo:[0,1] neg_hi:[0,1]
	v_mov_b32_e32 v90, v88
	v_pk_add_f32 v[78:79], v[84:85], v[82:83] neg_lo:[0,1] neg_hi:[0,1]
	v_mov_b32_e32 v89, v81
	v_pk_add_f32 v[82:83], v[90:91], v[78:79]
	s_nop 0
	v_pk_add_f32 v[84:85], v[82:83], v[82:83] op_sel:[0,1] op_sel_hi:[1,0]
	s_nop 0
	v_pk_add_f32 v[80:81], v[80:81], v[84:85] op_sel:[1,0] op_sel_hi:[0,1]
	v_mov_b32_e32 v83, v80
	v_pk_add_f32 v[86:87], v[82:83], v[88:89] neg_lo:[0,1] neg_hi:[0,1]
	v_mov_b32_e32 v79, v84
	v_sub_f32_e32 v77, v82, v86
	v_pk_add_f32 v[78:79], v[78:79], v[86:87] neg_lo:[0,1] neg_hi:[0,1]
	v_sub_f32_e32 v77, v88, v77
	v_add_f32_e32 v77, v78, v77
	v_add_f32_e32 v77, v77, v79
	v_add_f32_e32 v77, v80, v77
	v_cndmask_b32_e32 v77, v224, v77, vcc
	v_cmp_ngt_f32_e32 vcc, -1.0, v76
	s_nop 1
	v_cndmask_b32_e32 v77, v225, v77, vcc
	v_cmp_neq_f32_e32 vcc, -1.0, v76
	s_nop 1
	v_cndmask_b32_e32 v77, v226, v77, vcc
	v_cmp_lt_f32_e64 vcc, |v76|, s56
	s_nop 1
	v_cndmask_b32_e32 v76, v77, v76, vcc
	v_add_f32_e32 v73, v73, v76

.LBB0_1395:
	s_or_b64 exec, exec, s[6:7]
	s_and_saveexec_b64 s[8:9], s[12:13]
	s_cbranch_execz .LBB0_1416
	v_cndmask_b32_e64 v70, 0, 1, s[36:37]
	v_lshl_add_u64 v[68:69], v[66:67], 2, s[34:35]
	s_and_b64 vcc, exec, s[4:5]
	v_cmp_ne_u32_e64 s[6:7], 1, v70
	s_cbranch_vccnz .LBB0_1733
	s_and_b64 vcc, exec, s[6:7]
	v_mov_b32_e32 v70, v0
	s_cbranch_vccnz .LBB0_1399
	s_nop 0
	v_lshl_add_u64 v[70:71], v[66:67], 0, s[80:81]
	s_waitcnt lgkmcnt(0)
	v_lshl_add_u64 v[70:71], v[70:71], 2, s[10:11]
	v_mov_b32_e32 v70, v251
	s_nop 0
	v_add_f32_e32 v71, v0, v70
	v_max_f32_e32 v70, 0, v71
	v_mul_f32_e64 v71, |v71|, s73
	v_exp_f32_e32 v71, v71
	s_nop 0
	v_add_f32_e32 v76, 1.0, v71
	v_add_f32_e32 v72, -1.0, v76
	v_sub_f32_e32 v73, v72, v76
	v_add_f32_e32 v73, 1.0, v73
	v_sub_f32_e32 v72, v71, v72
	v_add_f32_e32 v77, v72, v73
	v_frexp_mant_f32_e32 v72, v76
	v_cmp_gt_f32_e32 vcc, s46, v72
	v_cvt_f64_f32_e32 v[72:73], v76
	v_frexp_exp_i32_f64_e32 v72, v[72:73]
	v_subbrev_co_u32_e32 v82, vcc, 0, v72, vcc
	v_sub_u32_e32 v72, 0, v82
	v_ldexp_f32 v73, v76, v72
	v_add_f32_e32 v76, -1.0, v73
	v_add_f32_e32 v78, 1.0, v73
	v_ldexp_f32 v72, v77, v72
	v_add_f32_e32 v77, 1.0, v76
	v_add_f32_e32 v79, -1.0, v78
	v_sub_f32_e32 v77, v73, v77
	v_sub_f32_e32 v73, v73, v79
	v_add_f32_e32 v77, v72, v77
	v_add_f32_e32 v72, v72, v73
	v_add_f32_e32 v83, v78, v72
	v_rcp_f32_e32 v85, v83
	v_sub_f32_e32 v73, v83, v78
	v_sub_f32_e32 v84, v72, v73
	v_add_f32_e32 v73, v76, v77
	v_mul_f32_e32 v87, v73, v85
	v_sub_f32_e32 v72, v73, v76
	v_mul_f32_e32 v76, v83, v87
	v_fma_f32 v78, v87, v83, -v76
	v_fmac_f32_e32 v78, v87, v84
	v_sub_f32_e32 v86, v77, v72
	v_add_f32_e32 v72, v76, v78
	v_sub_f32_e32 v77, v73, v72
	v_pk_add_f32 v[80:81], v[72:73], v[76:77] neg_lo:[0,1] neg_hi:[0,1]
	v_mov_b32_e32 v79, v72
	v_pk_add_f32 v[72:73], v[80:81], v[78:79] neg_lo:[0,1] neg_hi:[0,1]
	v_cmp_neq_f32_e32 vcc, s0, v71
	v_add_f32_e32 v73, v86, v73
	v_add_f32_e32 v72, v72, v73
	v_add_f32_e32 v73, v77, v72
	v_mul_f32_e32 v86, v85, v73
	v_mul_f32_e32 v76, v83, v86
	v_fma_f32 v78, v86, v83, -v76
	v_fmac_f32_e32 v78, v86, v84
	v_sub_f32_e32 v77, v77, v73
	v_add_f32_e32 v83, v72, v77
	v_add_f32_e32 v72, v76, v78
	v_sub_f32_e32 v77, v73, v72
	v_pk_add_f32 v[80:81], v[72:73], v[76:77] neg_lo:[0,1] neg_hi:[0,1]
	v_mov_b32_e32 v79, v72
	v_pk_add_f32 v[72:73], v[80:81], v[78:79] neg_lo:[0,1] neg_hi:[0,1]
	s_nop 0
	v_add_f32_e32 v73, v83, v73
	v_add_f32_e32 v72, v72, v73
	v_add_f32_e32 v73, v87, v86
	v_add_f32_e32 v72, v77, v72
	v_sub_f32_e32 v76, v73, v87
	v_mul_f32_e32 v72, v85, v72
	v_sub_f32_e32 v76, v86, v76
	v_add_f32_e32 v76, v76, v72
	v_add_f32_e32 v78, v73, v76
	v_mul_f32_e32 v79, v78, v78
	v_fmamk_f32 v72, v79, 0x3e9b6dac, v210
	v_fmaak_f32 v121, v79, v72, 0x3f2aaada
	v_cvt_f32_i32_e32 v72, v82
	v_sub_f32_e32 v73, v78, v73
	v_sub_f32_e32 v73, v76, v73
	v_ldexp_f32 v80, v73, 1
	v_mul_f32_e32 v73, v78, v79
	v_ldexp_f32 v77, v78, 1
	v_pk_mul_f32 v[78:79], v[72:73], v[120:121]
	s_nop 0
	v_fma_f32 v76, v72, s1, -v78
	v_fmac_f32_e32 v76, 0xb102e308, v72
	v_pk_add_f32 v[72:73], v[78:79], v[76:77]
	s_nop 0
	v_sub_f32_e32 v77, v73, v77
	v_sub_f32_e32 v77, v79, v77
	v_add_f32_e32 v81, v80, v77
	v_mov_b32_e32 v80, v78
	v_pk_add_f32 v[78:79], v[72:73], v[78:79] neg_lo:[0,1] neg_hi:[0,1]
	v_pk_add_f32 v[82:83], v[72:73], v[80:81]
	v_mov_b32_e32 v77, v72
	v_mov_b32_e32 v79, v83
	v_pk_add_f32 v[84:85], v[76:77], v[78:79] neg_lo:[0,1] neg_hi:[0,1]
	v_pk_add_f32 v[76:77], v[76:77], v[78:79]
	v_mov_b32_e32 v80, v81
	v_pk_add_f32 v[78:79], v[76:77], v[72:73] op_sel:[1,0] op_sel_hi:[0,1] neg_lo:[0,1] neg_hi:[0,1]
	v_pk_add_f32 v[86:87], v[82:83], v[78:79] op_sel_hi:[1,0] neg_lo:[0,1] neg_hi:[0,1]
	v_mov_b32_e32 v82, v83
	v_mov_b32_e32 v83, v77
	v_pk_mov_b32 v[78:79], v[72:73], v[78:79] op_sel:[1,0]
	v_mov_b32_e32 v81, v72
	v_pk_add_f32 v[78:79], v[82:83], v[78:79] neg_lo:[0,1] neg_hi:[0,1]
	v_mov_b32_e32 v86, v84
	v_pk_add_f32 v[72:73], v[80:81], v[78:79] neg_lo:[0,1] neg_hi:[0,1]
	v_mov_b32_e32 v85, v77
	v_pk_add_f32 v[78:79], v[86:87], v[72:73]
	s_nop 0
	v_pk_add_f32 v[80:81], v[78:79], v[78:79] op_sel:[0,1] op_sel_hi:[1,0]
	s_nop 0
	v_pk_add_f32 v[76:77], v[76:77], v[80:81] op_sel:[1,0] op_sel_hi:[0,1]
	v_mov_b32_e32 v79, v76
	v_pk_add_f32 v[82:83], v[78:79], v[84:85] neg_lo:[0,1] neg_hi:[0,1]
	v_mov_b32_e32 v73, v80
	v_sub_f32_e32 v77, v78, v82
	v_pk_add_f32 v[72:73], v[72:73], v[82:83] neg_lo:[0,1] neg_hi:[0,1]
	v_sub_f32_e32 v77, v84, v77
	v_add_f32_e32 v72, v72, v77
	v_add_f32_e32 v72, v72, v73
	v_add_f32_e32 v72, v76, v72
	v_cndmask_b32_e32 v72, v224, v72, vcc
	v_cmp_ngt_f32_e32 vcc, -1.0, v71
	s_nop 1
	v_cndmask_b32_e32 v72, v225, v72, vcc
	v_cmp_neq_f32_e32 vcc, -1.0, v71
	s_nop 1
	v_cndmask_b32_e32 v72, v226, v72, vcc
	v_cmp_lt_f32_e64 vcc, |v71|, s56
	s_nop 1
	v_cndmask_b32_e32 v71, v72, v71, vcc
	v_add_f32_e32 v70, v70, v71

.LBB0_1401:
	s_and_b64 vcc, exec, s[4:5]
	v_or_b32_e32 v72, 49, v74
	s_cbranch_vccnz .LBB0_1734
	s_and_b64 vcc, exec, s[6:7]
	v_mov_b32_e32 v73, v1
	s_cbranch_vccnz .LBB0_1404
	s_nop 0
	v_lshl_add_u64 v[76:77], v[66:67], 0, s[80:81]
	s_waitcnt lgkmcnt(0)
	v_lshl_add_u64 v[76:77], v[76:77], 2, s[10:11]
	v_mov_b32_e32 v73, v251
	s_nop 0
	v_add_f32_e32 v75, v1, v73
	v_max_f32_e32 v73, 0, v75
	v_mul_f32_e64 v75, |v75|, s73
	v_exp_f32_e32 v75, v75
	s_nop 0
	v_add_f32_e32 v78, 1.0, v75
	v_add_f32_e32 v76, -1.0, v78
	v_sub_f32_e32 v77, v76, v78
	v_add_f32_e32 v77, 1.0, v77
	v_sub_f32_e32 v76, v75, v76
	v_add_f32_e32 v79, v76, v77
	v_frexp_mant_f32_e32 v76, v78
	v_cmp_gt_f32_e32 vcc, s46, v76
	v_cvt_f64_f32_e32 v[76:77], v78
	v_frexp_exp_i32_f64_e32 v76, v[76:77]
	v_subbrev_co_u32_e32 v84, vcc, 0, v76, vcc
	v_sub_u32_e32 v76, 0, v84
	v_ldexp_f32 v77, v78, v76
	v_add_f32_e32 v78, -1.0, v77
	v_add_f32_e32 v80, 1.0, v77
	v_ldexp_f32 v76, v79, v76
	v_add_f32_e32 v79, 1.0, v78
	v_add_f32_e32 v81, -1.0, v80
	v_sub_f32_e32 v79, v77, v79
	v_sub_f32_e32 v77, v77, v81
	v_add_f32_e32 v79, v76, v79
	v_add_f32_e32 v76, v76, v77
	v_add_f32_e32 v85, v80, v76
	v_rcp_f32_e32 v87, v85
	v_sub_f32_e32 v77, v85, v80
	v_sub_f32_e32 v86, v76, v77
	v_add_f32_e32 v77, v78, v79
	v_mul_f32_e32 v89, v77, v87
	v_sub_f32_e32 v76, v77, v78
	v_mul_f32_e32 v78, v85, v89
	v_fma_f32 v80, v89, v85, -v78
	v_fmac_f32_e32 v80, v89, v86
	v_sub_f32_e32 v88, v79, v76
	v_add_f32_e32 v76, v78, v80
	v_sub_f32_e32 v79, v77, v76
	v_pk_add_f32 v[82:83], v[76:77], v[78:79] neg_lo:[0,1] neg_hi:[0,1]
	v_mov_b32_e32 v81, v76
	v_pk_add_f32 v[76:77], v[82:83], v[80:81] neg_lo:[0,1] neg_hi:[0,1]
	v_cmp_neq_f32_e32 vcc, s0, v75
	v_add_f32_e32 v77, v88, v77
	v_add_f32_e32 v76, v76, v77
	v_add_f32_e32 v77, v79, v76
	v_mul_f32_e32 v88, v87, v77
	v_mul_f32_e32 v78, v85, v88
	v_fma_f32 v80, v88, v85, -v78
	v_fmac_f32_e32 v80, v88, v86
	v_sub_f32_e32 v79, v79, v77
	v_add_f32_e32 v85, v76, v79
	v_add_f32_e32 v76, v78, v80
	v_sub_f32_e32 v79, v77, v76
	v_pk_add_f32 v[82:83], v[76:77], v[78:79] neg_lo:[0,1] neg_hi:[0,1]
	v_mov_b32_e32 v81, v76
	v_pk_add_f32 v[76:77], v[82:83], v[80:81] neg_lo:[0,1] neg_hi:[0,1]
	s_nop 0
	v_add_f32_e32 v77, v85, v77
	v_add_f32_e32 v76, v76, v77
	v_add_f32_e32 v77, v89, v88
	v_add_f32_e32 v76, v79, v76
	v_sub_f32_e32 v78, v77, v89
	v_mul_f32_e32 v76, v87, v76
	v_sub_f32_e32 v78, v88, v78
	v_add_f32_e32 v78, v78, v76
	v_add_f32_e32 v80, v77, v78
	v_mul_f32_e32 v81, v80, v80
	v_fmamk_f32 v76, v81, 0x3e9b6dac, v210
	v_fmaak_f32 v121, v81, v76, 0x3f2aaada
	v_cvt_f32_i32_e32 v76, v84
	v_sub_f32_e32 v77, v80, v77
	v_sub_f32_e32 v77, v78, v77
	v_ldexp_f32 v82, v77, 1
	v_mul_f32_e32 v77, v80, v81
	v_ldexp_f32 v79, v80, 1
	v_pk_mul_f32 v[80:81], v[76:77], v[120:121]
	s_nop 0
	v_fma_f32 v78, v76, s1, -v80
	v_fmac_f32_e32 v78, 0xb102e308, v76
	v_pk_add_f32 v[76:77], v[80:81], v[78:79]
	s_nop 0
	v_sub_f32_e32 v79, v77, v79
	v_sub_f32_e32 v79, v81, v79
	v_add_f32_e32 v83, v82, v79
	v_mov_b32_e32 v82, v80
	v_pk_add_f32 v[80:81], v[76:77], v[80:81] neg_lo:[0,1] neg_hi:[0,1]
	v_pk_add_f32 v[84:85], v[76:77], v[82:83]
	v_mov_b32_e32 v79, v76
	v_mov_b32_e32 v81, v85
	v_pk_add_f32 v[86:87], v[78:79], v[80:81] neg_lo:[0,1] neg_hi:[0,1]
	v_pk_add_f32 v[78:79], v[78:79], v[80:81]
	v_mov_b32_e32 v82, v83
	v_pk_add_f32 v[80:81], v[78:79], v[76:77] op_sel:[1,0] op_sel_hi:[0,1] neg_lo:[0,1] neg_hi:[0,1]
	v_pk_add_f32 v[88:89], v[84:85], v[80:81] op_sel_hi:[1,0] neg_lo:[0,1] neg_hi:[0,1]
	v_mov_b32_e32 v84, v85
	v_mov_b32_e32 v85, v79
	v_pk_mov_b32 v[80:81], v[76:77], v[80:81] op_sel:[1,0]
	v_mov_b32_e32 v83, v76
	v_pk_add_f32 v[80:81], v[84:85], v[80:81] neg_lo:[0,1] neg_hi:[0,1]
	v_mov_b32_e32 v88, v86
	v_pk_add_f32 v[76:77], v[82:83], v[80:81] neg_lo:[0,1] neg_hi:[0,1]
	v_mov_b32_e32 v87, v79
	v_pk_add_f32 v[80:81], v[88:89], v[76:77]
	s_nop 0
	v_pk_add_f32 v[82:83], v[80:81], v[80:81] op_sel:[0,1] op_sel_hi:[1,0]
	s_nop 0
	v_pk_add_f32 v[78:79], v[78:79], v[82:83] op_sel:[1,0] op_sel_hi:[0,1]
	v_mov_b32_e32 v81, v78
	v_pk_add_f32 v[84:85], v[80:81], v[86:87] neg_lo:[0,1] neg_hi:[0,1]
	v_mov_b32_e32 v77, v82
	v_sub_f32_e32 v79, v80, v84
	v_pk_add_f32 v[76:77], v[76:77], v[84:85] neg_lo:[0,1] neg_hi:[0,1]
	v_sub_f32_e32 v79, v86, v79
	v_add_f32_e32 v76, v76, v79
	v_add_f32_e32 v76, v76, v77
	v_add_f32_e32 v76, v78, v76
	v_cndmask_b32_e32 v76, v224, v76, vcc
	v_cmp_ngt_f32_e32 vcc, -1.0, v75
	s_nop 1
	v_cndmask_b32_e32 v76, v225, v76, vcc
	v_cmp_neq_f32_e32 vcc, -1.0, v75
	s_nop 1
	v_cndmask_b32_e32 v76, v226, v76, vcc
	v_cmp_lt_f32_e64 vcc, |v75|, s56
	s_nop 1
	v_cndmask_b32_e32 v75, v76, v75, vcc
	v_add_f32_e32 v73, v73, v75

.LBB0_1406:
	s_and_b64 vcc, exec, s[4:5]
	v_or_b32_e32 v72, 50, v74
	s_cbranch_vccnz .LBB0_1735
	s_and_b64 vcc, exec, s[6:7]
	v_mov_b32_e32 v73, v2
	s_cbranch_vccnz .LBB0_1409
	s_nop 0
	v_lshl_add_u64 v[76:77], v[66:67], 0, s[80:81]
	s_waitcnt lgkmcnt(0)
	v_lshl_add_u64 v[76:77], v[76:77], 2, s[10:11]
	v_mov_b32_e32 v73, v251
	s_nop 0
	v_add_f32_e32 v75, v2, v73
	v_max_f32_e32 v73, 0, v75
	v_mul_f32_e64 v75, |v75|, s73
	v_exp_f32_e32 v75, v75
	s_nop 0
	v_add_f32_e32 v78, 1.0, v75
	v_add_f32_e32 v76, -1.0, v78
	v_sub_f32_e32 v77, v76, v78
	v_add_f32_e32 v77, 1.0, v77
	v_sub_f32_e32 v76, v75, v76
	v_add_f32_e32 v79, v76, v77
	v_frexp_mant_f32_e32 v76, v78
	v_cmp_gt_f32_e32 vcc, s46, v76
	v_cvt_f64_f32_e32 v[76:77], v78
	v_frexp_exp_i32_f64_e32 v76, v[76:77]
	v_subbrev_co_u32_e32 v84, vcc, 0, v76, vcc
	v_sub_u32_e32 v76, 0, v84
	v_ldexp_f32 v77, v78, v76
	v_add_f32_e32 v78, -1.0, v77
	v_add_f32_e32 v80, 1.0, v77
	v_ldexp_f32 v76, v79, v76
	v_add_f32_e32 v79, 1.0, v78
	v_add_f32_e32 v81, -1.0, v80
	v_sub_f32_e32 v79, v77, v79
	v_sub_f32_e32 v77, v77, v81
	v_add_f32_e32 v79, v76, v79
	v_add_f32_e32 v76, v76, v77
	v_add_f32_e32 v85, v80, v76
	v_rcp_f32_e32 v87, v85
	v_sub_f32_e32 v77, v85, v80
	v_sub_f32_e32 v86, v76, v77
	v_add_f32_e32 v77, v78, v79
	v_mul_f32_e32 v89, v77, v87
	v_sub_f32_e32 v76, v77, v78
	v_mul_f32_e32 v78, v85, v89
	v_fma_f32 v80, v89, v85, -v78
	v_fmac_f32_e32 v80, v89, v86
	v_sub_f32_e32 v88, v79, v76
	v_add_f32_e32 v76, v78, v80
	v_sub_f32_e32 v79, v77, v76
	v_pk_add_f32 v[82:83], v[76:77], v[78:79] neg_lo:[0,1] neg_hi:[0,1]
	v_mov_b32_e32 v81, v76
	v_pk_add_f32 v[76:77], v[82:83], v[80:81] neg_lo:[0,1] neg_hi:[0,1]
	v_cmp_neq_f32_e32 vcc, s0, v75
	v_add_f32_e32 v77, v88, v77
	v_add_f32_e32 v76, v76, v77
	v_add_f32_e32 v77, v79, v76
	v_mul_f32_e32 v88, v87, v77
	v_mul_f32_e32 v78, v85, v88
	v_fma_f32 v80, v88, v85, -v78
	v_fmac_f32_e32 v80, v88, v86
	v_sub_f32_e32 v79, v79, v77
	v_add_f32_e32 v85, v76, v79
	v_add_f32_e32 v76, v78, v80
	v_sub_f32_e32 v79, v77, v76
	v_pk_add_f32 v[82:83], v[76:77], v[78:79] neg_lo:[0,1] neg_hi:[0,1]
	v_mov_b32_e32 v81, v76
	v_pk_add_f32 v[76:77], v[82:83], v[80:81] neg_lo:[0,1] neg_hi:[0,1]
	s_nop 0
	v_add_f32_e32 v77, v85, v77
	v_add_f32_e32 v76, v76, v77
	v_add_f32_e32 v77, v89, v88
	v_add_f32_e32 v76, v79, v76
	v_sub_f32_e32 v78, v77, v89
	v_mul_f32_e32 v76, v87, v76
	v_sub_f32_e32 v78, v88, v78
	v_add_f32_e32 v78, v78, v76
	v_add_f32_e32 v80, v77, v78
	v_mul_f32_e32 v81, v80, v80
	v_fmamk_f32 v76, v81, 0x3e9b6dac, v210
	v_fmaak_f32 v121, v81, v76, 0x3f2aaada
	v_cvt_f32_i32_e32 v76, v84
	v_sub_f32_e32 v77, v80, v77
	v_sub_f32_e32 v77, v78, v77
	v_ldexp_f32 v82, v77, 1
	v_mul_f32_e32 v77, v80, v81
	v_ldexp_f32 v79, v80, 1
	v_pk_mul_f32 v[80:81], v[76:77], v[120:121]
	s_nop 0
	v_fma_f32 v78, v76, s1, -v80
	v_fmac_f32_e32 v78, 0xb102e308, v76
	v_pk_add_f32 v[76:77], v[80:81], v[78:79]
	s_nop 0
	v_sub_f32_e32 v79, v77, v79
	v_sub_f32_e32 v79, v81, v79
	v_add_f32_e32 v83, v82, v79
	v_mov_b32_e32 v82, v80
	v_pk_add_f32 v[80:81], v[76:77], v[80:81] neg_lo:[0,1] neg_hi:[0,1]
	v_pk_add_f32 v[84:85], v[76:77], v[82:83]
	v_mov_b32_e32 v79, v76
	v_mov_b32_e32 v81, v85
	v_pk_add_f32 v[86:87], v[78:79], v[80:81] neg_lo:[0,1] neg_hi:[0,1]
	v_pk_add_f32 v[78:79], v[78:79], v[80:81]
	v_mov_b32_e32 v82, v83
	v_pk_add_f32 v[80:81], v[78:79], v[76:77] op_sel:[1,0] op_sel_hi:[0,1] neg_lo:[0,1] neg_hi:[0,1]
	v_pk_add_f32 v[88:89], v[84:85], v[80:81] op_sel_hi:[1,0] neg_lo:[0,1] neg_hi:[0,1]
	v_mov_b32_e32 v84, v85
	v_mov_b32_e32 v85, v79
	v_pk_mov_b32 v[80:81], v[76:77], v[80:81] op_sel:[1,0]
	v_mov_b32_e32 v83, v76
	v_pk_add_f32 v[80:81], v[84:85], v[80:81] neg_lo:[0,1] neg_hi:[0,1]
	v_mov_b32_e32 v88, v86
	v_pk_add_f32 v[76:77], v[82:83], v[80:81] neg_lo:[0,1] neg_hi:[0,1]
	v_mov_b32_e32 v87, v79
	v_pk_add_f32 v[80:81], v[88:89], v[76:77]
	s_nop 0
	v_pk_add_f32 v[82:83], v[80:81], v[80:81] op_sel:[0,1] op_sel_hi:[1,0]
	s_nop 0
	v_pk_add_f32 v[78:79], v[78:79], v[82:83] op_sel:[1,0] op_sel_hi:[0,1]
	v_mov_b32_e32 v81, v78
	v_pk_add_f32 v[84:85], v[80:81], v[86:87] neg_lo:[0,1] neg_hi:[0,1]
	v_mov_b32_e32 v77, v82
	v_sub_f32_e32 v79, v80, v84
	v_pk_add_f32 v[76:77], v[76:77], v[84:85] neg_lo:[0,1] neg_hi:[0,1]
	v_sub_f32_e32 v79, v86, v79
	v_add_f32_e32 v76, v76, v79
	v_add_f32_e32 v76, v76, v77
	v_add_f32_e32 v76, v78, v76
	v_cndmask_b32_e32 v76, v224, v76, vcc
	v_cmp_ngt_f32_e32 vcc, -1.0, v75
	s_nop 1
	v_cndmask_b32_e32 v76, v225, v76, vcc
	v_cmp_neq_f32_e32 vcc, -1.0, v75
	s_nop 1
	v_cndmask_b32_e32 v76, v226, v76, vcc
	v_cmp_lt_f32_e64 vcc, |v75|, s56
	s_nop 1
	v_cndmask_b32_e32 v75, v76, v75, vcc
	v_add_f32_e32 v73, v73, v75

.LBB0_1411:
	s_and_b64 vcc, exec, s[4:5]
	v_or_b32_e32 v72, 51, v74
	s_cbranch_vccnz .LBB0_1736
	s_and_b64 vcc, exec, s[6:7]
	v_mov_b32_e32 v73, v3
	s_cbranch_vccnz .LBB0_1414
	s_nop 0
	v_lshl_add_u64 v[66:67], v[66:67], 0, s[80:81]
	s_waitcnt lgkmcnt(0)
	v_lshl_add_u64 v[66:67], v[66:67], 2, s[4:5]
	v_mov_b32_e32 v66, v251
	s_nop 0
	v_add_f32_e32 v67, v3, v66
	v_max_f32_e32 v66, 0, v67
	v_mul_f32_e64 v67, |v67|, s73
	v_exp_f32_e32 v67, v67
	s_nop 0
	v_add_f32_e32 v73, 1.0, v67
	v_add_f32_e32 v74, -1.0, v73
	v_sub_f32_e32 v75, v74, v73
	v_add_f32_e32 v75, 1.0, v75
	v_sub_f32_e32 v74, v67, v74
	v_add_f32_e32 v76, v74, v75
	v_frexp_mant_f32_e32 v74, v73
	v_cmp_gt_f32_e32 vcc, s46, v74
	v_cvt_f64_f32_e32 v[74:75], v73
	v_frexp_exp_i32_f64_e32 v74, v[74:75]
	v_subbrev_co_u32_e32 v82, vcc, 0, v74, vcc
	v_sub_u32_e32 v74, 0, v82
	v_ldexp_f32 v73, v73, v74
	v_ldexp_f32 v74, v76, v74
	v_add_f32_e32 v76, -1.0, v73
	v_add_f32_e32 v75, 1.0, v76
	v_sub_f32_e32 v75, v73, v75
	v_add_f32_e32 v77, v74, v75
	v_add_f32_e32 v75, 1.0, v73
	v_add_f32_e32 v78, -1.0, v75
	v_sub_f32_e32 v73, v73, v78
	v_add_f32_e32 v73, v74, v73
	v_add_f32_e32 v83, v75, v73
	v_rcp_f32_e32 v84, v83
	v_sub_f32_e32 v74, v83, v75
	v_add_f32_e32 v75, v76, v77
	v_sub_f32_e32 v73, v73, v74
	v_mul_f32_e32 v86, v75, v84
	v_sub_f32_e32 v74, v75, v76
	v_mul_f32_e32 v76, v83, v86
	v_fma_f32 v78, v86, v83, -v76
	v_fmac_f32_e32 v78, v86, v73
	v_sub_f32_e32 v85, v77, v74
	v_add_f32_e32 v74, v76, v78
	v_sub_f32_e32 v77, v75, v74
	v_pk_add_f32 v[80:81], v[74:75], v[76:77] neg_lo:[0,1] neg_hi:[0,1]
	v_mov_b32_e32 v79, v74
	v_pk_add_f32 v[74:75], v[80:81], v[78:79] neg_lo:[0,1] neg_hi:[0,1]
	v_cmp_neq_f32_e32 vcc, s0, v67
	v_add_f32_e32 v75, v85, v75
	v_add_f32_e32 v74, v74, v75
	v_add_f32_e32 v75, v77, v74
	v_mul_f32_e32 v85, v84, v75
	v_mul_f32_e32 v76, v83, v85
	v_fma_f32 v78, v85, v83, -v76
	v_fmac_f32_e32 v78, v85, v73
	v_sub_f32_e32 v73, v77, v75
	v_add_f32_e32 v73, v74, v73
	v_add_f32_e32 v74, v76, v78
	v_sub_f32_e32 v77, v75, v74
	v_pk_add_f32 v[80:81], v[74:75], v[76:77] neg_lo:[0,1] neg_hi:[0,1]
	v_mov_b32_e32 v79, v74
	v_pk_add_f32 v[74:75], v[80:81], v[78:79] neg_lo:[0,1] neg_hi:[0,1]
	s_nop 0
	v_add_f32_e32 v73, v73, v75
	v_add_f32_e32 v73, v74, v73
	v_add_f32_e32 v75, v86, v85
	v_add_f32_e32 v73, v77, v73
	v_sub_f32_e32 v74, v75, v86
	v_mul_f32_e32 v73, v84, v73
	v_sub_f32_e32 v74, v85, v74
	v_add_f32_e32 v73, v74, v73
	v_add_f32_e32 v76, v75, v73
	v_mul_f32_e32 v78, v76, v76
	v_fmamk_f32 v74, v78, 0x3e9b6dac, v210
	v_fmaak_f32 v121, v78, v74, 0x3f2aaada
	v_cvt_f32_i32_e32 v74, v82
	v_sub_f32_e32 v75, v76, v75
	v_sub_f32_e32 v73, v73, v75
	v_mul_f32_e32 v75, v76, v78
	v_pk_mul_f32 v[78:79], v[74:75], v[120:121]
	v_ldexp_f32 v77, v76, 1
	v_fma_f32 v76, v74, s1, -v78
	v_fmac_f32_e32 v76, 0xb102e308, v74
	v_pk_add_f32 v[74:75], v[78:79], v[76:77]
	v_ldexp_f32 v73, v73, 1
	v_sub_f32_e32 v77, v75, v77
	v_sub_f32_e32 v77, v79, v77
	v_add_f32_e32 v81, v73, v77
	v_mov_b32_e32 v80, v78
	v_pk_add_f32 v[78:79], v[74:75], v[78:79] neg_lo:[0,1] neg_hi:[0,1]
	v_pk_add_f32 v[82:83], v[74:75], v[80:81]
	v_mov_b32_e32 v77, v74
	v_mov_b32_e32 v79, v83
	v_pk_add_f32 v[84:85], v[76:77], v[78:79] neg_lo:[0,1] neg_hi:[0,1]
	v_pk_add_f32 v[76:77], v[76:77], v[78:79]
	v_mov_b32_e32 v80, v81
	v_pk_add_f32 v[78:79], v[76:77], v[74:75] op_sel:[1,0] op_sel_hi:[0,1] neg_lo:[0,1] neg_hi:[0,1]
	v_pk_add_f32 v[86:87], v[82:83], v[78:79] op_sel_hi:[1,0] neg_lo:[0,1] neg_hi:[0,1]
	v_mov_b32_e32 v82, v83
	v_mov_b32_e32 v83, v77
	v_pk_mov_b32 v[78:79], v[74:75], v[78:79] op_sel:[1,0]
	v_mov_b32_e32 v81, v74
	v_pk_add_f32 v[78:79], v[82:83], v[78:79] neg_lo:[0,1] neg_hi:[0,1]
	v_mov_b32_e32 v86, v84
	v_pk_add_f32 v[74:75], v[80:81], v[78:79] neg_lo:[0,1] neg_hi:[0,1]
	v_mov_b32_e32 v85, v77
	v_pk_add_f32 v[78:79], v[86:87], v[74:75]
	s_nop 0
	v_pk_add_f32 v[80:81], v[78:79], v[78:79] op_sel:[0,1] op_sel_hi:[1,0]
	s_nop 0
	v_pk_add_f32 v[76:77], v[76:77], v[80:81] op_sel:[1,0] op_sel_hi:[0,1]
	v_mov_b32_e32 v79, v76
	v_pk_add_f32 v[82:83], v[78:79], v[84:85] neg_lo:[0,1] neg_hi:[0,1]
	v_mov_b32_e32 v75, v80
	v_sub_f32_e32 v73, v78, v82
	v_pk_add_f32 v[74:75], v[74:75], v[82:83] neg_lo:[0,1] neg_hi:[0,1]
	v_sub_f32_e32 v73, v84, v73
	v_add_f32_e32 v73, v74, v73
	v_add_f32_e32 v73, v73, v75
	v_add_f32_e32 v73, v76, v73
	v_cndmask_b32_e32 v73, v224, v73, vcc
	v_cmp_ngt_f32_e32 vcc, -1.0, v67
	s_nop 1
	v_cndmask_b32_e32 v73, v225, v73, vcc
	v_cmp_neq_f32_e32 vcc, -1.0, v67
	s_nop 1
	v_cndmask_b32_e32 v73, v226, v73, vcc
	v_cmp_lt_f32_e64 vcc, |v67|, s56
	s_nop 1
	v_cndmask_b32_e32 v67, v73, v67, vcc
	v_add_f32_e32 v73, v66, v67
